# same as previous version plus two wait states after packed-f32 ops in the row sum-of-squares (hazard-clean); no functional change
# speedup vs baseline: 1.0249x; 1.0041x over previous
; __device__ __forceinline__ unsigned pk_bf16(float lo, float hi) { const f32x2 v = {lo, hi}; const bf16x2_t b = __builtin_convertvector(v, bf16x2_t); return __builtin_bit_cast(unsigned, b); }
; template <bool HAS_F, bool HAS_H>
; __device__ __forceinline__ void phase_rows(const Params& p, int sp, int sn, float resw, bool from_input, bool write_x = true) {
;     ...
;         const float* xin = !from_input ? p.out + (size_t)row * D : (row < TP ? p.in[0] + (size_t)row * D : p.in[1] + (size_t)(row - TP) * D);
;         f32x4 v[4];
; #pragma unroll
;         for (int j = 0; j < 4; ++j) v[j] = *(const f32x4*)(xin + 4 * lane + 256 * j);
;     ...
;             float ss = 0.f;
; #pragma unroll
;             for (int j = 0; j < 4; ++j) ss += (v[j].x * v[j].x + v[j].y * v[j].y) + (v[j].z * v[j].z + v[j].w * v[j].w);
;             const float rs = 1.0f / sqrtf(wave_sum(ss) * (1.0f / D) + EPS);
;             const float* sh = mod + b * 9216 + sn * 3072; const float* scl = sh + 1024; const float* gq = p.in[6] + sn * D;
; #pragma unroll
;             for (int j = 0; j < 4; ++j) { const f32x4 a = *(const f32x4*)(sh + 4 * lane + 256 * j), s = *(const f32x4*)(scl + 4 * lane + 256 * j), q = *(const f32x4*)(gq + 4 * lane + 256 * j);
;                 const f32x4 h = (v[j] * rs * q) * (s + 1.0f) + a;
;                 u32x2 w; w.x = pk_bf16(h.x, h.y); w.y = pk_bf16(h.z, h.w);
;                 *(u32x2*)(H + (size_t)row * D + 4 * lane + 256 * j) = w; }
.Lrp1_pk4:
	s_waitcnt vmcnt(8)
	v_pk_mul_f32 v[102:103], v[4:5], v[4:5]
	v_pk_mul_f32 v[106:107], v[6:7], v[6:7]
	v_pk_fma_f32 v[102:103], v[8:9], v[8:9], v[102:103]
	v_pk_fma_f32 v[106:107], v[10:11], v[10:11], v[106:107]
	v_pk_fma_f32 v[102:103], v[12:13], v[12:13], v[102:103]
	v_pk_fma_f32 v[106:107], v[14:15], v[14:15], v[106:107]
	v_pk_fma_f32 v[102:103], v[16:17], v[16:17], v[102:103]
	v_pk_fma_f32 v[106:107], v[18:19], v[18:19], v[106:107]
	s_nop 0
	v_pk_add_f32 v[102:103], v[102:103], v[106:107]
	s_nop 0
	v_add_f32_e32 v102, v102, v103
	s_nop 1
	v_add_f32_dpp v102, v102, v102 quad_perm:[1,0,3,2] row_mask:0xf bank_mask:0xf
	s_nop 1
	v_add_f32_dpp v102, v102, v102 quad_perm:[2,3,0,1] row_mask:0xf bank_mask:0xf
	s_nop 1
	v_add_f32_dpp v102, v102, v102 row_half_mirror row_mask:0xf bank_mask:0xf
	s_nop 1
	v_add_f32_dpp v102, v102, v102 row_mirror row_mask:0xf bank_mask:0xf
	s_nop 1
	v_add_f32_dpp v102, v102, v102 row_bcast:15 row_mask:0xa bank_mask:0xf
	s_nop 1
	v_add_f32_dpp v102, v102, v102 row_bcast:31 row_mask:0xc bank_mask:0xf
	s_nop 1
	v_readlane_b32 s74, v102, 63
	s_nop 2
	v_mov_b32_e32 v102, s74
	v_fmamk_f32 v102, v102, 0x3a800000, v2
	v_mul_f32_e32 v103, 0x4f800000, v102
	v_cmp_gt_f32_e32 vcc, 0xf800000, v102
	s_nop 1
	v_cndmask_b32_e32 v102, v102, v103, vcc
	v_sqrt_f32_e32 v103, v102
	s_nop 0
	v_add_u32_e32 v104, -1, v103
	v_add_u32_e32 v106, 1, v103
	v_fma_f32 v107, -v104, v103, v102
	v_fma_f32 v108, -v106, v103, v102
	v_cmp_ge_f32_e64 s[76:77], 0, v107
	s_nop 1
	v_cndmask_b32_e64 v103, v103, v104, s[76:77]
	v_cmp_lt_f32_e64 s[76:77], 0, v108
	s_nop 1
	v_cndmask_b32_e64 v103, v103, v106, s[76:77]
	v_mul_f32_e32 v104, 0x37800000, v103
	v_cndmask_b32_e32 v103, v103, v104, vcc
	v_cmp_class_f32_e32 vcc, v102, v3
	s_nop 1
	v_cndmask_b32_e32 v102, v103, v102, vcc
	v_div_scale_f32 v103, s[76:77], v102, v102, 1.0
	v_rcp_f32_e32 v104, v103
	v_div_scale_f32 v106, vcc, 1.0, v102, 1.0
	v_fma_f32 v107, -v103, v104, 1.0
	v_fmac_f32_e32 v104, v107, v104
	v_mul_f32_e32 v107, v106, v104
	v_fma_f32 v108, -v103, v107, v106
	v_fmac_f32_e32 v107, v108, v104
	v_fma_f32 v103, -v103, v107, v106
	v_div_fmas_f32 v103, v103, v104, v107
	v_div_fixup_f32 v110, v103, v102, 1.0
	s_lshl_b32 s60, s55, 11
	s_add_u32 s70, s78, s60
	s_addc_u32 s71, s79, 0
	v_pk_mul_f32 v[112:113], v[4:5], v[110:111] op_sel_hi:[1,0]
	v_pk_mul_f32 v[114:115], v[6:7], v[110:111] op_sel_hi:[1,0]
	v_pk_mul_f32 v[116:117], v[8:9], v[110:111] op_sel_hi:[1,0]
	v_pk_mul_f32 v[118:119], v[10:11], v[110:111] op_sel_hi:[1,0]
	v_pk_mul_f32 v[120:121], v[12:13], v[110:111] op_sel_hi:[1,0]
	v_pk_mul_f32 v[122:123], v[14:15], v[110:111] op_sel_hi:[1,0]
	v_pk_mul_f32 v[124:125], v[16:17], v[110:111] op_sel_hi:[1,0]
	v_pk_mul_f32 v[100:101], v[18:19], v[110:111] op_sel_hi:[1,0]
	v_pk_mul_f32 v[112:113], v[160:161], v[112:113]
	v_pk_mul_f32 v[114:115], v[162:163], v[114:115]
	v_pk_mul_f32 v[116:117], v[164:165], v[116:117]
	v_pk_mul_f32 v[118:119], v[166:167], v[118:119]
	v_pk_mul_f32 v[120:121], v[168:169], v[120:121]
	v_pk_mul_f32 v[122:123], v[170:171], v[122:123]
	v_pk_mul_f32 v[124:125], v[172:173], v[124:125]
	v_pk_mul_f32 v[100:101], v[174:175], v[100:101]
	v_pk_fma_f32 v[112:113], v[176:177], v[112:113], v[192:193]
	v_pk_fma_f32 v[114:115], v[178:179], v[114:115], v[194:195]
	v_pk_fma_f32 v[116:117], v[180:181], v[116:117], v[196:197]
	v_pk_fma_f32 v[118:119], v[182:183], v[118:119], v[198:199]
	v_pk_fma_f32 v[120:121], v[184:185], v[120:121], v[200:201]
	v_pk_fma_f32 v[122:123], v[186:187], v[122:123], v[202:203]
	v_pk_fma_f32 v[124:125], v[188:189], v[124:125], v[204:205]
	v_pk_fma_f32 v[100:101], v[190:191], v[100:101], v[206:207]
	v_cvt_pk_bf16_f32 v240, v112, v113
	v_cvt_pk_bf16_f32 v241, v114, v115
	v_cvt_pk_bf16_f32 v242, v116, v117
	v_cvt_pk_bf16_f32 v243, v118, v119
	v_cvt_pk_bf16_f32 v244, v120, v121
	v_cvt_pk_bf16_f32 v245, v122, v123
	v_cvt_pk_bf16_f32 v246, v124, v125
	v_cvt_pk_bf16_f32 v247, v100, v101
	global_store_dwordx2 v1, v[240:241], s[70:71]
	global_store_dwordx2 v1, v[242:243], s[70:71] offset:512
	global_store_dwordx2 v1, v[244:245], s[70:71] offset:1024
	global_store_dwordx2 v1, v[246:247], s[70:71] offset:1536
	s_add_u32 s55, s55, 8
	s_add_u32 s57, s55, 16
	s_min_u32 s57, s57, s54
	s_cmp_lt_u32 s57, 0x8000
	s_cselect_b32 s64, s8, s10
	s_cselect_b32 s65, s9, s11
	s_cselect_b32 s60, 0, 0x8000
	s_sub_u32 s60, s57, s60
	s_lshl_b32 s60, s60, 12
	s_add_u32 s64, s64, s60
	s_addc_u32 s65, s65, 0
	global_load_dwordx4 v[4:7], v0, s[64:65] nt
	global_load_dwordx4 v[8:11], v0, s[64:65] offset:1024 nt
	global_load_dwordx4 v[12:15], v0, s[64:65] offset:2048 nt
	global_load_dwordx4 v[16:19], v0, s[64:65] offset:3072 nt
	s_lshr_b32 s60, s55, 11
	s_sub_u32 s61, s55, 0x8000
	s_lshr_b32 s61, s61, 12
	s_add_u32 s61, s61, 16
	s_cmp_lt_u32 s55, 0x8000
	s_cselect_b32 s63, s60, s61
	s_cmp_eq_u32 s63, s56
	s_cbranch_scc1 .Lrp1_pk5
	s_mov_b32 s56, s63
	s_add_u32 s0, s20, 0x0
	s_addc_u32 s1, s21, 0
	global_load_dwordx4 v[160:163], v0, s[0:1]
	global_load_dwordx4 v[164:167], v0, s[0:1] offset:1024
	global_load_dwordx4 v[168:171], v0, s[0:1] offset:2048
	global_load_dwordx4 v[172:175], v0, s[0:1] offset:3072
	s_mul_i32 s60, s56, 0x9000
	s_add_u32 s60, s60, 0x3181000
	s_add_u32 s0, s92, s60
	s_addc_u32 s1, s93, 0
	global_load_dwordx4 v[176:179], v0, s[0:1]
	global_load_dwordx4 v[180:183], v0, s[0:1] offset:1024
	global_load_dwordx4 v[184:187], v0, s[0:1] offset:2048
	global_load_dwordx4 v[188:191], v0, s[0:1] offset:3072
	s_mul_i32 s60, s56, 0x9000
	s_add_u32 s60, s60, 0x3180000
	s_add_u32 s0, s92, s60
	s_addc_u32 s1, s93, 0
	global_load_dwordx4 v[192:195], v0, s[0:1]
	global_load_dwordx4 v[196:199], v0, s[0:1] offset:1024
	global_load_dwordx4 v[200:203], v0, s[0:1] offset:2048
	global_load_dwordx4 v[204:207], v0, s[0:1] offset:3072
	s_waitcnt vmcnt(0)
	v_pk_add_f32 v[176:177], v[176:177], 1.0 op_sel_hi:[1,0]
	v_pk_add_f32 v[178:179], v[178:179], 1.0 op_sel_hi:[1,0]
	v_pk_add_f32 v[180:181], v[180:181], 1.0 op_sel_hi:[1,0]
	v_pk_add_f32 v[182:183], v[182:183], 1.0 op_sel_hi:[1,0]
	v_pk_add_f32 v[184:185], v[184:185], 1.0 op_sel_hi:[1,0]
	v_pk_add_f32 v[186:187], v[186:187], 1.0 op_sel_hi:[1,0]
	v_pk_add_f32 v[188:189], v[188:189], 1.0 op_sel_hi:[1,0]
	v_pk_add_f32 v[190:191], v[190:191], 1.0 op_sel_hi:[1,0]
; __device__ __forceinline__ unsigned pk_bf16(float lo, float hi) { const f32x2 v = {lo, hi}; const bf16x2_t b = __builtin_convertvector(v, bf16x2_t); return __builtin_bit_cast(unsigned, b); }
; template <bool HAS_F, bool HAS_H>
; __device__ __forceinline__ void phase_rows(const Params& p, int sp, int sn, float resw, bool from_input, bool write_x = true) {
;     ...
;         const float* xin = !from_input ? p.out + (size_t)row * D : (row < TP ? p.in[0] + (size_t)row * D : p.in[1] + (size_t)(row - TP) * D);
;         f32x4 v[4];
; #pragma unroll
;         for (int j = 0; j < 4; ++j) v[j] = *(const f32x4*)(xin + 4 * lane + 256 * j);
;     ...
;             float ss = 0.f;
; #pragma unroll
;             for (int j = 0; j < 4; ++j) ss += (v[j].x * v[j].x + v[j].y * v[j].y) + (v[j].z * v[j].z + v[j].w * v[j].w);
;             const float rs = 1.0f / sqrtf(wave_sum(ss) * (1.0f / D) + EPS);
;             const float* sh = mod + b * 9216 + sn * 3072; const float* scl = sh + 1024; const float* gq = p.in[6] + sn * D;
; #pragma unroll
;             for (int j = 0; j < 4; ++j) { const f32x4 a = *(const f32x4*)(sh + 4 * lane + 256 * j), s = *(const f32x4*)(scl + 4 * lane + 256 * j), q = *(const f32x4*)(gq + 4 * lane + 256 * j);
;                 const f32x4 h = (v[j] * rs * q) * (s + 1.0f) + a;
;                 u32x2 w; w.x = pk_bf16(h.x, h.y); w.y = pk_bf16(h.z, h.w);
;                 *(u32x2*)(H + (size_t)row * D + 4 * lane + 256 * j) = w; }
.Lrp1_pk5:
	s_waitcnt vmcnt(12)
	v_pk_mul_f32 v[102:103], v[36:37], v[36:37]
	v_pk_mul_f32 v[106:107], v[38:39], v[38:39]
	v_pk_fma_f32 v[102:103], v[40:41], v[40:41], v[102:103]
	v_pk_fma_f32 v[106:107], v[42:43], v[42:43], v[106:107]
	v_pk_fma_f32 v[102:103], v[44:45], v[44:45], v[102:103]
	v_pk_fma_f32 v[106:107], v[46:47], v[46:47], v[106:107]
	v_pk_fma_f32 v[102:103], v[48:49], v[48:49], v[102:103]
	v_pk_fma_f32 v[106:107], v[50:51], v[50:51], v[106:107]
	s_nop 0
	v_pk_add_f32 v[102:103], v[102:103], v[106:107]
	s_nop 0
	v_add_f32_e32 v102, v102, v103
	s_nop 1
	v_add_f32_dpp v102, v102, v102 quad_perm:[1,0,3,2] row_mask:0xf bank_mask:0xf
	s_nop 1
	v_add_f32_dpp v102, v102, v102 quad_perm:[2,3,0,1] row_mask:0xf bank_mask:0xf
	s_nop 1
	v_add_f32_dpp v102, v102, v102 row_half_mirror row_mask:0xf bank_mask:0xf
	s_nop 1
	v_add_f32_dpp v102, v102, v102 row_mirror row_mask:0xf bank_mask:0xf
	s_nop 1
	v_add_f32_dpp v102, v102, v102 row_bcast:15 row_mask:0xa bank_mask:0xf
	s_nop 1
	v_add_f32_dpp v102, v102, v102 row_bcast:31 row_mask:0xc bank_mask:0xf
	s_nop 1
	v_readlane_b32 s74, v102, 63
	s_nop 2
	v_mov_b32_e32 v102, s74
	v_fmamk_f32 v102, v102, 0x3a800000, v2
	v_mul_f32_e32 v103, 0x4f800000, v102
	v_cmp_gt_f32_e32 vcc, 0xf800000, v102
	s_nop 1
	v_cndmask_b32_e32 v102, v102, v103, vcc
	v_sqrt_f32_e32 v103, v102
	s_nop 0
	v_add_u32_e32 v104, -1, v103
	v_add_u32_e32 v106, 1, v103
	v_fma_f32 v107, -v104, v103, v102
	v_fma_f32 v108, -v106, v103, v102
	v_cmp_ge_f32_e64 s[76:77], 0, v107
	s_nop 1
	v_cndmask_b32_e64 v103, v103, v104, s[76:77]
	v_cmp_lt_f32_e64 s[76:77], 0, v108
	s_nop 1
	v_cndmask_b32_e64 v103, v103, v106, s[76:77]
	v_mul_f32_e32 v104, 0x37800000, v103
	v_cndmask_b32_e32 v103, v103, v104, vcc
	v_cmp_class_f32_e32 vcc, v102, v3
	s_nop 1
	v_cndmask_b32_e32 v102, v103, v102, vcc
	v_div_scale_f32 v103, s[76:77], v102, v102, 1.0
	v_rcp_f32_e32 v104, v103
	v_div_scale_f32 v106, vcc, 1.0, v102, 1.0
	v_fma_f32 v107, -v103, v104, 1.0
	v_fmac_f32_e32 v104, v107, v104
	v_mul_f32_e32 v107, v106, v104
	v_fma_f32 v108, -v103, v107, v106
	v_fmac_f32_e32 v107, v108, v104
	v_fma_f32 v103, -v103, v107, v106
	v_div_fmas_f32 v103, v103, v104, v107
	v_div_fixup_f32 v110, v103, v102, 1.0
	s_lshl_b32 s60, s55, 11
	s_add_u32 s70, s78, s60
	s_addc_u32 s71, s79, 0
	v_pk_mul_f32 v[112:113], v[36:37], v[110:111] op_sel_hi:[1,0]
	v_pk_mul_f32 v[114:115], v[38:39], v[110:111] op_sel_hi:[1,0]
	v_pk_mul_f32 v[116:117], v[40:41], v[110:111] op_sel_hi:[1,0]
	v_pk_mul_f32 v[118:119], v[42:43], v[110:111] op_sel_hi:[1,0]
	v_pk_mul_f32 v[120:121], v[44:45], v[110:111] op_sel_hi:[1,0]
	v_pk_mul_f32 v[122:123], v[46:47], v[110:111] op_sel_hi:[1,0]
	v_pk_mul_f32 v[124:125], v[48:49], v[110:111] op_sel_hi:[1,0]
	v_pk_mul_f32 v[100:101], v[50:51], v[110:111] op_sel_hi:[1,0]
	v_pk_mul_f32 v[112:113], v[160:161], v[112:113]
	v_pk_mul_f32 v[114:115], v[162:163], v[114:115]
	v_pk_mul_f32 v[116:117], v[164:165], v[116:117]
	v_pk_mul_f32 v[118:119], v[166:167], v[118:119]
	v_pk_mul_f32 v[120:121], v[168:169], v[120:121]
	v_pk_mul_f32 v[122:123], v[170:171], v[122:123]
	v_pk_mul_f32 v[124:125], v[172:173], v[124:125]
	v_pk_mul_f32 v[100:101], v[174:175], v[100:101]
	v_pk_fma_f32 v[112:113], v[176:177], v[112:113], v[192:193]
	v_pk_fma_f32 v[114:115], v[178:179], v[114:115], v[194:195]
	v_pk_fma_f32 v[116:117], v[180:181], v[116:117], v[196:197]
	v_pk_fma_f32 v[118:119], v[182:183], v[118:119], v[198:199]
	v_pk_fma_f32 v[120:121], v[184:185], v[120:121], v[200:201]
	v_pk_fma_f32 v[122:123], v[186:187], v[122:123], v[202:203]
	v_pk_fma_f32 v[124:125], v[188:189], v[124:125], v[204:205]
	v_pk_fma_f32 v[100:101], v[190:191], v[100:101], v[206:207]
	v_cvt_pk_bf16_f32 v240, v112, v113
	v_cvt_pk_bf16_f32 v241, v114, v115
	v_cvt_pk_bf16_f32 v242, v116, v117
	v_cvt_pk_bf16_f32 v243, v118, v119
	v_cvt_pk_bf16_f32 v244, v120, v121
	v_cvt_pk_bf16_f32 v245, v122, v123
	v_cvt_pk_bf16_f32 v246, v124, v125
	v_cvt_pk_bf16_f32 v247, v100, v101
	global_store_dwordx2 v1, v[240:241], s[70:71]
	global_store_dwordx2 v1, v[242:243], s[70:71] offset:512
	global_store_dwordx2 v1, v[244:245], s[70:71] offset:1024
	global_store_dwordx2 v1, v[246:247], s[70:71] offset:1536
	s_add_u32 s55, s55, 8
	s_add_u32 s57, s55, 16
	s_min_u32 s57, s57, s54
	s_cmp_lt_u32 s57, 0x8000
	s_cselect_b32 s64, s8, s10
	s_cselect_b32 s65, s9, s11
	s_cselect_b32 s60, 0, 0x8000
	s_sub_u32 s60, s57, s60
	s_lshl_b32 s60, s60, 12
	s_add_u32 s64, s64, s60
	s_addc_u32 s65, s65, 0
	global_load_dwordx4 v[36:39], v0, s[64:65] nt
	global_load_dwordx4 v[40:43], v0, s[64:65] offset:1024 nt
	global_load_dwordx4 v[44:47], v0, s[64:65] offset:2048 nt
	global_load_dwordx4 v[48:51], v0, s[64:65] offset:3072 nt
	s_lshr_b32 s60, s55, 11
	s_sub_u32 s61, s55, 0x8000
	s_lshr_b32 s61, s61, 12
	s_add_u32 s61, s61, 16
	s_cmp_lt_u32 s55, 0x8000
	s_cselect_b32 s63, s60, s61
	s_cmp_eq_u32 s63, s56
	s_cbranch_scc1 .Lrp1_pk6
	s_mov_b32 s56, s63
	s_add_u32 s0, s20, 0x0
	s_addc_u32 s1, s21, 0
	global_load_dwordx4 v[160:163], v0, s[0:1]
	global_load_dwordx4 v[164:167], v0, s[0:1] offset:1024
	global_load_dwordx4 v[168:171], v0, s[0:1] offset:2048
	global_load_dwordx4 v[172:175], v0, s[0:1] offset:3072
	s_mul_i32 s60, s56, 0x9000
	s_add_u32 s60, s60, 0x3181000
	s_add_u32 s0, s92, s60
	s_addc_u32 s1, s93, 0
	global_load_dwordx4 v[176:179], v0, s[0:1]
	global_load_dwordx4 v[180:183], v0, s[0:1] offset:1024
	global_load_dwordx4 v[184:187], v0, s[0:1] offset:2048
	global_load_dwordx4 v[188:191], v0, s[0:1] offset:3072
	s_mul_i32 s60, s56, 0x9000
	s_add_u32 s60, s60, 0x3180000
	s_add_u32 s0, s92, s60
	s_addc_u32 s1, s93, 0
	global_load_dwordx4 v[192:195], v0, s[0:1]
	global_load_dwordx4 v[196:199], v0, s[0:1] offset:1024
	global_load_dwordx4 v[200:203], v0, s[0:1] offset:2048
	global_load_dwordx4 v[204:207], v0, s[0:1] offset:3072
	s_waitcnt vmcnt(0)
	v_pk_add_f32 v[176:177], v[176:177], 1.0 op_sel_hi:[1,0]
	v_pk_add_f32 v[178:179], v[178:179], 1.0 op_sel_hi:[1,0]
	v_pk_add_f32 v[180:181], v[180:181], 1.0 op_sel_hi:[1,0]
	v_pk_add_f32 v[182:183], v[182:183], 1.0 op_sel_hi:[1,0]
	v_pk_add_f32 v[184:185], v[184:185], 1.0 op_sel_hi:[1,0]
	v_pk_add_f32 v[186:187], v[186:187], 1.0 op_sel_hi:[1,0]
	v_pk_add_f32 v[188:189], v[188:189], 1.0 op_sel_hi:[1,0]
	v_pk_add_f32 v[190:191], v[190:191], 1.0 op_sel_hi:[1,0]
; __device__ __forceinline__ unsigned pk_bf16(float lo, float hi) { const f32x2 v = {lo, hi}; const bf16x2_t b = __builtin_convertvector(v, bf16x2_t); return __builtin_bit_cast(unsigned, b); }
; template <bool HAS_F, bool HAS_H>
; __device__ __forceinline__ void phase_rows(const Params& p, int sp, int sn, float resw, bool from_input, bool write_x = true) {
;     ...
;             float ss = 0.f;
; #pragma unroll
;             for (int j = 0; j < 4; ++j) ss += (v[j].x * v[j].x + v[j].y * v[j].y) + (v[j].z * v[j].z + v[j].w * v[j].w);
;             const float rs = 1.0f / sqrtf(wave_sum(ss) * (1.0f / D) + EPS);
;             const float* sh = mod + b * 9216 + sn * 3072; const float* scl = sh + 1024; const float* gq = p.in[6] + sn * D;
; #pragma unroll
;             for (int j = 0; j < 4; ++j) { const f32x4 a = *(const f32x4*)(sh + 4 * lane + 256 * j), s = *(const f32x4*)(scl + 4 * lane + 256 * j), q = *(const f32x4*)(gq + 4 * lane + 256 * j);
;                 const f32x4 h = (v[j] * rs * q) * (s + 1.0f) + a;
;                 u32x2 w; w.x = pk_bf16(h.x, h.y); w.y = pk_bf16(h.z, h.w);
;                 *(u32x2*)(H + (size_t)row * D + 4 * lane + 256 * j) = w; }
.Lrp1_pk6:
	s_waitcnt vmcnt(16)
	v_pk_mul_f32 v[102:103], v[68:69], v[68:69]
	v_pk_mul_f32 v[106:107], v[70:71], v[70:71]
	v_pk_fma_f32 v[102:103], v[72:73], v[72:73], v[102:103]
	v_pk_fma_f32 v[106:107], v[74:75], v[74:75], v[106:107]
	v_pk_fma_f32 v[102:103], v[76:77], v[76:77], v[102:103]
	v_pk_fma_f32 v[106:107], v[78:79], v[78:79], v[106:107]
	v_pk_fma_f32 v[102:103], v[80:81], v[80:81], v[102:103]
	v_pk_fma_f32 v[106:107], v[82:83], v[82:83], v[106:107]
	s_nop 0
	v_pk_add_f32 v[102:103], v[102:103], v[106:107]
	s_nop 0
	v_add_f32_e32 v102, v102, v103
	s_nop 1
	v_add_f32_dpp v102, v102, v102 quad_perm:[1,0,3,2] row_mask:0xf bank_mask:0xf
	s_nop 1
	v_add_f32_dpp v102, v102, v102 quad_perm:[2,3,0,1] row_mask:0xf bank_mask:0xf
	s_nop 1
	v_add_f32_dpp v102, v102, v102 row_half_mirror row_mask:0xf bank_mask:0xf
	s_nop 1
	v_add_f32_dpp v102, v102, v102 row_mirror row_mask:0xf bank_mask:0xf
	s_nop 1
	v_add_f32_dpp v102, v102, v102 row_bcast:15 row_mask:0xa bank_mask:0xf
	s_nop 1
	v_add_f32_dpp v102, v102, v102 row_bcast:31 row_mask:0xc bank_mask:0xf
	s_nop 1
	v_readlane_b32 s74, v102, 63
	s_nop 2
	v_mov_b32_e32 v102, s74
	v_fmamk_f32 v102, v102, 0x3a800000, v2
	v_mul_f32_e32 v103, 0x4f800000, v102
	v_cmp_gt_f32_e32 vcc, 0xf800000, v102
	s_nop 1
	v_cndmask_b32_e32 v102, v102, v103, vcc
	v_sqrt_f32_e32 v103, v102
	s_nop 0
	v_add_u32_e32 v104, -1, v103
	v_add_u32_e32 v106, 1, v103
	v_fma_f32 v107, -v104, v103, v102
	v_fma_f32 v108, -v106, v103, v102
	v_cmp_ge_f32_e64 s[76:77], 0, v107
	s_nop 1
	v_cndmask_b32_e64 v103, v103, v104, s[76:77]
	v_cmp_lt_f32_e64 s[76:77], 0, v108
	s_nop 1
	v_cndmask_b32_e64 v103, v103, v106, s[76:77]
	v_mul_f32_e32 v104, 0x37800000, v103
	v_cndmask_b32_e32 v103, v103, v104, vcc
	v_cmp_class_f32_e32 vcc, v102, v3
	s_nop 1
	v_cndmask_b32_e32 v102, v103, v102, vcc
	v_div_scale_f32 v103, s[76:77], v102, v102, 1.0
	v_rcp_f32_e32 v104, v103
	v_div_scale_f32 v106, vcc, 1.0, v102, 1.0
	v_fma_f32 v107, -v103, v104, 1.0
	v_fmac_f32_e32 v104, v107, v104
	v_mul_f32_e32 v107, v106, v104
	v_fma_f32 v108, -v103, v107, v106
	v_fmac_f32_e32 v107, v108, v104
	v_fma_f32 v103, -v103, v107, v106
	v_div_fmas_f32 v103, v103, v104, v107
	v_div_fixup_f32 v110, v103, v102, 1.0
	s_lshl_b32 s60, s55, 11
	s_add_u32 s70, s78, s60
	s_addc_u32 s71, s79, 0
	v_pk_mul_f32 v[112:113], v[68:69], v[110:111] op_sel_hi:[1,0]
	v_pk_mul_f32 v[114:115], v[70:71], v[110:111] op_sel_hi:[1,0]
	v_pk_mul_f32 v[116:117], v[72:73], v[110:111] op_sel_hi:[1,0]
	v_pk_mul_f32 v[118:119], v[74:75], v[110:111] op_sel_hi:[1,0]
	v_pk_mul_f32 v[120:121], v[76:77], v[110:111] op_sel_hi:[1,0]
	v_pk_mul_f32 v[122:123], v[78:79], v[110:111] op_sel_hi:[1,0]
	v_pk_mul_f32 v[124:125], v[80:81], v[110:111] op_sel_hi:[1,0]
	v_pk_mul_f32 v[100:101], v[82:83], v[110:111] op_sel_hi:[1,0]
	v_pk_mul_f32 v[112:113], v[160:161], v[112:113]
	v_pk_mul_f32 v[114:115], v[162:163], v[114:115]
	v_pk_mul_f32 v[116:117], v[164:165], v[116:117]
	v_pk_mul_f32 v[118:119], v[166:167], v[118:119]
	v_pk_mul_f32 v[120:121], v[168:169], v[120:121]
	v_pk_mul_f32 v[122:123], v[170:171], v[122:123]
	v_pk_mul_f32 v[124:125], v[172:173], v[124:125]
	v_pk_mul_f32 v[100:101], v[174:175], v[100:101]
	v_pk_fma_f32 v[112:113], v[176:177], v[112:113], v[192:193]
	v_pk_fma_f32 v[114:115], v[178:179], v[114:115], v[194:195]
	v_pk_fma_f32 v[116:117], v[180:181], v[116:117], v[196:197]
	v_pk_fma_f32 v[118:119], v[182:183], v[118:119], v[198:199]
	v_pk_fma_f32 v[120:121], v[184:185], v[120:121], v[200:201]
	v_pk_fma_f32 v[122:123], v[186:187], v[122:123], v[202:203]
	v_pk_fma_f32 v[124:125], v[188:189], v[124:125], v[204:205]
	v_pk_fma_f32 v[100:101], v[190:191], v[100:101], v[206:207]
	v_cvt_pk_bf16_f32 v240, v112, v113
	v_cvt_pk_bf16_f32 v241, v114, v115
	v_cvt_pk_bf16_f32 v242, v116, v117
	v_cvt_pk_bf16_f32 v243, v118, v119
	v_cvt_pk_bf16_f32 v244, v120, v121
	v_cvt_pk_bf16_f32 v245, v122, v123
	v_cvt_pk_bf16_f32 v246, v124, v125
	v_cvt_pk_bf16_f32 v247, v100, v101
	global_store_dwordx2 v1, v[240:241], s[70:71]
	global_store_dwordx2 v1, v[242:243], s[70:71] offset:512
	global_store_dwordx2 v1, v[244:245], s[70:71] offset:1024
	global_store_dwordx2 v1, v[246:247], s[70:71] offset:1536
	s_add_u32 s55, s55, 8

; __device__ __forceinline__ unsigned pk_bf16(float lo, float hi) { const f32x2 v = {lo, hi}; const bf16x2_t b = __builtin_convertvector(v, bf16x2_t); return __builtin_bit_cast(unsigned, b); }
; template <bool HAS_F, bool HAS_H>
; __device__ __forceinline__ void phase_rows(const Params& p, int sp, int sn, float resw, bool from_input, bool write_x = true) {
;     ...
;         const float* xin = !from_input ? p.out + (size_t)row * D : (row < TP ? p.in[0] + (size_t)row * D : p.in[1] + (size_t)(row - TP) * D);
;         f32x4 v[4];
; #pragma unroll
;         for (int j = 0; j < 4; ++j) v[j] = *(const f32x4*)(xin + 4 * lane + 256 * j);
;     ...
;             float ss = 0.f;
; #pragma unroll
;             for (int j = 0; j < 4; ++j) ss += (v[j].x * v[j].x + v[j].y * v[j].y) + (v[j].z * v[j].z + v[j].w * v[j].w);
;             const float rs = 1.0f / sqrtf(wave_sum(ss) * (1.0f / D) + EPS);
;             const float* sh = mod + b * 9216 + sn * 3072; const float* scl = sh + 1024; const float* gq = p.in[6] + sn * D;
; #pragma unroll
;             for (int j = 0; j < 4; ++j) { const f32x4 a = *(const f32x4*)(sh + 4 * lane + 256 * j), s = *(const f32x4*)(scl + 4 * lane + 256 * j), q = *(const f32x4*)(gq + 4 * lane + 256 * j);
;                 const f32x4 h = (v[j] * rs * q) * (s + 1.0f) + a;
;                 u32x2 w; w.x = pk_bf16(h.x, h.y); w.y = pk_bf16(h.z, h.w);
;                 *(u32x2*)(H + (size_t)row * D + 4 * lane + 256 * j) = w; }
.Lrp1_pk7:
	s_waitcnt vmcnt(16)
	v_pk_mul_f32 v[102:103], v[4:5], v[4:5]
	v_pk_mul_f32 v[106:107], v[6:7], v[6:7]
	v_pk_fma_f32 v[102:103], v[8:9], v[8:9], v[102:103]
	v_pk_fma_f32 v[106:107], v[10:11], v[10:11], v[106:107]
	v_pk_fma_f32 v[102:103], v[12:13], v[12:13], v[102:103]
	v_pk_fma_f32 v[106:107], v[14:15], v[14:15], v[106:107]
	v_pk_fma_f32 v[102:103], v[16:17], v[16:17], v[102:103]
	v_pk_fma_f32 v[106:107], v[18:19], v[18:19], v[106:107]
	s_nop 0
	v_pk_add_f32 v[102:103], v[102:103], v[106:107]
	s_nop 0
	v_add_f32_e32 v102, v102, v103
	s_nop 1
	v_add_f32_dpp v102, v102, v102 quad_perm:[1,0,3,2] row_mask:0xf bank_mask:0xf
	s_nop 1
	v_add_f32_dpp v102, v102, v102 quad_perm:[2,3,0,1] row_mask:0xf bank_mask:0xf
	s_nop 1
	v_add_f32_dpp v102, v102, v102 row_half_mirror row_mask:0xf bank_mask:0xf
	s_nop 1
	v_add_f32_dpp v102, v102, v102 row_mirror row_mask:0xf bank_mask:0xf
	s_nop 1
	v_add_f32_dpp v102, v102, v102 row_bcast:15 row_mask:0xa bank_mask:0xf
	s_nop 1
	v_add_f32_dpp v102, v102, v102 row_bcast:31 row_mask:0xc bank_mask:0xf
	s_nop 1
	v_readlane_b32 s74, v102, 63
	s_nop 2
	v_mov_b32_e32 v102, s74
	v_fmamk_f32 v102, v102, 0x3a800000, v2
	v_mul_f32_e32 v103, 0x4f800000, v102
	v_cmp_gt_f32_e32 vcc, 0xf800000, v102
	s_nop 1
	v_cndmask_b32_e32 v102, v102, v103, vcc
	v_sqrt_f32_e32 v103, v102
	s_nop 0
	v_add_u32_e32 v104, -1, v103
	v_add_u32_e32 v106, 1, v103
	v_fma_f32 v107, -v104, v103, v102
	v_fma_f32 v108, -v106, v103, v102
	v_cmp_ge_f32_e64 s[76:77], 0, v107
	s_nop 1
	v_cndmask_b32_e64 v103, v103, v104, s[76:77]
	v_cmp_lt_f32_e64 s[76:77], 0, v108
	s_nop 1
	v_cndmask_b32_e64 v103, v103, v106, s[76:77]
	v_mul_f32_e32 v104, 0x37800000, v103
	v_cndmask_b32_e32 v103, v103, v104, vcc
	v_cmp_class_f32_e32 vcc, v102, v3
	s_nop 1
	v_cndmask_b32_e32 v102, v103, v102, vcc
	v_div_scale_f32 v103, s[76:77], v102, v102, 1.0
	v_rcp_f32_e32 v104, v103
	v_div_scale_f32 v106, vcc, 1.0, v102, 1.0
	v_fma_f32 v107, -v103, v104, 1.0
	v_fmac_f32_e32 v104, v107, v104
	v_mul_f32_e32 v107, v106, v104
	v_fma_f32 v108, -v103, v107, v106
	v_fmac_f32_e32 v107, v108, v104
	v_fma_f32 v103, -v103, v107, v106
	v_div_fmas_f32 v103, v103, v104, v107
	v_div_fixup_f32 v110, v103, v102, 1.0
	s_lshl_b32 s60, s55, 11
	s_add_u32 s70, s78, s60
	s_addc_u32 s71, s79, 0
	v_pk_mul_f32 v[112:113], v[4:5], v[110:111] op_sel_hi:[1,0]
	v_pk_mul_f32 v[114:115], v[6:7], v[110:111] op_sel_hi:[1,0]
	v_pk_mul_f32 v[116:117], v[8:9], v[110:111] op_sel_hi:[1,0]
	v_pk_mul_f32 v[118:119], v[10:11], v[110:111] op_sel_hi:[1,0]
	v_pk_mul_f32 v[120:121], v[12:13], v[110:111] op_sel_hi:[1,0]
	v_pk_mul_f32 v[122:123], v[14:15], v[110:111] op_sel_hi:[1,0]
	v_pk_mul_f32 v[124:125], v[16:17], v[110:111] op_sel_hi:[1,0]
	v_pk_mul_f32 v[100:101], v[18:19], v[110:111] op_sel_hi:[1,0]
	v_pk_mul_f32 v[112:113], v[160:161], v[112:113]
	v_pk_mul_f32 v[114:115], v[162:163], v[114:115]
	v_pk_mul_f32 v[116:117], v[164:165], v[116:117]
	v_pk_mul_f32 v[118:119], v[166:167], v[118:119]
	v_pk_mul_f32 v[120:121], v[168:169], v[120:121]
	v_pk_mul_f32 v[122:123], v[170:171], v[122:123]
	v_pk_mul_f32 v[124:125], v[172:173], v[124:125]
	v_pk_mul_f32 v[100:101], v[174:175], v[100:101]
	v_pk_fma_f32 v[112:113], v[176:177], v[112:113], v[192:193]
	v_pk_fma_f32 v[114:115], v[178:179], v[114:115], v[194:195]
	v_pk_fma_f32 v[116:117], v[180:181], v[116:117], v[196:197]
	v_pk_fma_f32 v[118:119], v[182:183], v[118:119], v[198:199]
	v_pk_fma_f32 v[120:121], v[184:185], v[120:121], v[200:201]
	v_pk_fma_f32 v[122:123], v[186:187], v[122:123], v[202:203]
	v_pk_fma_f32 v[124:125], v[188:189], v[124:125], v[204:205]
	v_pk_fma_f32 v[100:101], v[190:191], v[100:101], v[206:207]
	v_cvt_pk_bf16_f32 v240, v112, v113
	v_cvt_pk_bf16_f32 v241, v114, v115
	v_cvt_pk_bf16_f32 v242, v116, v117
	v_cvt_pk_bf16_f32 v243, v118, v119
	v_cvt_pk_bf16_f32 v244, v120, v121
	v_cvt_pk_bf16_f32 v245, v122, v123
	v_cvt_pk_bf16_f32 v246, v124, v125
	v_cvt_pk_bf16_f32 v247, v100, v101
	global_store_dwordx2 v1, v[240:241], s[70:71]
	global_store_dwordx2 v1, v[242:243], s[70:71] offset:512
	global_store_dwordx2 v1, v[244:245], s[70:71] offset:1024
	global_store_dwordx2 v1, v[246:247], s[70:71] offset:1536
	s_add_u32 s55, s55, 8
	s_add_u32 s57, s55, 16
	s_min_u32 s57, s57, s54
	s_cmp_lt_u32 s57, 0x8000
	s_cselect_b32 s64, s8, s10
	s_cselect_b32 s65, s9, s11
	s_cselect_b32 s60, 0, 0x8000
	s_sub_u32 s60, s57, s60
	s_lshl_b32 s60, s60, 12
	s_add_u32 s64, s64, s60
	s_addc_u32 s65, s65, 0
	global_load_dwordx4 v[4:7], v0, s[64:65] nt
	global_load_dwordx4 v[8:11], v0, s[64:65] offset:1024 nt
	global_load_dwordx4 v[12:15], v0, s[64:65] offset:2048 nt
	global_load_dwordx4 v[16:19], v0, s[64:65] offset:3072 nt
	s_lshr_b32 s60, s55, 11
	s_sub_u32 s61, s55, 0x8000
	s_lshr_b32 s61, s61, 12
	s_add_u32 s61, s61, 16
	s_cmp_lt_u32 s55, 0x8000
	s_cselect_b32 s63, s60, s61
	s_cmp_eq_u32 s63, s56
	s_cbranch_scc1 .Lrp1_pk8
	s_mov_b32 s56, s63
	s_add_u32 s0, s20, 0x0
	s_addc_u32 s1, s21, 0
	global_load_dwordx4 v[160:163], v0, s[0:1]
	global_load_dwordx4 v[164:167], v0, s[0:1] offset:1024
	global_load_dwordx4 v[168:171], v0, s[0:1] offset:2048
	global_load_dwordx4 v[172:175], v0, s[0:1] offset:3072
	s_mul_i32 s60, s56, 0x9000
	s_add_u32 s60, s60, 0x3181000
	s_add_u32 s0, s92, s60
	s_addc_u32 s1, s93, 0
	global_load_dwordx4 v[176:179], v0, s[0:1]
	global_load_dwordx4 v[180:183], v0, s[0:1] offset:1024
	global_load_dwordx4 v[184:187], v0, s[0:1] offset:2048
	global_load_dwordx4 v[188:191], v0, s[0:1] offset:3072
	s_mul_i32 s60, s56, 0x9000
	s_add_u32 s60, s60, 0x3180000
	s_add_u32 s0, s92, s60
	s_addc_u32 s1, s93, 0
	global_load_dwordx4 v[192:195], v0, s[0:1]
	global_load_dwordx4 v[196:199], v0, s[0:1] offset:1024
	global_load_dwordx4 v[200:203], v0, s[0:1] offset:2048
	global_load_dwordx4 v[204:207], v0, s[0:1] offset:3072
	s_waitcnt vmcnt(0)
	v_pk_add_f32 v[176:177], v[176:177], 1.0 op_sel_hi:[1,0]
	v_pk_add_f32 v[178:179], v[178:179], 1.0 op_sel_hi:[1,0]
	v_pk_add_f32 v[180:181], v[180:181], 1.0 op_sel_hi:[1,0]
	v_pk_add_f32 v[182:183], v[182:183], 1.0 op_sel_hi:[1,0]
	v_pk_add_f32 v[184:185], v[184:185], 1.0 op_sel_hi:[1,0]
	v_pk_add_f32 v[186:187], v[186:187], 1.0 op_sel_hi:[1,0]
	v_pk_add_f32 v[188:189], v[188:189], 1.0 op_sel_hi:[1,0]
	v_pk_add_f32 v[190:191], v[190:191], 1.0 op_sel_hi:[1,0]
; __device__ __forceinline__ unsigned pk_bf16(float lo, float hi) { const f32x2 v = {lo, hi}; const bf16x2_t b = __builtin_convertvector(v, bf16x2_t); return __builtin_bit_cast(unsigned, b); }
; template <bool HAS_F, bool HAS_H>
; __device__ __forceinline__ void phase_rows(const Params& p, int sp, int sn, float resw, bool from_input, bool write_x = true) {
;     ...
;         const float* xin = !from_input ? p.out + (size_t)row * D : (row < TP ? p.in[0] + (size_t)row * D : p.in[1] + (size_t)(row - TP) * D);
;         f32x4 v[4];
; #pragma unroll
;         for (int j = 0; j < 4; ++j) v[j] = *(const f32x4*)(xin + 4 * lane + 256 * j);
;     ...
;             float ss = 0.f;
; #pragma unroll
;             for (int j = 0; j < 4; ++j) ss += (v[j].x * v[j].x + v[j].y * v[j].y) + (v[j].z * v[j].z + v[j].w * v[j].w);
;             const float rs = 1.0f / sqrtf(wave_sum(ss) * (1.0f / D) + EPS);
;             const float* sh = mod + b * 9216 + sn * 3072; const float* scl = sh + 1024; const float* gq = p.in[6] + sn * D;
; #pragma unroll
;             for (int j = 0; j < 4; ++j) { const f32x4 a = *(const f32x4*)(sh + 4 * lane + 256 * j), s = *(const f32x4*)(scl + 4 * lane + 256 * j), q = *(const f32x4*)(gq + 4 * lane + 256 * j);
;                 const f32x4 h = (v[j] * rs * q) * (s + 1.0f) + a;
;                 u32x2 w; w.x = pk_bf16(h.x, h.y); w.y = pk_bf16(h.z, h.w);
;                 *(u32x2*)(H + (size_t)row * D + 4 * lane + 256 * j) = w; }
.Lrp1_pk8:
	s_waitcnt vmcnt(16)
	v_pk_mul_f32 v[102:103], v[36:37], v[36:37]
	v_pk_mul_f32 v[106:107], v[38:39], v[38:39]
	v_pk_fma_f32 v[102:103], v[40:41], v[40:41], v[102:103]
	v_pk_fma_f32 v[106:107], v[42:43], v[42:43], v[106:107]
	v_pk_fma_f32 v[102:103], v[44:45], v[44:45], v[102:103]
	v_pk_fma_f32 v[106:107], v[46:47], v[46:47], v[106:107]
	v_pk_fma_f32 v[102:103], v[48:49], v[48:49], v[102:103]
	v_pk_fma_f32 v[106:107], v[50:51], v[50:51], v[106:107]
	s_nop 0
	v_pk_add_f32 v[102:103], v[102:103], v[106:107]
	s_nop 0
	v_add_f32_e32 v102, v102, v103
	s_nop 1
	v_add_f32_dpp v102, v102, v102 quad_perm:[1,0,3,2] row_mask:0xf bank_mask:0xf
	s_nop 1
	v_add_f32_dpp v102, v102, v102 quad_perm:[2,3,0,1] row_mask:0xf bank_mask:0xf
	s_nop 1
	v_add_f32_dpp v102, v102, v102 row_half_mirror row_mask:0xf bank_mask:0xf
	s_nop 1
	v_add_f32_dpp v102, v102, v102 row_mirror row_mask:0xf bank_mask:0xf
	s_nop 1
	v_add_f32_dpp v102, v102, v102 row_bcast:15 row_mask:0xa bank_mask:0xf
	s_nop 1
	v_add_f32_dpp v102, v102, v102 row_bcast:31 row_mask:0xc bank_mask:0xf
	s_nop 1
	v_readlane_b32 s74, v102, 63
	s_nop 2
	v_mov_b32_e32 v102, s74
	v_fmamk_f32 v102, v102, 0x3a800000, v2
	v_mul_f32_e32 v103, 0x4f800000, v102
	v_cmp_gt_f32_e32 vcc, 0xf800000, v102
	s_nop 1
	v_cndmask_b32_e32 v102, v102, v103, vcc
	v_sqrt_f32_e32 v103, v102
	s_nop 0
	v_add_u32_e32 v104, -1, v103
	v_add_u32_e32 v106, 1, v103
	v_fma_f32 v107, -v104, v103, v102
	v_fma_f32 v108, -v106, v103, v102
	v_cmp_ge_f32_e64 s[76:77], 0, v107
	s_nop 1
	v_cndmask_b32_e64 v103, v103, v104, s[76:77]
	v_cmp_lt_f32_e64 s[76:77], 0, v108
	s_nop 1
	v_cndmask_b32_e64 v103, v103, v106, s[76:77]
	v_mul_f32_e32 v104, 0x37800000, v103
	v_cndmask_b32_e32 v103, v103, v104, vcc
	v_cmp_class_f32_e32 vcc, v102, v3
	s_nop 1
	v_cndmask_b32_e32 v102, v103, v102, vcc
	v_div_scale_f32 v103, s[76:77], v102, v102, 1.0
	v_rcp_f32_e32 v104, v103
	v_div_scale_f32 v106, vcc, 1.0, v102, 1.0
	v_fma_f32 v107, -v103, v104, 1.0
	v_fmac_f32_e32 v104, v107, v104
	v_mul_f32_e32 v107, v106, v104
	v_fma_f32 v108, -v103, v107, v106
	v_fmac_f32_e32 v107, v108, v104
	v_fma_f32 v103, -v103, v107, v106
	v_div_fmas_f32 v103, v103, v104, v107
	v_div_fixup_f32 v110, v103, v102, 1.0
	s_lshl_b32 s60, s55, 11
	s_add_u32 s70, s78, s60
	s_addc_u32 s71, s79, 0
	v_pk_mul_f32 v[112:113], v[36:37], v[110:111] op_sel_hi:[1,0]
	v_pk_mul_f32 v[114:115], v[38:39], v[110:111] op_sel_hi:[1,0]
	v_pk_mul_f32 v[116:117], v[40:41], v[110:111] op_sel_hi:[1,0]
	v_pk_mul_f32 v[118:119], v[42:43], v[110:111] op_sel_hi:[1,0]
	v_pk_mul_f32 v[120:121], v[44:45], v[110:111] op_sel_hi:[1,0]
	v_pk_mul_f32 v[122:123], v[46:47], v[110:111] op_sel_hi:[1,0]
	v_pk_mul_f32 v[124:125], v[48:49], v[110:111] op_sel_hi:[1,0]
	v_pk_mul_f32 v[100:101], v[50:51], v[110:111] op_sel_hi:[1,0]
	v_pk_mul_f32 v[112:113], v[160:161], v[112:113]
	v_pk_mul_f32 v[114:115], v[162:163], v[114:115]
	v_pk_mul_f32 v[116:117], v[164:165], v[116:117]
	v_pk_mul_f32 v[118:119], v[166:167], v[118:119]
	v_pk_mul_f32 v[120:121], v[168:169], v[120:121]
	v_pk_mul_f32 v[122:123], v[170:171], v[122:123]
	v_pk_mul_f32 v[124:125], v[172:173], v[124:125]
	v_pk_mul_f32 v[100:101], v[174:175], v[100:101]
	v_pk_fma_f32 v[112:113], v[176:177], v[112:113], v[192:193]
	v_pk_fma_f32 v[114:115], v[178:179], v[114:115], v[194:195]
	v_pk_fma_f32 v[116:117], v[180:181], v[116:117], v[196:197]
	v_pk_fma_f32 v[118:119], v[182:183], v[118:119], v[198:199]
	v_pk_fma_f32 v[120:121], v[184:185], v[120:121], v[200:201]
	v_pk_fma_f32 v[122:123], v[186:187], v[122:123], v[202:203]
	v_pk_fma_f32 v[124:125], v[188:189], v[124:125], v[204:205]
	v_pk_fma_f32 v[100:101], v[190:191], v[100:101], v[206:207]
	v_cvt_pk_bf16_f32 v240, v112, v113
	v_cvt_pk_bf16_f32 v241, v114, v115
	v_cvt_pk_bf16_f32 v242, v116, v117
	v_cvt_pk_bf16_f32 v243, v118, v119
	v_cvt_pk_bf16_f32 v244, v120, v121
	v_cvt_pk_bf16_f32 v245, v122, v123
	v_cvt_pk_bf16_f32 v246, v124, v125
	v_cvt_pk_bf16_f32 v247, v100, v101
	global_store_dwordx2 v1, v[240:241], s[70:71]
	global_store_dwordx2 v1, v[242:243], s[70:71] offset:512
	global_store_dwordx2 v1, v[244:245], s[70:71] offset:1024
	global_store_dwordx2 v1, v[246:247], s[70:71] offset:1536
	s_add_u32 s55, s55, 8
	s_add_u32 s57, s55, 16
	s_min_u32 s57, s57, s54
	s_cmp_lt_u32 s57, 0x8000
	s_cselect_b32 s64, s8, s10
	s_cselect_b32 s65, s9, s11
	s_cselect_b32 s60, 0, 0x8000
	s_sub_u32 s60, s57, s60
	s_lshl_b32 s60, s60, 12
	s_add_u32 s64, s64, s60
	s_addc_u32 s65, s65, 0
	global_load_dwordx4 v[36:39], v0, s[64:65] nt
	global_load_dwordx4 v[40:43], v0, s[64:65] offset:1024 nt
	global_load_dwordx4 v[44:47], v0, s[64:65] offset:2048 nt
	global_load_dwordx4 v[48:51], v0, s[64:65] offset:3072 nt
	s_lshr_b32 s60, s55, 11
	s_sub_u32 s61, s55, 0x8000
	s_lshr_b32 s61, s61, 12
	s_add_u32 s61, s61, 16
	s_cmp_lt_u32 s55, 0x8000
	s_cselect_b32 s63, s60, s61
	s_cmp_eq_u32 s63, s56
	s_cbranch_scc1 .Lrp1_pk9
	s_mov_b32 s56, s63
	s_add_u32 s0, s20, 0x0
	s_addc_u32 s1, s21, 0
	global_load_dwordx4 v[160:163], v0, s[0:1]
	global_load_dwordx4 v[164:167], v0, s[0:1] offset:1024
	global_load_dwordx4 v[168:171], v0, s[0:1] offset:2048
	global_load_dwordx4 v[172:175], v0, s[0:1] offset:3072
	s_mul_i32 s60, s56, 0x9000
	s_add_u32 s60, s60, 0x3181000
	s_add_u32 s0, s92, s60
	s_addc_u32 s1, s93, 0
	global_load_dwordx4 v[176:179], v0, s[0:1]
	global_load_dwordx4 v[180:183], v0, s[0:1] offset:1024
	global_load_dwordx4 v[184:187], v0, s[0:1] offset:2048
	global_load_dwordx4 v[188:191], v0, s[0:1] offset:3072
	s_mul_i32 s60, s56, 0x9000
	s_add_u32 s60, s60, 0x3180000
	s_add_u32 s0, s92, s60
	s_addc_u32 s1, s93, 0
	global_load_dwordx4 v[192:195], v0, s[0:1]
	global_load_dwordx4 v[196:199], v0, s[0:1] offset:1024
	global_load_dwordx4 v[200:203], v0, s[0:1] offset:2048
	global_load_dwordx4 v[204:207], v0, s[0:1] offset:3072
	s_waitcnt vmcnt(0)
	v_pk_add_f32 v[176:177], v[176:177], 1.0 op_sel_hi:[1,0]
	v_pk_add_f32 v[178:179], v[178:179], 1.0 op_sel_hi:[1,0]
	v_pk_add_f32 v[180:181], v[180:181], 1.0 op_sel_hi:[1,0]
	v_pk_add_f32 v[182:183], v[182:183], 1.0 op_sel_hi:[1,0]
	v_pk_add_f32 v[184:185], v[184:185], 1.0 op_sel_hi:[1,0]
	v_pk_add_f32 v[186:187], v[186:187], 1.0 op_sel_hi:[1,0]
	v_pk_add_f32 v[188:189], v[188:189], 1.0 op_sel_hi:[1,0]
	v_pk_add_f32 v[190:191], v[190:191], 1.0 op_sel_hi:[1,0]
; __device__ __forceinline__ unsigned pk_bf16(float lo, float hi) { const f32x2 v = {lo, hi}; const bf16x2_t b = __builtin_convertvector(v, bf16x2_t); return __builtin_bit_cast(unsigned, b); }
; template <bool HAS_F, bool HAS_H>
; __device__ __forceinline__ void phase_rows(const Params& p, int sp, int sn, float resw, bool from_input, bool write_x = true) {
;     ...
;             float ss = 0.f;
; #pragma unroll
;             for (int j = 0; j < 4; ++j) ss += (v[j].x * v[j].x + v[j].y * v[j].y) + (v[j].z * v[j].z + v[j].w * v[j].w);
;             const float rs = 1.0f / sqrtf(wave_sum(ss) * (1.0f / D) + EPS);
;             const float* sh = mod + b * 9216 + sn * 3072; const float* scl = sh + 1024; const float* gq = p.in[6] + sn * D;
; #pragma unroll
;             for (int j = 0; j < 4; ++j) { const f32x4 a = *(const f32x4*)(sh + 4 * lane + 256 * j), s = *(const f32x4*)(scl + 4 * lane + 256 * j), q = *(const f32x4*)(gq + 4 * lane + 256 * j);
;                 const f32x4 h = (v[j] * rs * q) * (s + 1.0f) + a;
;                 u32x2 w; w.x = pk_bf16(h.x, h.y); w.y = pk_bf16(h.z, h.w);
;                 *(u32x2*)(H + (size_t)row * D + 4 * lane + 256 * j) = w; }
;         }
.Lrp1_pk9:
	s_waitcnt vmcnt(16)
	v_pk_mul_f32 v[102:103], v[68:69], v[68:69]
	v_pk_mul_f32 v[106:107], v[70:71], v[70:71]
	v_pk_fma_f32 v[102:103], v[72:73], v[72:73], v[102:103]
	v_pk_fma_f32 v[106:107], v[74:75], v[74:75], v[106:107]
	v_pk_fma_f32 v[102:103], v[76:77], v[76:77], v[102:103]
	v_pk_fma_f32 v[106:107], v[78:79], v[78:79], v[106:107]
	v_pk_fma_f32 v[102:103], v[80:81], v[80:81], v[102:103]
	v_pk_fma_f32 v[106:107], v[82:83], v[82:83], v[106:107]
	s_nop 0
	v_pk_add_f32 v[102:103], v[102:103], v[106:107]
	s_nop 0
	v_add_f32_e32 v102, v102, v103
	s_nop 1
	v_add_f32_dpp v102, v102, v102 quad_perm:[1,0,3,2] row_mask:0xf bank_mask:0xf
	s_nop 1
	v_add_f32_dpp v102, v102, v102 quad_perm:[2,3,0,1] row_mask:0xf bank_mask:0xf
	s_nop 1
	v_add_f32_dpp v102, v102, v102 row_half_mirror row_mask:0xf bank_mask:0xf
	s_nop 1
	v_add_f32_dpp v102, v102, v102 row_mirror row_mask:0xf bank_mask:0xf
	s_nop 1
	v_add_f32_dpp v102, v102, v102 row_bcast:15 row_mask:0xa bank_mask:0xf
	s_nop 1
	v_add_f32_dpp v102, v102, v102 row_bcast:31 row_mask:0xc bank_mask:0xf
	s_nop 1
	v_readlane_b32 s74, v102, 63
	s_nop 2
	v_mov_b32_e32 v102, s74
	v_fmamk_f32 v102, v102, 0x3a800000, v2
	v_mul_f32_e32 v103, 0x4f800000, v102
	v_cmp_gt_f32_e32 vcc, 0xf800000, v102
	s_nop 1
	v_cndmask_b32_e32 v102, v102, v103, vcc
	v_sqrt_f32_e32 v103, v102
	s_nop 0
	v_add_u32_e32 v104, -1, v103
	v_add_u32_e32 v106, 1, v103
	v_fma_f32 v107, -v104, v103, v102
	v_fma_f32 v108, -v106, v103, v102
	v_cmp_ge_f32_e64 s[76:77], 0, v107
	s_nop 1
	v_cndmask_b32_e64 v103, v103, v104, s[76:77]
	v_cmp_lt_f32_e64 s[76:77], 0, v108
	s_nop 1
	v_cndmask_b32_e64 v103, v103, v106, s[76:77]
	v_mul_f32_e32 v104, 0x37800000, v103
	v_cndmask_b32_e32 v103, v103, v104, vcc
	v_cmp_class_f32_e32 vcc, v102, v3
	s_nop 1
	v_cndmask_b32_e32 v102, v103, v102, vcc
	v_div_scale_f32 v103, s[76:77], v102, v102, 1.0
	v_rcp_f32_e32 v104, v103
	v_div_scale_f32 v106, vcc, 1.0, v102, 1.0
	v_fma_f32 v107, -v103, v104, 1.0
	v_fmac_f32_e32 v104, v107, v104
	v_mul_f32_e32 v107, v106, v104
	v_fma_f32 v108, -v103, v107, v106
	v_fmac_f32_e32 v107, v108, v104
	v_fma_f32 v103, -v103, v107, v106
	v_div_fmas_f32 v103, v103, v104, v107
	v_div_fixup_f32 v110, v103, v102, 1.0
	s_lshl_b32 s60, s55, 11
	s_add_u32 s70, s78, s60
	s_addc_u32 s71, s79, 0
	v_pk_mul_f32 v[112:113], v[68:69], v[110:111] op_sel_hi:[1,0]
	v_pk_mul_f32 v[114:115], v[70:71], v[110:111] op_sel_hi:[1,0]
	v_pk_mul_f32 v[116:117], v[72:73], v[110:111] op_sel_hi:[1,0]
	v_pk_mul_f32 v[118:119], v[74:75], v[110:111] op_sel_hi:[1,0]
	v_pk_mul_f32 v[120:121], v[76:77], v[110:111] op_sel_hi:[1,0]
	v_pk_mul_f32 v[122:123], v[78:79], v[110:111] op_sel_hi:[1,0]
	v_pk_mul_f32 v[124:125], v[80:81], v[110:111] op_sel_hi:[1,0]
	v_pk_mul_f32 v[100:101], v[82:83], v[110:111] op_sel_hi:[1,0]
	v_pk_mul_f32 v[112:113], v[160:161], v[112:113]
	v_pk_mul_f32 v[114:115], v[162:163], v[114:115]
	v_pk_mul_f32 v[116:117], v[164:165], v[116:117]
	v_pk_mul_f32 v[118:119], v[166:167], v[118:119]
	v_pk_mul_f32 v[120:121], v[168:169], v[120:121]
	v_pk_mul_f32 v[122:123], v[170:171], v[122:123]
	v_pk_mul_f32 v[124:125], v[172:173], v[124:125]
	v_pk_mul_f32 v[100:101], v[174:175], v[100:101]
	v_pk_fma_f32 v[112:113], v[176:177], v[112:113], v[192:193]
	v_pk_fma_f32 v[114:115], v[178:179], v[114:115], v[194:195]
	v_pk_fma_f32 v[116:117], v[180:181], v[116:117], v[196:197]
	v_pk_fma_f32 v[118:119], v[182:183], v[118:119], v[198:199]
	v_pk_fma_f32 v[120:121], v[184:185], v[120:121], v[200:201]
	v_pk_fma_f32 v[122:123], v[186:187], v[122:123], v[202:203]
	v_pk_fma_f32 v[124:125], v[188:189], v[124:125], v[204:205]
	v_pk_fma_f32 v[100:101], v[190:191], v[100:101], v[206:207]
	v_cvt_pk_bf16_f32 v240, v112, v113
	v_cvt_pk_bf16_f32 v241, v114, v115
	v_cvt_pk_bf16_f32 v242, v116, v117
	v_cvt_pk_bf16_f32 v243, v118, v119
	v_cvt_pk_bf16_f32 v244, v120, v121
	v_cvt_pk_bf16_f32 v245, v122, v123
	v_cvt_pk_bf16_f32 v246, v124, v125
	v_cvt_pk_bf16_f32 v247, v100, v101
	global_store_dwordx2 v1, v[240:241], s[70:71]
	global_store_dwordx2 v1, v[242:243], s[70:71] offset:512
	global_store_dwordx2 v1, v[244:245], s[70:71] offset:1024
	global_store_dwordx2 v1, v[246:247], s[70:71] offset:1536
	s_add_u32 s55, s55, 8
	s_cmp_le_u32 s55, s54
	s_cbranch_scc1 .Lrp1_loop3
	s_add_u32 s51, s51, s52
	s_branch .Lrp1_chunk1

; __device__ __forceinline__ float lo_bf(unsigned w) { return __uint_as_float(w << 16); }
; __device__ __forceinline__ float hi_bf(unsigned w) { return __uint_as_float(w & 0xffff0000u); }
; template <bool HAS_F, bool HAS_H>
; __device__ __forceinline__ void phase_rows(const Params& p, int sp, int sn, float resw, bool from_input, bool write_x = true) {
;     ...
;         if (HAS_F) {
;             f32x4 f[4]; float ss = 0.f;
; #pragma unroll
;             for (int j = 0; j < 4; ++j) { const u32x2 w = *(const u32x2*)(F + (size_t)row * D + 4 * lane + 256 * j);
;                 f[j] = (f32x4){lo_bf(w.x), hi_bf(w.x), lo_bf(w.y), hi_bf(w.y)}; ss += (f[j].x * f[j].x + f[j].y * f[j].y) + (f[j].z * f[j].z + f[j].w * f[j].w); }
;             const float rs = 1.0f / sqrtf(wave_sum(ss) * (1.0f / D) + EPS) * resw;
;             const float* gate = mod + b * 9216 + sp * 3072 + 2048; const float* gp = p.in[7] + sp * D;
; #pragma unroll
;             for (int j = 0; j < 4; ++j) { const f32x4 g = *(const f32x4*)(gate + 4 * lane + 256 * j), q = *(const f32x4*)(gp + 4 * lane + 256 * j);
;                 v[j] = v[j] + g * (f[j] * rs * q);
;                 if (write_x) *(f32x4*)(p.out + (size_t)row * D + 4 * lane + 256 * j) = v[j]; }
;         }
;         if (HAS_H) {
;             float ss = 0.f;
; #pragma unroll
;             for (int j = 0; j < 4; ++j) ss += (v[j].x * v[j].x + v[j].y * v[j].y) + (v[j].z * v[j].z + v[j].w * v[j].w);
;             const float rs = 1.0f / sqrtf(wave_sum(ss) * (1.0f / D) + EPS);
.Lrp4_pk4:
	s_waitcnt vmcnt(16)
	v_lshlrev_b32_e32 v112, 16, v20
	v_and_b32_e32 v113, 0xffff0000, v20
	v_lshlrev_b32_e32 v114, 16, v21
	v_and_b32_e32 v115, 0xffff0000, v21
	v_lshlrev_b32_e32 v116, 16, v22
	v_and_b32_e32 v117, 0xffff0000, v22
	v_lshlrev_b32_e32 v118, 16, v23
	v_and_b32_e32 v119, 0xffff0000, v23
	v_lshlrev_b32_e32 v120, 16, v24
	v_and_b32_e32 v121, 0xffff0000, v24
	v_lshlrev_b32_e32 v122, 16, v25
	v_and_b32_e32 v123, 0xffff0000, v25
	v_lshlrev_b32_e32 v124, 16, v26
	v_and_b32_e32 v125, 0xffff0000, v26
	v_lshlrev_b32_e32 v100, 16, v27
	v_and_b32_e32 v101, 0xffff0000, v27
	v_pk_mul_f32 v[102:103], v[112:113], v[112:113]
	v_pk_mul_f32 v[106:107], v[114:115], v[114:115]
	v_pk_fma_f32 v[102:103], v[116:117], v[116:117], v[102:103]
	v_pk_fma_f32 v[106:107], v[118:119], v[118:119], v[106:107]
	v_pk_fma_f32 v[102:103], v[120:121], v[120:121], v[102:103]
	v_pk_fma_f32 v[106:107], v[122:123], v[122:123], v[106:107]
	v_pk_fma_f32 v[102:103], v[124:125], v[124:125], v[102:103]
	v_pk_fma_f32 v[106:107], v[100:101], v[100:101], v[106:107]
	s_nop 0
	v_pk_add_f32 v[102:103], v[102:103], v[106:107]
	s_nop 0
	v_add_f32_e32 v102, v102, v103
	s_nop 1
	v_add_f32_dpp v102, v102, v102 quad_perm:[1,0,3,2] row_mask:0xf bank_mask:0xf
	s_nop 1
	v_add_f32_dpp v102, v102, v102 quad_perm:[2,3,0,1] row_mask:0xf bank_mask:0xf
	s_nop 1
	v_add_f32_dpp v102, v102, v102 row_half_mirror row_mask:0xf bank_mask:0xf
	s_nop 1
	v_add_f32_dpp v102, v102, v102 row_mirror row_mask:0xf bank_mask:0xf
	s_nop 1
	v_add_f32_dpp v102, v102, v102 row_bcast:15 row_mask:0xa bank_mask:0xf
	s_nop 1
	v_add_f32_dpp v102, v102, v102 row_bcast:31 row_mask:0xc bank_mask:0xf
	s_nop 1
	v_readlane_b32 s74, v102, 63
	s_nop 2
	v_mov_b32_e32 v102, s74
	v_fmamk_f32 v102, v102, 0x3a800000, v2
	v_mul_f32_e32 v103, 0x4f800000, v102
	v_cmp_gt_f32_e32 vcc, 0xf800000, v102
	s_nop 1
	v_cndmask_b32_e32 v102, v102, v103, vcc
	v_sqrt_f32_e32 v103, v102
	s_nop 0
	v_add_u32_e32 v104, -1, v103
	v_add_u32_e32 v106, 1, v103
	v_fma_f32 v107, -v104, v103, v102
	v_fma_f32 v108, -v106, v103, v102
	v_cmp_ge_f32_e64 s[76:77], 0, v107
	s_nop 1
	v_cndmask_b32_e64 v103, v103, v104, s[76:77]
	v_cmp_lt_f32_e64 s[76:77], 0, v108
	s_nop 1
	v_cndmask_b32_e64 v103, v103, v106, s[76:77]
	v_mul_f32_e32 v104, 0x37800000, v103
	v_cndmask_b32_e32 v103, v103, v104, vcc
	v_cmp_class_f32_e32 vcc, v102, v3
	s_nop 1
	v_cndmask_b32_e32 v102, v103, v102, vcc
	v_div_scale_f32 v103, s[76:77], v102, v102, 1.0
	v_rcp_f32_e32 v104, v103
	v_div_scale_f32 v106, vcc, 1.0, v102, 1.0
	v_fma_f32 v107, -v103, v104, 1.0
	v_fmac_f32_e32 v104, v107, v104
	v_mul_f32_e32 v107, v106, v104
	v_fma_f32 v108, -v103, v107, v106
	v_fmac_f32_e32 v107, v108, v104
	v_fma_f32 v103, -v103, v107, v106
	v_div_fmas_f32 v103, v103, v104, v107
	v_div_fixup_f32 v110, v103, v102, 1.0
	v_mul_f32_e32 v110, 0.5, v110
	v_pk_mul_f32 v[112:113], v[112:113], v[110:111] op_sel_hi:[1,0]
	v_pk_mul_f32 v[114:115], v[114:115], v[110:111] op_sel_hi:[1,0]
	v_pk_mul_f32 v[116:117], v[116:117], v[110:111] op_sel_hi:[1,0]
	v_pk_mul_f32 v[118:119], v[118:119], v[110:111] op_sel_hi:[1,0]
	v_pk_mul_f32 v[120:121], v[120:121], v[110:111] op_sel_hi:[1,0]
	v_pk_mul_f32 v[122:123], v[122:123], v[110:111] op_sel_hi:[1,0]
	v_pk_mul_f32 v[124:125], v[124:125], v[110:111] op_sel_hi:[1,0]
	v_pk_mul_f32 v[100:101], v[100:101], v[110:111] op_sel_hi:[1,0]
	v_pk_mul_f32 v[112:113], v[176:177], v[112:113]
	v_pk_mul_f32 v[114:115], v[178:179], v[114:115]
	v_pk_mul_f32 v[116:117], v[180:181], v[116:117]
	v_pk_mul_f32 v[118:119], v[182:183], v[118:119]
	v_pk_mul_f32 v[120:121], v[184:185], v[120:121]
	v_pk_mul_f32 v[122:123], v[186:187], v[122:123]
	v_pk_mul_f32 v[124:125], v[188:189], v[124:125]
	v_pk_mul_f32 v[100:101], v[190:191], v[100:101]
	v_pk_fma_f32 v[4:5], v[160:161], v[112:113], v[4:5]
	v_pk_fma_f32 v[6:7], v[162:163], v[114:115], v[6:7]
	v_pk_fma_f32 v[8:9], v[164:165], v[116:117], v[8:9]
	v_pk_fma_f32 v[10:11], v[166:167], v[118:119], v[10:11]
	v_pk_fma_f32 v[12:13], v[168:169], v[120:121], v[12:13]
	v_pk_fma_f32 v[14:15], v[170:171], v[122:123], v[14:15]
	v_pk_fma_f32 v[16:17], v[172:173], v[124:125], v[16:17]
	v_pk_fma_f32 v[18:19], v[174:175], v[100:101], v[18:19]
	s_lshl_b32 s60, s55, 12
	s_add_u32 s72, s84, s60
	s_addc_u32 s73, s85, 0
	global_store_dwordx4 v0, v[4:7], s[72:73] sc1
	global_store_dwordx4 v0, v[8:11], s[72:73] offset:1024 sc1
	global_store_dwordx4 v0, v[12:15], s[72:73] offset:2048 sc1
	global_store_dwordx4 v0, v[16:19], s[72:73] offset:3072 sc1
	v_pk_mul_f32 v[102:103], v[4:5], v[4:5]
	v_pk_mul_f32 v[106:107], v[6:7], v[6:7]
	v_pk_fma_f32 v[102:103], v[8:9], v[8:9], v[102:103]
	v_pk_fma_f32 v[106:107], v[10:11], v[10:11], v[106:107]
	v_pk_fma_f32 v[102:103], v[12:13], v[12:13], v[102:103]
	v_pk_fma_f32 v[106:107], v[14:15], v[14:15], v[106:107]
	v_pk_fma_f32 v[102:103], v[16:17], v[16:17], v[102:103]
	v_pk_fma_f32 v[106:107], v[18:19], v[18:19], v[106:107]
	s_nop 0
	v_pk_add_f32 v[102:103], v[102:103], v[106:107]
	s_nop 0
	v_add_f32_e32 v102, v102, v103
	s_nop 1
	v_add_f32_dpp v102, v102, v102 quad_perm:[1,0,3,2] row_mask:0xf bank_mask:0xf
	s_nop 1
	v_add_f32_dpp v102, v102, v102 quad_perm:[2,3,0,1] row_mask:0xf bank_mask:0xf
	s_nop 1
	v_add_f32_dpp v102, v102, v102 row_half_mirror row_mask:0xf bank_mask:0xf
	s_nop 1
	v_add_f32_dpp v102, v102, v102 row_mirror row_mask:0xf bank_mask:0xf
	s_nop 1
	v_add_f32_dpp v102, v102, v102 row_bcast:15 row_mask:0xa bank_mask:0xf
	s_nop 1
	v_add_f32_dpp v102, v102, v102 row_bcast:31 row_mask:0xc bank_mask:0xf
	s_nop 1
	v_readlane_b32 s74, v102, 63
	s_nop 2
	v_mov_b32_e32 v102, s74
	v_fmamk_f32 v102, v102, 0x3a800000, v2
; __device__ __forceinline__ unsigned pk_bf16(float lo, float hi) { const f32x2 v = {lo, hi}; const bf16x2_t b = __builtin_convertvector(v, bf16x2_t); return __builtin_bit_cast(unsigned, b); }
; template <bool HAS_F, bool HAS_H>
; __device__ __forceinline__ void phase_rows(const Params& p, int sp, int sn, float resw, bool from_input, bool write_x = true) {
;     ...
;         const float* xin = !from_input ? p.out + (size_t)row * D : (row < TP ? p.in[0] + (size_t)row * D : p.in[1] + (size_t)(row - TP) * D);
;         f32x4 v[4];
; #pragma unroll
;         for (int j = 0; j < 4; ++j) v[j] = *(const f32x4*)(xin + 4 * lane + 256 * j);
;         if (HAS_F) {
;             f32x4 f[4]; float ss = 0.f;
; #pragma unroll
;             for (int j = 0; j < 4; ++j) { const u32x2 w = *(const u32x2*)(F + (size_t)row * D + 4 * lane + 256 * j);
;     ...
;             const float rs = 1.0f / sqrtf(wave_sum(ss) * (1.0f / D) + EPS);
;             const float* sh = mod + b * 9216 + sn * 3072; const float* scl = sh + 1024; const float* gq = p.in[6] + sn * D;
; #pragma unroll
;             for (int j = 0; j < 4; ++j) { const f32x4 a = *(const f32x4*)(sh + 4 * lane + 256 * j), s = *(const f32x4*)(scl + 4 * lane + 256 * j), q = *(const f32x4*)(gq + 4 * lane + 256 * j);
;                 const f32x4 h = (v[j] * rs * q) * (s + 1.0f) + a;
;                 u32x2 w; w.x = pk_bf16(h.x, h.y); w.y = pk_bf16(h.z, h.w);
;                 *(u32x2*)(H + (size_t)row * D + 4 * lane + 256 * j) = w; }
	v_mul_f32_e32 v103, 0x4f800000, v102
	v_cmp_gt_f32_e32 vcc, 0xf800000, v102
	s_nop 1
	v_cndmask_b32_e32 v102, v102, v103, vcc
	v_sqrt_f32_e32 v103, v102
	s_nop 0
	v_add_u32_e32 v104, -1, v103
	v_add_u32_e32 v106, 1, v103
	v_fma_f32 v107, -v104, v103, v102
	v_fma_f32 v108, -v106, v103, v102
	v_cmp_ge_f32_e64 s[76:77], 0, v107
	s_nop 1
	v_cndmask_b32_e64 v103, v103, v104, s[76:77]
	v_cmp_lt_f32_e64 s[76:77], 0, v108
	s_nop 1
	v_cndmask_b32_e64 v103, v103, v106, s[76:77]
	v_mul_f32_e32 v104, 0x37800000, v103
	v_cndmask_b32_e32 v103, v103, v104, vcc
	v_cmp_class_f32_e32 vcc, v102, v3
	s_nop 1
	v_cndmask_b32_e32 v102, v103, v102, vcc
	v_div_scale_f32 v103, s[76:77], v102, v102, 1.0
	v_rcp_f32_e32 v104, v103
	v_div_scale_f32 v106, vcc, 1.0, v102, 1.0
	v_fma_f32 v107, -v103, v104, 1.0
	v_fmac_f32_e32 v104, v107, v104
	v_mul_f32_e32 v107, v106, v104
	v_fma_f32 v108, -v103, v107, v106
	v_fmac_f32_e32 v107, v108, v104
	v_fma_f32 v103, -v103, v107, v106
	v_div_fmas_f32 v103, v103, v104, v107
	v_div_fixup_f32 v110, v103, v102, 1.0
	s_lshl_b32 s60, s55, 11
	s_add_u32 s70, s78, s60
	s_addc_u32 s71, s79, 0
	v_pk_mul_f32 v[112:113], v[4:5], v[110:111] op_sel_hi:[1,0]
	v_pk_mul_f32 v[114:115], v[6:7], v[110:111] op_sel_hi:[1,0]
	v_pk_mul_f32 v[116:117], v[8:9], v[110:111] op_sel_hi:[1,0]
	v_pk_mul_f32 v[118:119], v[10:11], v[110:111] op_sel_hi:[1,0]
	v_pk_mul_f32 v[120:121], v[12:13], v[110:111] op_sel_hi:[1,0]
	v_pk_mul_f32 v[122:123], v[14:15], v[110:111] op_sel_hi:[1,0]
	v_pk_mul_f32 v[124:125], v[16:17], v[110:111] op_sel_hi:[1,0]
	v_pk_mul_f32 v[100:101], v[18:19], v[110:111] op_sel_hi:[1,0]
	v_pk_mul_f32 v[112:113], v[192:193], v[112:113]
	v_pk_mul_f32 v[114:115], v[194:195], v[114:115]
	v_pk_mul_f32 v[116:117], v[196:197], v[116:117]
	v_pk_mul_f32 v[118:119], v[198:199], v[118:119]
	v_pk_mul_f32 v[120:121], v[200:201], v[120:121]
	v_pk_mul_f32 v[122:123], v[202:203], v[122:123]
	v_pk_mul_f32 v[124:125], v[204:205], v[124:125]
	v_pk_mul_f32 v[100:101], v[206:207], v[100:101]
	v_pk_fma_f32 v[112:113], v[208:209], v[112:113], v[224:225]
	v_pk_fma_f32 v[114:115], v[210:211], v[114:115], v[226:227]
	v_pk_fma_f32 v[116:117], v[212:213], v[116:117], v[228:229]
	v_pk_fma_f32 v[118:119], v[214:215], v[118:119], v[230:231]
	v_pk_fma_f32 v[120:121], v[216:217], v[120:121], v[232:233]
	v_pk_fma_f32 v[122:123], v[218:219], v[122:123], v[234:235]
	v_pk_fma_f32 v[124:125], v[220:221], v[124:125], v[236:237]
	v_pk_fma_f32 v[100:101], v[222:223], v[100:101], v[238:239]
	v_cvt_pk_bf16_f32 v240, v112, v113
	v_cvt_pk_bf16_f32 v241, v114, v115
	v_cvt_pk_bf16_f32 v242, v116, v117
	v_cvt_pk_bf16_f32 v243, v118, v119
	v_cvt_pk_bf16_f32 v244, v120, v121
	v_cvt_pk_bf16_f32 v245, v122, v123
	v_cvt_pk_bf16_f32 v246, v124, v125
	v_cvt_pk_bf16_f32 v247, v100, v101
	global_store_dwordx2 v1, v[240:241], s[70:71]
	global_store_dwordx2 v1, v[242:243], s[70:71] offset:512
	global_store_dwordx2 v1, v[244:245], s[70:71] offset:1024
	global_store_dwordx2 v1, v[246:247], s[70:71] offset:1536
	s_add_u32 s55, s55, 8
	s_add_u32 s57, s55, 16
	s_min_u32 s57, s57, s54
	s_cmp_lt_u32 s57, 0x8000
	s_cselect_b32 s64, s8, s10
	s_cselect_b32 s65, s9, s11
	s_cselect_b32 s60, 0, 0x8000
	s_sub_u32 s60, s57, s60
	s_lshl_b32 s60, s60, 12
	s_add_u32 s64, s64, s60
	s_addc_u32 s65, s65, 0
	s_lshl_b32 s60, s57, 11
	s_add_u32 s66, s82, s60
	s_addc_u32 s67, s83, 0
	global_load_dwordx4 v[4:7], v0, s[64:65] nt
	global_load_dwordx4 v[8:11], v0, s[64:65] offset:1024 nt
	global_load_dwordx4 v[12:15], v0, s[64:65] offset:2048 nt
	global_load_dwordx4 v[16:19], v0, s[64:65] offset:3072 nt
	global_load_dwordx2 v[20:21], v1, s[66:67] nt
	global_load_dwordx2 v[22:23], v1, s[66:67] offset:512 nt
	global_load_dwordx2 v[24:25], v1, s[66:67] offset:1024 nt
	global_load_dwordx2 v[26:27], v1, s[66:67] offset:1536 nt
	s_lshr_b32 s60, s55, 11
	s_sub_u32 s61, s55, 0x8000
	s_lshr_b32 s61, s61, 12
	s_add_u32 s61, s61, 16
	s_cmp_lt_u32 s55, 0x8000
	s_cselect_b32 s63, s60, s61
	s_cmp_eq_u32 s63, s56
	s_cbranch_scc1 .Lrp4_pk5
	s_mov_b32 s56, s63
	s_mul_i32 s60, s56, 0x9000
	s_add_u32 s60, s60, 0x3182000
	s_add_u32 s0, s92, s60
	s_addc_u32 s1, s93, 0
	global_load_dwordx4 v[160:163], v0, s[0:1]
	global_load_dwordx4 v[164:167], v0, s[0:1] offset:1024
	global_load_dwordx4 v[168:171], v0, s[0:1] offset:2048
	global_load_dwordx4 v[172:175], v0, s[0:1] offset:3072
	s_add_u32 s0, s22, 0x0
	s_addc_u32 s1, s23, 0
	global_load_dwordx4 v[176:179], v0, s[0:1]
	global_load_dwordx4 v[180:183], v0, s[0:1] offset:1024
	global_load_dwordx4 v[184:187], v0, s[0:1] offset:2048
	global_load_dwordx4 v[188:191], v0, s[0:1] offset:3072
	s_add_u32 s0, s20, 0x1000
	s_addc_u32 s1, s21, 0
	global_load_dwordx4 v[192:195], v0, s[0:1]
	global_load_dwordx4 v[196:199], v0, s[0:1] offset:1024
	global_load_dwordx4 v[200:203], v0, s[0:1] offset:2048
	global_load_dwordx4 v[204:207], v0, s[0:1] offset:3072
	s_mul_i32 s60, s56, 0x9000
	s_add_u32 s60, s60, 0x3184000
	s_add_u32 s0, s92, s60
	s_addc_u32 s1, s93, 0
	global_load_dwordx4 v[208:211], v0, s[0:1]
	global_load_dwordx4 v[212:215], v0, s[0:1] offset:1024
	global_load_dwordx4 v[216:219], v0, s[0:1] offset:2048
	global_load_dwordx4 v[220:223], v0, s[0:1] offset:3072
	s_mul_i32 s60, s56, 0x9000
	s_add_u32 s60, s60, 0x3183000
	s_add_u32 s0, s92, s60
	s_addc_u32 s1, s93, 0
	global_load_dwordx4 v[224:227], v0, s[0:1]
	global_load_dwordx4 v[228:231], v0, s[0:1] offset:1024
	global_load_dwordx4 v[232:235], v0, s[0:1] offset:2048
	global_load_dwordx4 v[236:239], v0, s[0:1] offset:3072
	s_waitcnt vmcnt(0)
	v_pk_add_f32 v[208:209], v[208:209], 1.0 op_sel_hi:[1,0]
	v_pk_add_f32 v[210:211], v[210:211], 1.0 op_sel_hi:[1,0]
	v_pk_add_f32 v[212:213], v[212:213], 1.0 op_sel_hi:[1,0]
	v_pk_add_f32 v[214:215], v[214:215], 1.0 op_sel_hi:[1,0]
	v_pk_add_f32 v[216:217], v[216:217], 1.0 op_sel_hi:[1,0]
	v_pk_add_f32 v[218:219], v[218:219], 1.0 op_sel_hi:[1,0]
	v_pk_add_f32 v[220:221], v[220:221], 1.0 op_sel_hi:[1,0]
	v_pk_add_f32 v[222:223], v[222:223], 1.0 op_sel_hi:[1,0]
; __device__ __forceinline__ float lo_bf(unsigned w) { return __uint_as_float(w << 16); }
; __device__ __forceinline__ float hi_bf(unsigned w) { return __uint_as_float(w & 0xffff0000u); }
; template <bool HAS_F, bool HAS_H>
; __device__ __forceinline__ void phase_rows(const Params& p, int sp, int sn, float resw, bool from_input, bool write_x = true) {
;     ...
;         if (HAS_F) {
;             f32x4 f[4]; float ss = 0.f;
; #pragma unroll
;             for (int j = 0; j < 4; ++j) { const u32x2 w = *(const u32x2*)(F + (size_t)row * D + 4 * lane + 256 * j);
;                 f[j] = (f32x4){lo_bf(w.x), hi_bf(w.x), lo_bf(w.y), hi_bf(w.y)}; ss += (f[j].x * f[j].x + f[j].y * f[j].y) + (f[j].z * f[j].z + f[j].w * f[j].w); }
;             const float rs = 1.0f / sqrtf(wave_sum(ss) * (1.0f / D) + EPS) * resw;
;             const float* gate = mod + b * 9216 + sp * 3072 + 2048; const float* gp = p.in[7] + sp * D;
; #pragma unroll
;             for (int j = 0; j < 4; ++j) { const f32x4 g = *(const f32x4*)(gate + 4 * lane + 256 * j), q = *(const f32x4*)(gp + 4 * lane + 256 * j);
;                 v[j] = v[j] + g * (f[j] * rs * q);
;                 if (write_x) *(f32x4*)(p.out + (size_t)row * D + 4 * lane + 256 * j) = v[j]; }
;         }
;         if (HAS_H) {
;             float ss = 0.f;
; #pragma unroll
;             for (int j = 0; j < 4; ++j) ss += (v[j].x * v[j].x + v[j].y * v[j].y) + (v[j].z * v[j].z + v[j].w * v[j].w);
;             const float rs = 1.0f / sqrtf(wave_sum(ss) * (1.0f / D) + EPS);
.Lrp4_pk5:
	s_waitcnt vmcnt(24)
	v_lshlrev_b32_e32 v112, 16, v52
	v_and_b32_e32 v113, 0xffff0000, v52
	v_lshlrev_b32_e32 v114, 16, v53
	v_and_b32_e32 v115, 0xffff0000, v53
	v_lshlrev_b32_e32 v116, 16, v54
	v_and_b32_e32 v117, 0xffff0000, v54
	v_lshlrev_b32_e32 v118, 16, v55
	v_and_b32_e32 v119, 0xffff0000, v55
	v_lshlrev_b32_e32 v120, 16, v56
	v_and_b32_e32 v121, 0xffff0000, v56
	v_lshlrev_b32_e32 v122, 16, v57
	v_and_b32_e32 v123, 0xffff0000, v57
	v_lshlrev_b32_e32 v124, 16, v58
	v_and_b32_e32 v125, 0xffff0000, v58
	v_lshlrev_b32_e32 v100, 16, v59
	v_and_b32_e32 v101, 0xffff0000, v59
	v_pk_mul_f32 v[102:103], v[112:113], v[112:113]
	v_pk_mul_f32 v[106:107], v[114:115], v[114:115]
	v_pk_fma_f32 v[102:103], v[116:117], v[116:117], v[102:103]
	v_pk_fma_f32 v[106:107], v[118:119], v[118:119], v[106:107]
	v_pk_fma_f32 v[102:103], v[120:121], v[120:121], v[102:103]
	v_pk_fma_f32 v[106:107], v[122:123], v[122:123], v[106:107]
	v_pk_fma_f32 v[102:103], v[124:125], v[124:125], v[102:103]
	v_pk_fma_f32 v[106:107], v[100:101], v[100:101], v[106:107]
	s_nop 0
	v_pk_add_f32 v[102:103], v[102:103], v[106:107]
	s_nop 0
	v_add_f32_e32 v102, v102, v103
	s_nop 1
	v_add_f32_dpp v102, v102, v102 quad_perm:[1,0,3,2] row_mask:0xf bank_mask:0xf
	s_nop 1
	v_add_f32_dpp v102, v102, v102 quad_perm:[2,3,0,1] row_mask:0xf bank_mask:0xf
	s_nop 1
	v_add_f32_dpp v102, v102, v102 row_half_mirror row_mask:0xf bank_mask:0xf
	s_nop 1
	v_add_f32_dpp v102, v102, v102 row_mirror row_mask:0xf bank_mask:0xf
	s_nop 1
	v_add_f32_dpp v102, v102, v102 row_bcast:15 row_mask:0xa bank_mask:0xf
	s_nop 1
	v_add_f32_dpp v102, v102, v102 row_bcast:31 row_mask:0xc bank_mask:0xf
	s_nop 1
	v_readlane_b32 s74, v102, 63
	s_nop 2
	v_mov_b32_e32 v102, s74
	v_fmamk_f32 v102, v102, 0x3a800000, v2
	v_mul_f32_e32 v103, 0x4f800000, v102
	v_cmp_gt_f32_e32 vcc, 0xf800000, v102
	s_nop 1
	v_cndmask_b32_e32 v102, v102, v103, vcc
	v_sqrt_f32_e32 v103, v102
	s_nop 0
	v_add_u32_e32 v104, -1, v103
	v_add_u32_e32 v106, 1, v103
	v_fma_f32 v107, -v104, v103, v102
	v_fma_f32 v108, -v106, v103, v102
	v_cmp_ge_f32_e64 s[76:77], 0, v107
	s_nop 1
	v_cndmask_b32_e64 v103, v103, v104, s[76:77]
	v_cmp_lt_f32_e64 s[76:77], 0, v108
	s_nop 1
	v_cndmask_b32_e64 v103, v103, v106, s[76:77]
	v_mul_f32_e32 v104, 0x37800000, v103
	v_cndmask_b32_e32 v103, v103, v104, vcc
	v_cmp_class_f32_e32 vcc, v102, v3
	s_nop 1
	v_cndmask_b32_e32 v102, v103, v102, vcc
	v_div_scale_f32 v103, s[76:77], v102, v102, 1.0
	v_rcp_f32_e32 v104, v103
	v_div_scale_f32 v106, vcc, 1.0, v102, 1.0
	v_fma_f32 v107, -v103, v104, 1.0
	v_fmac_f32_e32 v104, v107, v104
	v_mul_f32_e32 v107, v106, v104
	v_fma_f32 v108, -v103, v107, v106
	v_fmac_f32_e32 v107, v108, v104
	v_fma_f32 v103, -v103, v107, v106
	v_div_fmas_f32 v103, v103, v104, v107
	v_div_fixup_f32 v110, v103, v102, 1.0
	v_mul_f32_e32 v110, 0.5, v110
	v_pk_mul_f32 v[112:113], v[112:113], v[110:111] op_sel_hi:[1,0]
	v_pk_mul_f32 v[114:115], v[114:115], v[110:111] op_sel_hi:[1,0]
	v_pk_mul_f32 v[116:117], v[116:117], v[110:111] op_sel_hi:[1,0]
	v_pk_mul_f32 v[118:119], v[118:119], v[110:111] op_sel_hi:[1,0]
	v_pk_mul_f32 v[120:121], v[120:121], v[110:111] op_sel_hi:[1,0]
	v_pk_mul_f32 v[122:123], v[122:123], v[110:111] op_sel_hi:[1,0]
	v_pk_mul_f32 v[124:125], v[124:125], v[110:111] op_sel_hi:[1,0]
	v_pk_mul_f32 v[100:101], v[100:101], v[110:111] op_sel_hi:[1,0]
	v_pk_mul_f32 v[112:113], v[176:177], v[112:113]
	v_pk_mul_f32 v[114:115], v[178:179], v[114:115]
	v_pk_mul_f32 v[116:117], v[180:181], v[116:117]
	v_pk_mul_f32 v[118:119], v[182:183], v[118:119]
	v_pk_mul_f32 v[120:121], v[184:185], v[120:121]
	v_pk_mul_f32 v[122:123], v[186:187], v[122:123]
	v_pk_mul_f32 v[124:125], v[188:189], v[124:125]
	v_pk_mul_f32 v[100:101], v[190:191], v[100:101]
	v_pk_fma_f32 v[36:37], v[160:161], v[112:113], v[36:37]
	v_pk_fma_f32 v[38:39], v[162:163], v[114:115], v[38:39]
	v_pk_fma_f32 v[40:41], v[164:165], v[116:117], v[40:41]
	v_pk_fma_f32 v[42:43], v[166:167], v[118:119], v[42:43]
	v_pk_fma_f32 v[44:45], v[168:169], v[120:121], v[44:45]
	v_pk_fma_f32 v[46:47], v[170:171], v[122:123], v[46:47]
	v_pk_fma_f32 v[48:49], v[172:173], v[124:125], v[48:49]
	v_pk_fma_f32 v[50:51], v[174:175], v[100:101], v[50:51]
	s_lshl_b32 s60, s55, 12
	s_add_u32 s72, s84, s60
	s_addc_u32 s73, s85, 0
	global_store_dwordx4 v0, v[36:39], s[72:73] sc1
	global_store_dwordx4 v0, v[40:43], s[72:73] offset:1024 sc1
	global_store_dwordx4 v0, v[44:47], s[72:73] offset:2048 sc1
	global_store_dwordx4 v0, v[48:51], s[72:73] offset:3072 sc1
	v_pk_mul_f32 v[102:103], v[36:37], v[36:37]
	v_pk_mul_f32 v[106:107], v[38:39], v[38:39]
	v_pk_fma_f32 v[102:103], v[40:41], v[40:41], v[102:103]
	v_pk_fma_f32 v[106:107], v[42:43], v[42:43], v[106:107]
	v_pk_fma_f32 v[102:103], v[44:45], v[44:45], v[102:103]
	v_pk_fma_f32 v[106:107], v[46:47], v[46:47], v[106:107]
	v_pk_fma_f32 v[102:103], v[48:49], v[48:49], v[102:103]
	v_pk_fma_f32 v[106:107], v[50:51], v[50:51], v[106:107]
	s_nop 0
	v_pk_add_f32 v[102:103], v[102:103], v[106:107]
	s_nop 0
	v_add_f32_e32 v102, v102, v103
	s_nop 1
	v_add_f32_dpp v102, v102, v102 quad_perm:[1,0,3,2] row_mask:0xf bank_mask:0xf
	s_nop 1
	v_add_f32_dpp v102, v102, v102 quad_perm:[2,3,0,1] row_mask:0xf bank_mask:0xf
	s_nop 1
	v_add_f32_dpp v102, v102, v102 row_half_mirror row_mask:0xf bank_mask:0xf
	s_nop 1
	v_add_f32_dpp v102, v102, v102 row_mirror row_mask:0xf bank_mask:0xf
	s_nop 1
	v_add_f32_dpp v102, v102, v102 row_bcast:15 row_mask:0xa bank_mask:0xf
	s_nop 1
	v_add_f32_dpp v102, v102, v102 row_bcast:31 row_mask:0xc bank_mask:0xf
	s_nop 1
	v_readlane_b32 s74, v102, 63
	s_nop 2
	v_mov_b32_e32 v102, s74
	v_fmamk_f32 v102, v102, 0x3a800000, v2
; __device__ __forceinline__ unsigned pk_bf16(float lo, float hi) { const f32x2 v = {lo, hi}; const bf16x2_t b = __builtin_convertvector(v, bf16x2_t); return __builtin_bit_cast(unsigned, b); }
; template <bool HAS_F, bool HAS_H>
; __device__ __forceinline__ void phase_rows(const Params& p, int sp, int sn, float resw, bool from_input, bool write_x = true) {
;     ...
;         const float* xin = !from_input ? p.out + (size_t)row * D : (row < TP ? p.in[0] + (size_t)row * D : p.in[1] + (size_t)(row - TP) * D);
;         f32x4 v[4];
; #pragma unroll
;         for (int j = 0; j < 4; ++j) v[j] = *(const f32x4*)(xin + 4 * lane + 256 * j);
;         if (HAS_F) {
;             f32x4 f[4]; float ss = 0.f;
; #pragma unroll
;             for (int j = 0; j < 4; ++j) { const u32x2 w = *(const u32x2*)(F + (size_t)row * D + 4 * lane + 256 * j);
;     ...
;             const float rs = 1.0f / sqrtf(wave_sum(ss) * (1.0f / D) + EPS);
;             const float* sh = mod + b * 9216 + sn * 3072; const float* scl = sh + 1024; const float* gq = p.in[6] + sn * D;
; #pragma unroll
;             for (int j = 0; j < 4; ++j) { const f32x4 a = *(const f32x4*)(sh + 4 * lane + 256 * j), s = *(const f32x4*)(scl + 4 * lane + 256 * j), q = *(const f32x4*)(gq + 4 * lane + 256 * j);
;                 const f32x4 h = (v[j] * rs * q) * (s + 1.0f) + a;
;                 u32x2 w; w.x = pk_bf16(h.x, h.y); w.y = pk_bf16(h.z, h.w);
;                 *(u32x2*)(H + (size_t)row * D + 4 * lane + 256 * j) = w; }
	v_mul_f32_e32 v103, 0x4f800000, v102
	v_cmp_gt_f32_e32 vcc, 0xf800000, v102
	s_nop 1
	v_cndmask_b32_e32 v102, v102, v103, vcc
	v_sqrt_f32_e32 v103, v102
	s_nop 0
	v_add_u32_e32 v104, -1, v103
	v_add_u32_e32 v106, 1, v103
	v_fma_f32 v107, -v104, v103, v102
	v_fma_f32 v108, -v106, v103, v102
	v_cmp_ge_f32_e64 s[76:77], 0, v107
	s_nop 1
	v_cndmask_b32_e64 v103, v103, v104, s[76:77]
	v_cmp_lt_f32_e64 s[76:77], 0, v108
	s_nop 1
	v_cndmask_b32_e64 v103, v103, v106, s[76:77]
	v_mul_f32_e32 v104, 0x37800000, v103
	v_cndmask_b32_e32 v103, v103, v104, vcc
	v_cmp_class_f32_e32 vcc, v102, v3
	s_nop 1
	v_cndmask_b32_e32 v102, v103, v102, vcc
	v_div_scale_f32 v103, s[76:77], v102, v102, 1.0
	v_rcp_f32_e32 v104, v103
	v_div_scale_f32 v106, vcc, 1.0, v102, 1.0
	v_fma_f32 v107, -v103, v104, 1.0
	v_fmac_f32_e32 v104, v107, v104
	v_mul_f32_e32 v107, v106, v104
	v_fma_f32 v108, -v103, v107, v106
	v_fmac_f32_e32 v107, v108, v104
	v_fma_f32 v103, -v103, v107, v106
	v_div_fmas_f32 v103, v103, v104, v107
	v_div_fixup_f32 v110, v103, v102, 1.0
	s_lshl_b32 s60, s55, 11
	s_add_u32 s70, s78, s60
	s_addc_u32 s71, s79, 0
	v_pk_mul_f32 v[112:113], v[36:37], v[110:111] op_sel_hi:[1,0]
	v_pk_mul_f32 v[114:115], v[38:39], v[110:111] op_sel_hi:[1,0]
	v_pk_mul_f32 v[116:117], v[40:41], v[110:111] op_sel_hi:[1,0]
	v_pk_mul_f32 v[118:119], v[42:43], v[110:111] op_sel_hi:[1,0]
	v_pk_mul_f32 v[120:121], v[44:45], v[110:111] op_sel_hi:[1,0]
	v_pk_mul_f32 v[122:123], v[46:47], v[110:111] op_sel_hi:[1,0]
	v_pk_mul_f32 v[124:125], v[48:49], v[110:111] op_sel_hi:[1,0]
	v_pk_mul_f32 v[100:101], v[50:51], v[110:111] op_sel_hi:[1,0]
	v_pk_mul_f32 v[112:113], v[192:193], v[112:113]
	v_pk_mul_f32 v[114:115], v[194:195], v[114:115]
	v_pk_mul_f32 v[116:117], v[196:197], v[116:117]
	v_pk_mul_f32 v[118:119], v[198:199], v[118:119]
	v_pk_mul_f32 v[120:121], v[200:201], v[120:121]
	v_pk_mul_f32 v[122:123], v[202:203], v[122:123]
	v_pk_mul_f32 v[124:125], v[204:205], v[124:125]
	v_pk_mul_f32 v[100:101], v[206:207], v[100:101]
	v_pk_fma_f32 v[112:113], v[208:209], v[112:113], v[224:225]
	v_pk_fma_f32 v[114:115], v[210:211], v[114:115], v[226:227]
	v_pk_fma_f32 v[116:117], v[212:213], v[116:117], v[228:229]
	v_pk_fma_f32 v[118:119], v[214:215], v[118:119], v[230:231]
	v_pk_fma_f32 v[120:121], v[216:217], v[120:121], v[232:233]
	v_pk_fma_f32 v[122:123], v[218:219], v[122:123], v[234:235]
	v_pk_fma_f32 v[124:125], v[220:221], v[124:125], v[236:237]
	v_pk_fma_f32 v[100:101], v[222:223], v[100:101], v[238:239]
	v_cvt_pk_bf16_f32 v240, v112, v113
	v_cvt_pk_bf16_f32 v241, v114, v115
	v_cvt_pk_bf16_f32 v242, v116, v117
	v_cvt_pk_bf16_f32 v243, v118, v119
	v_cvt_pk_bf16_f32 v244, v120, v121
	v_cvt_pk_bf16_f32 v245, v122, v123
	v_cvt_pk_bf16_f32 v246, v124, v125
	v_cvt_pk_bf16_f32 v247, v100, v101
	global_store_dwordx2 v1, v[240:241], s[70:71]
	global_store_dwordx2 v1, v[242:243], s[70:71] offset:512
	global_store_dwordx2 v1, v[244:245], s[70:71] offset:1024
	global_store_dwordx2 v1, v[246:247], s[70:71] offset:1536
	s_add_u32 s55, s55, 8
	s_add_u32 s57, s55, 16
	s_min_u32 s57, s57, s54
	s_cmp_lt_u32 s57, 0x8000
	s_cselect_b32 s64, s8, s10
	s_cselect_b32 s65, s9, s11
	s_cselect_b32 s60, 0, 0x8000
	s_sub_u32 s60, s57, s60
	s_lshl_b32 s60, s60, 12
	s_add_u32 s64, s64, s60
	s_addc_u32 s65, s65, 0
	s_lshl_b32 s60, s57, 11
	s_add_u32 s66, s82, s60
	s_addc_u32 s67, s83, 0
	global_load_dwordx4 v[36:39], v0, s[64:65] nt
	global_load_dwordx4 v[40:43], v0, s[64:65] offset:1024 nt
	global_load_dwordx4 v[44:47], v0, s[64:65] offset:2048 nt
	global_load_dwordx4 v[48:51], v0, s[64:65] offset:3072 nt
	global_load_dwordx2 v[52:53], v1, s[66:67] nt
	global_load_dwordx2 v[54:55], v1, s[66:67] offset:512 nt
	global_load_dwordx2 v[56:57], v1, s[66:67] offset:1024 nt
	global_load_dwordx2 v[58:59], v1, s[66:67] offset:1536 nt
	s_lshr_b32 s60, s55, 11
	s_sub_u32 s61, s55, 0x8000
	s_lshr_b32 s61, s61, 12
	s_add_u32 s61, s61, 16
	s_cmp_lt_u32 s55, 0x8000
	s_cselect_b32 s63, s60, s61
	s_cmp_eq_u32 s63, s56
	s_cbranch_scc1 .Lrp4_pk6
	s_mov_b32 s56, s63
	s_mul_i32 s60, s56, 0x9000
	s_add_u32 s60, s60, 0x3182000
	s_add_u32 s0, s92, s60
	s_addc_u32 s1, s93, 0
	global_load_dwordx4 v[160:163], v0, s[0:1]
	global_load_dwordx4 v[164:167], v0, s[0:1] offset:1024
	global_load_dwordx4 v[168:171], v0, s[0:1] offset:2048
	global_load_dwordx4 v[172:175], v0, s[0:1] offset:3072
	s_add_u32 s0, s22, 0x0
	s_addc_u32 s1, s23, 0
	global_load_dwordx4 v[176:179], v0, s[0:1]
	global_load_dwordx4 v[180:183], v0, s[0:1] offset:1024
	global_load_dwordx4 v[184:187], v0, s[0:1] offset:2048
	global_load_dwordx4 v[188:191], v0, s[0:1] offset:3072
	s_add_u32 s0, s20, 0x1000
	s_addc_u32 s1, s21, 0
	global_load_dwordx4 v[192:195], v0, s[0:1]
	global_load_dwordx4 v[196:199], v0, s[0:1] offset:1024
	global_load_dwordx4 v[200:203], v0, s[0:1] offset:2048
	global_load_dwordx4 v[204:207], v0, s[0:1] offset:3072
	s_mul_i32 s60, s56, 0x9000
	s_add_u32 s60, s60, 0x3184000
	s_add_u32 s0, s92, s60
	s_addc_u32 s1, s93, 0
	global_load_dwordx4 v[208:211], v0, s[0:1]
	global_load_dwordx4 v[212:215], v0, s[0:1] offset:1024
	global_load_dwordx4 v[216:219], v0, s[0:1] offset:2048
	global_load_dwordx4 v[220:223], v0, s[0:1] offset:3072
	s_mul_i32 s60, s56, 0x9000
	s_add_u32 s60, s60, 0x3183000
	s_add_u32 s0, s92, s60
	s_addc_u32 s1, s93, 0
	global_load_dwordx4 v[224:227], v0, s[0:1]
	global_load_dwordx4 v[228:231], v0, s[0:1] offset:1024
	global_load_dwordx4 v[232:235], v0, s[0:1] offset:2048
	global_load_dwordx4 v[236:239], v0, s[0:1] offset:3072
	s_waitcnt vmcnt(0)
	v_pk_add_f32 v[208:209], v[208:209], 1.0 op_sel_hi:[1,0]
	v_pk_add_f32 v[210:211], v[210:211], 1.0 op_sel_hi:[1,0]
	v_pk_add_f32 v[212:213], v[212:213], 1.0 op_sel_hi:[1,0]
	v_pk_add_f32 v[214:215], v[214:215], 1.0 op_sel_hi:[1,0]
	v_pk_add_f32 v[216:217], v[216:217], 1.0 op_sel_hi:[1,0]
	v_pk_add_f32 v[218:219], v[218:219], 1.0 op_sel_hi:[1,0]
	v_pk_add_f32 v[220:221], v[220:221], 1.0 op_sel_hi:[1,0]
	v_pk_add_f32 v[222:223], v[222:223], 1.0 op_sel_hi:[1,0]
; __device__ __forceinline__ float lo_bf(unsigned w) { return __uint_as_float(w << 16); }
; __device__ __forceinline__ float hi_bf(unsigned w) { return __uint_as_float(w & 0xffff0000u); }
; template <bool HAS_F, bool HAS_H>
; __device__ __forceinline__ void phase_rows(const Params& p, int sp, int sn, float resw, bool from_input, bool write_x = true) {
;     ...
;         if (HAS_F) {
;             f32x4 f[4]; float ss = 0.f;
; #pragma unroll
;             for (int j = 0; j < 4; ++j) { const u32x2 w = *(const u32x2*)(F + (size_t)row * D + 4 * lane + 256 * j);
;                 f[j] = (f32x4){lo_bf(w.x), hi_bf(w.x), lo_bf(w.y), hi_bf(w.y)}; ss += (f[j].x * f[j].x + f[j].y * f[j].y) + (f[j].z * f[j].z + f[j].w * f[j].w); }
;             const float rs = 1.0f / sqrtf(wave_sum(ss) * (1.0f / D) + EPS) * resw;
;             const float* gate = mod + b * 9216 + sp * 3072 + 2048; const float* gp = p.in[7] + sp * D;
; #pragma unroll
;             for (int j = 0; j < 4; ++j) { const f32x4 g = *(const f32x4*)(gate + 4 * lane + 256 * j), q = *(const f32x4*)(gp + 4 * lane + 256 * j);
;                 v[j] = v[j] + g * (f[j] * rs * q);
;                 if (write_x) *(f32x4*)(p.out + (size_t)row * D + 4 * lane + 256 * j) = v[j]; }
.Lrp4_pk6:
	s_waitcnt vmcnt(32)
	v_lshlrev_b32_e32 v112, 16, v84
	v_and_b32_e32 v113, 0xffff0000, v84
	v_lshlrev_b32_e32 v114, 16, v85
	v_and_b32_e32 v115, 0xffff0000, v85
	v_lshlrev_b32_e32 v116, 16, v86
	v_and_b32_e32 v117, 0xffff0000, v86
	v_lshlrev_b32_e32 v118, 16, v87
	v_and_b32_e32 v119, 0xffff0000, v87
	v_lshlrev_b32_e32 v120, 16, v88
	v_and_b32_e32 v121, 0xffff0000, v88
	v_lshlrev_b32_e32 v122, 16, v89
	v_and_b32_e32 v123, 0xffff0000, v89
	v_lshlrev_b32_e32 v124, 16, v90
	v_and_b32_e32 v125, 0xffff0000, v90
	v_lshlrev_b32_e32 v100, 16, v91
	v_and_b32_e32 v101, 0xffff0000, v91
	v_pk_mul_f32 v[102:103], v[112:113], v[112:113]
	v_pk_mul_f32 v[106:107], v[114:115], v[114:115]
	v_pk_fma_f32 v[102:103], v[116:117], v[116:117], v[102:103]
	v_pk_fma_f32 v[106:107], v[118:119], v[118:119], v[106:107]
	v_pk_fma_f32 v[102:103], v[120:121], v[120:121], v[102:103]
	v_pk_fma_f32 v[106:107], v[122:123], v[122:123], v[106:107]
	v_pk_fma_f32 v[102:103], v[124:125], v[124:125], v[102:103]
	v_pk_fma_f32 v[106:107], v[100:101], v[100:101], v[106:107]
	s_nop 0
	v_pk_add_f32 v[102:103], v[102:103], v[106:107]
	s_nop 0
	v_add_f32_e32 v102, v102, v103
	s_nop 1
	v_add_f32_dpp v102, v102, v102 quad_perm:[1,0,3,2] row_mask:0xf bank_mask:0xf
	s_nop 1
	v_add_f32_dpp v102, v102, v102 quad_perm:[2,3,0,1] row_mask:0xf bank_mask:0xf
	s_nop 1
	v_add_f32_dpp v102, v102, v102 row_half_mirror row_mask:0xf bank_mask:0xf
	s_nop 1
	v_add_f32_dpp v102, v102, v102 row_mirror row_mask:0xf bank_mask:0xf
	s_nop 1
	v_add_f32_dpp v102, v102, v102 row_bcast:15 row_mask:0xa bank_mask:0xf
	s_nop 1
	v_add_f32_dpp v102, v102, v102 row_bcast:31 row_mask:0xc bank_mask:0xf
	s_nop 1
	v_readlane_b32 s74, v102, 63
	s_nop 2
	v_mov_b32_e32 v102, s74
	v_fmamk_f32 v102, v102, 0x3a800000, v2
	v_mul_f32_e32 v103, 0x4f800000, v102
	v_cmp_gt_f32_e32 vcc, 0xf800000, v102
	s_nop 1
	v_cndmask_b32_e32 v102, v102, v103, vcc
	v_sqrt_f32_e32 v103, v102
	s_nop 0
	v_add_u32_e32 v104, -1, v103
	v_add_u32_e32 v106, 1, v103
	v_fma_f32 v107, -v104, v103, v102
	v_fma_f32 v108, -v106, v103, v102
	v_cmp_ge_f32_e64 s[76:77], 0, v107
	s_nop 1
	v_cndmask_b32_e64 v103, v103, v104, s[76:77]
	v_cmp_lt_f32_e64 s[76:77], 0, v108
	s_nop 1
	v_cndmask_b32_e64 v103, v103, v106, s[76:77]
	v_mul_f32_e32 v104, 0x37800000, v103
	v_cndmask_b32_e32 v103, v103, v104, vcc
	v_cmp_class_f32_e32 vcc, v102, v3
	s_nop 1
	v_cndmask_b32_e32 v102, v103, v102, vcc
	v_div_scale_f32 v103, s[76:77], v102, v102, 1.0
	v_rcp_f32_e32 v104, v103
	v_div_scale_f32 v106, vcc, 1.0, v102, 1.0
	v_fma_f32 v107, -v103, v104, 1.0
	v_fmac_f32_e32 v104, v107, v104
	v_mul_f32_e32 v107, v106, v104
	v_fma_f32 v108, -v103, v107, v106
	v_fmac_f32_e32 v107, v108, v104
	v_fma_f32 v103, -v103, v107, v106
	v_div_fmas_f32 v103, v103, v104, v107
	v_div_fixup_f32 v110, v103, v102, 1.0
	v_mul_f32_e32 v110, 0.5, v110
	v_pk_mul_f32 v[112:113], v[112:113], v[110:111] op_sel_hi:[1,0]
	v_pk_mul_f32 v[114:115], v[114:115], v[110:111] op_sel_hi:[1,0]
	v_pk_mul_f32 v[116:117], v[116:117], v[110:111] op_sel_hi:[1,0]
	v_pk_mul_f32 v[118:119], v[118:119], v[110:111] op_sel_hi:[1,0]
	v_pk_mul_f32 v[120:121], v[120:121], v[110:111] op_sel_hi:[1,0]
	v_pk_mul_f32 v[122:123], v[122:123], v[110:111] op_sel_hi:[1,0]
	v_pk_mul_f32 v[124:125], v[124:125], v[110:111] op_sel_hi:[1,0]
	v_pk_mul_f32 v[100:101], v[100:101], v[110:111] op_sel_hi:[1,0]
	v_pk_mul_f32 v[112:113], v[176:177], v[112:113]
	v_pk_mul_f32 v[114:115], v[178:179], v[114:115]
	v_pk_mul_f32 v[116:117], v[180:181], v[116:117]
	v_pk_mul_f32 v[118:119], v[182:183], v[118:119]
	v_pk_mul_f32 v[120:121], v[184:185], v[120:121]
	v_pk_mul_f32 v[122:123], v[186:187], v[122:123]
	v_pk_mul_f32 v[124:125], v[188:189], v[124:125]
	v_pk_mul_f32 v[100:101], v[190:191], v[100:101]
	v_pk_fma_f32 v[68:69], v[160:161], v[112:113], v[68:69]
	v_pk_fma_f32 v[70:71], v[162:163], v[114:115], v[70:71]
	v_pk_fma_f32 v[72:73], v[164:165], v[116:117], v[72:73]
	v_pk_fma_f32 v[74:75], v[166:167], v[118:119], v[74:75]
	v_pk_fma_f32 v[76:77], v[168:169], v[120:121], v[76:77]
	v_pk_fma_f32 v[78:79], v[170:171], v[122:123], v[78:79]
	v_pk_fma_f32 v[80:81], v[172:173], v[124:125], v[80:81]
	v_pk_fma_f32 v[82:83], v[174:175], v[100:101], v[82:83]
	s_lshl_b32 s60, s55, 12
	s_add_u32 s72, s84, s60
	s_addc_u32 s73, s85, 0
	global_store_dwordx4 v0, v[68:71], s[72:73] sc1
; __device__ __forceinline__ unsigned pk_bf16(float lo, float hi) { const f32x2 v = {lo, hi}; const bf16x2_t b = __builtin_convertvector(v, bf16x2_t); return __builtin_bit_cast(unsigned, b); }
; template <bool HAS_F, bool HAS_H>
; __device__ __forceinline__ void phase_rows(const Params& p, int sp, int sn, float resw, bool from_input, bool write_x = true) {
;     ...
;                 if (write_x) *(f32x4*)(p.out + (size_t)row * D + 4 * lane + 256 * j) = v[j]; }
;         }
;         if (HAS_H) {
;             float ss = 0.f;
; #pragma unroll
;             for (int j = 0; j < 4; ++j) ss += (v[j].x * v[j].x + v[j].y * v[j].y) + (v[j].z * v[j].z + v[j].w * v[j].w);
;             const float rs = 1.0f / sqrtf(wave_sum(ss) * (1.0f / D) + EPS);
;             const float* sh = mod + b * 9216 + sn * 3072; const float* scl = sh + 1024; const float* gq = p.in[6] + sn * D;
; #pragma unroll
;             for (int j = 0; j < 4; ++j) { const f32x4 a = *(const f32x4*)(sh + 4 * lane + 256 * j), s = *(const f32x4*)(scl + 4 * lane + 256 * j), q = *(const f32x4*)(gq + 4 * lane + 256 * j);
;                 const f32x4 h = (v[j] * rs * q) * (s + 1.0f) + a;
;                 u32x2 w; w.x = pk_bf16(h.x, h.y); w.y = pk_bf16(h.z, h.w);
;                 *(u32x2*)(H + (size_t)row * D + 4 * lane + 256 * j) = w; }
	global_store_dwordx4 v0, v[72:75], s[72:73] offset:1024 sc1
	global_store_dwordx4 v0, v[76:79], s[72:73] offset:2048 sc1
	global_store_dwordx4 v0, v[80:83], s[72:73] offset:3072 sc1
	v_pk_mul_f32 v[102:103], v[68:69], v[68:69]
	v_pk_mul_f32 v[106:107], v[70:71], v[70:71]
	v_pk_fma_f32 v[102:103], v[72:73], v[72:73], v[102:103]
	v_pk_fma_f32 v[106:107], v[74:75], v[74:75], v[106:107]
	v_pk_fma_f32 v[102:103], v[76:77], v[76:77], v[102:103]
	v_pk_fma_f32 v[106:107], v[78:79], v[78:79], v[106:107]
	v_pk_fma_f32 v[102:103], v[80:81], v[80:81], v[102:103]
	v_pk_fma_f32 v[106:107], v[82:83], v[82:83], v[106:107]
	s_nop 0
	v_pk_add_f32 v[102:103], v[102:103], v[106:107]
	s_nop 0
	v_add_f32_e32 v102, v102, v103
	s_nop 1
	v_add_f32_dpp v102, v102, v102 quad_perm:[1,0,3,2] row_mask:0xf bank_mask:0xf
	s_nop 1
	v_add_f32_dpp v102, v102, v102 quad_perm:[2,3,0,1] row_mask:0xf bank_mask:0xf
	s_nop 1
	v_add_f32_dpp v102, v102, v102 row_half_mirror row_mask:0xf bank_mask:0xf
	s_nop 1
	v_add_f32_dpp v102, v102, v102 row_mirror row_mask:0xf bank_mask:0xf
	s_nop 1
	v_add_f32_dpp v102, v102, v102 row_bcast:15 row_mask:0xa bank_mask:0xf
	s_nop 1
	v_add_f32_dpp v102, v102, v102 row_bcast:31 row_mask:0xc bank_mask:0xf
	s_nop 1
	v_readlane_b32 s74, v102, 63
	s_nop 2
	v_mov_b32_e32 v102, s74
	v_fmamk_f32 v102, v102, 0x3a800000, v2
	v_mul_f32_e32 v103, 0x4f800000, v102
	v_cmp_gt_f32_e32 vcc, 0xf800000, v102
	s_nop 1
	v_cndmask_b32_e32 v102, v102, v103, vcc
	v_sqrt_f32_e32 v103, v102
	s_nop 0
	v_add_u32_e32 v104, -1, v103
	v_add_u32_e32 v106, 1, v103
	v_fma_f32 v107, -v104, v103, v102
	v_fma_f32 v108, -v106, v103, v102
	v_cmp_ge_f32_e64 s[76:77], 0, v107
	s_nop 1
	v_cndmask_b32_e64 v103, v103, v104, s[76:77]
	v_cmp_lt_f32_e64 s[76:77], 0, v108
	s_nop 1
	v_cndmask_b32_e64 v103, v103, v106, s[76:77]
	v_mul_f32_e32 v104, 0x37800000, v103
	v_cndmask_b32_e32 v103, v103, v104, vcc
	v_cmp_class_f32_e32 vcc, v102, v3
	s_nop 1
	v_cndmask_b32_e32 v102, v103, v102, vcc
	v_div_scale_f32 v103, s[76:77], v102, v102, 1.0
	v_rcp_f32_e32 v104, v103
	v_div_scale_f32 v106, vcc, 1.0, v102, 1.0
	v_fma_f32 v107, -v103, v104, 1.0
	v_fmac_f32_e32 v104, v107, v104
	v_mul_f32_e32 v107, v106, v104
	v_fma_f32 v108, -v103, v107, v106
	v_fmac_f32_e32 v107, v108, v104
	v_fma_f32 v103, -v103, v107, v106
	v_div_fmas_f32 v103, v103, v104, v107
	v_div_fixup_f32 v110, v103, v102, 1.0
	s_lshl_b32 s60, s55, 11
	s_add_u32 s70, s78, s60
	s_addc_u32 s71, s79, 0
	v_pk_mul_f32 v[112:113], v[68:69], v[110:111] op_sel_hi:[1,0]
	v_pk_mul_f32 v[114:115], v[70:71], v[110:111] op_sel_hi:[1,0]
	v_pk_mul_f32 v[116:117], v[72:73], v[110:111] op_sel_hi:[1,0]
	v_pk_mul_f32 v[118:119], v[74:75], v[110:111] op_sel_hi:[1,0]
	v_pk_mul_f32 v[120:121], v[76:77], v[110:111] op_sel_hi:[1,0]
	v_pk_mul_f32 v[122:123], v[78:79], v[110:111] op_sel_hi:[1,0]
	v_pk_mul_f32 v[124:125], v[80:81], v[110:111] op_sel_hi:[1,0]
	v_pk_mul_f32 v[100:101], v[82:83], v[110:111] op_sel_hi:[1,0]
	v_pk_mul_f32 v[112:113], v[192:193], v[112:113]
	v_pk_mul_f32 v[114:115], v[194:195], v[114:115]
	v_pk_mul_f32 v[116:117], v[196:197], v[116:117]
	v_pk_mul_f32 v[118:119], v[198:199], v[118:119]
	v_pk_mul_f32 v[120:121], v[200:201], v[120:121]
	v_pk_mul_f32 v[122:123], v[202:203], v[122:123]
	v_pk_mul_f32 v[124:125], v[204:205], v[124:125]
	v_pk_mul_f32 v[100:101], v[206:207], v[100:101]
	v_pk_fma_f32 v[112:113], v[208:209], v[112:113], v[224:225]
	v_pk_fma_f32 v[114:115], v[210:211], v[114:115], v[226:227]
	v_pk_fma_f32 v[116:117], v[212:213], v[116:117], v[228:229]
	v_pk_fma_f32 v[118:119], v[214:215], v[118:119], v[230:231]
	v_pk_fma_f32 v[120:121], v[216:217], v[120:121], v[232:233]
	v_pk_fma_f32 v[122:123], v[218:219], v[122:123], v[234:235]
	v_pk_fma_f32 v[124:125], v[220:221], v[124:125], v[236:237]
	v_pk_fma_f32 v[100:101], v[222:223], v[100:101], v[238:239]
	v_cvt_pk_bf16_f32 v240, v112, v113
	v_cvt_pk_bf16_f32 v241, v114, v115
	v_cvt_pk_bf16_f32 v242, v116, v117
	v_cvt_pk_bf16_f32 v243, v118, v119
	v_cvt_pk_bf16_f32 v244, v120, v121
	v_cvt_pk_bf16_f32 v245, v122, v123
	v_cvt_pk_bf16_f32 v246, v124, v125
	v_cvt_pk_bf16_f32 v247, v100, v101
	global_store_dwordx2 v1, v[240:241], s[70:71]
	global_store_dwordx2 v1, v[242:243], s[70:71] offset:512
	global_store_dwordx2 v1, v[244:245], s[70:71] offset:1024
	global_store_dwordx2 v1, v[246:247], s[70:71] offset:1536
	s_add_u32 s55, s55, 8

; __device__ __forceinline__ float lo_bf(unsigned w) { return __uint_as_float(w << 16); }
; __device__ __forceinline__ float hi_bf(unsigned w) { return __uint_as_float(w & 0xffff0000u); }
; template <bool HAS_F, bool HAS_H>
; __device__ __forceinline__ void phase_rows(const Params& p, int sp, int sn, float resw, bool from_input, bool write_x = true) {
;     ...
;         if (HAS_F) {
;             f32x4 f[4]; float ss = 0.f;
; #pragma unroll
;             for (int j = 0; j < 4; ++j) { const u32x2 w = *(const u32x2*)(F + (size_t)row * D + 4 * lane + 256 * j);
;                 f[j] = (f32x4){lo_bf(w.x), hi_bf(w.x), lo_bf(w.y), hi_bf(w.y)}; ss += (f[j].x * f[j].x + f[j].y * f[j].y) + (f[j].z * f[j].z + f[j].w * f[j].w); }
;             const float rs = 1.0f / sqrtf(wave_sum(ss) * (1.0f / D) + EPS) * resw;
;             const float* gate = mod + b * 9216 + sp * 3072 + 2048; const float* gp = p.in[7] + sp * D;
; #pragma unroll
;             for (int j = 0; j < 4; ++j) { const f32x4 g = *(const f32x4*)(gate + 4 * lane + 256 * j), q = *(const f32x4*)(gp + 4 * lane + 256 * j);
;                 v[j] = v[j] + g * (f[j] * rs * q);
;                 if (write_x) *(f32x4*)(p.out + (size_t)row * D + 4 * lane + 256 * j) = v[j]; }
;         }
;         if (HAS_H) {
;             float ss = 0.f;
; #pragma unroll
;             for (int j = 0; j < 4; ++j) ss += (v[j].x * v[j].x + v[j].y * v[j].y) + (v[j].z * v[j].z + v[j].w * v[j].w);
;             const float rs = 1.0f / sqrtf(wave_sum(ss) * (1.0f / D) + EPS);
.Lrp4_pk7:
	s_waitcnt vmcnt(32)
	v_lshlrev_b32_e32 v112, 16, v20
	v_and_b32_e32 v113, 0xffff0000, v20
	v_lshlrev_b32_e32 v114, 16, v21
	v_and_b32_e32 v115, 0xffff0000, v21
	v_lshlrev_b32_e32 v116, 16, v22
	v_and_b32_e32 v117, 0xffff0000, v22
	v_lshlrev_b32_e32 v118, 16, v23
	v_and_b32_e32 v119, 0xffff0000, v23
	v_lshlrev_b32_e32 v120, 16, v24
	v_and_b32_e32 v121, 0xffff0000, v24
	v_lshlrev_b32_e32 v122, 16, v25
	v_and_b32_e32 v123, 0xffff0000, v25
	v_lshlrev_b32_e32 v124, 16, v26
	v_and_b32_e32 v125, 0xffff0000, v26
	v_lshlrev_b32_e32 v100, 16, v27
	v_and_b32_e32 v101, 0xffff0000, v27
	v_pk_mul_f32 v[102:103], v[112:113], v[112:113]
	v_pk_mul_f32 v[106:107], v[114:115], v[114:115]
	v_pk_fma_f32 v[102:103], v[116:117], v[116:117], v[102:103]
	v_pk_fma_f32 v[106:107], v[118:119], v[118:119], v[106:107]
	v_pk_fma_f32 v[102:103], v[120:121], v[120:121], v[102:103]
	v_pk_fma_f32 v[106:107], v[122:123], v[122:123], v[106:107]
	v_pk_fma_f32 v[102:103], v[124:125], v[124:125], v[102:103]
	v_pk_fma_f32 v[106:107], v[100:101], v[100:101], v[106:107]
	s_nop 0
	v_pk_add_f32 v[102:103], v[102:103], v[106:107]
	s_nop 0
	v_add_f32_e32 v102, v102, v103
	s_nop 1
	v_add_f32_dpp v102, v102, v102 quad_perm:[1,0,3,2] row_mask:0xf bank_mask:0xf
	s_nop 1
	v_add_f32_dpp v102, v102, v102 quad_perm:[2,3,0,1] row_mask:0xf bank_mask:0xf
	s_nop 1
	v_add_f32_dpp v102, v102, v102 row_half_mirror row_mask:0xf bank_mask:0xf
	s_nop 1
	v_add_f32_dpp v102, v102, v102 row_mirror row_mask:0xf bank_mask:0xf
	s_nop 1
	v_add_f32_dpp v102, v102, v102 row_bcast:15 row_mask:0xa bank_mask:0xf
	s_nop 1
	v_add_f32_dpp v102, v102, v102 row_bcast:31 row_mask:0xc bank_mask:0xf
	s_nop 1
	v_readlane_b32 s74, v102, 63
	s_nop 2
	v_mov_b32_e32 v102, s74
	v_fmamk_f32 v102, v102, 0x3a800000, v2
	v_mul_f32_e32 v103, 0x4f800000, v102
	v_cmp_gt_f32_e32 vcc, 0xf800000, v102
	s_nop 1
	v_cndmask_b32_e32 v102, v102, v103, vcc
	v_sqrt_f32_e32 v103, v102
	s_nop 0
	v_add_u32_e32 v104, -1, v103
	v_add_u32_e32 v106, 1, v103
	v_fma_f32 v107, -v104, v103, v102
	v_fma_f32 v108, -v106, v103, v102
	v_cmp_ge_f32_e64 s[76:77], 0, v107
	s_nop 1
	v_cndmask_b32_e64 v103, v103, v104, s[76:77]
	v_cmp_lt_f32_e64 s[76:77], 0, v108
	s_nop 1
	v_cndmask_b32_e64 v103, v103, v106, s[76:77]
	v_mul_f32_e32 v104, 0x37800000, v103
	v_cndmask_b32_e32 v103, v103, v104, vcc
	v_cmp_class_f32_e32 vcc, v102, v3
	s_nop 1
	v_cndmask_b32_e32 v102, v103, v102, vcc
	v_div_scale_f32 v103, s[76:77], v102, v102, 1.0
	v_rcp_f32_e32 v104, v103
	v_div_scale_f32 v106, vcc, 1.0, v102, 1.0
	v_fma_f32 v107, -v103, v104, 1.0
	v_fmac_f32_e32 v104, v107, v104
	v_mul_f32_e32 v107, v106, v104
	v_fma_f32 v108, -v103, v107, v106
	v_fmac_f32_e32 v107, v108, v104
	v_fma_f32 v103, -v103, v107, v106
	v_div_fmas_f32 v103, v103, v104, v107
	v_div_fixup_f32 v110, v103, v102, 1.0
	v_mul_f32_e32 v110, 0.5, v110
	v_pk_mul_f32 v[112:113], v[112:113], v[110:111] op_sel_hi:[1,0]
	v_pk_mul_f32 v[114:115], v[114:115], v[110:111] op_sel_hi:[1,0]
	v_pk_mul_f32 v[116:117], v[116:117], v[110:111] op_sel_hi:[1,0]
	v_pk_mul_f32 v[118:119], v[118:119], v[110:111] op_sel_hi:[1,0]
	v_pk_mul_f32 v[120:121], v[120:121], v[110:111] op_sel_hi:[1,0]
	v_pk_mul_f32 v[122:123], v[122:123], v[110:111] op_sel_hi:[1,0]
	v_pk_mul_f32 v[124:125], v[124:125], v[110:111] op_sel_hi:[1,0]
	v_pk_mul_f32 v[100:101], v[100:101], v[110:111] op_sel_hi:[1,0]
	v_pk_mul_f32 v[112:113], v[176:177], v[112:113]
	v_pk_mul_f32 v[114:115], v[178:179], v[114:115]
	v_pk_mul_f32 v[116:117], v[180:181], v[116:117]
	v_pk_mul_f32 v[118:119], v[182:183], v[118:119]
	v_pk_mul_f32 v[120:121], v[184:185], v[120:121]
	v_pk_mul_f32 v[122:123], v[186:187], v[122:123]
	v_pk_mul_f32 v[124:125], v[188:189], v[124:125]
	v_pk_mul_f32 v[100:101], v[190:191], v[100:101]
	v_pk_fma_f32 v[4:5], v[160:161], v[112:113], v[4:5]
	v_pk_fma_f32 v[6:7], v[162:163], v[114:115], v[6:7]
	v_pk_fma_f32 v[8:9], v[164:165], v[116:117], v[8:9]
	v_pk_fma_f32 v[10:11], v[166:167], v[118:119], v[10:11]
	v_pk_fma_f32 v[12:13], v[168:169], v[120:121], v[12:13]
	v_pk_fma_f32 v[14:15], v[170:171], v[122:123], v[14:15]
	v_pk_fma_f32 v[16:17], v[172:173], v[124:125], v[16:17]
	v_pk_fma_f32 v[18:19], v[174:175], v[100:101], v[18:19]
	s_lshl_b32 s60, s55, 12
	s_add_u32 s72, s84, s60
	s_addc_u32 s73, s85, 0
	global_store_dwordx4 v0, v[4:7], s[72:73] sc1
	global_store_dwordx4 v0, v[8:11], s[72:73] offset:1024 sc1
	global_store_dwordx4 v0, v[12:15], s[72:73] offset:2048 sc1
	global_store_dwordx4 v0, v[16:19], s[72:73] offset:3072 sc1
	v_pk_mul_f32 v[102:103], v[4:5], v[4:5]
	v_pk_mul_f32 v[106:107], v[6:7], v[6:7]
	v_pk_fma_f32 v[102:103], v[8:9], v[8:9], v[102:103]
	v_pk_fma_f32 v[106:107], v[10:11], v[10:11], v[106:107]
	v_pk_fma_f32 v[102:103], v[12:13], v[12:13], v[102:103]
	v_pk_fma_f32 v[106:107], v[14:15], v[14:15], v[106:107]
	v_pk_fma_f32 v[102:103], v[16:17], v[16:17], v[102:103]
	v_pk_fma_f32 v[106:107], v[18:19], v[18:19], v[106:107]
	s_nop 0
	v_pk_add_f32 v[102:103], v[102:103], v[106:107]
	s_nop 0
	v_add_f32_e32 v102, v102, v103
	s_nop 1
	v_add_f32_dpp v102, v102, v102 quad_perm:[1,0,3,2] row_mask:0xf bank_mask:0xf
	s_nop 1
	v_add_f32_dpp v102, v102, v102 quad_perm:[2,3,0,1] row_mask:0xf bank_mask:0xf
	s_nop 1
	v_add_f32_dpp v102, v102, v102 row_half_mirror row_mask:0xf bank_mask:0xf
	s_nop 1
	v_add_f32_dpp v102, v102, v102 row_mirror row_mask:0xf bank_mask:0xf
	s_nop 1
	v_add_f32_dpp v102, v102, v102 row_bcast:15 row_mask:0xa bank_mask:0xf
	s_nop 1
	v_add_f32_dpp v102, v102, v102 row_bcast:31 row_mask:0xc bank_mask:0xf
	s_nop 1
	v_readlane_b32 s74, v102, 63
	s_nop 2
	v_mov_b32_e32 v102, s74
	v_fmamk_f32 v102, v102, 0x3a800000, v2
; __device__ __forceinline__ unsigned pk_bf16(float lo, float hi) { const f32x2 v = {lo, hi}; const bf16x2_t b = __builtin_convertvector(v, bf16x2_t); return __builtin_bit_cast(unsigned, b); }
; template <bool HAS_F, bool HAS_H>
; __device__ __forceinline__ void phase_rows(const Params& p, int sp, int sn, float resw, bool from_input, bool write_x = true) {
;     ...
;         const float* xin = !from_input ? p.out + (size_t)row * D : (row < TP ? p.in[0] + (size_t)row * D : p.in[1] + (size_t)(row - TP) * D);
;         f32x4 v[4];
; #pragma unroll
;         for (int j = 0; j < 4; ++j) v[j] = *(const f32x4*)(xin + 4 * lane + 256 * j);
;         if (HAS_F) {
;             f32x4 f[4]; float ss = 0.f;
; #pragma unroll
;             for (int j = 0; j < 4; ++j) { const u32x2 w = *(const u32x2*)(F + (size_t)row * D + 4 * lane + 256 * j);
;     ...
;             const float rs = 1.0f / sqrtf(wave_sum(ss) * (1.0f / D) + EPS);
;             const float* sh = mod + b * 9216 + sn * 3072; const float* scl = sh + 1024; const float* gq = p.in[6] + sn * D;
; #pragma unroll
;             for (int j = 0; j < 4; ++j) { const f32x4 a = *(const f32x4*)(sh + 4 * lane + 256 * j), s = *(const f32x4*)(scl + 4 * lane + 256 * j), q = *(const f32x4*)(gq + 4 * lane + 256 * j);
;                 const f32x4 h = (v[j] * rs * q) * (s + 1.0f) + a;
;                 u32x2 w; w.x = pk_bf16(h.x, h.y); w.y = pk_bf16(h.z, h.w);
;                 *(u32x2*)(H + (size_t)row * D + 4 * lane + 256 * j) = w; }
	v_mul_f32_e32 v103, 0x4f800000, v102
	v_cmp_gt_f32_e32 vcc, 0xf800000, v102
	s_nop 1
	v_cndmask_b32_e32 v102, v102, v103, vcc
	v_sqrt_f32_e32 v103, v102
	s_nop 0
	v_add_u32_e32 v104, -1, v103
	v_add_u32_e32 v106, 1, v103
	v_fma_f32 v107, -v104, v103, v102
	v_fma_f32 v108, -v106, v103, v102
	v_cmp_ge_f32_e64 s[76:77], 0, v107
	s_nop 1
	v_cndmask_b32_e64 v103, v103, v104, s[76:77]
	v_cmp_lt_f32_e64 s[76:77], 0, v108
	s_nop 1
	v_cndmask_b32_e64 v103, v103, v106, s[76:77]
	v_mul_f32_e32 v104, 0x37800000, v103
	v_cndmask_b32_e32 v103, v103, v104, vcc
	v_cmp_class_f32_e32 vcc, v102, v3
	s_nop 1
	v_cndmask_b32_e32 v102, v103, v102, vcc
	v_div_scale_f32 v103, s[76:77], v102, v102, 1.0
	v_rcp_f32_e32 v104, v103
	v_div_scale_f32 v106, vcc, 1.0, v102, 1.0
	v_fma_f32 v107, -v103, v104, 1.0
	v_fmac_f32_e32 v104, v107, v104
	v_mul_f32_e32 v107, v106, v104
	v_fma_f32 v108, -v103, v107, v106
	v_fmac_f32_e32 v107, v108, v104
	v_fma_f32 v103, -v103, v107, v106
	v_div_fmas_f32 v103, v103, v104, v107
	v_div_fixup_f32 v110, v103, v102, 1.0
	s_lshl_b32 s60, s55, 11
	s_add_u32 s70, s78, s60
	s_addc_u32 s71, s79, 0
	v_pk_mul_f32 v[112:113], v[4:5], v[110:111] op_sel_hi:[1,0]
	v_pk_mul_f32 v[114:115], v[6:7], v[110:111] op_sel_hi:[1,0]
	v_pk_mul_f32 v[116:117], v[8:9], v[110:111] op_sel_hi:[1,0]
	v_pk_mul_f32 v[118:119], v[10:11], v[110:111] op_sel_hi:[1,0]
	v_pk_mul_f32 v[120:121], v[12:13], v[110:111] op_sel_hi:[1,0]
	v_pk_mul_f32 v[122:123], v[14:15], v[110:111] op_sel_hi:[1,0]
	v_pk_mul_f32 v[124:125], v[16:17], v[110:111] op_sel_hi:[1,0]
	v_pk_mul_f32 v[100:101], v[18:19], v[110:111] op_sel_hi:[1,0]
	v_pk_mul_f32 v[112:113], v[192:193], v[112:113]
	v_pk_mul_f32 v[114:115], v[194:195], v[114:115]
	v_pk_mul_f32 v[116:117], v[196:197], v[116:117]
	v_pk_mul_f32 v[118:119], v[198:199], v[118:119]
	v_pk_mul_f32 v[120:121], v[200:201], v[120:121]
	v_pk_mul_f32 v[122:123], v[202:203], v[122:123]
	v_pk_mul_f32 v[124:125], v[204:205], v[124:125]
	v_pk_mul_f32 v[100:101], v[206:207], v[100:101]
	v_pk_fma_f32 v[112:113], v[208:209], v[112:113], v[224:225]
	v_pk_fma_f32 v[114:115], v[210:211], v[114:115], v[226:227]
	v_pk_fma_f32 v[116:117], v[212:213], v[116:117], v[228:229]
	v_pk_fma_f32 v[118:119], v[214:215], v[118:119], v[230:231]
	v_pk_fma_f32 v[120:121], v[216:217], v[120:121], v[232:233]
	v_pk_fma_f32 v[122:123], v[218:219], v[122:123], v[234:235]
	v_pk_fma_f32 v[124:125], v[220:221], v[124:125], v[236:237]
	v_pk_fma_f32 v[100:101], v[222:223], v[100:101], v[238:239]
	v_cvt_pk_bf16_f32 v240, v112, v113
	v_cvt_pk_bf16_f32 v241, v114, v115
	v_cvt_pk_bf16_f32 v242, v116, v117
	v_cvt_pk_bf16_f32 v243, v118, v119
	v_cvt_pk_bf16_f32 v244, v120, v121
	v_cvt_pk_bf16_f32 v245, v122, v123
	v_cvt_pk_bf16_f32 v246, v124, v125
	v_cvt_pk_bf16_f32 v247, v100, v101
	global_store_dwordx2 v1, v[240:241], s[70:71]
	global_store_dwordx2 v1, v[242:243], s[70:71] offset:512
	global_store_dwordx2 v1, v[244:245], s[70:71] offset:1024
	global_store_dwordx2 v1, v[246:247], s[70:71] offset:1536
	s_add_u32 s55, s55, 8
	s_add_u32 s57, s55, 16
	s_min_u32 s57, s57, s54
	s_cmp_lt_u32 s57, 0x8000
	s_cselect_b32 s64, s8, s10
	s_cselect_b32 s65, s9, s11
	s_cselect_b32 s60, 0, 0x8000
	s_sub_u32 s60, s57, s60
	s_lshl_b32 s60, s60, 12
	s_add_u32 s64, s64, s60
	s_addc_u32 s65, s65, 0
	s_lshl_b32 s60, s57, 11
	s_add_u32 s66, s82, s60
	s_addc_u32 s67, s83, 0
	global_load_dwordx4 v[4:7], v0, s[64:65] nt
	global_load_dwordx4 v[8:11], v0, s[64:65] offset:1024 nt
	global_load_dwordx4 v[12:15], v0, s[64:65] offset:2048 nt
	global_load_dwordx4 v[16:19], v0, s[64:65] offset:3072 nt
	global_load_dwordx2 v[20:21], v1, s[66:67] nt
	global_load_dwordx2 v[22:23], v1, s[66:67] offset:512 nt
	global_load_dwordx2 v[24:25], v1, s[66:67] offset:1024 nt
	global_load_dwordx2 v[26:27], v1, s[66:67] offset:1536 nt
	s_lshr_b32 s60, s55, 11
	s_sub_u32 s61, s55, 0x8000
	s_lshr_b32 s61, s61, 12
	s_add_u32 s61, s61, 16
	s_cmp_lt_u32 s55, 0x8000
	s_cselect_b32 s63, s60, s61
	s_cmp_eq_u32 s63, s56
	s_cbranch_scc1 .Lrp4_pk8
	s_mov_b32 s56, s63
	s_mul_i32 s60, s56, 0x9000
	s_add_u32 s60, s60, 0x3182000
	s_add_u32 s0, s92, s60
	s_addc_u32 s1, s93, 0
	global_load_dwordx4 v[160:163], v0, s[0:1]
	global_load_dwordx4 v[164:167], v0, s[0:1] offset:1024
	global_load_dwordx4 v[168:171], v0, s[0:1] offset:2048
	global_load_dwordx4 v[172:175], v0, s[0:1] offset:3072
	s_add_u32 s0, s22, 0x0
	s_addc_u32 s1, s23, 0
	global_load_dwordx4 v[176:179], v0, s[0:1]
	global_load_dwordx4 v[180:183], v0, s[0:1] offset:1024
	global_load_dwordx4 v[184:187], v0, s[0:1] offset:2048
	global_load_dwordx4 v[188:191], v0, s[0:1] offset:3072
	s_add_u32 s0, s20, 0x1000
	s_addc_u32 s1, s21, 0
	global_load_dwordx4 v[192:195], v0, s[0:1]
	global_load_dwordx4 v[196:199], v0, s[0:1] offset:1024
	global_load_dwordx4 v[200:203], v0, s[0:1] offset:2048
	global_load_dwordx4 v[204:207], v0, s[0:1] offset:3072
	s_mul_i32 s60, s56, 0x9000
	s_add_u32 s60, s60, 0x3184000
	s_add_u32 s0, s92, s60
	s_addc_u32 s1, s93, 0
	global_load_dwordx4 v[208:211], v0, s[0:1]
	global_load_dwordx4 v[212:215], v0, s[0:1] offset:1024
	global_load_dwordx4 v[216:219], v0, s[0:1] offset:2048
	global_load_dwordx4 v[220:223], v0, s[0:1] offset:3072
	s_mul_i32 s60, s56, 0x9000
	s_add_u32 s60, s60, 0x3183000
	s_add_u32 s0, s92, s60
	s_addc_u32 s1, s93, 0
	global_load_dwordx4 v[224:227], v0, s[0:1]
	global_load_dwordx4 v[228:231], v0, s[0:1] offset:1024
	global_load_dwordx4 v[232:235], v0, s[0:1] offset:2048
	global_load_dwordx4 v[236:239], v0, s[0:1] offset:3072
	s_waitcnt vmcnt(0)
	v_pk_add_f32 v[208:209], v[208:209], 1.0 op_sel_hi:[1,0]
	v_pk_add_f32 v[210:211], v[210:211], 1.0 op_sel_hi:[1,0]
	v_pk_add_f32 v[212:213], v[212:213], 1.0 op_sel_hi:[1,0]
	v_pk_add_f32 v[214:215], v[214:215], 1.0 op_sel_hi:[1,0]
	v_pk_add_f32 v[216:217], v[216:217], 1.0 op_sel_hi:[1,0]
	v_pk_add_f32 v[218:219], v[218:219], 1.0 op_sel_hi:[1,0]
	v_pk_add_f32 v[220:221], v[220:221], 1.0 op_sel_hi:[1,0]
	v_pk_add_f32 v[222:223], v[222:223], 1.0 op_sel_hi:[1,0]
; __device__ __forceinline__ float lo_bf(unsigned w) { return __uint_as_float(w << 16); }
; __device__ __forceinline__ float hi_bf(unsigned w) { return __uint_as_float(w & 0xffff0000u); }
; template <bool HAS_F, bool HAS_H>
; __device__ __forceinline__ void phase_rows(const Params& p, int sp, int sn, float resw, bool from_input, bool write_x = true) {
;     ...
;         if (HAS_F) {
;             f32x4 f[4]; float ss = 0.f;
; #pragma unroll
;             for (int j = 0; j < 4; ++j) { const u32x2 w = *(const u32x2*)(F + (size_t)row * D + 4 * lane + 256 * j);
;                 f[j] = (f32x4){lo_bf(w.x), hi_bf(w.x), lo_bf(w.y), hi_bf(w.y)}; ss += (f[j].x * f[j].x + f[j].y * f[j].y) + (f[j].z * f[j].z + f[j].w * f[j].w); }
;             const float rs = 1.0f / sqrtf(wave_sum(ss) * (1.0f / D) + EPS) * resw;
;             const float* gate = mod + b * 9216 + sp * 3072 + 2048; const float* gp = p.in[7] + sp * D;
; #pragma unroll
;             for (int j = 0; j < 4; ++j) { const f32x4 g = *(const f32x4*)(gate + 4 * lane + 256 * j), q = *(const f32x4*)(gp + 4 * lane + 256 * j);
;                 v[j] = v[j] + g * (f[j] * rs * q);
;                 if (write_x) *(f32x4*)(p.out + (size_t)row * D + 4 * lane + 256 * j) = v[j]; }
;         }
;         if (HAS_H) {
;             float ss = 0.f;
; #pragma unroll
;             for (int j = 0; j < 4; ++j) ss += (v[j].x * v[j].x + v[j].y * v[j].y) + (v[j].z * v[j].z + v[j].w * v[j].w);
;             const float rs = 1.0f / sqrtf(wave_sum(ss) * (1.0f / D) + EPS);
.Lrp4_pk8:
	s_waitcnt vmcnt(32)
	v_lshlrev_b32_e32 v112, 16, v52
	v_and_b32_e32 v113, 0xffff0000, v52
	v_lshlrev_b32_e32 v114, 16, v53
	v_and_b32_e32 v115, 0xffff0000, v53
	v_lshlrev_b32_e32 v116, 16, v54
	v_and_b32_e32 v117, 0xffff0000, v54
	v_lshlrev_b32_e32 v118, 16, v55
	v_and_b32_e32 v119, 0xffff0000, v55
	v_lshlrev_b32_e32 v120, 16, v56
	v_and_b32_e32 v121, 0xffff0000, v56
	v_lshlrev_b32_e32 v122, 16, v57
	v_and_b32_e32 v123, 0xffff0000, v57
	v_lshlrev_b32_e32 v124, 16, v58
	v_and_b32_e32 v125, 0xffff0000, v58
	v_lshlrev_b32_e32 v100, 16, v59
	v_and_b32_e32 v101, 0xffff0000, v59
	v_pk_mul_f32 v[102:103], v[112:113], v[112:113]
	v_pk_mul_f32 v[106:107], v[114:115], v[114:115]
	v_pk_fma_f32 v[102:103], v[116:117], v[116:117], v[102:103]
	v_pk_fma_f32 v[106:107], v[118:119], v[118:119], v[106:107]
	v_pk_fma_f32 v[102:103], v[120:121], v[120:121], v[102:103]
	v_pk_fma_f32 v[106:107], v[122:123], v[122:123], v[106:107]
	v_pk_fma_f32 v[102:103], v[124:125], v[124:125], v[102:103]
	v_pk_fma_f32 v[106:107], v[100:101], v[100:101], v[106:107]
	s_nop 0
	v_pk_add_f32 v[102:103], v[102:103], v[106:107]
	s_nop 0
	v_add_f32_e32 v102, v102, v103
	s_nop 1
	v_add_f32_dpp v102, v102, v102 quad_perm:[1,0,3,2] row_mask:0xf bank_mask:0xf
	s_nop 1
	v_add_f32_dpp v102, v102, v102 quad_perm:[2,3,0,1] row_mask:0xf bank_mask:0xf
	s_nop 1
	v_add_f32_dpp v102, v102, v102 row_half_mirror row_mask:0xf bank_mask:0xf
	s_nop 1
	v_add_f32_dpp v102, v102, v102 row_mirror row_mask:0xf bank_mask:0xf
	s_nop 1
	v_add_f32_dpp v102, v102, v102 row_bcast:15 row_mask:0xa bank_mask:0xf
	s_nop 1
	v_add_f32_dpp v102, v102, v102 row_bcast:31 row_mask:0xc bank_mask:0xf
	s_nop 1
	v_readlane_b32 s74, v102, 63
	s_nop 2
	v_mov_b32_e32 v102, s74
	v_fmamk_f32 v102, v102, 0x3a800000, v2
	v_mul_f32_e32 v103, 0x4f800000, v102
	v_cmp_gt_f32_e32 vcc, 0xf800000, v102
	s_nop 1
	v_cndmask_b32_e32 v102, v102, v103, vcc
	v_sqrt_f32_e32 v103, v102
	s_nop 0
	v_add_u32_e32 v104, -1, v103
	v_add_u32_e32 v106, 1, v103
	v_fma_f32 v107, -v104, v103, v102
	v_fma_f32 v108, -v106, v103, v102
	v_cmp_ge_f32_e64 s[76:77], 0, v107
	s_nop 1
	v_cndmask_b32_e64 v103, v103, v104, s[76:77]
	v_cmp_lt_f32_e64 s[76:77], 0, v108
	s_nop 1
	v_cndmask_b32_e64 v103, v103, v106, s[76:77]
	v_mul_f32_e32 v104, 0x37800000, v103
	v_cndmask_b32_e32 v103, v103, v104, vcc
	v_cmp_class_f32_e32 vcc, v102, v3
	s_nop 1
	v_cndmask_b32_e32 v102, v103, v102, vcc
	v_div_scale_f32 v103, s[76:77], v102, v102, 1.0
	v_rcp_f32_e32 v104, v103
	v_div_scale_f32 v106, vcc, 1.0, v102, 1.0
	v_fma_f32 v107, -v103, v104, 1.0
	v_fmac_f32_e32 v104, v107, v104
	v_mul_f32_e32 v107, v106, v104
	v_fma_f32 v108, -v103, v107, v106
	v_fmac_f32_e32 v107, v108, v104
	v_fma_f32 v103, -v103, v107, v106
	v_div_fmas_f32 v103, v103, v104, v107
	v_div_fixup_f32 v110, v103, v102, 1.0
	v_mul_f32_e32 v110, 0.5, v110
	v_pk_mul_f32 v[112:113], v[112:113], v[110:111] op_sel_hi:[1,0]
	v_pk_mul_f32 v[114:115], v[114:115], v[110:111] op_sel_hi:[1,0]
	v_pk_mul_f32 v[116:117], v[116:117], v[110:111] op_sel_hi:[1,0]
	v_pk_mul_f32 v[118:119], v[118:119], v[110:111] op_sel_hi:[1,0]
	v_pk_mul_f32 v[120:121], v[120:121], v[110:111] op_sel_hi:[1,0]
	v_pk_mul_f32 v[122:123], v[122:123], v[110:111] op_sel_hi:[1,0]
	v_pk_mul_f32 v[124:125], v[124:125], v[110:111] op_sel_hi:[1,0]
	v_pk_mul_f32 v[100:101], v[100:101], v[110:111] op_sel_hi:[1,0]
	v_pk_mul_f32 v[112:113], v[176:177], v[112:113]
	v_pk_mul_f32 v[114:115], v[178:179], v[114:115]
	v_pk_mul_f32 v[116:117], v[180:181], v[116:117]
	v_pk_mul_f32 v[118:119], v[182:183], v[118:119]
	v_pk_mul_f32 v[120:121], v[184:185], v[120:121]
	v_pk_mul_f32 v[122:123], v[186:187], v[122:123]
	v_pk_mul_f32 v[124:125], v[188:189], v[124:125]
	v_pk_mul_f32 v[100:101], v[190:191], v[100:101]
	v_pk_fma_f32 v[36:37], v[160:161], v[112:113], v[36:37]
	v_pk_fma_f32 v[38:39], v[162:163], v[114:115], v[38:39]
	v_pk_fma_f32 v[40:41], v[164:165], v[116:117], v[40:41]
	v_pk_fma_f32 v[42:43], v[166:167], v[118:119], v[42:43]
	v_pk_fma_f32 v[44:45], v[168:169], v[120:121], v[44:45]
	v_pk_fma_f32 v[46:47], v[170:171], v[122:123], v[46:47]
	v_pk_fma_f32 v[48:49], v[172:173], v[124:125], v[48:49]
	v_pk_fma_f32 v[50:51], v[174:175], v[100:101], v[50:51]
	s_lshl_b32 s60, s55, 12
	s_add_u32 s72, s84, s60
	s_addc_u32 s73, s85, 0
	global_store_dwordx4 v0, v[36:39], s[72:73] sc1
	global_store_dwordx4 v0, v[40:43], s[72:73] offset:1024 sc1
	global_store_dwordx4 v0, v[44:47], s[72:73] offset:2048 sc1
	global_store_dwordx4 v0, v[48:51], s[72:73] offset:3072 sc1
	v_pk_mul_f32 v[102:103], v[36:37], v[36:37]
	v_pk_mul_f32 v[106:107], v[38:39], v[38:39]
	v_pk_fma_f32 v[102:103], v[40:41], v[40:41], v[102:103]
	v_pk_fma_f32 v[106:107], v[42:43], v[42:43], v[106:107]
	v_pk_fma_f32 v[102:103], v[44:45], v[44:45], v[102:103]
	v_pk_fma_f32 v[106:107], v[46:47], v[46:47], v[106:107]
	v_pk_fma_f32 v[102:103], v[48:49], v[48:49], v[102:103]
	v_pk_fma_f32 v[106:107], v[50:51], v[50:51], v[106:107]
	s_nop 0
	v_pk_add_f32 v[102:103], v[102:103], v[106:107]
	s_nop 0
	v_add_f32_e32 v102, v102, v103
	s_nop 1
	v_add_f32_dpp v102, v102, v102 quad_perm:[1,0,3,2] row_mask:0xf bank_mask:0xf
	s_nop 1
	v_add_f32_dpp v102, v102, v102 quad_perm:[2,3,0,1] row_mask:0xf bank_mask:0xf
	s_nop 1
	v_add_f32_dpp v102, v102, v102 row_half_mirror row_mask:0xf bank_mask:0xf
	s_nop 1
	v_add_f32_dpp v102, v102, v102 row_mirror row_mask:0xf bank_mask:0xf
	s_nop 1
	v_add_f32_dpp v102, v102, v102 row_bcast:15 row_mask:0xa bank_mask:0xf
	s_nop 1
	v_add_f32_dpp v102, v102, v102 row_bcast:31 row_mask:0xc bank_mask:0xf
	s_nop 1
	v_readlane_b32 s74, v102, 63
	s_nop 2
	v_mov_b32_e32 v102, s74
	v_fmamk_f32 v102, v102, 0x3a800000, v2
; __device__ __forceinline__ unsigned pk_bf16(float lo, float hi) { const f32x2 v = {lo, hi}; const bf16x2_t b = __builtin_convertvector(v, bf16x2_t); return __builtin_bit_cast(unsigned, b); }
; template <bool HAS_F, bool HAS_H>
; __device__ __forceinline__ void phase_rows(const Params& p, int sp, int sn, float resw, bool from_input, bool write_x = true) {
;     ...
;     for (int row = gw; row < T; row += NGW) {
;         const int b = row_batch(row);
;         const float* xin = !from_input ? p.out + (size_t)row * D : (row < TP ? p.in[0] + (size_t)row * D : p.in[1] + (size_t)(row - TP) * D);
;         f32x4 v[4];
; #pragma unroll
;         for (int j = 0; j < 4; ++j) v[j] = *(const f32x4*)(xin + 4 * lane + 256 * j);
;     ...
;             const float rs = 1.0f / sqrtf(wave_sum(ss) * (1.0f / D) + EPS);
;             const float* sh = mod + b * 9216 + sn * 3072; const float* scl = sh + 1024; const float* gq = p.in[6] + sn * D;
; #pragma unroll
;             for (int j = 0; j < 4; ++j) { const f32x4 a = *(const f32x4*)(sh + 4 * lane + 256 * j), s = *(const f32x4*)(scl + 4 * lane + 256 * j), q = *(const f32x4*)(gq + 4 * lane + 256 * j);
;                 const f32x4 h = (v[j] * rs * q) * (s + 1.0f) + a;
;                 u32x2 w; w.x = pk_bf16(h.x, h.y); w.y = pk_bf16(h.z, h.w);
;                 *(u32x2*)(H + (size_t)row * D + 4 * lane + 256 * j) = w; }
	v_mul_f32_e32 v103, 0x4f800000, v102
	v_cmp_gt_f32_e32 vcc, 0xf800000, v102
	s_nop 1
	v_cndmask_b32_e32 v102, v102, v103, vcc
	v_sqrt_f32_e32 v103, v102
	s_nop 0
	v_add_u32_e32 v104, -1, v103
	v_add_u32_e32 v106, 1, v103
	v_fma_f32 v107, -v104, v103, v102
	v_fma_f32 v108, -v106, v103, v102
	v_cmp_ge_f32_e64 s[76:77], 0, v107
	s_nop 1
	v_cndmask_b32_e64 v103, v103, v104, s[76:77]
	v_cmp_lt_f32_e64 s[76:77], 0, v108
	s_nop 1
	v_cndmask_b32_e64 v103, v103, v106, s[76:77]
	v_mul_f32_e32 v104, 0x37800000, v103
	v_cndmask_b32_e32 v103, v103, v104, vcc
	v_cmp_class_f32_e32 vcc, v102, v3
	s_nop 1
	v_cndmask_b32_e32 v102, v103, v102, vcc
	v_div_scale_f32 v103, s[76:77], v102, v102, 1.0
	v_rcp_f32_e32 v104, v103
	v_div_scale_f32 v106, vcc, 1.0, v102, 1.0
	v_fma_f32 v107, -v103, v104, 1.0
	v_fmac_f32_e32 v104, v107, v104
	v_mul_f32_e32 v107, v106, v104
	v_fma_f32 v108, -v103, v107, v106
	v_fmac_f32_e32 v107, v108, v104
	v_fma_f32 v103, -v103, v107, v106
	v_div_fmas_f32 v103, v103, v104, v107
	v_div_fixup_f32 v110, v103, v102, 1.0
	s_lshl_b32 s60, s55, 11
	s_add_u32 s70, s78, s60
	s_addc_u32 s71, s79, 0
	v_pk_mul_f32 v[112:113], v[36:37], v[110:111] op_sel_hi:[1,0]
	v_pk_mul_f32 v[114:115], v[38:39], v[110:111] op_sel_hi:[1,0]
	v_pk_mul_f32 v[116:117], v[40:41], v[110:111] op_sel_hi:[1,0]
	v_pk_mul_f32 v[118:119], v[42:43], v[110:111] op_sel_hi:[1,0]
	v_pk_mul_f32 v[120:121], v[44:45], v[110:111] op_sel_hi:[1,0]
	v_pk_mul_f32 v[122:123], v[46:47], v[110:111] op_sel_hi:[1,0]
	v_pk_mul_f32 v[124:125], v[48:49], v[110:111] op_sel_hi:[1,0]
	v_pk_mul_f32 v[100:101], v[50:51], v[110:111] op_sel_hi:[1,0]
	v_pk_mul_f32 v[112:113], v[192:193], v[112:113]
	v_pk_mul_f32 v[114:115], v[194:195], v[114:115]
	v_pk_mul_f32 v[116:117], v[196:197], v[116:117]
	v_pk_mul_f32 v[118:119], v[198:199], v[118:119]
	v_pk_mul_f32 v[120:121], v[200:201], v[120:121]
	v_pk_mul_f32 v[122:123], v[202:203], v[122:123]
	v_pk_mul_f32 v[124:125], v[204:205], v[124:125]
	v_pk_mul_f32 v[100:101], v[206:207], v[100:101]
	v_pk_fma_f32 v[112:113], v[208:209], v[112:113], v[224:225]
	v_pk_fma_f32 v[114:115], v[210:211], v[114:115], v[226:227]
	v_pk_fma_f32 v[116:117], v[212:213], v[116:117], v[228:229]
	v_pk_fma_f32 v[118:119], v[214:215], v[118:119], v[230:231]
	v_pk_fma_f32 v[120:121], v[216:217], v[120:121], v[232:233]
	v_pk_fma_f32 v[122:123], v[218:219], v[122:123], v[234:235]
	v_pk_fma_f32 v[124:125], v[220:221], v[124:125], v[236:237]
	v_pk_fma_f32 v[100:101], v[222:223], v[100:101], v[238:239]
	v_cvt_pk_bf16_f32 v240, v112, v113
	v_cvt_pk_bf16_f32 v241, v114, v115
	v_cvt_pk_bf16_f32 v242, v116, v117
	v_cvt_pk_bf16_f32 v243, v118, v119
	v_cvt_pk_bf16_f32 v244, v120, v121
	v_cvt_pk_bf16_f32 v245, v122, v123
	v_cvt_pk_bf16_f32 v246, v124, v125
	v_cvt_pk_bf16_f32 v247, v100, v101
	global_store_dwordx2 v1, v[240:241], s[70:71]
	global_store_dwordx2 v1, v[242:243], s[70:71] offset:512
	global_store_dwordx2 v1, v[244:245], s[70:71] offset:1024
	global_store_dwordx2 v1, v[246:247], s[70:71] offset:1536
	s_add_u32 s55, s55, 8
	s_add_u32 s57, s55, 16
	s_min_u32 s57, s57, s54
	s_cmp_lt_u32 s57, 0x8000
	s_cselect_b32 s64, s8, s10
	s_cselect_b32 s65, s9, s11
	s_cselect_b32 s60, 0, 0x8000
	s_sub_u32 s60, s57, s60
	s_lshl_b32 s60, s60, 12
	s_add_u32 s64, s64, s60
	s_addc_u32 s65, s65, 0
	s_lshl_b32 s60, s57, 11
	s_add_u32 s66, s82, s60
	s_addc_u32 s67, s83, 0
	global_load_dwordx4 v[36:39], v0, s[64:65] nt
	global_load_dwordx4 v[40:43], v0, s[64:65] offset:1024 nt
	global_load_dwordx4 v[44:47], v0, s[64:65] offset:2048 nt
	global_load_dwordx4 v[48:51], v0, s[64:65] offset:3072 nt
	global_load_dwordx2 v[52:53], v1, s[66:67] nt
	global_load_dwordx2 v[54:55], v1, s[66:67] offset:512 nt
	global_load_dwordx2 v[56:57], v1, s[66:67] offset:1024 nt
	global_load_dwordx2 v[58:59], v1, s[66:67] offset:1536 nt
	s_lshr_b32 s60, s55, 11
	s_sub_u32 s61, s55, 0x8000
	s_lshr_b32 s61, s61, 12
	s_add_u32 s61, s61, 16
	s_cmp_lt_u32 s55, 0x8000
	s_cselect_b32 s63, s60, s61
	s_cmp_eq_u32 s63, s56
	s_cbranch_scc1 .Lrp4_pk9
	s_mov_b32 s56, s63
	s_mul_i32 s60, s56, 0x9000
	s_add_u32 s60, s60, 0x3182000
	s_add_u32 s0, s92, s60
	s_addc_u32 s1, s93, 0
	global_load_dwordx4 v[160:163], v0, s[0:1]
	global_load_dwordx4 v[164:167], v0, s[0:1] offset:1024
	global_load_dwordx4 v[168:171], v0, s[0:1] offset:2048
	global_load_dwordx4 v[172:175], v0, s[0:1] offset:3072
	s_add_u32 s0, s22, 0x0
	s_addc_u32 s1, s23, 0
	global_load_dwordx4 v[176:179], v0, s[0:1]
	global_load_dwordx4 v[180:183], v0, s[0:1] offset:1024
	global_load_dwordx4 v[184:187], v0, s[0:1] offset:2048
	global_load_dwordx4 v[188:191], v0, s[0:1] offset:3072
	s_add_u32 s0, s20, 0x1000
	s_addc_u32 s1, s21, 0
	global_load_dwordx4 v[192:195], v0, s[0:1]
	global_load_dwordx4 v[196:199], v0, s[0:1] offset:1024
	global_load_dwordx4 v[200:203], v0, s[0:1] offset:2048
	global_load_dwordx4 v[204:207], v0, s[0:1] offset:3072
	s_mul_i32 s60, s56, 0x9000
	s_add_u32 s60, s60, 0x3184000
	s_add_u32 s0, s92, s60
	s_addc_u32 s1, s93, 0
	global_load_dwordx4 v[208:211], v0, s[0:1]
	global_load_dwordx4 v[212:215], v0, s[0:1] offset:1024
	global_load_dwordx4 v[216:219], v0, s[0:1] offset:2048
	global_load_dwordx4 v[220:223], v0, s[0:1] offset:3072
	s_mul_i32 s60, s56, 0x9000
	s_add_u32 s60, s60, 0x3183000
	s_add_u32 s0, s92, s60
	s_addc_u32 s1, s93, 0
	global_load_dwordx4 v[224:227], v0, s[0:1]
	global_load_dwordx4 v[228:231], v0, s[0:1] offset:1024
	global_load_dwordx4 v[232:235], v0, s[0:1] offset:2048
	global_load_dwordx4 v[236:239], v0, s[0:1] offset:3072
	s_waitcnt vmcnt(0)
	v_pk_add_f32 v[208:209], v[208:209], 1.0 op_sel_hi:[1,0]
	v_pk_add_f32 v[210:211], v[210:211], 1.0 op_sel_hi:[1,0]
	v_pk_add_f32 v[212:213], v[212:213], 1.0 op_sel_hi:[1,0]
	v_pk_add_f32 v[214:215], v[214:215], 1.0 op_sel_hi:[1,0]
	v_pk_add_f32 v[216:217], v[216:217], 1.0 op_sel_hi:[1,0]
	v_pk_add_f32 v[218:219], v[218:219], 1.0 op_sel_hi:[1,0]
	v_pk_add_f32 v[220:221], v[220:221], 1.0 op_sel_hi:[1,0]
	v_pk_add_f32 v[222:223], v[222:223], 1.0 op_sel_hi:[1,0]
; __device__ __forceinline__ float lo_bf(unsigned w) { return __uint_as_float(w << 16); }
; __device__ __forceinline__ float hi_bf(unsigned w) { return __uint_as_float(w & 0xffff0000u); }
; template <bool HAS_F, bool HAS_H>
; __device__ __forceinline__ void phase_rows(const Params& p, int sp, int sn, float resw, bool from_input, bool write_x = true) {
;     ...
;         if (HAS_F) {
;             f32x4 f[4]; float ss = 0.f;
; #pragma unroll
;             for (int j = 0; j < 4; ++j) { const u32x2 w = *(const u32x2*)(F + (size_t)row * D + 4 * lane + 256 * j);
;                 f[j] = (f32x4){lo_bf(w.x), hi_bf(w.x), lo_bf(w.y), hi_bf(w.y)}; ss += (f[j].x * f[j].x + f[j].y * f[j].y) + (f[j].z * f[j].z + f[j].w * f[j].w); }
;             const float rs = 1.0f / sqrtf(wave_sum(ss) * (1.0f / D) + EPS) * resw;
;             const float* gate = mod + b * 9216 + sp * 3072 + 2048; const float* gp = p.in[7] + sp * D;
; #pragma unroll
;             for (int j = 0; j < 4; ++j) { const f32x4 g = *(const f32x4*)(gate + 4 * lane + 256 * j), q = *(const f32x4*)(gp + 4 * lane + 256 * j);
;                 v[j] = v[j] + g * (f[j] * rs * q);
;                 if (write_x) *(f32x4*)(p.out + (size_t)row * D + 4 * lane + 256 * j) = v[j]; }
.Lrp4_pk9:
	s_waitcnt vmcnt(32)
	v_lshlrev_b32_e32 v112, 16, v84
	v_and_b32_e32 v113, 0xffff0000, v84
	v_lshlrev_b32_e32 v114, 16, v85
	v_and_b32_e32 v115, 0xffff0000, v85
	v_lshlrev_b32_e32 v116, 16, v86
	v_and_b32_e32 v117, 0xffff0000, v86
	v_lshlrev_b32_e32 v118, 16, v87
	v_and_b32_e32 v119, 0xffff0000, v87
	v_lshlrev_b32_e32 v120, 16, v88
	v_and_b32_e32 v121, 0xffff0000, v88
	v_lshlrev_b32_e32 v122, 16, v89
	v_and_b32_e32 v123, 0xffff0000, v89
	v_lshlrev_b32_e32 v124, 16, v90
	v_and_b32_e32 v125, 0xffff0000, v90
	v_lshlrev_b32_e32 v100, 16, v91
	v_and_b32_e32 v101, 0xffff0000, v91
	v_pk_mul_f32 v[102:103], v[112:113], v[112:113]
	v_pk_mul_f32 v[106:107], v[114:115], v[114:115]
	v_pk_fma_f32 v[102:103], v[116:117], v[116:117], v[102:103]
	v_pk_fma_f32 v[106:107], v[118:119], v[118:119], v[106:107]
	v_pk_fma_f32 v[102:103], v[120:121], v[120:121], v[102:103]
	v_pk_fma_f32 v[106:107], v[122:123], v[122:123], v[106:107]
	v_pk_fma_f32 v[102:103], v[124:125], v[124:125], v[102:103]
	v_pk_fma_f32 v[106:107], v[100:101], v[100:101], v[106:107]
	s_nop 0
	v_pk_add_f32 v[102:103], v[102:103], v[106:107]
	s_nop 0
	v_add_f32_e32 v102, v102, v103
	s_nop 1
	v_add_f32_dpp v102, v102, v102 quad_perm:[1,0,3,2] row_mask:0xf bank_mask:0xf
	s_nop 1
	v_add_f32_dpp v102, v102, v102 quad_perm:[2,3,0,1] row_mask:0xf bank_mask:0xf
	s_nop 1
	v_add_f32_dpp v102, v102, v102 row_half_mirror row_mask:0xf bank_mask:0xf
	s_nop 1
	v_add_f32_dpp v102, v102, v102 row_mirror row_mask:0xf bank_mask:0xf
	s_nop 1
	v_add_f32_dpp v102, v102, v102 row_bcast:15 row_mask:0xa bank_mask:0xf
	s_nop 1
	v_add_f32_dpp v102, v102, v102 row_bcast:31 row_mask:0xc bank_mask:0xf
	s_nop 1
	v_readlane_b32 s74, v102, 63
	s_nop 2
	v_mov_b32_e32 v102, s74
	v_fmamk_f32 v102, v102, 0x3a800000, v2
	v_mul_f32_e32 v103, 0x4f800000, v102
	v_cmp_gt_f32_e32 vcc, 0xf800000, v102
	s_nop 1
	v_cndmask_b32_e32 v102, v102, v103, vcc
	v_sqrt_f32_e32 v103, v102
	s_nop 0
	v_add_u32_e32 v104, -1, v103
	v_add_u32_e32 v106, 1, v103
	v_fma_f32 v107, -v104, v103, v102
	v_fma_f32 v108, -v106, v103, v102
	v_cmp_ge_f32_e64 s[76:77], 0, v107
	s_nop 1
	v_cndmask_b32_e64 v103, v103, v104, s[76:77]
	v_cmp_lt_f32_e64 s[76:77], 0, v108
	s_nop 1
	v_cndmask_b32_e64 v103, v103, v106, s[76:77]
	v_mul_f32_e32 v104, 0x37800000, v103
	v_cndmask_b32_e32 v103, v103, v104, vcc
	v_cmp_class_f32_e32 vcc, v102, v3
	s_nop 1
	v_cndmask_b32_e32 v102, v103, v102, vcc
	v_div_scale_f32 v103, s[76:77], v102, v102, 1.0
	v_rcp_f32_e32 v104, v103
	v_div_scale_f32 v106, vcc, 1.0, v102, 1.0
	v_fma_f32 v107, -v103, v104, 1.0
	v_fmac_f32_e32 v104, v107, v104
	v_mul_f32_e32 v107, v106, v104
	v_fma_f32 v108, -v103, v107, v106
	v_fmac_f32_e32 v107, v108, v104
	v_fma_f32 v103, -v103, v107, v106
	v_div_fmas_f32 v103, v103, v104, v107
	v_div_fixup_f32 v110, v103, v102, 1.0
	v_mul_f32_e32 v110, 0.5, v110
	v_pk_mul_f32 v[112:113], v[112:113], v[110:111] op_sel_hi:[1,0]
	v_pk_mul_f32 v[114:115], v[114:115], v[110:111] op_sel_hi:[1,0]
	v_pk_mul_f32 v[116:117], v[116:117], v[110:111] op_sel_hi:[1,0]
	v_pk_mul_f32 v[118:119], v[118:119], v[110:111] op_sel_hi:[1,0]
	v_pk_mul_f32 v[120:121], v[120:121], v[110:111] op_sel_hi:[1,0]
	v_pk_mul_f32 v[122:123], v[122:123], v[110:111] op_sel_hi:[1,0]
	v_pk_mul_f32 v[124:125], v[124:125], v[110:111] op_sel_hi:[1,0]
	v_pk_mul_f32 v[100:101], v[100:101], v[110:111] op_sel_hi:[1,0]
	v_pk_mul_f32 v[112:113], v[176:177], v[112:113]
	v_pk_mul_f32 v[114:115], v[178:179], v[114:115]
	v_pk_mul_f32 v[116:117], v[180:181], v[116:117]
	v_pk_mul_f32 v[118:119], v[182:183], v[118:119]
	v_pk_mul_f32 v[120:121], v[184:185], v[120:121]
	v_pk_mul_f32 v[122:123], v[186:187], v[122:123]
	v_pk_mul_f32 v[124:125], v[188:189], v[124:125]
	v_pk_mul_f32 v[100:101], v[190:191], v[100:101]
	v_pk_fma_f32 v[68:69], v[160:161], v[112:113], v[68:69]
	v_pk_fma_f32 v[70:71], v[162:163], v[114:115], v[70:71]
	v_pk_fma_f32 v[72:73], v[164:165], v[116:117], v[72:73]
	v_pk_fma_f32 v[74:75], v[166:167], v[118:119], v[74:75]
	v_pk_fma_f32 v[76:77], v[168:169], v[120:121], v[76:77]
	v_pk_fma_f32 v[78:79], v[170:171], v[122:123], v[78:79]
	v_pk_fma_f32 v[80:81], v[172:173], v[124:125], v[80:81]
	v_pk_fma_f32 v[82:83], v[174:175], v[100:101], v[82:83]
	s_lshl_b32 s60, s55, 12
	s_add_u32 s72, s84, s60
	s_addc_u32 s73, s85, 0
	global_store_dwordx4 v0, v[68:71], s[72:73] sc1
	global_store_dwordx4 v0, v[72:75], s[72:73] offset:1024 sc1
; __device__ __forceinline__ unsigned pk_bf16(float lo, float hi) { const f32x2 v = {lo, hi}; const bf16x2_t b = __builtin_convertvector(v, bf16x2_t); return __builtin_bit_cast(unsigned, b); }
; template <bool HAS_F, bool HAS_H>
; __device__ __forceinline__ void phase_rows(const Params& p, int sp, int sn, float resw, bool from_input, bool write_x = true) {
;     ...
;         if (HAS_H) {
;             float ss = 0.f;
; #pragma unroll
;             for (int j = 0; j < 4; ++j) ss += (v[j].x * v[j].x + v[j].y * v[j].y) + (v[j].z * v[j].z + v[j].w * v[j].w);
;             const float rs = 1.0f / sqrtf(wave_sum(ss) * (1.0f / D) + EPS);
;             const float* sh = mod + b * 9216 + sn * 3072; const float* scl = sh + 1024; const float* gq = p.in[6] + sn * D;
; #pragma unroll
;             for (int j = 0; j < 4; ++j) { const f32x4 a = *(const f32x4*)(sh + 4 * lane + 256 * j), s = *(const f32x4*)(scl + 4 * lane + 256 * j), q = *(const f32x4*)(gq + 4 * lane + 256 * j);
;                 const f32x4 h = (v[j] * rs * q) * (s + 1.0f) + a;
;                 u32x2 w; w.x = pk_bf16(h.x, h.y); w.y = pk_bf16(h.z, h.w);
;                 *(u32x2*)(H + (size_t)row * D + 4 * lane + 256 * j) = w; }
	global_store_dwordx4 v0, v[76:79], s[72:73] offset:2048 sc1
	global_store_dwordx4 v0, v[80:83], s[72:73] offset:3072 sc1
	v_pk_mul_f32 v[102:103], v[68:69], v[68:69]
	v_pk_mul_f32 v[106:107], v[70:71], v[70:71]
	v_pk_fma_f32 v[102:103], v[72:73], v[72:73], v[102:103]
	v_pk_fma_f32 v[106:107], v[74:75], v[74:75], v[106:107]
	v_pk_fma_f32 v[102:103], v[76:77], v[76:77], v[102:103]
	v_pk_fma_f32 v[106:107], v[78:79], v[78:79], v[106:107]
	v_pk_fma_f32 v[102:103], v[80:81], v[80:81], v[102:103]
	v_pk_fma_f32 v[106:107], v[82:83], v[82:83], v[106:107]
	s_nop 0
	v_pk_add_f32 v[102:103], v[102:103], v[106:107]
	s_nop 0
	v_add_f32_e32 v102, v102, v103
	s_nop 1
	v_add_f32_dpp v102, v102, v102 quad_perm:[1,0,3,2] row_mask:0xf bank_mask:0xf
	s_nop 1
	v_add_f32_dpp v102, v102, v102 quad_perm:[2,3,0,1] row_mask:0xf bank_mask:0xf
	s_nop 1
	v_add_f32_dpp v102, v102, v102 row_half_mirror row_mask:0xf bank_mask:0xf
	s_nop 1
	v_add_f32_dpp v102, v102, v102 row_mirror row_mask:0xf bank_mask:0xf
	s_nop 1
	v_add_f32_dpp v102, v102, v102 row_bcast:15 row_mask:0xa bank_mask:0xf
	s_nop 1
	v_add_f32_dpp v102, v102, v102 row_bcast:31 row_mask:0xc bank_mask:0xf
	s_nop 1
	v_readlane_b32 s74, v102, 63
	s_nop 2
	v_mov_b32_e32 v102, s74
	v_fmamk_f32 v102, v102, 0x3a800000, v2
	v_mul_f32_e32 v103, 0x4f800000, v102
	v_cmp_gt_f32_e32 vcc, 0xf800000, v102
	s_nop 1
	v_cndmask_b32_e32 v102, v102, v103, vcc
	v_sqrt_f32_e32 v103, v102
	s_nop 0
	v_add_u32_e32 v104, -1, v103
	v_add_u32_e32 v106, 1, v103
	v_fma_f32 v107, -v104, v103, v102
	v_fma_f32 v108, -v106, v103, v102
	v_cmp_ge_f32_e64 s[76:77], 0, v107
	s_nop 1
	v_cndmask_b32_e64 v103, v103, v104, s[76:77]
	v_cmp_lt_f32_e64 s[76:77], 0, v108
	s_nop 1
	v_cndmask_b32_e64 v103, v103, v106, s[76:77]
	v_mul_f32_e32 v104, 0x37800000, v103
	v_cndmask_b32_e32 v103, v103, v104, vcc
	v_cmp_class_f32_e32 vcc, v102, v3
	s_nop 1
	v_cndmask_b32_e32 v102, v103, v102, vcc
	v_div_scale_f32 v103, s[76:77], v102, v102, 1.0
	v_rcp_f32_e32 v104, v103
	v_div_scale_f32 v106, vcc, 1.0, v102, 1.0
	v_fma_f32 v107, -v103, v104, 1.0
	v_fmac_f32_e32 v104, v107, v104
	v_mul_f32_e32 v107, v106, v104
	v_fma_f32 v108, -v103, v107, v106
	v_fmac_f32_e32 v107, v108, v104
	v_fma_f32 v103, -v103, v107, v106
	v_div_fmas_f32 v103, v103, v104, v107
	v_div_fixup_f32 v110, v103, v102, 1.0
	s_lshl_b32 s60, s55, 11
	s_add_u32 s70, s78, s60
	s_addc_u32 s71, s79, 0
	v_pk_mul_f32 v[112:113], v[68:69], v[110:111] op_sel_hi:[1,0]
	v_pk_mul_f32 v[114:115], v[70:71], v[110:111] op_sel_hi:[1,0]
	v_pk_mul_f32 v[116:117], v[72:73], v[110:111] op_sel_hi:[1,0]
	v_pk_mul_f32 v[118:119], v[74:75], v[110:111] op_sel_hi:[1,0]
	v_pk_mul_f32 v[120:121], v[76:77], v[110:111] op_sel_hi:[1,0]
	v_pk_mul_f32 v[122:123], v[78:79], v[110:111] op_sel_hi:[1,0]
	v_pk_mul_f32 v[124:125], v[80:81], v[110:111] op_sel_hi:[1,0]
	v_pk_mul_f32 v[100:101], v[82:83], v[110:111] op_sel_hi:[1,0]
	v_pk_mul_f32 v[112:113], v[192:193], v[112:113]
	v_pk_mul_f32 v[114:115], v[194:195], v[114:115]
	v_pk_mul_f32 v[116:117], v[196:197], v[116:117]
	v_pk_mul_f32 v[118:119], v[198:199], v[118:119]
	v_pk_mul_f32 v[120:121], v[200:201], v[120:121]
	v_pk_mul_f32 v[122:123], v[202:203], v[122:123]
	v_pk_mul_f32 v[124:125], v[204:205], v[124:125]
	v_pk_mul_f32 v[100:101], v[206:207], v[100:101]
	v_pk_fma_f32 v[112:113], v[208:209], v[112:113], v[224:225]
	v_pk_fma_f32 v[114:115], v[210:211], v[114:115], v[226:227]
	v_pk_fma_f32 v[116:117], v[212:213], v[116:117], v[228:229]
	v_pk_fma_f32 v[118:119], v[214:215], v[118:119], v[230:231]
	v_pk_fma_f32 v[120:121], v[216:217], v[120:121], v[232:233]
	v_pk_fma_f32 v[122:123], v[218:219], v[122:123], v[234:235]
	v_pk_fma_f32 v[124:125], v[220:221], v[124:125], v[236:237]
	v_pk_fma_f32 v[100:101], v[222:223], v[100:101], v[238:239]
	v_cvt_pk_bf16_f32 v240, v112, v113
	v_cvt_pk_bf16_f32 v241, v114, v115
	v_cvt_pk_bf16_f32 v242, v116, v117
	v_cvt_pk_bf16_f32 v243, v118, v119
	v_cvt_pk_bf16_f32 v244, v120, v121
	v_cvt_pk_bf16_f32 v245, v122, v123
	v_cvt_pk_bf16_f32 v246, v124, v125
	v_cvt_pk_bf16_f32 v247, v100, v101
	global_store_dwordx2 v1, v[240:241], s[70:71]
	global_store_dwordx2 v1, v[242:243], s[70:71] offset:512
	global_store_dwordx2 v1, v[244:245], s[70:71] offset:1024
	global_store_dwordx2 v1, v[246:247], s[70:71] offset:1536
	s_add_u32 s55, s55, 8
	s_cmp_le_u32 s55, s54
	s_cbranch_scc1 .Lrp4_loop3
	s_add_u32 s51, s51, s52
	s_branch .Lrp4_chunk1

; __device__ __forceinline__ float lo_bf(unsigned w) { return __uint_as_float(w << 16); }
; __device__ __forceinline__ float hi_bf(unsigned w) { return __uint_as_float(w & 0xffff0000u); }
; template <bool HAS_F, bool HAS_H>
; __device__ __forceinline__ void phase_rows(const Params& p, int sp, int sn, float resw, bool from_input, bool write_x = true) {
;     ...
;         if (HAS_F) {
;             f32x4 f[4]; float ss = 0.f;
; #pragma unroll
;             for (int j = 0; j < 4; ++j) { const u32x2 w = *(const u32x2*)(F + (size_t)row * D + 4 * lane + 256 * j);
;                 f[j] = (f32x4){lo_bf(w.x), hi_bf(w.x), lo_bf(w.y), hi_bf(w.y)}; ss += (f[j].x * f[j].x + f[j].y * f[j].y) + (f[j].z * f[j].z + f[j].w * f[j].w); }
;             const float rs = 1.0f / sqrtf(wave_sum(ss) * (1.0f / D) + EPS) * resw;
;             const float* gate = mod + b * 9216 + sp * 3072 + 2048; const float* gp = p.in[7] + sp * D;
; #pragma unroll
;             for (int j = 0; j < 4; ++j) { const f32x4 g = *(const f32x4*)(gate + 4 * lane + 256 * j), q = *(const f32x4*)(gp + 4 * lane + 256 * j);
;                 v[j] = v[j] + g * (f[j] * rs * q);
;                 if (write_x) *(f32x4*)(p.out + (size_t)row * D + 4 * lane + 256 * j) = v[j]; }
;         }
;         if (HAS_H) {
;             float ss = 0.f;
; #pragma unroll
;             for (int j = 0; j < 4; ++j) ss += (v[j].x * v[j].x + v[j].y * v[j].y) + (v[j].z * v[j].z + v[j].w * v[j].w);
;             const float rs = 1.0f / sqrtf(wave_sum(ss) * (1.0f / D) + EPS);
.Lrp12_pk4:
	s_waitcnt vmcnt(16)
	v_lshlrev_b32_e32 v112, 16, v20
	v_and_b32_e32 v113, 0xffff0000, v20
	v_lshlrev_b32_e32 v114, 16, v21
	v_and_b32_e32 v115, 0xffff0000, v21
	v_lshlrev_b32_e32 v116, 16, v22
	v_and_b32_e32 v117, 0xffff0000, v22
	v_lshlrev_b32_e32 v118, 16, v23
	v_and_b32_e32 v119, 0xffff0000, v23
	v_lshlrev_b32_e32 v120, 16, v24
	v_and_b32_e32 v121, 0xffff0000, v24
	v_lshlrev_b32_e32 v122, 16, v25
	v_and_b32_e32 v123, 0xffff0000, v25
	v_lshlrev_b32_e32 v124, 16, v26
	v_and_b32_e32 v125, 0xffff0000, v26
	v_lshlrev_b32_e32 v100, 16, v27
	v_and_b32_e32 v101, 0xffff0000, v27
	v_pk_mul_f32 v[102:103], v[112:113], v[112:113]
	v_pk_mul_f32 v[106:107], v[114:115], v[114:115]
	v_pk_fma_f32 v[102:103], v[116:117], v[116:117], v[102:103]
	v_pk_fma_f32 v[106:107], v[118:119], v[118:119], v[106:107]
	v_pk_fma_f32 v[102:103], v[120:121], v[120:121], v[102:103]
	v_pk_fma_f32 v[106:107], v[122:123], v[122:123], v[106:107]
	v_pk_fma_f32 v[102:103], v[124:125], v[124:125], v[102:103]
	v_pk_fma_f32 v[106:107], v[100:101], v[100:101], v[106:107]
	s_nop 0
	v_pk_add_f32 v[102:103], v[102:103], v[106:107]
	s_nop 0
	v_add_f32_e32 v102, v102, v103
	s_nop 1
	v_add_f32_dpp v102, v102, v102 quad_perm:[1,0,3,2] row_mask:0xf bank_mask:0xf
	s_nop 1
	v_add_f32_dpp v102, v102, v102 quad_perm:[2,3,0,1] row_mask:0xf bank_mask:0xf
	s_nop 1
	v_add_f32_dpp v102, v102, v102 row_half_mirror row_mask:0xf bank_mask:0xf
	s_nop 1
	v_add_f32_dpp v102, v102, v102 row_mirror row_mask:0xf bank_mask:0xf
	s_nop 1
	v_add_f32_dpp v102, v102, v102 row_bcast:15 row_mask:0xa bank_mask:0xf
	s_nop 1
	v_add_f32_dpp v102, v102, v102 row_bcast:31 row_mask:0xc bank_mask:0xf
	s_nop 1
	v_readlane_b32 s74, v102, 63
	s_nop 2
	v_mov_b32_e32 v102, s74
	v_fmamk_f32 v102, v102, 0x3a800000, v2
	v_mul_f32_e32 v103, 0x4f800000, v102
	v_cmp_gt_f32_e32 vcc, 0xf800000, v102
	s_nop 1
	v_cndmask_b32_e32 v102, v102, v103, vcc
	v_sqrt_f32_e32 v103, v102
	s_nop 0
	v_add_u32_e32 v104, -1, v103
	v_add_u32_e32 v106, 1, v103
	v_fma_f32 v107, -v104, v103, v102
	v_fma_f32 v108, -v106, v103, v102
	v_cmp_ge_f32_e64 s[76:77], 0, v107
	s_nop 1
	v_cndmask_b32_e64 v103, v103, v104, s[76:77]
	v_cmp_lt_f32_e64 s[76:77], 0, v108
	s_nop 1
	v_cndmask_b32_e64 v103, v103, v106, s[76:77]
	v_mul_f32_e32 v104, 0x37800000, v103
	v_cndmask_b32_e32 v103, v103, v104, vcc
	v_cmp_class_f32_e32 vcc, v102, v3
	s_nop 1
	v_cndmask_b32_e32 v102, v103, v102, vcc
	v_div_scale_f32 v103, s[76:77], v102, v102, 1.0
	v_rcp_f32_e32 v104, v103
	v_div_scale_f32 v106, vcc, 1.0, v102, 1.0
	v_fma_f32 v107, -v103, v104, 1.0
	v_fmac_f32_e32 v104, v107, v104
	v_mul_f32_e32 v107, v106, v104
	v_fma_f32 v108, -v103, v107, v106
	v_fmac_f32_e32 v107, v108, v104
	v_fma_f32 v103, -v103, v107, v106
	v_div_fmas_f32 v103, v103, v104, v107
	v_div_fixup_f32 v110, v103, v102, 1.0
	v_pk_mul_f32 v[112:113], v[112:113], v[110:111] op_sel_hi:[1,0]
	v_pk_mul_f32 v[114:115], v[114:115], v[110:111] op_sel_hi:[1,0]
	v_pk_mul_f32 v[116:117], v[116:117], v[110:111] op_sel_hi:[1,0]
	v_pk_mul_f32 v[118:119], v[118:119], v[110:111] op_sel_hi:[1,0]
	v_pk_mul_f32 v[120:121], v[120:121], v[110:111] op_sel_hi:[1,0]
	v_pk_mul_f32 v[122:123], v[122:123], v[110:111] op_sel_hi:[1,0]
	v_pk_mul_f32 v[124:125], v[124:125], v[110:111] op_sel_hi:[1,0]
	v_pk_mul_f32 v[100:101], v[100:101], v[110:111] op_sel_hi:[1,0]
	v_pk_mul_f32 v[112:113], v[176:177], v[112:113]
	v_pk_mul_f32 v[114:115], v[178:179], v[114:115]
	v_pk_mul_f32 v[116:117], v[180:181], v[116:117]
	v_pk_mul_f32 v[118:119], v[182:183], v[118:119]
	v_pk_mul_f32 v[120:121], v[184:185], v[120:121]
	v_pk_mul_f32 v[122:123], v[186:187], v[122:123]
	v_pk_mul_f32 v[124:125], v[188:189], v[124:125]
	v_pk_mul_f32 v[100:101], v[190:191], v[100:101]
	v_pk_fma_f32 v[4:5], v[160:161], v[112:113], v[4:5]
	v_pk_fma_f32 v[6:7], v[162:163], v[114:115], v[6:7]
	v_pk_fma_f32 v[8:9], v[164:165], v[116:117], v[8:9]
	v_pk_fma_f32 v[10:11], v[166:167], v[118:119], v[10:11]
	v_pk_fma_f32 v[12:13], v[168:169], v[120:121], v[12:13]
	v_pk_fma_f32 v[14:15], v[170:171], v[122:123], v[14:15]
	v_pk_fma_f32 v[16:17], v[172:173], v[124:125], v[16:17]
	v_pk_fma_f32 v[18:19], v[174:175], v[100:101], v[18:19]
	v_pk_mul_f32 v[102:103], v[4:5], v[4:5]
	v_pk_mul_f32 v[106:107], v[6:7], v[6:7]
	v_pk_fma_f32 v[102:103], v[8:9], v[8:9], v[102:103]
	v_pk_fma_f32 v[106:107], v[10:11], v[10:11], v[106:107]
	v_pk_fma_f32 v[102:103], v[12:13], v[12:13], v[102:103]
	v_pk_fma_f32 v[106:107], v[14:15], v[14:15], v[106:107]
	v_pk_fma_f32 v[102:103], v[16:17], v[16:17], v[102:103]
	v_pk_fma_f32 v[106:107], v[18:19], v[18:19], v[106:107]
	s_nop 0
	v_pk_add_f32 v[102:103], v[102:103], v[106:107]
	s_nop 0
	v_add_f32_e32 v102, v102, v103
	s_nop 1
	v_add_f32_dpp v102, v102, v102 quad_perm:[1,0,3,2] row_mask:0xf bank_mask:0xf
	s_nop 1
	v_add_f32_dpp v102, v102, v102 quad_perm:[2,3,0,1] row_mask:0xf bank_mask:0xf
	s_nop 1
	v_add_f32_dpp v102, v102, v102 row_half_mirror row_mask:0xf bank_mask:0xf
	s_nop 1
	v_add_f32_dpp v102, v102, v102 row_mirror row_mask:0xf bank_mask:0xf
	s_nop 1
	v_add_f32_dpp v102, v102, v102 row_bcast:15 row_mask:0xa bank_mask:0xf
	s_nop 1
	v_add_f32_dpp v102, v102, v102 row_bcast:31 row_mask:0xc bank_mask:0xf
	s_nop 1
	v_readlane_b32 s74, v102, 63
	s_nop 2
	v_mov_b32_e32 v102, s74
	v_fmamk_f32 v102, v102, 0x3a800000, v2
	v_mul_f32_e32 v103, 0x4f800000, v102
	v_cmp_gt_f32_e32 vcc, 0xf800000, v102
	s_nop 1
	v_cndmask_b32_e32 v102, v102, v103, vcc
	v_sqrt_f32_e32 v103, v102
	s_nop 0
	v_add_u32_e32 v104, -1, v103
	v_add_u32_e32 v106, 1, v103
	v_fma_f32 v107, -v104, v103, v102
	v_fma_f32 v108, -v106, v103, v102
	v_cmp_ge_f32_e64 s[76:77], 0, v107
	s_nop 1
; __device__ __forceinline__ unsigned pk_bf16(float lo, float hi) { const f32x2 v = {lo, hi}; const bf16x2_t b = __builtin_convertvector(v, bf16x2_t); return __builtin_bit_cast(unsigned, b); }
; template <bool HAS_F, bool HAS_H>
; __device__ __forceinline__ void phase_rows(const Params& p, int sp, int sn, float resw, bool from_input, bool write_x = true) {
;     ...
;     for (int row = gw; row < T; row += NGW) {
;         const int b = row_batch(row);
;         const float* xin = !from_input ? p.out + (size_t)row * D : (row < TP ? p.in[0] + (size_t)row * D : p.in[1] + (size_t)(row - TP) * D);
;         f32x4 v[4];
; #pragma unroll
;         for (int j = 0; j < 4; ++j) v[j] = *(const f32x4*)(xin + 4 * lane + 256 * j);
;     ...
;             const float rs = 1.0f / sqrtf(wave_sum(ss) * (1.0f / D) + EPS);
;             const float* sh = mod + b * 9216 + sn * 3072; const float* scl = sh + 1024; const float* gq = p.in[6] + sn * D;
; #pragma unroll
;             for (int j = 0; j < 4; ++j) { const f32x4 a = *(const f32x4*)(sh + 4 * lane + 256 * j), s = *(const f32x4*)(scl + 4 * lane + 256 * j), q = *(const f32x4*)(gq + 4 * lane + 256 * j);
;                 const f32x4 h = (v[j] * rs * q) * (s + 1.0f) + a;
;                 u32x2 w; w.x = pk_bf16(h.x, h.y); w.y = pk_bf16(h.z, h.w);
;                 *(u32x2*)(H + (size_t)row * D + 4 * lane + 256 * j) = w; }
	v_cndmask_b32_e64 v103, v103, v104, s[76:77]
	v_cmp_lt_f32_e64 s[76:77], 0, v108
	s_nop 1
	v_cndmask_b32_e64 v103, v103, v106, s[76:77]
	v_mul_f32_e32 v104, 0x37800000, v103
	v_cndmask_b32_e32 v103, v103, v104, vcc
	v_cmp_class_f32_e32 vcc, v102, v3
	s_nop 1
	v_cndmask_b32_e32 v102, v103, v102, vcc
	v_div_scale_f32 v103, s[76:77], v102, v102, 1.0
	v_rcp_f32_e32 v104, v103
	v_div_scale_f32 v106, vcc, 1.0, v102, 1.0
	v_fma_f32 v107, -v103, v104, 1.0
	v_fmac_f32_e32 v104, v107, v104
	v_mul_f32_e32 v107, v106, v104
	v_fma_f32 v108, -v103, v107, v106
	v_fmac_f32_e32 v107, v108, v104
	v_fma_f32 v103, -v103, v107, v106
	v_div_fmas_f32 v103, v103, v104, v107
	v_div_fixup_f32 v110, v103, v102, 1.0
	s_lshl_b32 s60, s55, 11
	s_add_u32 s70, s78, s60
	s_addc_u32 s71, s79, 0
	v_pk_mul_f32 v[112:113], v[4:5], v[110:111] op_sel_hi:[1,0]
	v_pk_mul_f32 v[114:115], v[6:7], v[110:111] op_sel_hi:[1,0]
	v_pk_mul_f32 v[116:117], v[8:9], v[110:111] op_sel_hi:[1,0]
	v_pk_mul_f32 v[118:119], v[10:11], v[110:111] op_sel_hi:[1,0]
	v_pk_mul_f32 v[120:121], v[12:13], v[110:111] op_sel_hi:[1,0]
	v_pk_mul_f32 v[122:123], v[14:15], v[110:111] op_sel_hi:[1,0]
	v_pk_mul_f32 v[124:125], v[16:17], v[110:111] op_sel_hi:[1,0]
	v_pk_mul_f32 v[100:101], v[18:19], v[110:111] op_sel_hi:[1,0]
	v_pk_mul_f32 v[112:113], v[192:193], v[112:113]
	v_pk_mul_f32 v[114:115], v[194:195], v[114:115]
	v_pk_mul_f32 v[116:117], v[196:197], v[116:117]
	v_pk_mul_f32 v[118:119], v[198:199], v[118:119]
	v_pk_mul_f32 v[120:121], v[200:201], v[120:121]
	v_pk_mul_f32 v[122:123], v[202:203], v[122:123]
	v_pk_mul_f32 v[124:125], v[204:205], v[124:125]
	v_pk_mul_f32 v[100:101], v[206:207], v[100:101]
	v_pk_fma_f32 v[112:113], v[208:209], v[112:113], v[224:225]
	v_pk_fma_f32 v[114:115], v[210:211], v[114:115], v[226:227]
	v_pk_fma_f32 v[116:117], v[212:213], v[116:117], v[228:229]
	v_pk_fma_f32 v[118:119], v[214:215], v[118:119], v[230:231]
	v_pk_fma_f32 v[120:121], v[216:217], v[120:121], v[232:233]
	v_pk_fma_f32 v[122:123], v[218:219], v[122:123], v[234:235]
	v_pk_fma_f32 v[124:125], v[220:221], v[124:125], v[236:237]
	v_pk_fma_f32 v[100:101], v[222:223], v[100:101], v[238:239]
	v_cvt_pk_bf16_f32 v240, v112, v113
	v_cvt_pk_bf16_f32 v241, v114, v115
	v_cvt_pk_bf16_f32 v242, v116, v117
	v_cvt_pk_bf16_f32 v243, v118, v119
	v_cvt_pk_bf16_f32 v244, v120, v121
	v_cvt_pk_bf16_f32 v245, v122, v123
	v_cvt_pk_bf16_f32 v246, v124, v125
	v_cvt_pk_bf16_f32 v247, v100, v101
	global_store_dwordx2 v1, v[240:241], s[70:71]
	global_store_dwordx2 v1, v[242:243], s[70:71] offset:512
	global_store_dwordx2 v1, v[244:245], s[70:71] offset:1024
	global_store_dwordx2 v1, v[246:247], s[70:71] offset:1536
	s_add_u32 s55, s55, 8
	s_add_u32 s57, s55, 16
	s_min_u32 s57, s57, s54
	s_lshl_b32 s60, s57, 12
	s_add_u32 s64, s84, s60
	s_addc_u32 s65, s85, 0
	s_lshl_b32 s60, s57, 11
	s_add_u32 s66, s82, s60
	s_addc_u32 s67, s83, 0
	global_load_dwordx4 v[4:7], v0, s[64:65] nt
	global_load_dwordx4 v[8:11], v0, s[64:65] offset:1024 nt
	global_load_dwordx4 v[12:15], v0, s[64:65] offset:2048 nt
	global_load_dwordx4 v[16:19], v0, s[64:65] offset:3072 nt
	global_load_dwordx2 v[20:21], v1, s[66:67] nt
	global_load_dwordx2 v[22:23], v1, s[66:67] offset:512 nt
	global_load_dwordx2 v[24:25], v1, s[66:67] offset:1024 nt
	global_load_dwordx2 v[26:27], v1, s[66:67] offset:1536 nt
	s_lshr_b32 s60, s55, 11
	s_sub_u32 s61, s55, 0x8000
	s_lshr_b32 s61, s61, 12
	s_add_u32 s61, s61, 16
	s_cmp_lt_u32 s55, 0x8000
	s_cselect_b32 s63, s60, s61
	s_cmp_eq_u32 s63, s56
	s_cbranch_scc1 .Lrp12_pk5
	s_mov_b32 s56, s63
	s_mul_i32 s60, s56, 0x9000
	s_add_u32 s60, s60, 0x3185000
	s_add_u32 s0, s92, s60
	s_addc_u32 s1, s93, 0
	global_load_dwordx4 v[160:163], v0, s[0:1]
	global_load_dwordx4 v[164:167], v0, s[0:1] offset:1024
	global_load_dwordx4 v[168:171], v0, s[0:1] offset:2048
	global_load_dwordx4 v[172:175], v0, s[0:1] offset:3072
	s_add_u32 s0, s22, 0x1000
	s_addc_u32 s1, s23, 0
	global_load_dwordx4 v[176:179], v0, s[0:1]
	global_load_dwordx4 v[180:183], v0, s[0:1] offset:1024
	global_load_dwordx4 v[184:187], v0, s[0:1] offset:2048
	global_load_dwordx4 v[188:191], v0, s[0:1] offset:3072
	s_add_u32 s0, s20, 0x2000
	s_addc_u32 s1, s21, 0
	global_load_dwordx4 v[192:195], v0, s[0:1]
	global_load_dwordx4 v[196:199], v0, s[0:1] offset:1024
	global_load_dwordx4 v[200:203], v0, s[0:1] offset:2048
	global_load_dwordx4 v[204:207], v0, s[0:1] offset:3072
	s_mul_i32 s60, s56, 0x9000
	s_add_u32 s60, s60, 0x3187000
	s_add_u32 s0, s92, s60
	s_addc_u32 s1, s93, 0
	global_load_dwordx4 v[208:211], v0, s[0:1]
	global_load_dwordx4 v[212:215], v0, s[0:1] offset:1024
	global_load_dwordx4 v[216:219], v0, s[0:1] offset:2048
	global_load_dwordx4 v[220:223], v0, s[0:1] offset:3072
	s_mul_i32 s60, s56, 0x9000
	s_add_u32 s60, s60, 0x3186000
	s_add_u32 s0, s92, s60
	s_addc_u32 s1, s93, 0
	global_load_dwordx4 v[224:227], v0, s[0:1]
	global_load_dwordx4 v[228:231], v0, s[0:1] offset:1024
	global_load_dwordx4 v[232:235], v0, s[0:1] offset:2048
	global_load_dwordx4 v[236:239], v0, s[0:1] offset:3072
	s_waitcnt vmcnt(0)
	v_pk_add_f32 v[208:209], v[208:209], 1.0 op_sel_hi:[1,0]
	v_pk_add_f32 v[210:211], v[210:211], 1.0 op_sel_hi:[1,0]
	v_pk_add_f32 v[212:213], v[212:213], 1.0 op_sel_hi:[1,0]
	v_pk_add_f32 v[214:215], v[214:215], 1.0 op_sel_hi:[1,0]
	v_pk_add_f32 v[216:217], v[216:217], 1.0 op_sel_hi:[1,0]
	v_pk_add_f32 v[218:219], v[218:219], 1.0 op_sel_hi:[1,0]
	v_pk_add_f32 v[220:221], v[220:221], 1.0 op_sel_hi:[1,0]
	v_pk_add_f32 v[222:223], v[222:223], 1.0 op_sel_hi:[1,0]
; __device__ __forceinline__ float lo_bf(unsigned w) { return __uint_as_float(w << 16); }
; __device__ __forceinline__ float hi_bf(unsigned w) { return __uint_as_float(w & 0xffff0000u); }
; template <bool HAS_F, bool HAS_H>
; __device__ __forceinline__ void phase_rows(const Params& p, int sp, int sn, float resw, bool from_input, bool write_x = true) {
;     ...
;         if (HAS_F) {
;             f32x4 f[4]; float ss = 0.f;
; #pragma unroll
;             for (int j = 0; j < 4; ++j) { const u32x2 w = *(const u32x2*)(F + (size_t)row * D + 4 * lane + 256 * j);
;                 f[j] = (f32x4){lo_bf(w.x), hi_bf(w.x), lo_bf(w.y), hi_bf(w.y)}; ss += (f[j].x * f[j].x + f[j].y * f[j].y) + (f[j].z * f[j].z + f[j].w * f[j].w); }
;             const float rs = 1.0f / sqrtf(wave_sum(ss) * (1.0f / D) + EPS) * resw;
;             const float* gate = mod + b * 9216 + sp * 3072 + 2048; const float* gp = p.in[7] + sp * D;
; #pragma unroll
;             for (int j = 0; j < 4; ++j) { const f32x4 g = *(const f32x4*)(gate + 4 * lane + 256 * j), q = *(const f32x4*)(gp + 4 * lane + 256 * j);
;                 v[j] = v[j] + g * (f[j] * rs * q);
;                 if (write_x) *(f32x4*)(p.out + (size_t)row * D + 4 * lane + 256 * j) = v[j]; }
;         }
;         if (HAS_H) {
;             float ss = 0.f;
; #pragma unroll
;             for (int j = 0; j < 4; ++j) ss += (v[j].x * v[j].x + v[j].y * v[j].y) + (v[j].z * v[j].z + v[j].w * v[j].w);
;             const float rs = 1.0f / sqrtf(wave_sum(ss) * (1.0f / D) + EPS);
.Lrp12_pk5:
	s_waitcnt vmcnt(20)
	v_lshlrev_b32_e32 v112, 16, v52
	v_and_b32_e32 v113, 0xffff0000, v52
	v_lshlrev_b32_e32 v114, 16, v53
	v_and_b32_e32 v115, 0xffff0000, v53
	v_lshlrev_b32_e32 v116, 16, v54
	v_and_b32_e32 v117, 0xffff0000, v54
	v_lshlrev_b32_e32 v118, 16, v55
	v_and_b32_e32 v119, 0xffff0000, v55
	v_lshlrev_b32_e32 v120, 16, v56
	v_and_b32_e32 v121, 0xffff0000, v56
	v_lshlrev_b32_e32 v122, 16, v57
	v_and_b32_e32 v123, 0xffff0000, v57
	v_lshlrev_b32_e32 v124, 16, v58
	v_and_b32_e32 v125, 0xffff0000, v58
	v_lshlrev_b32_e32 v100, 16, v59
	v_and_b32_e32 v101, 0xffff0000, v59
	v_pk_mul_f32 v[102:103], v[112:113], v[112:113]
	v_pk_mul_f32 v[106:107], v[114:115], v[114:115]
	v_pk_fma_f32 v[102:103], v[116:117], v[116:117], v[102:103]
	v_pk_fma_f32 v[106:107], v[118:119], v[118:119], v[106:107]
	v_pk_fma_f32 v[102:103], v[120:121], v[120:121], v[102:103]
	v_pk_fma_f32 v[106:107], v[122:123], v[122:123], v[106:107]
	v_pk_fma_f32 v[102:103], v[124:125], v[124:125], v[102:103]
	v_pk_fma_f32 v[106:107], v[100:101], v[100:101], v[106:107]
	s_nop 0
	v_pk_add_f32 v[102:103], v[102:103], v[106:107]
	s_nop 0
	v_add_f32_e32 v102, v102, v103
	s_nop 1
	v_add_f32_dpp v102, v102, v102 quad_perm:[1,0,3,2] row_mask:0xf bank_mask:0xf
	s_nop 1
	v_add_f32_dpp v102, v102, v102 quad_perm:[2,3,0,1] row_mask:0xf bank_mask:0xf
	s_nop 1
	v_add_f32_dpp v102, v102, v102 row_half_mirror row_mask:0xf bank_mask:0xf
	s_nop 1
	v_add_f32_dpp v102, v102, v102 row_mirror row_mask:0xf bank_mask:0xf
	s_nop 1
	v_add_f32_dpp v102, v102, v102 row_bcast:15 row_mask:0xa bank_mask:0xf
	s_nop 1
	v_add_f32_dpp v102, v102, v102 row_bcast:31 row_mask:0xc bank_mask:0xf
	s_nop 1
	v_readlane_b32 s74, v102, 63
	s_nop 2
	v_mov_b32_e32 v102, s74
	v_fmamk_f32 v102, v102, 0x3a800000, v2
	v_mul_f32_e32 v103, 0x4f800000, v102
	v_cmp_gt_f32_e32 vcc, 0xf800000, v102
	s_nop 1
	v_cndmask_b32_e32 v102, v102, v103, vcc
	v_sqrt_f32_e32 v103, v102
	s_nop 0
	v_add_u32_e32 v104, -1, v103
	v_add_u32_e32 v106, 1, v103
	v_fma_f32 v107, -v104, v103, v102
	v_fma_f32 v108, -v106, v103, v102
	v_cmp_ge_f32_e64 s[76:77], 0, v107
	s_nop 1
	v_cndmask_b32_e64 v103, v103, v104, s[76:77]
	v_cmp_lt_f32_e64 s[76:77], 0, v108
	s_nop 1
	v_cndmask_b32_e64 v103, v103, v106, s[76:77]
	v_mul_f32_e32 v104, 0x37800000, v103
	v_cndmask_b32_e32 v103, v103, v104, vcc
	v_cmp_class_f32_e32 vcc, v102, v3
	s_nop 1
	v_cndmask_b32_e32 v102, v103, v102, vcc
	v_div_scale_f32 v103, s[76:77], v102, v102, 1.0
	v_rcp_f32_e32 v104, v103
	v_div_scale_f32 v106, vcc, 1.0, v102, 1.0
	v_fma_f32 v107, -v103, v104, 1.0
	v_fmac_f32_e32 v104, v107, v104
	v_mul_f32_e32 v107, v106, v104
	v_fma_f32 v108, -v103, v107, v106
	v_fmac_f32_e32 v107, v108, v104
	v_fma_f32 v103, -v103, v107, v106
	v_div_fmas_f32 v103, v103, v104, v107
	v_div_fixup_f32 v110, v103, v102, 1.0
	v_pk_mul_f32 v[112:113], v[112:113], v[110:111] op_sel_hi:[1,0]
	v_pk_mul_f32 v[114:115], v[114:115], v[110:111] op_sel_hi:[1,0]
	v_pk_mul_f32 v[116:117], v[116:117], v[110:111] op_sel_hi:[1,0]
	v_pk_mul_f32 v[118:119], v[118:119], v[110:111] op_sel_hi:[1,0]
	v_pk_mul_f32 v[120:121], v[120:121], v[110:111] op_sel_hi:[1,0]
	v_pk_mul_f32 v[122:123], v[122:123], v[110:111] op_sel_hi:[1,0]
	v_pk_mul_f32 v[124:125], v[124:125], v[110:111] op_sel_hi:[1,0]
	v_pk_mul_f32 v[100:101], v[100:101], v[110:111] op_sel_hi:[1,0]
	v_pk_mul_f32 v[112:113], v[176:177], v[112:113]
	v_pk_mul_f32 v[114:115], v[178:179], v[114:115]
	v_pk_mul_f32 v[116:117], v[180:181], v[116:117]
	v_pk_mul_f32 v[118:119], v[182:183], v[118:119]
	v_pk_mul_f32 v[120:121], v[184:185], v[120:121]
	v_pk_mul_f32 v[122:123], v[186:187], v[122:123]
	v_pk_mul_f32 v[124:125], v[188:189], v[124:125]
	v_pk_mul_f32 v[100:101], v[190:191], v[100:101]
	v_pk_fma_f32 v[36:37], v[160:161], v[112:113], v[36:37]
	v_pk_fma_f32 v[38:39], v[162:163], v[114:115], v[38:39]
	v_pk_fma_f32 v[40:41], v[164:165], v[116:117], v[40:41]
	v_pk_fma_f32 v[42:43], v[166:167], v[118:119], v[42:43]
	v_pk_fma_f32 v[44:45], v[168:169], v[120:121], v[44:45]
	v_pk_fma_f32 v[46:47], v[170:171], v[122:123], v[46:47]
	v_pk_fma_f32 v[48:49], v[172:173], v[124:125], v[48:49]
	v_pk_fma_f32 v[50:51], v[174:175], v[100:101], v[50:51]
	v_pk_mul_f32 v[102:103], v[36:37], v[36:37]
	v_pk_mul_f32 v[106:107], v[38:39], v[38:39]
	v_pk_fma_f32 v[102:103], v[40:41], v[40:41], v[102:103]
	v_pk_fma_f32 v[106:107], v[42:43], v[42:43], v[106:107]
	v_pk_fma_f32 v[102:103], v[44:45], v[44:45], v[102:103]
	v_pk_fma_f32 v[106:107], v[46:47], v[46:47], v[106:107]
	v_pk_fma_f32 v[102:103], v[48:49], v[48:49], v[102:103]
	v_pk_fma_f32 v[106:107], v[50:51], v[50:51], v[106:107]
	s_nop 0
	v_pk_add_f32 v[102:103], v[102:103], v[106:107]
	s_nop 0
	v_add_f32_e32 v102, v102, v103
	s_nop 1
	v_add_f32_dpp v102, v102, v102 quad_perm:[1,0,3,2] row_mask:0xf bank_mask:0xf
	s_nop 1
	v_add_f32_dpp v102, v102, v102 quad_perm:[2,3,0,1] row_mask:0xf bank_mask:0xf
	s_nop 1
	v_add_f32_dpp v102, v102, v102 row_half_mirror row_mask:0xf bank_mask:0xf
	s_nop 1
	v_add_f32_dpp v102, v102, v102 row_mirror row_mask:0xf bank_mask:0xf
	s_nop 1
	v_add_f32_dpp v102, v102, v102 row_bcast:15 row_mask:0xa bank_mask:0xf
	s_nop 1
	v_add_f32_dpp v102, v102, v102 row_bcast:31 row_mask:0xc bank_mask:0xf
	s_nop 1
	v_readlane_b32 s74, v102, 63
	s_nop 2
	v_mov_b32_e32 v102, s74
	v_fmamk_f32 v102, v102, 0x3a800000, v2
	v_mul_f32_e32 v103, 0x4f800000, v102
	v_cmp_gt_f32_e32 vcc, 0xf800000, v102
	s_nop 1
	v_cndmask_b32_e32 v102, v102, v103, vcc
	v_sqrt_f32_e32 v103, v102
	s_nop 0
	v_add_u32_e32 v104, -1, v103
	v_add_u32_e32 v106, 1, v103
	v_fma_f32 v107, -v104, v103, v102
	v_fma_f32 v108, -v106, v103, v102
	v_cmp_ge_f32_e64 s[76:77], 0, v107
; __device__ __forceinline__ unsigned pk_bf16(float lo, float hi) { const f32x2 v = {lo, hi}; const bf16x2_t b = __builtin_convertvector(v, bf16x2_t); return __builtin_bit_cast(unsigned, b); }
; template <bool HAS_F, bool HAS_H>
; __device__ __forceinline__ void phase_rows(const Params& p, int sp, int sn, float resw, bool from_input, bool write_x = true) {
;     ...
;     for (int row = gw; row < T; row += NGW) {
;         const int b = row_batch(row);
;         const float* xin = !from_input ? p.out + (size_t)row * D : (row < TP ? p.in[0] + (size_t)row * D : p.in[1] + (size_t)(row - TP) * D);
;         f32x4 v[4];
; #pragma unroll
;         for (int j = 0; j < 4; ++j) v[j] = *(const f32x4*)(xin + 4 * lane + 256 * j);
;     ...
;             const float rs = 1.0f / sqrtf(wave_sum(ss) * (1.0f / D) + EPS);
;             const float* sh = mod + b * 9216 + sn * 3072; const float* scl = sh + 1024; const float* gq = p.in[6] + sn * D;
; #pragma unroll
;             for (int j = 0; j < 4; ++j) { const f32x4 a = *(const f32x4*)(sh + 4 * lane + 256 * j), s = *(const f32x4*)(scl + 4 * lane + 256 * j), q = *(const f32x4*)(gq + 4 * lane + 256 * j);
;                 const f32x4 h = (v[j] * rs * q) * (s + 1.0f) + a;
;                 u32x2 w; w.x = pk_bf16(h.x, h.y); w.y = pk_bf16(h.z, h.w);
;                 *(u32x2*)(H + (size_t)row * D + 4 * lane + 256 * j) = w; }
	s_nop 1
	v_cndmask_b32_e64 v103, v103, v104, s[76:77]
	v_cmp_lt_f32_e64 s[76:77], 0, v108
	s_nop 1
	v_cndmask_b32_e64 v103, v103, v106, s[76:77]
	v_mul_f32_e32 v104, 0x37800000, v103
	v_cndmask_b32_e32 v103, v103, v104, vcc
	v_cmp_class_f32_e32 vcc, v102, v3
	s_nop 1
	v_cndmask_b32_e32 v102, v103, v102, vcc
	v_div_scale_f32 v103, s[76:77], v102, v102, 1.0
	v_rcp_f32_e32 v104, v103
	v_div_scale_f32 v106, vcc, 1.0, v102, 1.0
	v_fma_f32 v107, -v103, v104, 1.0
	v_fmac_f32_e32 v104, v107, v104
	v_mul_f32_e32 v107, v106, v104
	v_fma_f32 v108, -v103, v107, v106
	v_fmac_f32_e32 v107, v108, v104
	v_fma_f32 v103, -v103, v107, v106
	v_div_fmas_f32 v103, v103, v104, v107
	v_div_fixup_f32 v110, v103, v102, 1.0
	s_lshl_b32 s60, s55, 11
	s_add_u32 s70, s78, s60
	s_addc_u32 s71, s79, 0
	v_pk_mul_f32 v[112:113], v[36:37], v[110:111] op_sel_hi:[1,0]
	v_pk_mul_f32 v[114:115], v[38:39], v[110:111] op_sel_hi:[1,0]
	v_pk_mul_f32 v[116:117], v[40:41], v[110:111] op_sel_hi:[1,0]
	v_pk_mul_f32 v[118:119], v[42:43], v[110:111] op_sel_hi:[1,0]
	v_pk_mul_f32 v[120:121], v[44:45], v[110:111] op_sel_hi:[1,0]
	v_pk_mul_f32 v[122:123], v[46:47], v[110:111] op_sel_hi:[1,0]
	v_pk_mul_f32 v[124:125], v[48:49], v[110:111] op_sel_hi:[1,0]
	v_pk_mul_f32 v[100:101], v[50:51], v[110:111] op_sel_hi:[1,0]
	v_pk_mul_f32 v[112:113], v[192:193], v[112:113]
	v_pk_mul_f32 v[114:115], v[194:195], v[114:115]
	v_pk_mul_f32 v[116:117], v[196:197], v[116:117]
	v_pk_mul_f32 v[118:119], v[198:199], v[118:119]
	v_pk_mul_f32 v[120:121], v[200:201], v[120:121]
	v_pk_mul_f32 v[122:123], v[202:203], v[122:123]
	v_pk_mul_f32 v[124:125], v[204:205], v[124:125]
	v_pk_mul_f32 v[100:101], v[206:207], v[100:101]
	v_pk_fma_f32 v[112:113], v[208:209], v[112:113], v[224:225]
	v_pk_fma_f32 v[114:115], v[210:211], v[114:115], v[226:227]
	v_pk_fma_f32 v[116:117], v[212:213], v[116:117], v[228:229]
	v_pk_fma_f32 v[118:119], v[214:215], v[118:119], v[230:231]
	v_pk_fma_f32 v[120:121], v[216:217], v[120:121], v[232:233]
	v_pk_fma_f32 v[122:123], v[218:219], v[122:123], v[234:235]
	v_pk_fma_f32 v[124:125], v[220:221], v[124:125], v[236:237]
	v_pk_fma_f32 v[100:101], v[222:223], v[100:101], v[238:239]
	v_cvt_pk_bf16_f32 v240, v112, v113
	v_cvt_pk_bf16_f32 v241, v114, v115
	v_cvt_pk_bf16_f32 v242, v116, v117
	v_cvt_pk_bf16_f32 v243, v118, v119
	v_cvt_pk_bf16_f32 v244, v120, v121
	v_cvt_pk_bf16_f32 v245, v122, v123
	v_cvt_pk_bf16_f32 v246, v124, v125
	v_cvt_pk_bf16_f32 v247, v100, v101
	global_store_dwordx2 v1, v[240:241], s[70:71]
	global_store_dwordx2 v1, v[242:243], s[70:71] offset:512
	global_store_dwordx2 v1, v[244:245], s[70:71] offset:1024
	global_store_dwordx2 v1, v[246:247], s[70:71] offset:1536
	s_add_u32 s55, s55, 8
	s_add_u32 s57, s55, 16
	s_min_u32 s57, s57, s54
	s_lshl_b32 s60, s57, 12
	s_add_u32 s64, s84, s60
	s_addc_u32 s65, s85, 0
	s_lshl_b32 s60, s57, 11
	s_add_u32 s66, s82, s60
	s_addc_u32 s67, s83, 0
	global_load_dwordx4 v[36:39], v0, s[64:65] nt
	global_load_dwordx4 v[40:43], v0, s[64:65] offset:1024 nt
	global_load_dwordx4 v[44:47], v0, s[64:65] offset:2048 nt
	global_load_dwordx4 v[48:51], v0, s[64:65] offset:3072 nt
	global_load_dwordx2 v[52:53], v1, s[66:67] nt
	global_load_dwordx2 v[54:55], v1, s[66:67] offset:512 nt
	global_load_dwordx2 v[56:57], v1, s[66:67] offset:1024 nt
	global_load_dwordx2 v[58:59], v1, s[66:67] offset:1536 nt
	s_lshr_b32 s60, s55, 11
	s_sub_u32 s61, s55, 0x8000
	s_lshr_b32 s61, s61, 12
	s_add_u32 s61, s61, 16
	s_cmp_lt_u32 s55, 0x8000
	s_cselect_b32 s63, s60, s61
	s_cmp_eq_u32 s63, s56
	s_cbranch_scc1 .Lrp12_pk6
	s_mov_b32 s56, s63
	s_mul_i32 s60, s56, 0x9000
	s_add_u32 s60, s60, 0x3185000
	s_add_u32 s0, s92, s60
	s_addc_u32 s1, s93, 0
	global_load_dwordx4 v[160:163], v0, s[0:1]
	global_load_dwordx4 v[164:167], v0, s[0:1] offset:1024
	global_load_dwordx4 v[168:171], v0, s[0:1] offset:2048
	global_load_dwordx4 v[172:175], v0, s[0:1] offset:3072
	s_add_u32 s0, s22, 0x1000
	s_addc_u32 s1, s23, 0
	global_load_dwordx4 v[176:179], v0, s[0:1]
	global_load_dwordx4 v[180:183], v0, s[0:1] offset:1024
	global_load_dwordx4 v[184:187], v0, s[0:1] offset:2048
	global_load_dwordx4 v[188:191], v0, s[0:1] offset:3072
	s_add_u32 s0, s20, 0x2000
	s_addc_u32 s1, s21, 0
	global_load_dwordx4 v[192:195], v0, s[0:1]
	global_load_dwordx4 v[196:199], v0, s[0:1] offset:1024
	global_load_dwordx4 v[200:203], v0, s[0:1] offset:2048
	global_load_dwordx4 v[204:207], v0, s[0:1] offset:3072
	s_mul_i32 s60, s56, 0x9000
	s_add_u32 s60, s60, 0x3187000
	s_add_u32 s0, s92, s60
	s_addc_u32 s1, s93, 0
	global_load_dwordx4 v[208:211], v0, s[0:1]
	global_load_dwordx4 v[212:215], v0, s[0:1] offset:1024
	global_load_dwordx4 v[216:219], v0, s[0:1] offset:2048
	global_load_dwordx4 v[220:223], v0, s[0:1] offset:3072
	s_mul_i32 s60, s56, 0x9000
	s_add_u32 s60, s60, 0x3186000
	s_add_u32 s0, s92, s60
	s_addc_u32 s1, s93, 0
	global_load_dwordx4 v[224:227], v0, s[0:1]
	global_load_dwordx4 v[228:231], v0, s[0:1] offset:1024
	global_load_dwordx4 v[232:235], v0, s[0:1] offset:2048
	global_load_dwordx4 v[236:239], v0, s[0:1] offset:3072
	s_waitcnt vmcnt(0)
	v_pk_add_f32 v[208:209], v[208:209], 1.0 op_sel_hi:[1,0]
	v_pk_add_f32 v[210:211], v[210:211], 1.0 op_sel_hi:[1,0]
	v_pk_add_f32 v[212:213], v[212:213], 1.0 op_sel_hi:[1,0]
	v_pk_add_f32 v[214:215], v[214:215], 1.0 op_sel_hi:[1,0]
	v_pk_add_f32 v[216:217], v[216:217], 1.0 op_sel_hi:[1,0]
	v_pk_add_f32 v[218:219], v[218:219], 1.0 op_sel_hi:[1,0]
	v_pk_add_f32 v[220:221], v[220:221], 1.0 op_sel_hi:[1,0]
	v_pk_add_f32 v[222:223], v[222:223], 1.0 op_sel_hi:[1,0]
; __device__ __forceinline__ float lo_bf(unsigned w) { return __uint_as_float(w << 16); }
; __device__ __forceinline__ float hi_bf(unsigned w) { return __uint_as_float(w & 0xffff0000u); }
; template <bool HAS_F, bool HAS_H>
; __device__ __forceinline__ void phase_rows(const Params& p, int sp, int sn, float resw, bool from_input, bool write_x = true) {
;     ...
;         if (HAS_F) {
;             f32x4 f[4]; float ss = 0.f;
; #pragma unroll
;             for (int j = 0; j < 4; ++j) { const u32x2 w = *(const u32x2*)(F + (size_t)row * D + 4 * lane + 256 * j);
;                 f[j] = (f32x4){lo_bf(w.x), hi_bf(w.x), lo_bf(w.y), hi_bf(w.y)}; ss += (f[j].x * f[j].x + f[j].y * f[j].y) + (f[j].z * f[j].z + f[j].w * f[j].w); }
;             const float rs = 1.0f / sqrtf(wave_sum(ss) * (1.0f / D) + EPS) * resw;
;             const float* gate = mod + b * 9216 + sp * 3072 + 2048; const float* gp = p.in[7] + sp * D;
; #pragma unroll
;             for (int j = 0; j < 4; ++j) { const f32x4 g = *(const f32x4*)(gate + 4 * lane + 256 * j), q = *(const f32x4*)(gp + 4 * lane + 256 * j);
;                 v[j] = v[j] + g * (f[j] * rs * q);
;                 if (write_x) *(f32x4*)(p.out + (size_t)row * D + 4 * lane + 256 * j) = v[j]; }
.Lrp12_pk6:
	s_waitcnt vmcnt(24)
	v_lshlrev_b32_e32 v112, 16, v84
	v_and_b32_e32 v113, 0xffff0000, v84
	v_lshlrev_b32_e32 v114, 16, v85
	v_and_b32_e32 v115, 0xffff0000, v85
	v_lshlrev_b32_e32 v116, 16, v86
	v_and_b32_e32 v117, 0xffff0000, v86
	v_lshlrev_b32_e32 v118, 16, v87
	v_and_b32_e32 v119, 0xffff0000, v87
	v_lshlrev_b32_e32 v120, 16, v88
	v_and_b32_e32 v121, 0xffff0000, v88
	v_lshlrev_b32_e32 v122, 16, v89
	v_and_b32_e32 v123, 0xffff0000, v89
	v_lshlrev_b32_e32 v124, 16, v90
	v_and_b32_e32 v125, 0xffff0000, v90
	v_lshlrev_b32_e32 v100, 16, v91
	v_and_b32_e32 v101, 0xffff0000, v91
	v_pk_mul_f32 v[102:103], v[112:113], v[112:113]
	v_pk_mul_f32 v[106:107], v[114:115], v[114:115]
	v_pk_fma_f32 v[102:103], v[116:117], v[116:117], v[102:103]
	v_pk_fma_f32 v[106:107], v[118:119], v[118:119], v[106:107]
	v_pk_fma_f32 v[102:103], v[120:121], v[120:121], v[102:103]
	v_pk_fma_f32 v[106:107], v[122:123], v[122:123], v[106:107]
	v_pk_fma_f32 v[102:103], v[124:125], v[124:125], v[102:103]
	v_pk_fma_f32 v[106:107], v[100:101], v[100:101], v[106:107]
	s_nop 0
	v_pk_add_f32 v[102:103], v[102:103], v[106:107]
	s_nop 0
	v_add_f32_e32 v102, v102, v103
	s_nop 1
	v_add_f32_dpp v102, v102, v102 quad_perm:[1,0,3,2] row_mask:0xf bank_mask:0xf
	s_nop 1
	v_add_f32_dpp v102, v102, v102 quad_perm:[2,3,0,1] row_mask:0xf bank_mask:0xf
	s_nop 1
	v_add_f32_dpp v102, v102, v102 row_half_mirror row_mask:0xf bank_mask:0xf
	s_nop 1
	v_add_f32_dpp v102, v102, v102 row_mirror row_mask:0xf bank_mask:0xf
	s_nop 1
	v_add_f32_dpp v102, v102, v102 row_bcast:15 row_mask:0xa bank_mask:0xf
	s_nop 1
	v_add_f32_dpp v102, v102, v102 row_bcast:31 row_mask:0xc bank_mask:0xf
	s_nop 1
	v_readlane_b32 s74, v102, 63
	s_nop 2
	v_mov_b32_e32 v102, s74
	v_fmamk_f32 v102, v102, 0x3a800000, v2
	v_mul_f32_e32 v103, 0x4f800000, v102
	v_cmp_gt_f32_e32 vcc, 0xf800000, v102
	s_nop 1
	v_cndmask_b32_e32 v102, v102, v103, vcc
	v_sqrt_f32_e32 v103, v102
	s_nop 0
	v_add_u32_e32 v104, -1, v103
	v_add_u32_e32 v106, 1, v103
	v_fma_f32 v107, -v104, v103, v102
	v_fma_f32 v108, -v106, v103, v102
	v_cmp_ge_f32_e64 s[76:77], 0, v107
	s_nop 1
	v_cndmask_b32_e64 v103, v103, v104, s[76:77]
	v_cmp_lt_f32_e64 s[76:77], 0, v108
	s_nop 1
	v_cndmask_b32_e64 v103, v103, v106, s[76:77]
	v_mul_f32_e32 v104, 0x37800000, v103
	v_cndmask_b32_e32 v103, v103, v104, vcc
	v_cmp_class_f32_e32 vcc, v102, v3
	s_nop 1
	v_cndmask_b32_e32 v102, v103, v102, vcc
	v_div_scale_f32 v103, s[76:77], v102, v102, 1.0
	v_rcp_f32_e32 v104, v103
	v_div_scale_f32 v106, vcc, 1.0, v102, 1.0
	v_fma_f32 v107, -v103, v104, 1.0
	v_fmac_f32_e32 v104, v107, v104
	v_mul_f32_e32 v107, v106, v104
	v_fma_f32 v108, -v103, v107, v106
	v_fmac_f32_e32 v107, v108, v104
	v_fma_f32 v103, -v103, v107, v106
	v_div_fmas_f32 v103, v103, v104, v107
	v_div_fixup_f32 v110, v103, v102, 1.0
	v_pk_mul_f32 v[112:113], v[112:113], v[110:111] op_sel_hi:[1,0]
	v_pk_mul_f32 v[114:115], v[114:115], v[110:111] op_sel_hi:[1,0]
	v_pk_mul_f32 v[116:117], v[116:117], v[110:111] op_sel_hi:[1,0]
	v_pk_mul_f32 v[118:119], v[118:119], v[110:111] op_sel_hi:[1,0]
	v_pk_mul_f32 v[120:121], v[120:121], v[110:111] op_sel_hi:[1,0]
	v_pk_mul_f32 v[122:123], v[122:123], v[110:111] op_sel_hi:[1,0]
	v_pk_mul_f32 v[124:125], v[124:125], v[110:111] op_sel_hi:[1,0]
	v_pk_mul_f32 v[100:101], v[100:101], v[110:111] op_sel_hi:[1,0]
	v_pk_mul_f32 v[112:113], v[176:177], v[112:113]
	v_pk_mul_f32 v[114:115], v[178:179], v[114:115]
	v_pk_mul_f32 v[116:117], v[180:181], v[116:117]
	v_pk_mul_f32 v[118:119], v[182:183], v[118:119]
	v_pk_mul_f32 v[120:121], v[184:185], v[120:121]
	v_pk_mul_f32 v[122:123], v[186:187], v[122:123]
	v_pk_mul_f32 v[124:125], v[188:189], v[124:125]
	v_pk_mul_f32 v[100:101], v[190:191], v[100:101]
	v_pk_fma_f32 v[68:69], v[160:161], v[112:113], v[68:69]
	v_pk_fma_f32 v[70:71], v[162:163], v[114:115], v[70:71]
	v_pk_fma_f32 v[72:73], v[164:165], v[116:117], v[72:73]
	v_pk_fma_f32 v[74:75], v[166:167], v[118:119], v[74:75]
	v_pk_fma_f32 v[76:77], v[168:169], v[120:121], v[76:77]
	v_pk_fma_f32 v[78:79], v[170:171], v[122:123], v[78:79]
	v_pk_fma_f32 v[80:81], v[172:173], v[124:125], v[80:81]
	v_pk_fma_f32 v[82:83], v[174:175], v[100:101], v[82:83]
; __device__ __forceinline__ unsigned pk_bf16(float lo, float hi) { const f32x2 v = {lo, hi}; const bf16x2_t b = __builtin_convertvector(v, bf16x2_t); return __builtin_bit_cast(unsigned, b); }
; template <bool HAS_F, bool HAS_H>
; __device__ __forceinline__ void phase_rows(const Params& p, int sp, int sn, float resw, bool from_input, bool write_x = true) {
;     ...
;         if (HAS_H) {
;             float ss = 0.f;
; #pragma unroll
;             for (int j = 0; j < 4; ++j) ss += (v[j].x * v[j].x + v[j].y * v[j].y) + (v[j].z * v[j].z + v[j].w * v[j].w);
;             const float rs = 1.0f / sqrtf(wave_sum(ss) * (1.0f / D) + EPS);
;             const float* sh = mod + b * 9216 + sn * 3072; const float* scl = sh + 1024; const float* gq = p.in[6] + sn * D;
; #pragma unroll
;             for (int j = 0; j < 4; ++j) { const f32x4 a = *(const f32x4*)(sh + 4 * lane + 256 * j), s = *(const f32x4*)(scl + 4 * lane + 256 * j), q = *(const f32x4*)(gq + 4 * lane + 256 * j);
;                 const f32x4 h = (v[j] * rs * q) * (s + 1.0f) + a;
;                 u32x2 w; w.x = pk_bf16(h.x, h.y); w.y = pk_bf16(h.z, h.w);
;                 *(u32x2*)(H + (size_t)row * D + 4 * lane + 256 * j) = w; }
	v_pk_mul_f32 v[102:103], v[68:69], v[68:69]
	v_pk_mul_f32 v[106:107], v[70:71], v[70:71]
	v_pk_fma_f32 v[102:103], v[72:73], v[72:73], v[102:103]
	v_pk_fma_f32 v[106:107], v[74:75], v[74:75], v[106:107]
	v_pk_fma_f32 v[102:103], v[76:77], v[76:77], v[102:103]
	v_pk_fma_f32 v[106:107], v[78:79], v[78:79], v[106:107]
	v_pk_fma_f32 v[102:103], v[80:81], v[80:81], v[102:103]
	v_pk_fma_f32 v[106:107], v[82:83], v[82:83], v[106:107]
	s_nop 0
	v_pk_add_f32 v[102:103], v[102:103], v[106:107]
	s_nop 0
	v_add_f32_e32 v102, v102, v103
	s_nop 1
	v_add_f32_dpp v102, v102, v102 quad_perm:[1,0,3,2] row_mask:0xf bank_mask:0xf
	s_nop 1
	v_add_f32_dpp v102, v102, v102 quad_perm:[2,3,0,1] row_mask:0xf bank_mask:0xf
	s_nop 1
	v_add_f32_dpp v102, v102, v102 row_half_mirror row_mask:0xf bank_mask:0xf
	s_nop 1
	v_add_f32_dpp v102, v102, v102 row_mirror row_mask:0xf bank_mask:0xf
	s_nop 1
	v_add_f32_dpp v102, v102, v102 row_bcast:15 row_mask:0xa bank_mask:0xf
	s_nop 1
	v_add_f32_dpp v102, v102, v102 row_bcast:31 row_mask:0xc bank_mask:0xf
	s_nop 1
	v_readlane_b32 s74, v102, 63
	s_nop 2
	v_mov_b32_e32 v102, s74
	v_fmamk_f32 v102, v102, 0x3a800000, v2
	v_mul_f32_e32 v103, 0x4f800000, v102
	v_cmp_gt_f32_e32 vcc, 0xf800000, v102
	s_nop 1
	v_cndmask_b32_e32 v102, v102, v103, vcc
	v_sqrt_f32_e32 v103, v102
	s_nop 0
	v_add_u32_e32 v104, -1, v103
	v_add_u32_e32 v106, 1, v103
	v_fma_f32 v107, -v104, v103, v102
	v_fma_f32 v108, -v106, v103, v102
	v_cmp_ge_f32_e64 s[76:77], 0, v107
	s_nop 1
	v_cndmask_b32_e64 v103, v103, v104, s[76:77]
	v_cmp_lt_f32_e64 s[76:77], 0, v108
	s_nop 1
	v_cndmask_b32_e64 v103, v103, v106, s[76:77]
	v_mul_f32_e32 v104, 0x37800000, v103
	v_cndmask_b32_e32 v103, v103, v104, vcc
	v_cmp_class_f32_e32 vcc, v102, v3
	s_nop 1
	v_cndmask_b32_e32 v102, v103, v102, vcc
	v_div_scale_f32 v103, s[76:77], v102, v102, 1.0
	v_rcp_f32_e32 v104, v103
	v_div_scale_f32 v106, vcc, 1.0, v102, 1.0
	v_fma_f32 v107, -v103, v104, 1.0
	v_fmac_f32_e32 v104, v107, v104
	v_mul_f32_e32 v107, v106, v104
	v_fma_f32 v108, -v103, v107, v106
	v_fmac_f32_e32 v107, v108, v104
	v_fma_f32 v103, -v103, v107, v106
	v_div_fmas_f32 v103, v103, v104, v107
	v_div_fixup_f32 v110, v103, v102, 1.0
	s_lshl_b32 s60, s55, 11
	s_add_u32 s70, s78, s60
	s_addc_u32 s71, s79, 0
	v_pk_mul_f32 v[112:113], v[68:69], v[110:111] op_sel_hi:[1,0]
	v_pk_mul_f32 v[114:115], v[70:71], v[110:111] op_sel_hi:[1,0]
	v_pk_mul_f32 v[116:117], v[72:73], v[110:111] op_sel_hi:[1,0]
	v_pk_mul_f32 v[118:119], v[74:75], v[110:111] op_sel_hi:[1,0]
	v_pk_mul_f32 v[120:121], v[76:77], v[110:111] op_sel_hi:[1,0]
	v_pk_mul_f32 v[122:123], v[78:79], v[110:111] op_sel_hi:[1,0]
	v_pk_mul_f32 v[124:125], v[80:81], v[110:111] op_sel_hi:[1,0]
	v_pk_mul_f32 v[100:101], v[82:83], v[110:111] op_sel_hi:[1,0]
	v_pk_mul_f32 v[112:113], v[192:193], v[112:113]
	v_pk_mul_f32 v[114:115], v[194:195], v[114:115]
	v_pk_mul_f32 v[116:117], v[196:197], v[116:117]
	v_pk_mul_f32 v[118:119], v[198:199], v[118:119]
	v_pk_mul_f32 v[120:121], v[200:201], v[120:121]
	v_pk_mul_f32 v[122:123], v[202:203], v[122:123]
	v_pk_mul_f32 v[124:125], v[204:205], v[124:125]
	v_pk_mul_f32 v[100:101], v[206:207], v[100:101]
	v_pk_fma_f32 v[112:113], v[208:209], v[112:113], v[224:225]
	v_pk_fma_f32 v[114:115], v[210:211], v[114:115], v[226:227]
	v_pk_fma_f32 v[116:117], v[212:213], v[116:117], v[228:229]
	v_pk_fma_f32 v[118:119], v[214:215], v[118:119], v[230:231]
	v_pk_fma_f32 v[120:121], v[216:217], v[120:121], v[232:233]
	v_pk_fma_f32 v[122:123], v[218:219], v[122:123], v[234:235]
	v_pk_fma_f32 v[124:125], v[220:221], v[124:125], v[236:237]
	v_pk_fma_f32 v[100:101], v[222:223], v[100:101], v[238:239]
	v_cvt_pk_bf16_f32 v240, v112, v113
	v_cvt_pk_bf16_f32 v241, v114, v115
	v_cvt_pk_bf16_f32 v242, v116, v117
	v_cvt_pk_bf16_f32 v243, v118, v119
	v_cvt_pk_bf16_f32 v244, v120, v121
	v_cvt_pk_bf16_f32 v245, v122, v123
	v_cvt_pk_bf16_f32 v246, v124, v125
	v_cvt_pk_bf16_f32 v247, v100, v101
	global_store_dwordx2 v1, v[240:241], s[70:71]
	global_store_dwordx2 v1, v[242:243], s[70:71] offset:512
	global_store_dwordx2 v1, v[244:245], s[70:71] offset:1024
	global_store_dwordx2 v1, v[246:247], s[70:71] offset:1536
	s_add_u32 s55, s55, 8

; __device__ __forceinline__ float lo_bf(unsigned w) { return __uint_as_float(w << 16); }
; __device__ __forceinline__ float hi_bf(unsigned w) { return __uint_as_float(w & 0xffff0000u); }
; template <bool HAS_F, bool HAS_H>
; __device__ __forceinline__ void phase_rows(const Params& p, int sp, int sn, float resw, bool from_input, bool write_x = true) {
;     ...
;         if (HAS_F) {
;             f32x4 f[4]; float ss = 0.f;
; #pragma unroll
;             for (int j = 0; j < 4; ++j) { const u32x2 w = *(const u32x2*)(F + (size_t)row * D + 4 * lane + 256 * j);
;                 f[j] = (f32x4){lo_bf(w.x), hi_bf(w.x), lo_bf(w.y), hi_bf(w.y)}; ss += (f[j].x * f[j].x + f[j].y * f[j].y) + (f[j].z * f[j].z + f[j].w * f[j].w); }
;             const float rs = 1.0f / sqrtf(wave_sum(ss) * (1.0f / D) + EPS) * resw;
;             const float* gate = mod + b * 9216 + sp * 3072 + 2048; const float* gp = p.in[7] + sp * D;
; #pragma unroll
;             for (int j = 0; j < 4; ++j) { const f32x4 g = *(const f32x4*)(gate + 4 * lane + 256 * j), q = *(const f32x4*)(gp + 4 * lane + 256 * j);
;                 v[j] = v[j] + g * (f[j] * rs * q);
;                 if (write_x) *(f32x4*)(p.out + (size_t)row * D + 4 * lane + 256 * j) = v[j]; }
;         }
;         if (HAS_H) {
;             float ss = 0.f;
; #pragma unroll
;             for (int j = 0; j < 4; ++j) ss += (v[j].x * v[j].x + v[j].y * v[j].y) + (v[j].z * v[j].z + v[j].w * v[j].w);
;             const float rs = 1.0f / sqrtf(wave_sum(ss) * (1.0f / D) + EPS);
.Lrp12_pk7:
	s_waitcnt vmcnt(24)
	v_lshlrev_b32_e32 v112, 16, v20
	v_and_b32_e32 v113, 0xffff0000, v20
	v_lshlrev_b32_e32 v114, 16, v21
	v_and_b32_e32 v115, 0xffff0000, v21
	v_lshlrev_b32_e32 v116, 16, v22
	v_and_b32_e32 v117, 0xffff0000, v22
	v_lshlrev_b32_e32 v118, 16, v23
	v_and_b32_e32 v119, 0xffff0000, v23
	v_lshlrev_b32_e32 v120, 16, v24
	v_and_b32_e32 v121, 0xffff0000, v24
	v_lshlrev_b32_e32 v122, 16, v25
	v_and_b32_e32 v123, 0xffff0000, v25
	v_lshlrev_b32_e32 v124, 16, v26
	v_and_b32_e32 v125, 0xffff0000, v26
	v_lshlrev_b32_e32 v100, 16, v27
	v_and_b32_e32 v101, 0xffff0000, v27
	v_pk_mul_f32 v[102:103], v[112:113], v[112:113]
	v_pk_mul_f32 v[106:107], v[114:115], v[114:115]
	v_pk_fma_f32 v[102:103], v[116:117], v[116:117], v[102:103]
	v_pk_fma_f32 v[106:107], v[118:119], v[118:119], v[106:107]
	v_pk_fma_f32 v[102:103], v[120:121], v[120:121], v[102:103]
	v_pk_fma_f32 v[106:107], v[122:123], v[122:123], v[106:107]
	v_pk_fma_f32 v[102:103], v[124:125], v[124:125], v[102:103]
	v_pk_fma_f32 v[106:107], v[100:101], v[100:101], v[106:107]
	s_nop 0
	v_pk_add_f32 v[102:103], v[102:103], v[106:107]
	s_nop 0
	v_add_f32_e32 v102, v102, v103
	s_nop 1
	v_add_f32_dpp v102, v102, v102 quad_perm:[1,0,3,2] row_mask:0xf bank_mask:0xf
	s_nop 1
	v_add_f32_dpp v102, v102, v102 quad_perm:[2,3,0,1] row_mask:0xf bank_mask:0xf
	s_nop 1
	v_add_f32_dpp v102, v102, v102 row_half_mirror row_mask:0xf bank_mask:0xf
	s_nop 1
	v_add_f32_dpp v102, v102, v102 row_mirror row_mask:0xf bank_mask:0xf
	s_nop 1
	v_add_f32_dpp v102, v102, v102 row_bcast:15 row_mask:0xa bank_mask:0xf
	s_nop 1
	v_add_f32_dpp v102, v102, v102 row_bcast:31 row_mask:0xc bank_mask:0xf
	s_nop 1
	v_readlane_b32 s74, v102, 63
	s_nop 2
	v_mov_b32_e32 v102, s74
	v_fmamk_f32 v102, v102, 0x3a800000, v2
	v_mul_f32_e32 v103, 0x4f800000, v102
	v_cmp_gt_f32_e32 vcc, 0xf800000, v102
	s_nop 1
	v_cndmask_b32_e32 v102, v102, v103, vcc
	v_sqrt_f32_e32 v103, v102
	s_nop 0
	v_add_u32_e32 v104, -1, v103
	v_add_u32_e32 v106, 1, v103
	v_fma_f32 v107, -v104, v103, v102
	v_fma_f32 v108, -v106, v103, v102
	v_cmp_ge_f32_e64 s[76:77], 0, v107
	s_nop 1
	v_cndmask_b32_e64 v103, v103, v104, s[76:77]
	v_cmp_lt_f32_e64 s[76:77], 0, v108
	s_nop 1
	v_cndmask_b32_e64 v103, v103, v106, s[76:77]
	v_mul_f32_e32 v104, 0x37800000, v103
	v_cndmask_b32_e32 v103, v103, v104, vcc
	v_cmp_class_f32_e32 vcc, v102, v3
	s_nop 1
	v_cndmask_b32_e32 v102, v103, v102, vcc
	v_div_scale_f32 v103, s[76:77], v102, v102, 1.0
	v_rcp_f32_e32 v104, v103
	v_div_scale_f32 v106, vcc, 1.0, v102, 1.0
	v_fma_f32 v107, -v103, v104, 1.0
	v_fmac_f32_e32 v104, v107, v104
	v_mul_f32_e32 v107, v106, v104
	v_fma_f32 v108, -v103, v107, v106
	v_fmac_f32_e32 v107, v108, v104
	v_fma_f32 v103, -v103, v107, v106
	v_div_fmas_f32 v103, v103, v104, v107
	v_div_fixup_f32 v110, v103, v102, 1.0
	v_pk_mul_f32 v[112:113], v[112:113], v[110:111] op_sel_hi:[1,0]
	v_pk_mul_f32 v[114:115], v[114:115], v[110:111] op_sel_hi:[1,0]
	v_pk_mul_f32 v[116:117], v[116:117], v[110:111] op_sel_hi:[1,0]
	v_pk_mul_f32 v[118:119], v[118:119], v[110:111] op_sel_hi:[1,0]
	v_pk_mul_f32 v[120:121], v[120:121], v[110:111] op_sel_hi:[1,0]
	v_pk_mul_f32 v[122:123], v[122:123], v[110:111] op_sel_hi:[1,0]
	v_pk_mul_f32 v[124:125], v[124:125], v[110:111] op_sel_hi:[1,0]
	v_pk_mul_f32 v[100:101], v[100:101], v[110:111] op_sel_hi:[1,0]
	v_pk_mul_f32 v[112:113], v[176:177], v[112:113]
	v_pk_mul_f32 v[114:115], v[178:179], v[114:115]
	v_pk_mul_f32 v[116:117], v[180:181], v[116:117]
	v_pk_mul_f32 v[118:119], v[182:183], v[118:119]
	v_pk_mul_f32 v[120:121], v[184:185], v[120:121]
	v_pk_mul_f32 v[122:123], v[186:187], v[122:123]
	v_pk_mul_f32 v[124:125], v[188:189], v[124:125]
	v_pk_mul_f32 v[100:101], v[190:191], v[100:101]
	v_pk_fma_f32 v[4:5], v[160:161], v[112:113], v[4:5]
	v_pk_fma_f32 v[6:7], v[162:163], v[114:115], v[6:7]
	v_pk_fma_f32 v[8:9], v[164:165], v[116:117], v[8:9]
	v_pk_fma_f32 v[10:11], v[166:167], v[118:119], v[10:11]
	v_pk_fma_f32 v[12:13], v[168:169], v[120:121], v[12:13]
	v_pk_fma_f32 v[14:15], v[170:171], v[122:123], v[14:15]
	v_pk_fma_f32 v[16:17], v[172:173], v[124:125], v[16:17]
	v_pk_fma_f32 v[18:19], v[174:175], v[100:101], v[18:19]
	v_pk_mul_f32 v[102:103], v[4:5], v[4:5]
	v_pk_mul_f32 v[106:107], v[6:7], v[6:7]
	v_pk_fma_f32 v[102:103], v[8:9], v[8:9], v[102:103]
	v_pk_fma_f32 v[106:107], v[10:11], v[10:11], v[106:107]
	v_pk_fma_f32 v[102:103], v[12:13], v[12:13], v[102:103]
	v_pk_fma_f32 v[106:107], v[14:15], v[14:15], v[106:107]
	v_pk_fma_f32 v[102:103], v[16:17], v[16:17], v[102:103]
	v_pk_fma_f32 v[106:107], v[18:19], v[18:19], v[106:107]
	s_nop 0
	v_pk_add_f32 v[102:103], v[102:103], v[106:107]
	s_nop 0
	v_add_f32_e32 v102, v102, v103
	s_nop 1
	v_add_f32_dpp v102, v102, v102 quad_perm:[1,0,3,2] row_mask:0xf bank_mask:0xf
	s_nop 1
	v_add_f32_dpp v102, v102, v102 quad_perm:[2,3,0,1] row_mask:0xf bank_mask:0xf
	s_nop 1
	v_add_f32_dpp v102, v102, v102 row_half_mirror row_mask:0xf bank_mask:0xf
	s_nop 1
	v_add_f32_dpp v102, v102, v102 row_mirror row_mask:0xf bank_mask:0xf
	s_nop 1
	v_add_f32_dpp v102, v102, v102 row_bcast:15 row_mask:0xa bank_mask:0xf
	s_nop 1
	v_add_f32_dpp v102, v102, v102 row_bcast:31 row_mask:0xc bank_mask:0xf
	s_nop 1
	v_readlane_b32 s74, v102, 63
	s_nop 2
	v_mov_b32_e32 v102, s74
	v_fmamk_f32 v102, v102, 0x3a800000, v2
	v_mul_f32_e32 v103, 0x4f800000, v102
	v_cmp_gt_f32_e32 vcc, 0xf800000, v102
	s_nop 1
	v_cndmask_b32_e32 v102, v102, v103, vcc
	v_sqrt_f32_e32 v103, v102
	s_nop 0
	v_add_u32_e32 v104, -1, v103
	v_add_u32_e32 v106, 1, v103
	v_fma_f32 v107, -v104, v103, v102
	v_fma_f32 v108, -v106, v103, v102
	v_cmp_ge_f32_e64 s[76:77], 0, v107
	s_nop 1
; __device__ __forceinline__ unsigned pk_bf16(float lo, float hi) { const f32x2 v = {lo, hi}; const bf16x2_t b = __builtin_convertvector(v, bf16x2_t); return __builtin_bit_cast(unsigned, b); }
; template <bool HAS_F, bool HAS_H>
; __device__ __forceinline__ void phase_rows(const Params& p, int sp, int sn, float resw, bool from_input, bool write_x = true) {
;     ...
;     for (int row = gw; row < T; row += NGW) {
;         const int b = row_batch(row);
;         const float* xin = !from_input ? p.out + (size_t)row * D : (row < TP ? p.in[0] + (size_t)row * D : p.in[1] + (size_t)(row - TP) * D);
;         f32x4 v[4];
; #pragma unroll
;         for (int j = 0; j < 4; ++j) v[j] = *(const f32x4*)(xin + 4 * lane + 256 * j);
;     ...
;             const float rs = 1.0f / sqrtf(wave_sum(ss) * (1.0f / D) + EPS);
;             const float* sh = mod + b * 9216 + sn * 3072; const float* scl = sh + 1024; const float* gq = p.in[6] + sn * D;
; #pragma unroll
;             for (int j = 0; j < 4; ++j) { const f32x4 a = *(const f32x4*)(sh + 4 * lane + 256 * j), s = *(const f32x4*)(scl + 4 * lane + 256 * j), q = *(const f32x4*)(gq + 4 * lane + 256 * j);
;                 const f32x4 h = (v[j] * rs * q) * (s + 1.0f) + a;
;                 u32x2 w; w.x = pk_bf16(h.x, h.y); w.y = pk_bf16(h.z, h.w);
;                 *(u32x2*)(H + (size_t)row * D + 4 * lane + 256 * j) = w; }
	v_cndmask_b32_e64 v103, v103, v104, s[76:77]
	v_cmp_lt_f32_e64 s[76:77], 0, v108
	s_nop 1
	v_cndmask_b32_e64 v103, v103, v106, s[76:77]
	v_mul_f32_e32 v104, 0x37800000, v103
	v_cndmask_b32_e32 v103, v103, v104, vcc
	v_cmp_class_f32_e32 vcc, v102, v3
	s_nop 1
	v_cndmask_b32_e32 v102, v103, v102, vcc
	v_div_scale_f32 v103, s[76:77], v102, v102, 1.0
	v_rcp_f32_e32 v104, v103
	v_div_scale_f32 v106, vcc, 1.0, v102, 1.0
	v_fma_f32 v107, -v103, v104, 1.0
	v_fmac_f32_e32 v104, v107, v104
	v_mul_f32_e32 v107, v106, v104
	v_fma_f32 v108, -v103, v107, v106
	v_fmac_f32_e32 v107, v108, v104
	v_fma_f32 v103, -v103, v107, v106
	v_div_fmas_f32 v103, v103, v104, v107
	v_div_fixup_f32 v110, v103, v102, 1.0
	s_lshl_b32 s60, s55, 11
	s_add_u32 s70, s78, s60
	s_addc_u32 s71, s79, 0
	v_pk_mul_f32 v[112:113], v[4:5], v[110:111] op_sel_hi:[1,0]
	v_pk_mul_f32 v[114:115], v[6:7], v[110:111] op_sel_hi:[1,0]
	v_pk_mul_f32 v[116:117], v[8:9], v[110:111] op_sel_hi:[1,0]
	v_pk_mul_f32 v[118:119], v[10:11], v[110:111] op_sel_hi:[1,0]
	v_pk_mul_f32 v[120:121], v[12:13], v[110:111] op_sel_hi:[1,0]
	v_pk_mul_f32 v[122:123], v[14:15], v[110:111] op_sel_hi:[1,0]
	v_pk_mul_f32 v[124:125], v[16:17], v[110:111] op_sel_hi:[1,0]
	v_pk_mul_f32 v[100:101], v[18:19], v[110:111] op_sel_hi:[1,0]
	v_pk_mul_f32 v[112:113], v[192:193], v[112:113]
	v_pk_mul_f32 v[114:115], v[194:195], v[114:115]
	v_pk_mul_f32 v[116:117], v[196:197], v[116:117]
	v_pk_mul_f32 v[118:119], v[198:199], v[118:119]
	v_pk_mul_f32 v[120:121], v[200:201], v[120:121]
	v_pk_mul_f32 v[122:123], v[202:203], v[122:123]
	v_pk_mul_f32 v[124:125], v[204:205], v[124:125]
	v_pk_mul_f32 v[100:101], v[206:207], v[100:101]
	v_pk_fma_f32 v[112:113], v[208:209], v[112:113], v[224:225]
	v_pk_fma_f32 v[114:115], v[210:211], v[114:115], v[226:227]
	v_pk_fma_f32 v[116:117], v[212:213], v[116:117], v[228:229]
	v_pk_fma_f32 v[118:119], v[214:215], v[118:119], v[230:231]
	v_pk_fma_f32 v[120:121], v[216:217], v[120:121], v[232:233]
	v_pk_fma_f32 v[122:123], v[218:219], v[122:123], v[234:235]
	v_pk_fma_f32 v[124:125], v[220:221], v[124:125], v[236:237]
	v_pk_fma_f32 v[100:101], v[222:223], v[100:101], v[238:239]
	v_cvt_pk_bf16_f32 v240, v112, v113
	v_cvt_pk_bf16_f32 v241, v114, v115
	v_cvt_pk_bf16_f32 v242, v116, v117
	v_cvt_pk_bf16_f32 v243, v118, v119
	v_cvt_pk_bf16_f32 v244, v120, v121
	v_cvt_pk_bf16_f32 v245, v122, v123
	v_cvt_pk_bf16_f32 v246, v124, v125
	v_cvt_pk_bf16_f32 v247, v100, v101
	global_store_dwordx2 v1, v[240:241], s[70:71]
	global_store_dwordx2 v1, v[242:243], s[70:71] offset:512
	global_store_dwordx2 v1, v[244:245], s[70:71] offset:1024
	global_store_dwordx2 v1, v[246:247], s[70:71] offset:1536
	s_add_u32 s55, s55, 8
	s_add_u32 s57, s55, 16
	s_min_u32 s57, s57, s54
	s_lshl_b32 s60, s57, 12
	s_add_u32 s64, s84, s60
	s_addc_u32 s65, s85, 0
	s_lshl_b32 s60, s57, 11
	s_add_u32 s66, s82, s60
	s_addc_u32 s67, s83, 0
	global_load_dwordx4 v[4:7], v0, s[64:65] nt
	global_load_dwordx4 v[8:11], v0, s[64:65] offset:1024 nt
	global_load_dwordx4 v[12:15], v0, s[64:65] offset:2048 nt
	global_load_dwordx4 v[16:19], v0, s[64:65] offset:3072 nt
	global_load_dwordx2 v[20:21], v1, s[66:67] nt
	global_load_dwordx2 v[22:23], v1, s[66:67] offset:512 nt
	global_load_dwordx2 v[24:25], v1, s[66:67] offset:1024 nt
	global_load_dwordx2 v[26:27], v1, s[66:67] offset:1536 nt
	s_lshr_b32 s60, s55, 11
	s_sub_u32 s61, s55, 0x8000
	s_lshr_b32 s61, s61, 12
	s_add_u32 s61, s61, 16
	s_cmp_lt_u32 s55, 0x8000
	s_cselect_b32 s63, s60, s61
	s_cmp_eq_u32 s63, s56
	s_cbranch_scc1 .Lrp12_pk8
	s_mov_b32 s56, s63
	s_mul_i32 s60, s56, 0x9000
	s_add_u32 s60, s60, 0x3185000
	s_add_u32 s0, s92, s60
	s_addc_u32 s1, s93, 0
	global_load_dwordx4 v[160:163], v0, s[0:1]
	global_load_dwordx4 v[164:167], v0, s[0:1] offset:1024
	global_load_dwordx4 v[168:171], v0, s[0:1] offset:2048
	global_load_dwordx4 v[172:175], v0, s[0:1] offset:3072
	s_add_u32 s0, s22, 0x1000
	s_addc_u32 s1, s23, 0
	global_load_dwordx4 v[176:179], v0, s[0:1]
	global_load_dwordx4 v[180:183], v0, s[0:1] offset:1024
	global_load_dwordx4 v[184:187], v0, s[0:1] offset:2048
	global_load_dwordx4 v[188:191], v0, s[0:1] offset:3072
	s_add_u32 s0, s20, 0x2000
	s_addc_u32 s1, s21, 0
	global_load_dwordx4 v[192:195], v0, s[0:1]
	global_load_dwordx4 v[196:199], v0, s[0:1] offset:1024
	global_load_dwordx4 v[200:203], v0, s[0:1] offset:2048
	global_load_dwordx4 v[204:207], v0, s[0:1] offset:3072
	s_mul_i32 s60, s56, 0x9000
	s_add_u32 s60, s60, 0x3187000
	s_add_u32 s0, s92, s60
	s_addc_u32 s1, s93, 0
	global_load_dwordx4 v[208:211], v0, s[0:1]
	global_load_dwordx4 v[212:215], v0, s[0:1] offset:1024
	global_load_dwordx4 v[216:219], v0, s[0:1] offset:2048
	global_load_dwordx4 v[220:223], v0, s[0:1] offset:3072
	s_mul_i32 s60, s56, 0x9000
	s_add_u32 s60, s60, 0x3186000
	s_add_u32 s0, s92, s60
	s_addc_u32 s1, s93, 0
	global_load_dwordx4 v[224:227], v0, s[0:1]
	global_load_dwordx4 v[228:231], v0, s[0:1] offset:1024
	global_load_dwordx4 v[232:235], v0, s[0:1] offset:2048
	global_load_dwordx4 v[236:239], v0, s[0:1] offset:3072
	s_waitcnt vmcnt(0)
	v_pk_add_f32 v[208:209], v[208:209], 1.0 op_sel_hi:[1,0]
	v_pk_add_f32 v[210:211], v[210:211], 1.0 op_sel_hi:[1,0]
	v_pk_add_f32 v[212:213], v[212:213], 1.0 op_sel_hi:[1,0]
	v_pk_add_f32 v[214:215], v[214:215], 1.0 op_sel_hi:[1,0]
	v_pk_add_f32 v[216:217], v[216:217], 1.0 op_sel_hi:[1,0]
	v_pk_add_f32 v[218:219], v[218:219], 1.0 op_sel_hi:[1,0]
	v_pk_add_f32 v[220:221], v[220:221], 1.0 op_sel_hi:[1,0]
	v_pk_add_f32 v[222:223], v[222:223], 1.0 op_sel_hi:[1,0]
; __device__ __forceinline__ float lo_bf(unsigned w) { return __uint_as_float(w << 16); }
; __device__ __forceinline__ float hi_bf(unsigned w) { return __uint_as_float(w & 0xffff0000u); }
; template <bool HAS_F, bool HAS_H>
; __device__ __forceinline__ void phase_rows(const Params& p, int sp, int sn, float resw, bool from_input, bool write_x = true) {
;     ...
;         if (HAS_F) {
;             f32x4 f[4]; float ss = 0.f;
; #pragma unroll
;             for (int j = 0; j < 4; ++j) { const u32x2 w = *(const u32x2*)(F + (size_t)row * D + 4 * lane + 256 * j);
;                 f[j] = (f32x4){lo_bf(w.x), hi_bf(w.x), lo_bf(w.y), hi_bf(w.y)}; ss += (f[j].x * f[j].x + f[j].y * f[j].y) + (f[j].z * f[j].z + f[j].w * f[j].w); }
;             const float rs = 1.0f / sqrtf(wave_sum(ss) * (1.0f / D) + EPS) * resw;
;             const float* gate = mod + b * 9216 + sp * 3072 + 2048; const float* gp = p.in[7] + sp * D;
; #pragma unroll
;             for (int j = 0; j < 4; ++j) { const f32x4 g = *(const f32x4*)(gate + 4 * lane + 256 * j), q = *(const f32x4*)(gp + 4 * lane + 256 * j);
;                 v[j] = v[j] + g * (f[j] * rs * q);
;                 if (write_x) *(f32x4*)(p.out + (size_t)row * D + 4 * lane + 256 * j) = v[j]; }
;         }
;         if (HAS_H) {
;             float ss = 0.f;
; #pragma unroll
;             for (int j = 0; j < 4; ++j) ss += (v[j].x * v[j].x + v[j].y * v[j].y) + (v[j].z * v[j].z + v[j].w * v[j].w);
;             const float rs = 1.0f / sqrtf(wave_sum(ss) * (1.0f / D) + EPS);
.Lrp12_pk8:
	s_waitcnt vmcnt(24)
	v_lshlrev_b32_e32 v112, 16, v52
	v_and_b32_e32 v113, 0xffff0000, v52
	v_lshlrev_b32_e32 v114, 16, v53
	v_and_b32_e32 v115, 0xffff0000, v53
	v_lshlrev_b32_e32 v116, 16, v54
	v_and_b32_e32 v117, 0xffff0000, v54
	v_lshlrev_b32_e32 v118, 16, v55
	v_and_b32_e32 v119, 0xffff0000, v55
	v_lshlrev_b32_e32 v120, 16, v56
	v_and_b32_e32 v121, 0xffff0000, v56
	v_lshlrev_b32_e32 v122, 16, v57
	v_and_b32_e32 v123, 0xffff0000, v57
	v_lshlrev_b32_e32 v124, 16, v58
	v_and_b32_e32 v125, 0xffff0000, v58
	v_lshlrev_b32_e32 v100, 16, v59
	v_and_b32_e32 v101, 0xffff0000, v59
	v_pk_mul_f32 v[102:103], v[112:113], v[112:113]
	v_pk_mul_f32 v[106:107], v[114:115], v[114:115]
	v_pk_fma_f32 v[102:103], v[116:117], v[116:117], v[102:103]
	v_pk_fma_f32 v[106:107], v[118:119], v[118:119], v[106:107]
	v_pk_fma_f32 v[102:103], v[120:121], v[120:121], v[102:103]
	v_pk_fma_f32 v[106:107], v[122:123], v[122:123], v[106:107]
	v_pk_fma_f32 v[102:103], v[124:125], v[124:125], v[102:103]
	v_pk_fma_f32 v[106:107], v[100:101], v[100:101], v[106:107]
	s_nop 0
	v_pk_add_f32 v[102:103], v[102:103], v[106:107]
	s_nop 0
	v_add_f32_e32 v102, v102, v103
	s_nop 1
	v_add_f32_dpp v102, v102, v102 quad_perm:[1,0,3,2] row_mask:0xf bank_mask:0xf
	s_nop 1
	v_add_f32_dpp v102, v102, v102 quad_perm:[2,3,0,1] row_mask:0xf bank_mask:0xf
	s_nop 1
	v_add_f32_dpp v102, v102, v102 row_half_mirror row_mask:0xf bank_mask:0xf
	s_nop 1
	v_add_f32_dpp v102, v102, v102 row_mirror row_mask:0xf bank_mask:0xf
	s_nop 1
	v_add_f32_dpp v102, v102, v102 row_bcast:15 row_mask:0xa bank_mask:0xf
	s_nop 1
	v_add_f32_dpp v102, v102, v102 row_bcast:31 row_mask:0xc bank_mask:0xf
	s_nop 1
	v_readlane_b32 s74, v102, 63
	s_nop 2
	v_mov_b32_e32 v102, s74
	v_fmamk_f32 v102, v102, 0x3a800000, v2
	v_mul_f32_e32 v103, 0x4f800000, v102
	v_cmp_gt_f32_e32 vcc, 0xf800000, v102
	s_nop 1
	v_cndmask_b32_e32 v102, v102, v103, vcc
	v_sqrt_f32_e32 v103, v102
	s_nop 0
	v_add_u32_e32 v104, -1, v103
	v_add_u32_e32 v106, 1, v103
	v_fma_f32 v107, -v104, v103, v102
	v_fma_f32 v108, -v106, v103, v102
	v_cmp_ge_f32_e64 s[76:77], 0, v107
	s_nop 1
	v_cndmask_b32_e64 v103, v103, v104, s[76:77]
	v_cmp_lt_f32_e64 s[76:77], 0, v108
	s_nop 1
	v_cndmask_b32_e64 v103, v103, v106, s[76:77]
	v_mul_f32_e32 v104, 0x37800000, v103
	v_cndmask_b32_e32 v103, v103, v104, vcc
	v_cmp_class_f32_e32 vcc, v102, v3
	s_nop 1
	v_cndmask_b32_e32 v102, v103, v102, vcc
	v_div_scale_f32 v103, s[76:77], v102, v102, 1.0
	v_rcp_f32_e32 v104, v103
	v_div_scale_f32 v106, vcc, 1.0, v102, 1.0
	v_fma_f32 v107, -v103, v104, 1.0
	v_fmac_f32_e32 v104, v107, v104
	v_mul_f32_e32 v107, v106, v104
	v_fma_f32 v108, -v103, v107, v106
	v_fmac_f32_e32 v107, v108, v104
	v_fma_f32 v103, -v103, v107, v106
	v_div_fmas_f32 v103, v103, v104, v107
	v_div_fixup_f32 v110, v103, v102, 1.0
	v_pk_mul_f32 v[112:113], v[112:113], v[110:111] op_sel_hi:[1,0]
	v_pk_mul_f32 v[114:115], v[114:115], v[110:111] op_sel_hi:[1,0]
	v_pk_mul_f32 v[116:117], v[116:117], v[110:111] op_sel_hi:[1,0]
	v_pk_mul_f32 v[118:119], v[118:119], v[110:111] op_sel_hi:[1,0]
	v_pk_mul_f32 v[120:121], v[120:121], v[110:111] op_sel_hi:[1,0]
	v_pk_mul_f32 v[122:123], v[122:123], v[110:111] op_sel_hi:[1,0]
	v_pk_mul_f32 v[124:125], v[124:125], v[110:111] op_sel_hi:[1,0]
	v_pk_mul_f32 v[100:101], v[100:101], v[110:111] op_sel_hi:[1,0]
	v_pk_mul_f32 v[112:113], v[176:177], v[112:113]
	v_pk_mul_f32 v[114:115], v[178:179], v[114:115]
	v_pk_mul_f32 v[116:117], v[180:181], v[116:117]
	v_pk_mul_f32 v[118:119], v[182:183], v[118:119]
	v_pk_mul_f32 v[120:121], v[184:185], v[120:121]
	v_pk_mul_f32 v[122:123], v[186:187], v[122:123]
	v_pk_mul_f32 v[124:125], v[188:189], v[124:125]
	v_pk_mul_f32 v[100:101], v[190:191], v[100:101]
	v_pk_fma_f32 v[36:37], v[160:161], v[112:113], v[36:37]
	v_pk_fma_f32 v[38:39], v[162:163], v[114:115], v[38:39]
	v_pk_fma_f32 v[40:41], v[164:165], v[116:117], v[40:41]
	v_pk_fma_f32 v[42:43], v[166:167], v[118:119], v[42:43]
	v_pk_fma_f32 v[44:45], v[168:169], v[120:121], v[44:45]
	v_pk_fma_f32 v[46:47], v[170:171], v[122:123], v[46:47]
	v_pk_fma_f32 v[48:49], v[172:173], v[124:125], v[48:49]
	v_pk_fma_f32 v[50:51], v[174:175], v[100:101], v[50:51]
	v_pk_mul_f32 v[102:103], v[36:37], v[36:37]
	v_pk_mul_f32 v[106:107], v[38:39], v[38:39]
	v_pk_fma_f32 v[102:103], v[40:41], v[40:41], v[102:103]
	v_pk_fma_f32 v[106:107], v[42:43], v[42:43], v[106:107]
	v_pk_fma_f32 v[102:103], v[44:45], v[44:45], v[102:103]
	v_pk_fma_f32 v[106:107], v[46:47], v[46:47], v[106:107]
	v_pk_fma_f32 v[102:103], v[48:49], v[48:49], v[102:103]
	v_pk_fma_f32 v[106:107], v[50:51], v[50:51], v[106:107]
	s_nop 0
	v_pk_add_f32 v[102:103], v[102:103], v[106:107]
	s_nop 0
	v_add_f32_e32 v102, v102, v103
	s_nop 1
	v_add_f32_dpp v102, v102, v102 quad_perm:[1,0,3,2] row_mask:0xf bank_mask:0xf
	s_nop 1
	v_add_f32_dpp v102, v102, v102 quad_perm:[2,3,0,1] row_mask:0xf bank_mask:0xf
	s_nop 1
	v_add_f32_dpp v102, v102, v102 row_half_mirror row_mask:0xf bank_mask:0xf
	s_nop 1
	v_add_f32_dpp v102, v102, v102 row_mirror row_mask:0xf bank_mask:0xf
	s_nop 1
	v_add_f32_dpp v102, v102, v102 row_bcast:15 row_mask:0xa bank_mask:0xf
	s_nop 1
	v_add_f32_dpp v102, v102, v102 row_bcast:31 row_mask:0xc bank_mask:0xf
	s_nop 1
	v_readlane_b32 s74, v102, 63
	s_nop 2
	v_mov_b32_e32 v102, s74
	v_fmamk_f32 v102, v102, 0x3a800000, v2
	v_mul_f32_e32 v103, 0x4f800000, v102
	v_cmp_gt_f32_e32 vcc, 0xf800000, v102
	s_nop 1
	v_cndmask_b32_e32 v102, v102, v103, vcc
	v_sqrt_f32_e32 v103, v102
	s_nop 0
	v_add_u32_e32 v104, -1, v103
	v_add_u32_e32 v106, 1, v103
	v_fma_f32 v107, -v104, v103, v102
	v_fma_f32 v108, -v106, v103, v102
	v_cmp_ge_f32_e64 s[76:77], 0, v107
; __device__ __forceinline__ unsigned pk_bf16(float lo, float hi) { const f32x2 v = {lo, hi}; const bf16x2_t b = __builtin_convertvector(v, bf16x2_t); return __builtin_bit_cast(unsigned, b); }
; template <bool HAS_F, bool HAS_H>
; __device__ __forceinline__ void phase_rows(const Params& p, int sp, int sn, float resw, bool from_input, bool write_x = true) {
;     ...
;     for (int row = gw; row < T; row += NGW) {
;         const int b = row_batch(row);
;         const float* xin = !from_input ? p.out + (size_t)row * D : (row < TP ? p.in[0] + (size_t)row * D : p.in[1] + (size_t)(row - TP) * D);
;         f32x4 v[4];
; #pragma unroll
;         for (int j = 0; j < 4; ++j) v[j] = *(const f32x4*)(xin + 4 * lane + 256 * j);
;     ...
;             const float rs = 1.0f / sqrtf(wave_sum(ss) * (1.0f / D) + EPS);
;             const float* sh = mod + b * 9216 + sn * 3072; const float* scl = sh + 1024; const float* gq = p.in[6] + sn * D;
; #pragma unroll
;             for (int j = 0; j < 4; ++j) { const f32x4 a = *(const f32x4*)(sh + 4 * lane + 256 * j), s = *(const f32x4*)(scl + 4 * lane + 256 * j), q = *(const f32x4*)(gq + 4 * lane + 256 * j);
;                 const f32x4 h = (v[j] * rs * q) * (s + 1.0f) + a;
;                 u32x2 w; w.x = pk_bf16(h.x, h.y); w.y = pk_bf16(h.z, h.w);
;                 *(u32x2*)(H + (size_t)row * D + 4 * lane + 256 * j) = w; }
	s_nop 1
	v_cndmask_b32_e64 v103, v103, v104, s[76:77]
	v_cmp_lt_f32_e64 s[76:77], 0, v108
	s_nop 1
	v_cndmask_b32_e64 v103, v103, v106, s[76:77]
	v_mul_f32_e32 v104, 0x37800000, v103
	v_cndmask_b32_e32 v103, v103, v104, vcc
	v_cmp_class_f32_e32 vcc, v102, v3
	s_nop 1
	v_cndmask_b32_e32 v102, v103, v102, vcc
	v_div_scale_f32 v103, s[76:77], v102, v102, 1.0
	v_rcp_f32_e32 v104, v103
	v_div_scale_f32 v106, vcc, 1.0, v102, 1.0
	v_fma_f32 v107, -v103, v104, 1.0
	v_fmac_f32_e32 v104, v107, v104
	v_mul_f32_e32 v107, v106, v104
	v_fma_f32 v108, -v103, v107, v106
	v_fmac_f32_e32 v107, v108, v104
	v_fma_f32 v103, -v103, v107, v106
	v_div_fmas_f32 v103, v103, v104, v107
	v_div_fixup_f32 v110, v103, v102, 1.0
	s_lshl_b32 s60, s55, 11
	s_add_u32 s70, s78, s60
	s_addc_u32 s71, s79, 0
	v_pk_mul_f32 v[112:113], v[36:37], v[110:111] op_sel_hi:[1,0]
	v_pk_mul_f32 v[114:115], v[38:39], v[110:111] op_sel_hi:[1,0]
	v_pk_mul_f32 v[116:117], v[40:41], v[110:111] op_sel_hi:[1,0]
	v_pk_mul_f32 v[118:119], v[42:43], v[110:111] op_sel_hi:[1,0]
	v_pk_mul_f32 v[120:121], v[44:45], v[110:111] op_sel_hi:[1,0]
	v_pk_mul_f32 v[122:123], v[46:47], v[110:111] op_sel_hi:[1,0]
	v_pk_mul_f32 v[124:125], v[48:49], v[110:111] op_sel_hi:[1,0]
	v_pk_mul_f32 v[100:101], v[50:51], v[110:111] op_sel_hi:[1,0]
	v_pk_mul_f32 v[112:113], v[192:193], v[112:113]
	v_pk_mul_f32 v[114:115], v[194:195], v[114:115]
	v_pk_mul_f32 v[116:117], v[196:197], v[116:117]
	v_pk_mul_f32 v[118:119], v[198:199], v[118:119]
	v_pk_mul_f32 v[120:121], v[200:201], v[120:121]
	v_pk_mul_f32 v[122:123], v[202:203], v[122:123]
	v_pk_mul_f32 v[124:125], v[204:205], v[124:125]
	v_pk_mul_f32 v[100:101], v[206:207], v[100:101]
	v_pk_fma_f32 v[112:113], v[208:209], v[112:113], v[224:225]
	v_pk_fma_f32 v[114:115], v[210:211], v[114:115], v[226:227]
	v_pk_fma_f32 v[116:117], v[212:213], v[116:117], v[228:229]
	v_pk_fma_f32 v[118:119], v[214:215], v[118:119], v[230:231]
	v_pk_fma_f32 v[120:121], v[216:217], v[120:121], v[232:233]
	v_pk_fma_f32 v[122:123], v[218:219], v[122:123], v[234:235]
	v_pk_fma_f32 v[124:125], v[220:221], v[124:125], v[236:237]
	v_pk_fma_f32 v[100:101], v[222:223], v[100:101], v[238:239]
	v_cvt_pk_bf16_f32 v240, v112, v113
	v_cvt_pk_bf16_f32 v241, v114, v115
	v_cvt_pk_bf16_f32 v242, v116, v117
	v_cvt_pk_bf16_f32 v243, v118, v119
	v_cvt_pk_bf16_f32 v244, v120, v121
	v_cvt_pk_bf16_f32 v245, v122, v123
	v_cvt_pk_bf16_f32 v246, v124, v125
	v_cvt_pk_bf16_f32 v247, v100, v101
	global_store_dwordx2 v1, v[240:241], s[70:71]
	global_store_dwordx2 v1, v[242:243], s[70:71] offset:512
	global_store_dwordx2 v1, v[244:245], s[70:71] offset:1024
	global_store_dwordx2 v1, v[246:247], s[70:71] offset:1536
	s_add_u32 s55, s55, 8
	s_add_u32 s57, s55, 16
	s_min_u32 s57, s57, s54
	s_lshl_b32 s60, s57, 12
	s_add_u32 s64, s84, s60
	s_addc_u32 s65, s85, 0
	s_lshl_b32 s60, s57, 11
	s_add_u32 s66, s82, s60
	s_addc_u32 s67, s83, 0
	global_load_dwordx4 v[36:39], v0, s[64:65] nt
	global_load_dwordx4 v[40:43], v0, s[64:65] offset:1024 nt
	global_load_dwordx4 v[44:47], v0, s[64:65] offset:2048 nt
	global_load_dwordx4 v[48:51], v0, s[64:65] offset:3072 nt
	global_load_dwordx2 v[52:53], v1, s[66:67] nt
	global_load_dwordx2 v[54:55], v1, s[66:67] offset:512 nt
	global_load_dwordx2 v[56:57], v1, s[66:67] offset:1024 nt
	global_load_dwordx2 v[58:59], v1, s[66:67] offset:1536 nt
	s_lshr_b32 s60, s55, 11
	s_sub_u32 s61, s55, 0x8000
	s_lshr_b32 s61, s61, 12
	s_add_u32 s61, s61, 16
	s_cmp_lt_u32 s55, 0x8000
	s_cselect_b32 s63, s60, s61
	s_cmp_eq_u32 s63, s56
	s_cbranch_scc1 .Lrp12_pk9
	s_mov_b32 s56, s63
	s_mul_i32 s60, s56, 0x9000
	s_add_u32 s60, s60, 0x3185000
	s_add_u32 s0, s92, s60
	s_addc_u32 s1, s93, 0
	global_load_dwordx4 v[160:163], v0, s[0:1]
	global_load_dwordx4 v[164:167], v0, s[0:1] offset:1024
	global_load_dwordx4 v[168:171], v0, s[0:1] offset:2048
	global_load_dwordx4 v[172:175], v0, s[0:1] offset:3072
	s_add_u32 s0, s22, 0x1000
	s_addc_u32 s1, s23, 0
	global_load_dwordx4 v[176:179], v0, s[0:1]
	global_load_dwordx4 v[180:183], v0, s[0:1] offset:1024
	global_load_dwordx4 v[184:187], v0, s[0:1] offset:2048
	global_load_dwordx4 v[188:191], v0, s[0:1] offset:3072
	s_add_u32 s0, s20, 0x2000
	s_addc_u32 s1, s21, 0
	global_load_dwordx4 v[192:195], v0, s[0:1]
	global_load_dwordx4 v[196:199], v0, s[0:1] offset:1024
	global_load_dwordx4 v[200:203], v0, s[0:1] offset:2048
	global_load_dwordx4 v[204:207], v0, s[0:1] offset:3072
	s_mul_i32 s60, s56, 0x9000
	s_add_u32 s60, s60, 0x3187000
	s_add_u32 s0, s92, s60
	s_addc_u32 s1, s93, 0
	global_load_dwordx4 v[208:211], v0, s[0:1]
	global_load_dwordx4 v[212:215], v0, s[0:1] offset:1024
	global_load_dwordx4 v[216:219], v0, s[0:1] offset:2048
	global_load_dwordx4 v[220:223], v0, s[0:1] offset:3072
	s_mul_i32 s60, s56, 0x9000
	s_add_u32 s60, s60, 0x3186000
	s_add_u32 s0, s92, s60
	s_addc_u32 s1, s93, 0
	global_load_dwordx4 v[224:227], v0, s[0:1]
	global_load_dwordx4 v[228:231], v0, s[0:1] offset:1024
	global_load_dwordx4 v[232:235], v0, s[0:1] offset:2048
	global_load_dwordx4 v[236:239], v0, s[0:1] offset:3072
	s_waitcnt vmcnt(0)
	v_pk_add_f32 v[208:209], v[208:209], 1.0 op_sel_hi:[1,0]
	v_pk_add_f32 v[210:211], v[210:211], 1.0 op_sel_hi:[1,0]
	v_pk_add_f32 v[212:213], v[212:213], 1.0 op_sel_hi:[1,0]
	v_pk_add_f32 v[214:215], v[214:215], 1.0 op_sel_hi:[1,0]
	v_pk_add_f32 v[216:217], v[216:217], 1.0 op_sel_hi:[1,0]
	v_pk_add_f32 v[218:219], v[218:219], 1.0 op_sel_hi:[1,0]
	v_pk_add_f32 v[220:221], v[220:221], 1.0 op_sel_hi:[1,0]
	v_pk_add_f32 v[222:223], v[222:223], 1.0 op_sel_hi:[1,0]
; __device__ __forceinline__ float lo_bf(unsigned w) { return __uint_as_float(w << 16); }
; __device__ __forceinline__ float hi_bf(unsigned w) { return __uint_as_float(w & 0xffff0000u); }
; template <bool HAS_F, bool HAS_H>
; __device__ __forceinline__ void phase_rows(const Params& p, int sp, int sn, float resw, bool from_input, bool write_x = true) {
;     ...
;         if (HAS_F) {
;             f32x4 f[4]; float ss = 0.f;
; #pragma unroll
;             for (int j = 0; j < 4; ++j) { const u32x2 w = *(const u32x2*)(F + (size_t)row * D + 4 * lane + 256 * j);
;                 f[j] = (f32x4){lo_bf(w.x), hi_bf(w.x), lo_bf(w.y), hi_bf(w.y)}; ss += (f[j].x * f[j].x + f[j].y * f[j].y) + (f[j].z * f[j].z + f[j].w * f[j].w); }
;             const float rs = 1.0f / sqrtf(wave_sum(ss) * (1.0f / D) + EPS) * resw;
;             const float* gate = mod + b * 9216 + sp * 3072 + 2048; const float* gp = p.in[7] + sp * D;
; #pragma unroll
;             for (int j = 0; j < 4; ++j) { const f32x4 g = *(const f32x4*)(gate + 4 * lane + 256 * j), q = *(const f32x4*)(gp + 4 * lane + 256 * j);
;                 v[j] = v[j] + g * (f[j] * rs * q);
;                 if (write_x) *(f32x4*)(p.out + (size_t)row * D + 4 * lane + 256 * j) = v[j]; }
.Lrp12_pk9:
	s_waitcnt vmcnt(24)
	v_lshlrev_b32_e32 v112, 16, v84
	v_and_b32_e32 v113, 0xffff0000, v84
	v_lshlrev_b32_e32 v114, 16, v85
	v_and_b32_e32 v115, 0xffff0000, v85
	v_lshlrev_b32_e32 v116, 16, v86
	v_and_b32_e32 v117, 0xffff0000, v86
	v_lshlrev_b32_e32 v118, 16, v87
	v_and_b32_e32 v119, 0xffff0000, v87
	v_lshlrev_b32_e32 v120, 16, v88
	v_and_b32_e32 v121, 0xffff0000, v88
	v_lshlrev_b32_e32 v122, 16, v89
	v_and_b32_e32 v123, 0xffff0000, v89
	v_lshlrev_b32_e32 v124, 16, v90
	v_and_b32_e32 v125, 0xffff0000, v90
	v_lshlrev_b32_e32 v100, 16, v91
	v_and_b32_e32 v101, 0xffff0000, v91
	v_pk_mul_f32 v[102:103], v[112:113], v[112:113]
	v_pk_mul_f32 v[106:107], v[114:115], v[114:115]
	v_pk_fma_f32 v[102:103], v[116:117], v[116:117], v[102:103]
	v_pk_fma_f32 v[106:107], v[118:119], v[118:119], v[106:107]
	v_pk_fma_f32 v[102:103], v[120:121], v[120:121], v[102:103]
	v_pk_fma_f32 v[106:107], v[122:123], v[122:123], v[106:107]
	v_pk_fma_f32 v[102:103], v[124:125], v[124:125], v[102:103]
	v_pk_fma_f32 v[106:107], v[100:101], v[100:101], v[106:107]
	s_nop 0
	v_pk_add_f32 v[102:103], v[102:103], v[106:107]
	s_nop 0
	v_add_f32_e32 v102, v102, v103
	s_nop 1
	v_add_f32_dpp v102, v102, v102 quad_perm:[1,0,3,2] row_mask:0xf bank_mask:0xf
	s_nop 1
	v_add_f32_dpp v102, v102, v102 quad_perm:[2,3,0,1] row_mask:0xf bank_mask:0xf
	s_nop 1
	v_add_f32_dpp v102, v102, v102 row_half_mirror row_mask:0xf bank_mask:0xf
	s_nop 1
	v_add_f32_dpp v102, v102, v102 row_mirror row_mask:0xf bank_mask:0xf
	s_nop 1
	v_add_f32_dpp v102, v102, v102 row_bcast:15 row_mask:0xa bank_mask:0xf
	s_nop 1
	v_add_f32_dpp v102, v102, v102 row_bcast:31 row_mask:0xc bank_mask:0xf
	s_nop 1
	v_readlane_b32 s74, v102, 63
	s_nop 2
	v_mov_b32_e32 v102, s74
	v_fmamk_f32 v102, v102, 0x3a800000, v2
	v_mul_f32_e32 v103, 0x4f800000, v102
	v_cmp_gt_f32_e32 vcc, 0xf800000, v102
	s_nop 1
	v_cndmask_b32_e32 v102, v102, v103, vcc
	v_sqrt_f32_e32 v103, v102
	s_nop 0
	v_add_u32_e32 v104, -1, v103
	v_add_u32_e32 v106, 1, v103
	v_fma_f32 v107, -v104, v103, v102
	v_fma_f32 v108, -v106, v103, v102
	v_cmp_ge_f32_e64 s[76:77], 0, v107
	s_nop 1
	v_cndmask_b32_e64 v103, v103, v104, s[76:77]
	v_cmp_lt_f32_e64 s[76:77], 0, v108
	s_nop 1
	v_cndmask_b32_e64 v103, v103, v106, s[76:77]
	v_mul_f32_e32 v104, 0x37800000, v103
	v_cndmask_b32_e32 v103, v103, v104, vcc
	v_cmp_class_f32_e32 vcc, v102, v3
	s_nop 1
	v_cndmask_b32_e32 v102, v103, v102, vcc
	v_div_scale_f32 v103, s[76:77], v102, v102, 1.0
	v_rcp_f32_e32 v104, v103
	v_div_scale_f32 v106, vcc, 1.0, v102, 1.0
	v_fma_f32 v107, -v103, v104, 1.0
	v_fmac_f32_e32 v104, v107, v104
	v_mul_f32_e32 v107, v106, v104
	v_fma_f32 v108, -v103, v107, v106
	v_fmac_f32_e32 v107, v108, v104
	v_fma_f32 v103, -v103, v107, v106
	v_div_fmas_f32 v103, v103, v104, v107
	v_div_fixup_f32 v110, v103, v102, 1.0
	v_pk_mul_f32 v[112:113], v[112:113], v[110:111] op_sel_hi:[1,0]
	v_pk_mul_f32 v[114:115], v[114:115], v[110:111] op_sel_hi:[1,0]
	v_pk_mul_f32 v[116:117], v[116:117], v[110:111] op_sel_hi:[1,0]
	v_pk_mul_f32 v[118:119], v[118:119], v[110:111] op_sel_hi:[1,0]
	v_pk_mul_f32 v[120:121], v[120:121], v[110:111] op_sel_hi:[1,0]
	v_pk_mul_f32 v[122:123], v[122:123], v[110:111] op_sel_hi:[1,0]
	v_pk_mul_f32 v[124:125], v[124:125], v[110:111] op_sel_hi:[1,0]
	v_pk_mul_f32 v[100:101], v[100:101], v[110:111] op_sel_hi:[1,0]
	v_pk_mul_f32 v[112:113], v[176:177], v[112:113]
	v_pk_mul_f32 v[114:115], v[178:179], v[114:115]
	v_pk_mul_f32 v[116:117], v[180:181], v[116:117]
	v_pk_mul_f32 v[118:119], v[182:183], v[118:119]
	v_pk_mul_f32 v[120:121], v[184:185], v[120:121]
	v_pk_mul_f32 v[122:123], v[186:187], v[122:123]
	v_pk_mul_f32 v[124:125], v[188:189], v[124:125]
	v_pk_mul_f32 v[100:101], v[190:191], v[100:101]
	v_pk_fma_f32 v[68:69], v[160:161], v[112:113], v[68:69]
	v_pk_fma_f32 v[70:71], v[162:163], v[114:115], v[70:71]
	v_pk_fma_f32 v[72:73], v[164:165], v[116:117], v[72:73]
	v_pk_fma_f32 v[74:75], v[166:167], v[118:119], v[74:75]
	v_pk_fma_f32 v[76:77], v[168:169], v[120:121], v[76:77]
	v_pk_fma_f32 v[78:79], v[170:171], v[122:123], v[78:79]
	v_pk_fma_f32 v[80:81], v[172:173], v[124:125], v[80:81]
	v_pk_fma_f32 v[82:83], v[174:175], v[100:101], v[82:83]
	v_pk_mul_f32 v[102:103], v[68:69], v[68:69]
; __device__ __forceinline__ unsigned pk_bf16(float lo, float hi) { const f32x2 v = {lo, hi}; const bf16x2_t b = __builtin_convertvector(v, bf16x2_t); return __builtin_bit_cast(unsigned, b); }
; template <bool HAS_F, bool HAS_H>
; __device__ __forceinline__ void phase_rows(const Params& p, int sp, int sn, float resw, bool from_input, bool write_x = true) {
;     ...
;         if (HAS_H) {
;             float ss = 0.f;
; #pragma unroll
;             for (int j = 0; j < 4; ++j) ss += (v[j].x * v[j].x + v[j].y * v[j].y) + (v[j].z * v[j].z + v[j].w * v[j].w);
;             const float rs = 1.0f / sqrtf(wave_sum(ss) * (1.0f / D) + EPS);
;             const float* sh = mod + b * 9216 + sn * 3072; const float* scl = sh + 1024; const float* gq = p.in[6] + sn * D;
; #pragma unroll
;             for (int j = 0; j < 4; ++j) { const f32x4 a = *(const f32x4*)(sh + 4 * lane + 256 * j), s = *(const f32x4*)(scl + 4 * lane + 256 * j), q = *(const f32x4*)(gq + 4 * lane + 256 * j);
;                 const f32x4 h = (v[j] * rs * q) * (s + 1.0f) + a;
;                 u32x2 w; w.x = pk_bf16(h.x, h.y); w.y = pk_bf16(h.z, h.w);
;                 *(u32x2*)(H + (size_t)row * D + 4 * lane + 256 * j) = w; }
	v_pk_mul_f32 v[106:107], v[70:71], v[70:71]
	v_pk_fma_f32 v[102:103], v[72:73], v[72:73], v[102:103]
	v_pk_fma_f32 v[106:107], v[74:75], v[74:75], v[106:107]
	v_pk_fma_f32 v[102:103], v[76:77], v[76:77], v[102:103]
	v_pk_fma_f32 v[106:107], v[78:79], v[78:79], v[106:107]
	v_pk_fma_f32 v[102:103], v[80:81], v[80:81], v[102:103]
	v_pk_fma_f32 v[106:107], v[82:83], v[82:83], v[106:107]
	s_nop 0
	v_pk_add_f32 v[102:103], v[102:103], v[106:107]
	s_nop 0
	v_add_f32_e32 v102, v102, v103
	s_nop 1
	v_add_f32_dpp v102, v102, v102 quad_perm:[1,0,3,2] row_mask:0xf bank_mask:0xf
	s_nop 1
	v_add_f32_dpp v102, v102, v102 quad_perm:[2,3,0,1] row_mask:0xf bank_mask:0xf
	s_nop 1
	v_add_f32_dpp v102, v102, v102 row_half_mirror row_mask:0xf bank_mask:0xf
	s_nop 1
	v_add_f32_dpp v102, v102, v102 row_mirror row_mask:0xf bank_mask:0xf
	s_nop 1
	v_add_f32_dpp v102, v102, v102 row_bcast:15 row_mask:0xa bank_mask:0xf
	s_nop 1
	v_add_f32_dpp v102, v102, v102 row_bcast:31 row_mask:0xc bank_mask:0xf
	s_nop 1
	v_readlane_b32 s74, v102, 63
	s_nop 2
	v_mov_b32_e32 v102, s74
	v_fmamk_f32 v102, v102, 0x3a800000, v2
	v_mul_f32_e32 v103, 0x4f800000, v102
	v_cmp_gt_f32_e32 vcc, 0xf800000, v102
	s_nop 1
	v_cndmask_b32_e32 v102, v102, v103, vcc
	v_sqrt_f32_e32 v103, v102
	s_nop 0
	v_add_u32_e32 v104, -1, v103
	v_add_u32_e32 v106, 1, v103
	v_fma_f32 v107, -v104, v103, v102
	v_fma_f32 v108, -v106, v103, v102
	v_cmp_ge_f32_e64 s[76:77], 0, v107
	s_nop 1
	v_cndmask_b32_e64 v103, v103, v104, s[76:77]
	v_cmp_lt_f32_e64 s[76:77], 0, v108
	s_nop 1
	v_cndmask_b32_e64 v103, v103, v106, s[76:77]
	v_mul_f32_e32 v104, 0x37800000, v103
	v_cndmask_b32_e32 v103, v103, v104, vcc
	v_cmp_class_f32_e32 vcc, v102, v3
	s_nop 1
	v_cndmask_b32_e32 v102, v103, v102, vcc
	v_div_scale_f32 v103, s[76:77], v102, v102, 1.0
	v_rcp_f32_e32 v104, v103
	v_div_scale_f32 v106, vcc, 1.0, v102, 1.0
	v_fma_f32 v107, -v103, v104, 1.0
	v_fmac_f32_e32 v104, v107, v104
	v_mul_f32_e32 v107, v106, v104
	v_fma_f32 v108, -v103, v107, v106
	v_fmac_f32_e32 v107, v108, v104
	v_fma_f32 v103, -v103, v107, v106
	v_div_fmas_f32 v103, v103, v104, v107
	v_div_fixup_f32 v110, v103, v102, 1.0
	s_lshl_b32 s60, s55, 11
	s_add_u32 s70, s78, s60
	s_addc_u32 s71, s79, 0
	v_pk_mul_f32 v[112:113], v[68:69], v[110:111] op_sel_hi:[1,0]
	v_pk_mul_f32 v[114:115], v[70:71], v[110:111] op_sel_hi:[1,0]
	v_pk_mul_f32 v[116:117], v[72:73], v[110:111] op_sel_hi:[1,0]
	v_pk_mul_f32 v[118:119], v[74:75], v[110:111] op_sel_hi:[1,0]
	v_pk_mul_f32 v[120:121], v[76:77], v[110:111] op_sel_hi:[1,0]
	v_pk_mul_f32 v[122:123], v[78:79], v[110:111] op_sel_hi:[1,0]
	v_pk_mul_f32 v[124:125], v[80:81], v[110:111] op_sel_hi:[1,0]
	v_pk_mul_f32 v[100:101], v[82:83], v[110:111] op_sel_hi:[1,0]
	v_pk_mul_f32 v[112:113], v[192:193], v[112:113]
	v_pk_mul_f32 v[114:115], v[194:195], v[114:115]
	v_pk_mul_f32 v[116:117], v[196:197], v[116:117]
	v_pk_mul_f32 v[118:119], v[198:199], v[118:119]
	v_pk_mul_f32 v[120:121], v[200:201], v[120:121]
	v_pk_mul_f32 v[122:123], v[202:203], v[122:123]
	v_pk_mul_f32 v[124:125], v[204:205], v[124:125]
	v_pk_mul_f32 v[100:101], v[206:207], v[100:101]
	v_pk_fma_f32 v[112:113], v[208:209], v[112:113], v[224:225]
	v_pk_fma_f32 v[114:115], v[210:211], v[114:115], v[226:227]
	v_pk_fma_f32 v[116:117], v[212:213], v[116:117], v[228:229]
	v_pk_fma_f32 v[118:119], v[214:215], v[118:119], v[230:231]
	v_pk_fma_f32 v[120:121], v[216:217], v[120:121], v[232:233]
	v_pk_fma_f32 v[122:123], v[218:219], v[122:123], v[234:235]
	v_pk_fma_f32 v[124:125], v[220:221], v[124:125], v[236:237]
	v_pk_fma_f32 v[100:101], v[222:223], v[100:101], v[238:239]
	v_cvt_pk_bf16_f32 v240, v112, v113
	v_cvt_pk_bf16_f32 v241, v114, v115
	v_cvt_pk_bf16_f32 v242, v116, v117
	v_cvt_pk_bf16_f32 v243, v118, v119
	v_cvt_pk_bf16_f32 v244, v120, v121
	v_cvt_pk_bf16_f32 v245, v122, v123
	v_cvt_pk_bf16_f32 v246, v124, v125
	v_cvt_pk_bf16_f32 v247, v100, v101
	global_store_dwordx2 v1, v[240:241], s[70:71]
	global_store_dwordx2 v1, v[242:243], s[70:71] offset:512
	global_store_dwordx2 v1, v[244:245], s[70:71] offset:1024
	global_store_dwordx2 v1, v[246:247], s[70:71] offset:1536
	s_add_u32 s55, s55, 8
	s_cmp_le_u32 s55, s54
	s_cbranch_scc1 .Lrp12_loop3
	s_add_u32 s51, s51, s52
	s_branch .Lrp12_chunk1

; __device__ __forceinline__ float lo_bf(unsigned w) { return __uint_as_float(w << 16); }
; __device__ __forceinline__ float hi_bf(unsigned w) { return __uint_as_float(w & 0xffff0000u); }
; __device__ __forceinline__ void phase_final(const Params& p) {
;     ...
;         f32x4 v[4], m[4], f[4]; float sm = 0.f, sf = 0.f;
; #pragma unroll
;         for (int j = 0; j < 4; ++j) { v[j] = *(const f32x4*)(p.out + (size_t)row * D + 4 * lane + 256 * j);
;             const u32x2 wm = *(const u32x2*)(Fm + (size_t)row * D + 4 * lane + 256 * j), wf = *(const u32x2*)(F2 + (size_t)row * D + 4 * lane + 256 * j);
;             m[j] = (f32x4){lo_bf(wm.x), hi_bf(wm.x), lo_bf(wm.y), hi_bf(wm.y)}; f[j] = (f32x4){lo_bf(wf.x), hi_bf(wf.x), lo_bf(wf.y), hi_bf(wf.y)};
;             sm += (m[j].x * m[j].x + m[j].y * m[j].y) + (m[j].z * m[j].z + m[j].w * m[j].w); sf += (f[j].x * f[j].x + f[j].y * f[j].y) + (f[j].z * f[j].z + f[j].w * f[j].w); }
;         const float rm = 1.0f / sqrtf(wave_sum(sm) * (1.0f / D) + EPS), rf = 1.0f / sqrtf(wave_sum(sf) * (1.0f / D) + EPS) * 0.5f;
.Lrp15_pk4:
	s_waitcnt vmcnt(24)
	v_lshlrev_b32_e32 v112, 16, v20
	v_and_b32_e32 v113, 0xffff0000, v20
	v_lshlrev_b32_e32 v114, 16, v21
	v_and_b32_e32 v115, 0xffff0000, v21
	v_lshlrev_b32_e32 v116, 16, v22
	v_and_b32_e32 v117, 0xffff0000, v22
	v_lshlrev_b32_e32 v118, 16, v23
	v_and_b32_e32 v119, 0xffff0000, v23
	v_lshlrev_b32_e32 v120, 16, v24
	v_and_b32_e32 v121, 0xffff0000, v24
	v_lshlrev_b32_e32 v122, 16, v25
	v_and_b32_e32 v123, 0xffff0000, v25
	v_lshlrev_b32_e32 v124, 16, v26
	v_and_b32_e32 v125, 0xffff0000, v26
	v_lshlrev_b32_e32 v100, 16, v27
	v_and_b32_e32 v101, 0xffff0000, v27
	v_pk_mul_f32 v[102:103], v[112:113], v[112:113]
	v_pk_mul_f32 v[106:107], v[114:115], v[114:115]
	v_pk_fma_f32 v[102:103], v[116:117], v[116:117], v[102:103]
	v_pk_fma_f32 v[106:107], v[118:119], v[118:119], v[106:107]
	v_pk_fma_f32 v[102:103], v[120:121], v[120:121], v[102:103]
	v_pk_fma_f32 v[106:107], v[122:123], v[122:123], v[106:107]
	v_pk_fma_f32 v[102:103], v[124:125], v[124:125], v[102:103]
	v_pk_fma_f32 v[106:107], v[100:101], v[100:101], v[106:107]
	s_nop 0
	v_pk_add_f32 v[102:103], v[102:103], v[106:107]
	s_nop 0
	v_add_f32_e32 v102, v102, v103
	v_mov_b32_e32 v104, v102
	v_lshlrev_b32_e32 v112, 16, v28
	v_and_b32_e32 v113, 0xffff0000, v28
	v_lshlrev_b32_e32 v114, 16, v29
	v_and_b32_e32 v115, 0xffff0000, v29
	v_lshlrev_b32_e32 v116, 16, v30
	v_and_b32_e32 v117, 0xffff0000, v30
	v_lshlrev_b32_e32 v118, 16, v31
	v_and_b32_e32 v119, 0xffff0000, v31
	v_lshlrev_b32_e32 v120, 16, v32
	v_and_b32_e32 v121, 0xffff0000, v32
	v_lshlrev_b32_e32 v122, 16, v33
	v_and_b32_e32 v123, 0xffff0000, v33
	v_lshlrev_b32_e32 v124, 16, v34
	v_and_b32_e32 v125, 0xffff0000, v34
	v_lshlrev_b32_e32 v100, 16, v35
	v_and_b32_e32 v101, 0xffff0000, v35
	v_pk_mul_f32 v[102:103], v[112:113], v[112:113]
	v_pk_mul_f32 v[106:107], v[114:115], v[114:115]
	v_pk_fma_f32 v[102:103], v[116:117], v[116:117], v[102:103]
	v_pk_fma_f32 v[106:107], v[118:119], v[118:119], v[106:107]
	v_pk_fma_f32 v[102:103], v[120:121], v[120:121], v[102:103]
	v_pk_fma_f32 v[106:107], v[122:123], v[122:123], v[106:107]
	v_pk_fma_f32 v[102:103], v[124:125], v[124:125], v[102:103]
	v_pk_fma_f32 v[106:107], v[100:101], v[100:101], v[106:107]
	s_nop 0
	v_pk_add_f32 v[102:103], v[102:103], v[106:107]
	s_nop 0
	v_add_f32_e32 v102, v102, v103
	s_nop 1
	v_add_f32_dpp v104, v104, v104 quad_perm:[1,0,3,2] row_mask:0xf bank_mask:0xf
	v_add_f32_dpp v102, v102, v102 quad_perm:[1,0,3,2] row_mask:0xf bank_mask:0xf
	s_nop 1
	v_add_f32_dpp v104, v104, v104 quad_perm:[2,3,0,1] row_mask:0xf bank_mask:0xf
	v_add_f32_dpp v102, v102, v102 quad_perm:[2,3,0,1] row_mask:0xf bank_mask:0xf
	s_nop 1
	v_add_f32_dpp v104, v104, v104 row_half_mirror row_mask:0xf bank_mask:0xf
	v_add_f32_dpp v102, v102, v102 row_half_mirror row_mask:0xf bank_mask:0xf
	s_nop 1
	v_add_f32_dpp v104, v104, v104 row_mirror row_mask:0xf bank_mask:0xf
	v_add_f32_dpp v102, v102, v102 row_mirror row_mask:0xf bank_mask:0xf
	s_nop 1
	v_add_f32_dpp v104, v104, v104 row_bcast:15 row_mask:0xa bank_mask:0xf
	v_add_f32_dpp v102, v102, v102 row_bcast:15 row_mask:0xa bank_mask:0xf
	s_nop 1
	v_add_f32_dpp v104, v104, v104 row_bcast:31 row_mask:0xc bank_mask:0xf
	v_add_f32_dpp v102, v102, v102 row_bcast:31 row_mask:0xc bank_mask:0xf
	s_nop 1
	v_readlane_b32 s74, v104, 63
	v_readlane_b32 s75, v102, 63
	s_nop 2
	v_mov_b32_e32 v102, s74
	v_fmamk_f32 v102, v102, 0x3a800000, v2
	v_mul_f32_e32 v103, 0x4f800000, v102
	v_cmp_gt_f32_e32 vcc, 0xf800000, v102
	s_nop 1
	v_cndmask_b32_e32 v102, v102, v103, vcc
	v_sqrt_f32_e32 v103, v102
	s_nop 0
	v_add_u32_e32 v104, -1, v103
	v_add_u32_e32 v106, 1, v103
	v_fma_f32 v107, -v104, v103, v102
	v_fma_f32 v108, -v106, v103, v102
	v_cmp_ge_f32_e64 s[76:77], 0, v107
	s_nop 1
	v_cndmask_b32_e64 v103, v103, v104, s[76:77]
	v_cmp_lt_f32_e64 s[76:77], 0, v108
	s_nop 1
	v_cndmask_b32_e64 v103, v103, v106, s[76:77]
	v_mul_f32_e32 v104, 0x37800000, v103
	v_cndmask_b32_e32 v103, v103, v104, vcc
	v_cmp_class_f32_e32 vcc, v102, v3
	s_nop 1
	v_cndmask_b32_e32 v102, v103, v102, vcc
	v_div_scale_f32 v103, s[76:77], v102, v102, 1.0
	v_rcp_f32_e32 v104, v103
	v_div_scale_f32 v106, vcc, 1.0, v102, 1.0
	v_fma_f32 v107, -v103, v104, 1.0
	v_fmac_f32_e32 v104, v107, v104
	v_mul_f32_e32 v107, v106, v104
	v_fma_f32 v108, -v103, v107, v106
	v_fmac_f32_e32 v107, v108, v104
	v_fma_f32 v103, -v103, v107, v106
	v_div_fmas_f32 v103, v103, v104, v107
	v_div_fixup_f32 v110, v103, v102, 1.0
	v_mov_b32_e32 v102, s75
	v_fmamk_f32 v102, v102, 0x3a800000, v2
	v_mul_f32_e32 v103, 0x4f800000, v102
	v_cmp_gt_f32_e32 vcc, 0xf800000, v102
	s_nop 1
	v_cndmask_b32_e32 v102, v102, v103, vcc
	v_sqrt_f32_e32 v103, v102
	s_nop 0
	v_add_u32_e32 v104, -1, v103
	v_add_u32_e32 v106, 1, v103
	v_fma_f32 v107, -v104, v103, v102
	v_fma_f32 v108, -v106, v103, v102
	v_cmp_ge_f32_e64 s[76:77], 0, v107
	s_nop 1
	v_cndmask_b32_e64 v103, v103, v104, s[76:77]
	v_cmp_lt_f32_e64 s[76:77], 0, v108
	s_nop 1
	v_cndmask_b32_e64 v103, v103, v106, s[76:77]
	v_mul_f32_e32 v104, 0x37800000, v103
	v_cndmask_b32_e32 v103, v103, v104, vcc
	v_cmp_class_f32_e32 vcc, v102, v3
	s_nop 1
	v_cndmask_b32_e32 v102, v103, v102, vcc
	v_div_scale_f32 v103, s[76:77], v102, v102, 1.0
	v_rcp_f32_e32 v104, v103
	v_div_scale_f32 v106, vcc, 1.0, v102, 1.0
	v_fma_f32 v107, -v103, v104, 1.0
	v_fmac_f32_e32 v104, v107, v104
	v_mul_f32_e32 v107, v106, v104
	v_fma_f32 v108, -v103, v107, v106
	v_fmac_f32_e32 v107, v108, v104
	v_fma_f32 v103, -v103, v107, v106
	v_div_fmas_f32 v103, v103, v104, v107
	v_div_fixup_f32 v108, v103, v102, 1.0
	v_mul_f32_e32 v108, 0.5, v108
	v_pk_mul_f32 v[112:113], v[112:113], v[108:109] op_sel_hi:[1,0]
; __device__ __forceinline__ float lo_bf(unsigned w) { return __uint_as_float(w << 16); }
; __device__ __forceinline__ float hi_bf(unsigned w) { return __uint_as_float(w & 0xffff0000u); }
; __device__ __forceinline__ void phase_final(const Params& p) {
;     ...
;     for (int row = gw; row < T; row += NGW) {
;         const int b = row_batch(row);
;         f32x4 v[4], m[4], f[4]; float sm = 0.f, sf = 0.f;
; #pragma unroll
;         for (int j = 0; j < 4; ++j) { v[j] = *(const f32x4*)(p.out + (size_t)row * D + 4 * lane + 256 * j);
;             const u32x2 wm = *(const u32x2*)(Fm + (size_t)row * D + 4 * lane + 256 * j), wf = *(const u32x2*)(F2 + (size_t)row * D + 4 * lane + 256 * j);
;             m[j] = (f32x4){lo_bf(wm.x), hi_bf(wm.x), lo_bf(wm.y), hi_bf(wm.y)}; f[j] = (f32x4){lo_bf(wf.x), hi_bf(wf.x), lo_bf(wf.y), hi_bf(wf.y)};
;     ...
;         const float rm = 1.0f / sqrtf(wave_sum(sm) * (1.0f / D) + EPS), rf = 1.0f / sqrtf(wave_sum(sf) * (1.0f / D) + EPS) * 0.5f;
;         const float* g1 = mod + b * 9216 + 1 * 3072 + 2048; const float* g2 = mod + b * 9216 + 2 * 3072 + 2048;
;         const float* q1 = p.in[7] + 1 * D; const float* q2 = p.in[7] + 2 * D;
; #pragma unroll
;         for (int j = 0; j < 4; ++j) { const int c = 4 * lane + 256 * j;
;             const f32x4 x2 = v[j] + *(const f32x4*)(g1 + c) * (m[j] * rm * *(const f32x4*)(q1 + c));
;             *(f32x4*)(p.out + (size_t)row * D + c) = x2 + *(const f32x4*)(g2 + c) * (f[j] * rf * *(const f32x4*)(q2 + c)); }
	v_pk_mul_f32 v[114:115], v[114:115], v[108:109] op_sel_hi:[1,0]
	v_pk_mul_f32 v[116:117], v[116:117], v[108:109] op_sel_hi:[1,0]
	v_pk_mul_f32 v[118:119], v[118:119], v[108:109] op_sel_hi:[1,0]
	v_pk_mul_f32 v[120:121], v[120:121], v[108:109] op_sel_hi:[1,0]
	v_pk_mul_f32 v[122:123], v[122:123], v[108:109] op_sel_hi:[1,0]
	v_pk_mul_f32 v[124:125], v[124:125], v[108:109] op_sel_hi:[1,0]
	v_pk_mul_f32 v[100:101], v[100:101], v[108:109] op_sel_hi:[1,0]
	v_pk_mul_f32 v[112:113], v[112:113], v[208:209]
	v_pk_mul_f32 v[114:115], v[114:115], v[210:211]
	v_pk_mul_f32 v[116:117], v[116:117], v[212:213]
	v_pk_mul_f32 v[118:119], v[118:119], v[214:215]
	v_pk_mul_f32 v[120:121], v[120:121], v[216:217]
	v_pk_mul_f32 v[122:123], v[122:123], v[218:219]
	v_pk_mul_f32 v[124:125], v[124:125], v[220:221]
	v_pk_mul_f32 v[100:101], v[100:101], v[222:223]
	v_lshlrev_b32_e32 v28, 16, v20
	v_and_b32_e32 v29, 0xffff0000, v20
	v_lshlrev_b32_e32 v30, 16, v21
	v_and_b32_e32 v31, 0xffff0000, v21
	v_lshlrev_b32_e32 v32, 16, v22
	v_and_b32_e32 v33, 0xffff0000, v22
	v_lshlrev_b32_e32 v34, 16, v23
	v_and_b32_e32 v35, 0xffff0000, v23
	v_lshlrev_b32_e32 v240, 16, v24
	v_and_b32_e32 v241, 0xffff0000, v24
	v_lshlrev_b32_e32 v242, 16, v25
	v_and_b32_e32 v243, 0xffff0000, v25
	v_lshlrev_b32_e32 v244, 16, v26
	v_and_b32_e32 v245, 0xffff0000, v26
	v_lshlrev_b32_e32 v246, 16, v27
	v_and_b32_e32 v247, 0xffff0000, v27
	v_pk_mul_f32 v[28:29], v[28:29], v[110:111] op_sel_hi:[1,0]
	v_pk_mul_f32 v[30:31], v[30:31], v[110:111] op_sel_hi:[1,0]
	v_pk_mul_f32 v[32:33], v[32:33], v[110:111] op_sel_hi:[1,0]
	v_pk_mul_f32 v[34:35], v[34:35], v[110:111] op_sel_hi:[1,0]
	v_pk_mul_f32 v[240:241], v[240:241], v[110:111] op_sel_hi:[1,0]
	v_pk_mul_f32 v[242:243], v[242:243], v[110:111] op_sel_hi:[1,0]
	v_pk_mul_f32 v[244:245], v[244:245], v[110:111] op_sel_hi:[1,0]
	v_pk_mul_f32 v[246:247], v[246:247], v[110:111] op_sel_hi:[1,0]
	v_pk_mul_f32 v[28:29], v[28:29], v[176:177]
	v_pk_mul_f32 v[30:31], v[30:31], v[178:179]
	v_pk_mul_f32 v[32:33], v[32:33], v[180:181]
	v_pk_mul_f32 v[34:35], v[34:35], v[182:183]
	v_pk_mul_f32 v[240:241], v[240:241], v[184:185]
	v_pk_mul_f32 v[242:243], v[242:243], v[186:187]
	v_pk_mul_f32 v[244:245], v[244:245], v[188:189]
	v_pk_mul_f32 v[246:247], v[246:247], v[190:191]
	v_pk_fma_f32 v[4:5], v[160:161], v[28:29], v[4:5]
	v_pk_fma_f32 v[6:7], v[162:163], v[30:31], v[6:7]
	v_pk_fma_f32 v[8:9], v[164:165], v[32:33], v[8:9]
	v_pk_fma_f32 v[10:11], v[166:167], v[34:35], v[10:11]
	v_pk_fma_f32 v[12:13], v[168:169], v[240:241], v[12:13]
	v_pk_fma_f32 v[14:15], v[170:171], v[242:243], v[14:15]
	v_pk_fma_f32 v[16:17], v[172:173], v[244:245], v[16:17]
	v_pk_fma_f32 v[18:19], v[174:175], v[246:247], v[18:19]
	v_pk_fma_f32 v[4:5], v[192:193], v[112:113], v[4:5]
	v_pk_fma_f32 v[6:7], v[194:195], v[114:115], v[6:7]
	v_pk_fma_f32 v[8:9], v[196:197], v[116:117], v[8:9]
	v_pk_fma_f32 v[10:11], v[198:199], v[118:119], v[10:11]
	v_pk_fma_f32 v[12:13], v[200:201], v[120:121], v[12:13]
	v_pk_fma_f32 v[14:15], v[202:203], v[122:123], v[14:15]
	v_pk_fma_f32 v[16:17], v[204:205], v[124:125], v[16:17]
	v_pk_fma_f32 v[18:19], v[206:207], v[100:101], v[18:19]
	s_lshl_b32 s60, s55, 12
	s_add_u32 s72, s84, s60
	s_addc_u32 s73, s85, 0
	global_store_dwordx4 v0, v[4:7], s[72:73] sc1
	global_store_dwordx4 v0, v[8:11], s[72:73] offset:1024 sc1
	global_store_dwordx4 v0, v[12:15], s[72:73] offset:2048 sc1
	global_store_dwordx4 v0, v[16:19], s[72:73] offset:3072 sc1
	s_add_u32 s55, s55, 8
	s_add_u32 s57, s55, 16
	s_min_u32 s57, s57, s54
	s_lshl_b32 s60, s57, 12
	s_add_u32 s64, s84, s60
	s_addc_u32 s65, s85, 0
	s_lshl_b32 s60, s57, 11
	s_add_u32 s66, s82, s60
	s_addc_u32 s67, s83, 0
	s_lshl_b32 s60, s57, 11
	s_add_u32 s68, s78, s60
	s_addc_u32 s69, s79, 0
	global_load_dwordx4 v[4:7], v0, s[64:65] nt
	global_load_dwordx4 v[8:11], v0, s[64:65] offset:1024 nt
	global_load_dwordx4 v[12:15], v0, s[64:65] offset:2048 nt
	global_load_dwordx4 v[16:19], v0, s[64:65] offset:3072 nt
	global_load_dwordx2 v[20:21], v1, s[66:67] nt
	global_load_dwordx2 v[22:23], v1, s[66:67] offset:512 nt
	global_load_dwordx2 v[24:25], v1, s[66:67] offset:1024 nt
	global_load_dwordx2 v[26:27], v1, s[66:67] offset:1536 nt
	global_load_dwordx2 v[28:29], v1, s[68:69] nt
	global_load_dwordx2 v[30:31], v1, s[68:69] offset:512 nt
	global_load_dwordx2 v[32:33], v1, s[68:69] offset:1024 nt
	global_load_dwordx2 v[34:35], v1, s[68:69] offset:1536 nt
	s_lshr_b32 s60, s55, 11
	s_sub_u32 s61, s55, 0x8000
	s_lshr_b32 s61, s61, 12
	s_add_u32 s61, s61, 16
	s_cmp_lt_u32 s55, 0x8000
	s_cselect_b32 s63, s60, s61
	s_cmp_eq_u32 s63, s56
	s_cbranch_scc1 .Lrp15_pk5
	s_mov_b32 s56, s63
	s_mul_i32 s60, s56, 0x9000
	s_add_u32 s60, s60, 0x3185000
	s_add_u32 s0, s92, s60
	s_addc_u32 s1, s93, 0
	global_load_dwordx4 v[160:163], v0, s[0:1]
	global_load_dwordx4 v[164:167], v0, s[0:1] offset:1024
	global_load_dwordx4 v[168:171], v0, s[0:1] offset:2048
	global_load_dwordx4 v[172:175], v0, s[0:1] offset:3072
	s_add_u32 s0, s22, 0x1000
	s_addc_u32 s1, s23, 0
	global_load_dwordx4 v[176:179], v0, s[0:1]
	global_load_dwordx4 v[180:183], v0, s[0:1] offset:1024
	global_load_dwordx4 v[184:187], v0, s[0:1] offset:2048
	global_load_dwordx4 v[188:191], v0, s[0:1] offset:3072
	s_mul_i32 s60, s56, 0x9000
	s_add_u32 s60, s60, 0x3188000
	s_add_u32 s0, s92, s60
	s_addc_u32 s1, s93, 0
	global_load_dwordx4 v[192:195], v0, s[0:1]
	global_load_dwordx4 v[196:199], v0, s[0:1] offset:1024
	global_load_dwordx4 v[200:203], v0, s[0:1] offset:2048
	global_load_dwordx4 v[204:207], v0, s[0:1] offset:3072
	s_add_u32 s0, s22, 0x2000
	s_addc_u32 s1, s23, 0
	global_load_dwordx4 v[208:211], v0, s[0:1]
	global_load_dwordx4 v[212:215], v0, s[0:1] offset:1024
	global_load_dwordx4 v[216:219], v0, s[0:1] offset:2048
	global_load_dwordx4 v[220:223], v0, s[0:1] offset:3072
	s_waitcnt vmcnt(0)
; __device__ __forceinline__ float lo_bf(unsigned w) { return __uint_as_float(w << 16); }
; __device__ __forceinline__ float hi_bf(unsigned w) { return __uint_as_float(w & 0xffff0000u); }
; __device__ __forceinline__ void phase_final(const Params& p) {
;     ...
;         f32x4 v[4], m[4], f[4]; float sm = 0.f, sf = 0.f;
; #pragma unroll
;         for (int j = 0; j < 4; ++j) { v[j] = *(const f32x4*)(p.out + (size_t)row * D + 4 * lane + 256 * j);
;             const u32x2 wm = *(const u32x2*)(Fm + (size_t)row * D + 4 * lane + 256 * j), wf = *(const u32x2*)(F2 + (size_t)row * D + 4 * lane + 256 * j);
;             m[j] = (f32x4){lo_bf(wm.x), hi_bf(wm.x), lo_bf(wm.y), hi_bf(wm.y)}; f[j] = (f32x4){lo_bf(wf.x), hi_bf(wf.x), lo_bf(wf.y), hi_bf(wf.y)};
;             sm += (m[j].x * m[j].x + m[j].y * m[j].y) + (m[j].z * m[j].z + m[j].w * m[j].w); sf += (f[j].x * f[j].x + f[j].y * f[j].y) + (f[j].z * f[j].z + f[j].w * f[j].w); }
;         const float rm = 1.0f / sqrtf(wave_sum(sm) * (1.0f / D) + EPS), rf = 1.0f / sqrtf(wave_sum(sf) * (1.0f / D) + EPS) * 0.5f;
.Lrp15_pk5:
	s_waitcnt vmcnt(28)
	v_lshlrev_b32_e32 v112, 16, v52
	v_and_b32_e32 v113, 0xffff0000, v52
	v_lshlrev_b32_e32 v114, 16, v53
	v_and_b32_e32 v115, 0xffff0000, v53
	v_lshlrev_b32_e32 v116, 16, v54
	v_and_b32_e32 v117, 0xffff0000, v54
	v_lshlrev_b32_e32 v118, 16, v55
	v_and_b32_e32 v119, 0xffff0000, v55
	v_lshlrev_b32_e32 v120, 16, v56
	v_and_b32_e32 v121, 0xffff0000, v56
	v_lshlrev_b32_e32 v122, 16, v57
	v_and_b32_e32 v123, 0xffff0000, v57
	v_lshlrev_b32_e32 v124, 16, v58
	v_and_b32_e32 v125, 0xffff0000, v58
	v_lshlrev_b32_e32 v100, 16, v59
	v_and_b32_e32 v101, 0xffff0000, v59
	v_pk_mul_f32 v[102:103], v[112:113], v[112:113]
	v_pk_mul_f32 v[106:107], v[114:115], v[114:115]
	v_pk_fma_f32 v[102:103], v[116:117], v[116:117], v[102:103]
	v_pk_fma_f32 v[106:107], v[118:119], v[118:119], v[106:107]
	v_pk_fma_f32 v[102:103], v[120:121], v[120:121], v[102:103]
	v_pk_fma_f32 v[106:107], v[122:123], v[122:123], v[106:107]
	v_pk_fma_f32 v[102:103], v[124:125], v[124:125], v[102:103]
	v_pk_fma_f32 v[106:107], v[100:101], v[100:101], v[106:107]
	s_nop 0
	v_pk_add_f32 v[102:103], v[102:103], v[106:107]
	s_nop 0
	v_add_f32_e32 v102, v102, v103
	v_mov_b32_e32 v104, v102
	v_lshlrev_b32_e32 v112, 16, v60
	v_and_b32_e32 v113, 0xffff0000, v60
	v_lshlrev_b32_e32 v114, 16, v61
	v_and_b32_e32 v115, 0xffff0000, v61
	v_lshlrev_b32_e32 v116, 16, v62
	v_and_b32_e32 v117, 0xffff0000, v62
	v_lshlrev_b32_e32 v118, 16, v63
	v_and_b32_e32 v119, 0xffff0000, v63
	v_lshlrev_b32_e32 v120, 16, v64
	v_and_b32_e32 v121, 0xffff0000, v64
	v_lshlrev_b32_e32 v122, 16, v65
	v_and_b32_e32 v123, 0xffff0000, v65
	v_lshlrev_b32_e32 v124, 16, v66
	v_and_b32_e32 v125, 0xffff0000, v66
	v_lshlrev_b32_e32 v100, 16, v67
	v_and_b32_e32 v101, 0xffff0000, v67
	v_pk_mul_f32 v[102:103], v[112:113], v[112:113]
	v_pk_mul_f32 v[106:107], v[114:115], v[114:115]
	v_pk_fma_f32 v[102:103], v[116:117], v[116:117], v[102:103]
	v_pk_fma_f32 v[106:107], v[118:119], v[118:119], v[106:107]
	v_pk_fma_f32 v[102:103], v[120:121], v[120:121], v[102:103]
	v_pk_fma_f32 v[106:107], v[122:123], v[122:123], v[106:107]
	v_pk_fma_f32 v[102:103], v[124:125], v[124:125], v[102:103]
	v_pk_fma_f32 v[106:107], v[100:101], v[100:101], v[106:107]
	s_nop 0
	v_pk_add_f32 v[102:103], v[102:103], v[106:107]
	s_nop 0
	v_add_f32_e32 v102, v102, v103
	s_nop 1
	v_add_f32_dpp v104, v104, v104 quad_perm:[1,0,3,2] row_mask:0xf bank_mask:0xf
	v_add_f32_dpp v102, v102, v102 quad_perm:[1,0,3,2] row_mask:0xf bank_mask:0xf
	s_nop 1
	v_add_f32_dpp v104, v104, v104 quad_perm:[2,3,0,1] row_mask:0xf bank_mask:0xf
	v_add_f32_dpp v102, v102, v102 quad_perm:[2,3,0,1] row_mask:0xf bank_mask:0xf
	s_nop 1
	v_add_f32_dpp v104, v104, v104 row_half_mirror row_mask:0xf bank_mask:0xf
	v_add_f32_dpp v102, v102, v102 row_half_mirror row_mask:0xf bank_mask:0xf
	s_nop 1
	v_add_f32_dpp v104, v104, v104 row_mirror row_mask:0xf bank_mask:0xf
	v_add_f32_dpp v102, v102, v102 row_mirror row_mask:0xf bank_mask:0xf
	s_nop 1
	v_add_f32_dpp v104, v104, v104 row_bcast:15 row_mask:0xa bank_mask:0xf
	v_add_f32_dpp v102, v102, v102 row_bcast:15 row_mask:0xa bank_mask:0xf
	s_nop 1
	v_add_f32_dpp v104, v104, v104 row_bcast:31 row_mask:0xc bank_mask:0xf
	v_add_f32_dpp v102, v102, v102 row_bcast:31 row_mask:0xc bank_mask:0xf
	s_nop 1
	v_readlane_b32 s74, v104, 63
	v_readlane_b32 s75, v102, 63
	s_nop 2
	v_mov_b32_e32 v102, s74
	v_fmamk_f32 v102, v102, 0x3a800000, v2
	v_mul_f32_e32 v103, 0x4f800000, v102
	v_cmp_gt_f32_e32 vcc, 0xf800000, v102
	s_nop 1
	v_cndmask_b32_e32 v102, v102, v103, vcc
	v_sqrt_f32_e32 v103, v102
	s_nop 0
	v_add_u32_e32 v104, -1, v103
	v_add_u32_e32 v106, 1, v103
	v_fma_f32 v107, -v104, v103, v102
	v_fma_f32 v108, -v106, v103, v102
	v_cmp_ge_f32_e64 s[76:77], 0, v107
	s_nop 1
	v_cndmask_b32_e64 v103, v103, v104, s[76:77]
	v_cmp_lt_f32_e64 s[76:77], 0, v108
	s_nop 1
	v_cndmask_b32_e64 v103, v103, v106, s[76:77]
	v_mul_f32_e32 v104, 0x37800000, v103
	v_cndmask_b32_e32 v103, v103, v104, vcc
	v_cmp_class_f32_e32 vcc, v102, v3
	s_nop 1
	v_cndmask_b32_e32 v102, v103, v102, vcc
	v_div_scale_f32 v103, s[76:77], v102, v102, 1.0
	v_rcp_f32_e32 v104, v103
	v_div_scale_f32 v106, vcc, 1.0, v102, 1.0
	v_fma_f32 v107, -v103, v104, 1.0
	v_fmac_f32_e32 v104, v107, v104
	v_mul_f32_e32 v107, v106, v104
	v_fma_f32 v108, -v103, v107, v106
	v_fmac_f32_e32 v107, v108, v104
	v_fma_f32 v103, -v103, v107, v106
	v_div_fmas_f32 v103, v103, v104, v107
	v_div_fixup_f32 v110, v103, v102, 1.0
	v_mov_b32_e32 v102, s75
	v_fmamk_f32 v102, v102, 0x3a800000, v2
	v_mul_f32_e32 v103, 0x4f800000, v102
	v_cmp_gt_f32_e32 vcc, 0xf800000, v102
	s_nop 1
	v_cndmask_b32_e32 v102, v102, v103, vcc
	v_sqrt_f32_e32 v103, v102
	s_nop 0
	v_add_u32_e32 v104, -1, v103
	v_add_u32_e32 v106, 1, v103
	v_fma_f32 v107, -v104, v103, v102
	v_fma_f32 v108, -v106, v103, v102
	v_cmp_ge_f32_e64 s[76:77], 0, v107
	s_nop 1
	v_cndmask_b32_e64 v103, v103, v104, s[76:77]
	v_cmp_lt_f32_e64 s[76:77], 0, v108
	s_nop 1
	v_cndmask_b32_e64 v103, v103, v106, s[76:77]
	v_mul_f32_e32 v104, 0x37800000, v103
	v_cndmask_b32_e32 v103, v103, v104, vcc
	v_cmp_class_f32_e32 vcc, v102, v3
	s_nop 1
	v_cndmask_b32_e32 v102, v103, v102, vcc
	v_div_scale_f32 v103, s[76:77], v102, v102, 1.0
	v_rcp_f32_e32 v104, v103
	v_div_scale_f32 v106, vcc, 1.0, v102, 1.0
	v_fma_f32 v107, -v103, v104, 1.0
	v_fmac_f32_e32 v104, v107, v104
	v_mul_f32_e32 v107, v106, v104
	v_fma_f32 v108, -v103, v107, v106
	v_fmac_f32_e32 v107, v108, v104
	v_fma_f32 v103, -v103, v107, v106
	v_div_fmas_f32 v103, v103, v104, v107
	v_div_fixup_f32 v108, v103, v102, 1.0
	v_mul_f32_e32 v108, 0.5, v108
	v_pk_mul_f32 v[112:113], v[112:113], v[108:109] op_sel_hi:[1,0]
; __device__ __forceinline__ float lo_bf(unsigned w) { return __uint_as_float(w << 16); }
; __device__ __forceinline__ float hi_bf(unsigned w) { return __uint_as_float(w & 0xffff0000u); }
; __device__ __forceinline__ void phase_final(const Params& p) {
;     ...
;     for (int row = gw; row < T; row += NGW) {
;         const int b = row_batch(row);
;         f32x4 v[4], m[4], f[4]; float sm = 0.f, sf = 0.f;
; #pragma unroll
;         for (int j = 0; j < 4; ++j) { v[j] = *(const f32x4*)(p.out + (size_t)row * D + 4 * lane + 256 * j);
;             const u32x2 wm = *(const u32x2*)(Fm + (size_t)row * D + 4 * lane + 256 * j), wf = *(const u32x2*)(F2 + (size_t)row * D + 4 * lane + 256 * j);
;             m[j] = (f32x4){lo_bf(wm.x), hi_bf(wm.x), lo_bf(wm.y), hi_bf(wm.y)}; f[j] = (f32x4){lo_bf(wf.x), hi_bf(wf.x), lo_bf(wf.y), hi_bf(wf.y)};
;     ...
;         const float rm = 1.0f / sqrtf(wave_sum(sm) * (1.0f / D) + EPS), rf = 1.0f / sqrtf(wave_sum(sf) * (1.0f / D) + EPS) * 0.5f;
;         const float* g1 = mod + b * 9216 + 1 * 3072 + 2048; const float* g2 = mod + b * 9216 + 2 * 3072 + 2048;
;         const float* q1 = p.in[7] + 1 * D; const float* q2 = p.in[7] + 2 * D;
; #pragma unroll
;         for (int j = 0; j < 4; ++j) { const int c = 4 * lane + 256 * j;
;             const f32x4 x2 = v[j] + *(const f32x4*)(g1 + c) * (m[j] * rm * *(const f32x4*)(q1 + c));
;             *(f32x4*)(p.out + (size_t)row * D + c) = x2 + *(const f32x4*)(g2 + c) * (f[j] * rf * *(const f32x4*)(q2 + c)); }
	v_pk_mul_f32 v[114:115], v[114:115], v[108:109] op_sel_hi:[1,0]
	v_pk_mul_f32 v[116:117], v[116:117], v[108:109] op_sel_hi:[1,0]
	v_pk_mul_f32 v[118:119], v[118:119], v[108:109] op_sel_hi:[1,0]
	v_pk_mul_f32 v[120:121], v[120:121], v[108:109] op_sel_hi:[1,0]
	v_pk_mul_f32 v[122:123], v[122:123], v[108:109] op_sel_hi:[1,0]
	v_pk_mul_f32 v[124:125], v[124:125], v[108:109] op_sel_hi:[1,0]
	v_pk_mul_f32 v[100:101], v[100:101], v[108:109] op_sel_hi:[1,0]
	v_pk_mul_f32 v[112:113], v[112:113], v[208:209]
	v_pk_mul_f32 v[114:115], v[114:115], v[210:211]
	v_pk_mul_f32 v[116:117], v[116:117], v[212:213]
	v_pk_mul_f32 v[118:119], v[118:119], v[214:215]
	v_pk_mul_f32 v[120:121], v[120:121], v[216:217]
	v_pk_mul_f32 v[122:123], v[122:123], v[218:219]
	v_pk_mul_f32 v[124:125], v[124:125], v[220:221]
	v_pk_mul_f32 v[100:101], v[100:101], v[222:223]
	v_lshlrev_b32_e32 v60, 16, v52
	v_and_b32_e32 v61, 0xffff0000, v52
	v_lshlrev_b32_e32 v62, 16, v53
	v_and_b32_e32 v63, 0xffff0000, v53
	v_lshlrev_b32_e32 v64, 16, v54
	v_and_b32_e32 v65, 0xffff0000, v54
	v_lshlrev_b32_e32 v66, 16, v55
	v_and_b32_e32 v67, 0xffff0000, v55
	v_lshlrev_b32_e32 v240, 16, v56
	v_and_b32_e32 v241, 0xffff0000, v56
	v_lshlrev_b32_e32 v242, 16, v57
	v_and_b32_e32 v243, 0xffff0000, v57
	v_lshlrev_b32_e32 v244, 16, v58
	v_and_b32_e32 v245, 0xffff0000, v58
	v_lshlrev_b32_e32 v246, 16, v59
	v_and_b32_e32 v247, 0xffff0000, v59
	v_pk_mul_f32 v[60:61], v[60:61], v[110:111] op_sel_hi:[1,0]
	v_pk_mul_f32 v[62:63], v[62:63], v[110:111] op_sel_hi:[1,0]
	v_pk_mul_f32 v[64:65], v[64:65], v[110:111] op_sel_hi:[1,0]
	v_pk_mul_f32 v[66:67], v[66:67], v[110:111] op_sel_hi:[1,0]
	v_pk_mul_f32 v[240:241], v[240:241], v[110:111] op_sel_hi:[1,0]
	v_pk_mul_f32 v[242:243], v[242:243], v[110:111] op_sel_hi:[1,0]
	v_pk_mul_f32 v[244:245], v[244:245], v[110:111] op_sel_hi:[1,0]
	v_pk_mul_f32 v[246:247], v[246:247], v[110:111] op_sel_hi:[1,0]
	v_pk_mul_f32 v[60:61], v[60:61], v[176:177]
	v_pk_mul_f32 v[62:63], v[62:63], v[178:179]
	v_pk_mul_f32 v[64:65], v[64:65], v[180:181]
	v_pk_mul_f32 v[66:67], v[66:67], v[182:183]
	v_pk_mul_f32 v[240:241], v[240:241], v[184:185]
	v_pk_mul_f32 v[242:243], v[242:243], v[186:187]
	v_pk_mul_f32 v[244:245], v[244:245], v[188:189]
	v_pk_mul_f32 v[246:247], v[246:247], v[190:191]
	v_pk_fma_f32 v[36:37], v[160:161], v[60:61], v[36:37]
	v_pk_fma_f32 v[38:39], v[162:163], v[62:63], v[38:39]
	v_pk_fma_f32 v[40:41], v[164:165], v[64:65], v[40:41]
	v_pk_fma_f32 v[42:43], v[166:167], v[66:67], v[42:43]
	v_pk_fma_f32 v[44:45], v[168:169], v[240:241], v[44:45]
	v_pk_fma_f32 v[46:47], v[170:171], v[242:243], v[46:47]
	v_pk_fma_f32 v[48:49], v[172:173], v[244:245], v[48:49]
	v_pk_fma_f32 v[50:51], v[174:175], v[246:247], v[50:51]
	v_pk_fma_f32 v[36:37], v[192:193], v[112:113], v[36:37]
	v_pk_fma_f32 v[38:39], v[194:195], v[114:115], v[38:39]
	v_pk_fma_f32 v[40:41], v[196:197], v[116:117], v[40:41]
	v_pk_fma_f32 v[42:43], v[198:199], v[118:119], v[42:43]
	v_pk_fma_f32 v[44:45], v[200:201], v[120:121], v[44:45]
	v_pk_fma_f32 v[46:47], v[202:203], v[122:123], v[46:47]
	v_pk_fma_f32 v[48:49], v[204:205], v[124:125], v[48:49]
	v_pk_fma_f32 v[50:51], v[206:207], v[100:101], v[50:51]
	s_lshl_b32 s60, s55, 12
	s_add_u32 s72, s84, s60
	s_addc_u32 s73, s85, 0
	global_store_dwordx4 v0, v[36:39], s[72:73] sc1
	global_store_dwordx4 v0, v[40:43], s[72:73] offset:1024 sc1
	global_store_dwordx4 v0, v[44:47], s[72:73] offset:2048 sc1
	global_store_dwordx4 v0, v[48:51], s[72:73] offset:3072 sc1
	s_add_u32 s55, s55, 8
	s_add_u32 s57, s55, 16
	s_min_u32 s57, s57, s54
	s_lshl_b32 s60, s57, 12
	s_add_u32 s64, s84, s60
	s_addc_u32 s65, s85, 0
	s_lshl_b32 s60, s57, 11
	s_add_u32 s66, s82, s60
	s_addc_u32 s67, s83, 0
	s_lshl_b32 s60, s57, 11
	s_add_u32 s68, s78, s60
	s_addc_u32 s69, s79, 0
	global_load_dwordx4 v[36:39], v0, s[64:65] nt
	global_load_dwordx4 v[40:43], v0, s[64:65] offset:1024 nt
	global_load_dwordx4 v[44:47], v0, s[64:65] offset:2048 nt
	global_load_dwordx4 v[48:51], v0, s[64:65] offset:3072 nt
	global_load_dwordx2 v[52:53], v1, s[66:67] nt
	global_load_dwordx2 v[54:55], v1, s[66:67] offset:512 nt
	global_load_dwordx2 v[56:57], v1, s[66:67] offset:1024 nt
	global_load_dwordx2 v[58:59], v1, s[66:67] offset:1536 nt
	global_load_dwordx2 v[60:61], v1, s[68:69] nt
	global_load_dwordx2 v[62:63], v1, s[68:69] offset:512 nt
	global_load_dwordx2 v[64:65], v1, s[68:69] offset:1024 nt
	global_load_dwordx2 v[66:67], v1, s[68:69] offset:1536 nt
	s_lshr_b32 s60, s55, 11
	s_sub_u32 s61, s55, 0x8000
	s_lshr_b32 s61, s61, 12
	s_add_u32 s61, s61, 16
	s_cmp_lt_u32 s55, 0x8000
	s_cselect_b32 s63, s60, s61
	s_cmp_eq_u32 s63, s56
	s_cbranch_scc1 .Lrp15_pk6
	s_mov_b32 s56, s63
	s_mul_i32 s60, s56, 0x9000
	s_add_u32 s60, s60, 0x3185000
	s_add_u32 s0, s92, s60
	s_addc_u32 s1, s93, 0
	global_load_dwordx4 v[160:163], v0, s[0:1]
	global_load_dwordx4 v[164:167], v0, s[0:1] offset:1024
	global_load_dwordx4 v[168:171], v0, s[0:1] offset:2048
	global_load_dwordx4 v[172:175], v0, s[0:1] offset:3072
	s_add_u32 s0, s22, 0x1000
	s_addc_u32 s1, s23, 0
	global_load_dwordx4 v[176:179], v0, s[0:1]
	global_load_dwordx4 v[180:183], v0, s[0:1] offset:1024
	global_load_dwordx4 v[184:187], v0, s[0:1] offset:2048
	global_load_dwordx4 v[188:191], v0, s[0:1] offset:3072
	s_mul_i32 s60, s56, 0x9000
	s_add_u32 s60, s60, 0x3188000
	s_add_u32 s0, s92, s60
	s_addc_u32 s1, s93, 0
	global_load_dwordx4 v[192:195], v0, s[0:1]
	global_load_dwordx4 v[196:199], v0, s[0:1] offset:1024
	global_load_dwordx4 v[200:203], v0, s[0:1] offset:2048
	global_load_dwordx4 v[204:207], v0, s[0:1] offset:3072
	s_add_u32 s0, s22, 0x2000
	s_addc_u32 s1, s23, 0
	global_load_dwordx4 v[208:211], v0, s[0:1]
	global_load_dwordx4 v[212:215], v0, s[0:1] offset:1024
	global_load_dwordx4 v[216:219], v0, s[0:1] offset:2048
	global_load_dwordx4 v[220:223], v0, s[0:1] offset:3072
	s_waitcnt vmcnt(0)
; __device__ __forceinline__ float lo_bf(unsigned w) { return __uint_as_float(w << 16); }
; __device__ __forceinline__ float hi_bf(unsigned w) { return __uint_as_float(w & 0xffff0000u); }
; __device__ __forceinline__ void phase_final(const Params& p) {
;     ...
;         f32x4 v[4], m[4], f[4]; float sm = 0.f, sf = 0.f;
; #pragma unroll
;         for (int j = 0; j < 4; ++j) { v[j] = *(const f32x4*)(p.out + (size_t)row * D + 4 * lane + 256 * j);
;             const u32x2 wm = *(const u32x2*)(Fm + (size_t)row * D + 4 * lane + 256 * j), wf = *(const u32x2*)(F2 + (size_t)row * D + 4 * lane + 256 * j);
;             m[j] = (f32x4){lo_bf(wm.x), hi_bf(wm.x), lo_bf(wm.y), hi_bf(wm.y)}; f[j] = (f32x4){lo_bf(wf.x), hi_bf(wf.x), lo_bf(wf.y), hi_bf(wf.y)};
;             sm += (m[j].x * m[j].x + m[j].y * m[j].y) + (m[j].z * m[j].z + m[j].w * m[j].w); sf += (f[j].x * f[j].x + f[j].y * f[j].y) + (f[j].z * f[j].z + f[j].w * f[j].w); }
;         const float rm = 1.0f / sqrtf(wave_sum(sm) * (1.0f / D) + EPS), rf = 1.0f / sqrtf(wave_sum(sf) * (1.0f / D) + EPS) * 0.5f;
.Lrp15_pk6:
	s_waitcnt vmcnt(32)
	v_lshlrev_b32_e32 v112, 16, v84
	v_and_b32_e32 v113, 0xffff0000, v84
	v_lshlrev_b32_e32 v114, 16, v85
	v_and_b32_e32 v115, 0xffff0000, v85
	v_lshlrev_b32_e32 v116, 16, v86
	v_and_b32_e32 v117, 0xffff0000, v86
	v_lshlrev_b32_e32 v118, 16, v87
	v_and_b32_e32 v119, 0xffff0000, v87
	v_lshlrev_b32_e32 v120, 16, v88
	v_and_b32_e32 v121, 0xffff0000, v88
	v_lshlrev_b32_e32 v122, 16, v89
	v_and_b32_e32 v123, 0xffff0000, v89
	v_lshlrev_b32_e32 v124, 16, v90
	v_and_b32_e32 v125, 0xffff0000, v90
	v_lshlrev_b32_e32 v100, 16, v91
	v_and_b32_e32 v101, 0xffff0000, v91
	v_pk_mul_f32 v[102:103], v[112:113], v[112:113]
	v_pk_mul_f32 v[106:107], v[114:115], v[114:115]
	v_pk_fma_f32 v[102:103], v[116:117], v[116:117], v[102:103]
	v_pk_fma_f32 v[106:107], v[118:119], v[118:119], v[106:107]
	v_pk_fma_f32 v[102:103], v[120:121], v[120:121], v[102:103]
	v_pk_fma_f32 v[106:107], v[122:123], v[122:123], v[106:107]
	v_pk_fma_f32 v[102:103], v[124:125], v[124:125], v[102:103]
	v_pk_fma_f32 v[106:107], v[100:101], v[100:101], v[106:107]
	s_nop 0
	v_pk_add_f32 v[102:103], v[102:103], v[106:107]
	s_nop 0
	v_add_f32_e32 v102, v102, v103
	v_mov_b32_e32 v104, v102
	v_lshlrev_b32_e32 v112, 16, v92
	v_and_b32_e32 v113, 0xffff0000, v92
	v_lshlrev_b32_e32 v114, 16, v93
	v_and_b32_e32 v115, 0xffff0000, v93
	v_lshlrev_b32_e32 v116, 16, v94
	v_and_b32_e32 v117, 0xffff0000, v94
	v_lshlrev_b32_e32 v118, 16, v95
	v_and_b32_e32 v119, 0xffff0000, v95
	v_lshlrev_b32_e32 v120, 16, v96
	v_and_b32_e32 v121, 0xffff0000, v96
	v_lshlrev_b32_e32 v122, 16, v97
	v_and_b32_e32 v123, 0xffff0000, v97
	v_lshlrev_b32_e32 v124, 16, v98
	v_and_b32_e32 v125, 0xffff0000, v98
	v_lshlrev_b32_e32 v100, 16, v99
	v_and_b32_e32 v101, 0xffff0000, v99
	v_pk_mul_f32 v[102:103], v[112:113], v[112:113]
	v_pk_mul_f32 v[106:107], v[114:115], v[114:115]
	v_pk_fma_f32 v[102:103], v[116:117], v[116:117], v[102:103]
	v_pk_fma_f32 v[106:107], v[118:119], v[118:119], v[106:107]
	v_pk_fma_f32 v[102:103], v[120:121], v[120:121], v[102:103]
	v_pk_fma_f32 v[106:107], v[122:123], v[122:123], v[106:107]
	v_pk_fma_f32 v[102:103], v[124:125], v[124:125], v[102:103]
	v_pk_fma_f32 v[106:107], v[100:101], v[100:101], v[106:107]
	s_nop 0
	v_pk_add_f32 v[102:103], v[102:103], v[106:107]
	s_nop 0
	v_add_f32_e32 v102, v102, v103
	s_nop 1
	v_add_f32_dpp v104, v104, v104 quad_perm:[1,0,3,2] row_mask:0xf bank_mask:0xf
	v_add_f32_dpp v102, v102, v102 quad_perm:[1,0,3,2] row_mask:0xf bank_mask:0xf
	s_nop 1
	v_add_f32_dpp v104, v104, v104 quad_perm:[2,3,0,1] row_mask:0xf bank_mask:0xf
	v_add_f32_dpp v102, v102, v102 quad_perm:[2,3,0,1] row_mask:0xf bank_mask:0xf
	s_nop 1
	v_add_f32_dpp v104, v104, v104 row_half_mirror row_mask:0xf bank_mask:0xf
	v_add_f32_dpp v102, v102, v102 row_half_mirror row_mask:0xf bank_mask:0xf
	s_nop 1
	v_add_f32_dpp v104, v104, v104 row_mirror row_mask:0xf bank_mask:0xf
	v_add_f32_dpp v102, v102, v102 row_mirror row_mask:0xf bank_mask:0xf
	s_nop 1
	v_add_f32_dpp v104, v104, v104 row_bcast:15 row_mask:0xa bank_mask:0xf
	v_add_f32_dpp v102, v102, v102 row_bcast:15 row_mask:0xa bank_mask:0xf
	s_nop 1
	v_add_f32_dpp v104, v104, v104 row_bcast:31 row_mask:0xc bank_mask:0xf
	v_add_f32_dpp v102, v102, v102 row_bcast:31 row_mask:0xc bank_mask:0xf
	s_nop 1
	v_readlane_b32 s74, v104, 63
	v_readlane_b32 s75, v102, 63
	s_nop 2
	v_mov_b32_e32 v102, s74
	v_fmamk_f32 v102, v102, 0x3a800000, v2
	v_mul_f32_e32 v103, 0x4f800000, v102
	v_cmp_gt_f32_e32 vcc, 0xf800000, v102
	s_nop 1
	v_cndmask_b32_e32 v102, v102, v103, vcc
	v_sqrt_f32_e32 v103, v102
	s_nop 0
	v_add_u32_e32 v104, -1, v103
	v_add_u32_e32 v106, 1, v103
	v_fma_f32 v107, -v104, v103, v102
	v_fma_f32 v108, -v106, v103, v102
	v_cmp_ge_f32_e64 s[76:77], 0, v107
	s_nop 1
	v_cndmask_b32_e64 v103, v103, v104, s[76:77]
	v_cmp_lt_f32_e64 s[76:77], 0, v108
	s_nop 1
	v_cndmask_b32_e64 v103, v103, v106, s[76:77]
	v_mul_f32_e32 v104, 0x37800000, v103
	v_cndmask_b32_e32 v103, v103, v104, vcc
	v_cmp_class_f32_e32 vcc, v102, v3
	s_nop 1
	v_cndmask_b32_e32 v102, v103, v102, vcc
	v_div_scale_f32 v103, s[76:77], v102, v102, 1.0
	v_rcp_f32_e32 v104, v103
	v_div_scale_f32 v106, vcc, 1.0, v102, 1.0
	v_fma_f32 v107, -v103, v104, 1.0
	v_fmac_f32_e32 v104, v107, v104
	v_mul_f32_e32 v107, v106, v104
	v_fma_f32 v108, -v103, v107, v106
	v_fmac_f32_e32 v107, v108, v104
	v_fma_f32 v103, -v103, v107, v106
	v_div_fmas_f32 v103, v103, v104, v107
	v_div_fixup_f32 v110, v103, v102, 1.0
	v_mov_b32_e32 v102, s75
	v_fmamk_f32 v102, v102, 0x3a800000, v2
	v_mul_f32_e32 v103, 0x4f800000, v102
	v_cmp_gt_f32_e32 vcc, 0xf800000, v102
; __device__ __forceinline__ void phase_final(const Params& p) {
;     ...
;         const float rm = 1.0f / sqrtf(wave_sum(sm) * (1.0f / D) + EPS), rf = 1.0f / sqrtf(wave_sum(sf) * (1.0f / D) + EPS) * 0.5f;
;         const float* g1 = mod + b * 9216 + 1 * 3072 + 2048; const float* g2 = mod + b * 9216 + 2 * 3072 + 2048;
;         const float* q1 = p.in[7] + 1 * D; const float* q2 = p.in[7] + 2 * D;
; #pragma unroll
;         for (int j = 0; j < 4; ++j) { const int c = 4 * lane + 256 * j;
;             const f32x4 x2 = v[j] + *(const f32x4*)(g1 + c) * (m[j] * rm * *(const f32x4*)(q1 + c));
;             *(f32x4*)(p.out + (size_t)row * D + c) = x2 + *(const f32x4*)(g2 + c) * (f[j] * rf * *(const f32x4*)(q2 + c)); }
	s_nop 1
	v_cndmask_b32_e32 v102, v102, v103, vcc
	v_sqrt_f32_e32 v103, v102
	s_nop 0
	v_add_u32_e32 v104, -1, v103
	v_add_u32_e32 v106, 1, v103
	v_fma_f32 v107, -v104, v103, v102
	v_fma_f32 v108, -v106, v103, v102
	v_cmp_ge_f32_e64 s[76:77], 0, v107
	s_nop 1
	v_cndmask_b32_e64 v103, v103, v104, s[76:77]
	v_cmp_lt_f32_e64 s[76:77], 0, v108
	s_nop 1
	v_cndmask_b32_e64 v103, v103, v106, s[76:77]
	v_mul_f32_e32 v104, 0x37800000, v103
	v_cndmask_b32_e32 v103, v103, v104, vcc
	v_cmp_class_f32_e32 vcc, v102, v3
	s_nop 1
	v_cndmask_b32_e32 v102, v103, v102, vcc
	v_div_scale_f32 v103, s[76:77], v102, v102, 1.0
	v_rcp_f32_e32 v104, v103
	v_div_scale_f32 v106, vcc, 1.0, v102, 1.0
	v_fma_f32 v107, -v103, v104, 1.0
	v_fmac_f32_e32 v104, v107, v104
	v_mul_f32_e32 v107, v106, v104
	v_fma_f32 v108, -v103, v107, v106
	v_fmac_f32_e32 v107, v108, v104
	v_fma_f32 v103, -v103, v107, v106
	v_div_fmas_f32 v103, v103, v104, v107
	v_div_fixup_f32 v108, v103, v102, 1.0
	v_mul_f32_e32 v108, 0.5, v108
	v_pk_mul_f32 v[112:113], v[112:113], v[108:109] op_sel_hi:[1,0]
	v_pk_mul_f32 v[114:115], v[114:115], v[108:109] op_sel_hi:[1,0]
	v_pk_mul_f32 v[116:117], v[116:117], v[108:109] op_sel_hi:[1,0]
	v_pk_mul_f32 v[118:119], v[118:119], v[108:109] op_sel_hi:[1,0]
	v_pk_mul_f32 v[120:121], v[120:121], v[108:109] op_sel_hi:[1,0]
	v_pk_mul_f32 v[122:123], v[122:123], v[108:109] op_sel_hi:[1,0]
	v_pk_mul_f32 v[124:125], v[124:125], v[108:109] op_sel_hi:[1,0]
	v_pk_mul_f32 v[100:101], v[100:101], v[108:109] op_sel_hi:[1,0]
	v_pk_mul_f32 v[112:113], v[112:113], v[208:209]
	v_pk_mul_f32 v[114:115], v[114:115], v[210:211]
	v_pk_mul_f32 v[116:117], v[116:117], v[212:213]
	v_pk_mul_f32 v[118:119], v[118:119], v[214:215]
	v_pk_mul_f32 v[120:121], v[120:121], v[216:217]
	v_pk_mul_f32 v[122:123], v[122:123], v[218:219]
	v_pk_mul_f32 v[124:125], v[124:125], v[220:221]
	v_pk_mul_f32 v[100:101], v[100:101], v[222:223]
	v_lshlrev_b32_e32 v92, 16, v84
	v_and_b32_e32 v93, 0xffff0000, v84
	v_lshlrev_b32_e32 v94, 16, v85
	v_and_b32_e32 v95, 0xffff0000, v85
	v_lshlrev_b32_e32 v96, 16, v86
	v_and_b32_e32 v97, 0xffff0000, v86
	v_lshlrev_b32_e32 v98, 16, v87
	v_and_b32_e32 v99, 0xffff0000, v87
	v_lshlrev_b32_e32 v240, 16, v88
	v_and_b32_e32 v241, 0xffff0000, v88
	v_lshlrev_b32_e32 v242, 16, v89
	v_and_b32_e32 v243, 0xffff0000, v89
	v_lshlrev_b32_e32 v244, 16, v90
	v_and_b32_e32 v245, 0xffff0000, v90
	v_lshlrev_b32_e32 v246, 16, v91
	v_and_b32_e32 v247, 0xffff0000, v91
	v_pk_mul_f32 v[92:93], v[92:93], v[110:111] op_sel_hi:[1,0]
	v_pk_mul_f32 v[94:95], v[94:95], v[110:111] op_sel_hi:[1,0]
	v_pk_mul_f32 v[96:97], v[96:97], v[110:111] op_sel_hi:[1,0]
	v_pk_mul_f32 v[98:99], v[98:99], v[110:111] op_sel_hi:[1,0]
	v_pk_mul_f32 v[240:241], v[240:241], v[110:111] op_sel_hi:[1,0]
	v_pk_mul_f32 v[242:243], v[242:243], v[110:111] op_sel_hi:[1,0]
	v_pk_mul_f32 v[244:245], v[244:245], v[110:111] op_sel_hi:[1,0]
	v_pk_mul_f32 v[246:247], v[246:247], v[110:111] op_sel_hi:[1,0]
	v_pk_mul_f32 v[92:93], v[92:93], v[176:177]
	v_pk_mul_f32 v[94:95], v[94:95], v[178:179]
	v_pk_mul_f32 v[96:97], v[96:97], v[180:181]
	v_pk_mul_f32 v[98:99], v[98:99], v[182:183]
	v_pk_mul_f32 v[240:241], v[240:241], v[184:185]
	v_pk_mul_f32 v[242:243], v[242:243], v[186:187]
	v_pk_mul_f32 v[244:245], v[244:245], v[188:189]
	v_pk_mul_f32 v[246:247], v[246:247], v[190:191]
	v_pk_fma_f32 v[68:69], v[160:161], v[92:93], v[68:69]
	v_pk_fma_f32 v[70:71], v[162:163], v[94:95], v[70:71]
	v_pk_fma_f32 v[72:73], v[164:165], v[96:97], v[72:73]
	v_pk_fma_f32 v[74:75], v[166:167], v[98:99], v[74:75]
	v_pk_fma_f32 v[76:77], v[168:169], v[240:241], v[76:77]
	v_pk_fma_f32 v[78:79], v[170:171], v[242:243], v[78:79]
	v_pk_fma_f32 v[80:81], v[172:173], v[244:245], v[80:81]
	v_pk_fma_f32 v[82:83], v[174:175], v[246:247], v[82:83]
	v_pk_fma_f32 v[68:69], v[192:193], v[112:113], v[68:69]
	v_pk_fma_f32 v[70:71], v[194:195], v[114:115], v[70:71]
	v_pk_fma_f32 v[72:73], v[196:197], v[116:117], v[72:73]
	v_pk_fma_f32 v[74:75], v[198:199], v[118:119], v[74:75]
	v_pk_fma_f32 v[76:77], v[200:201], v[120:121], v[76:77]
	v_pk_fma_f32 v[78:79], v[202:203], v[122:123], v[78:79]
	v_pk_fma_f32 v[80:81], v[204:205], v[124:125], v[80:81]
	v_pk_fma_f32 v[82:83], v[206:207], v[100:101], v[82:83]
	s_lshl_b32 s60, s55, 12
	s_add_u32 s72, s84, s60
	s_addc_u32 s73, s85, 0
	global_store_dwordx4 v0, v[68:71], s[72:73] sc1
	global_store_dwordx4 v0, v[72:75], s[72:73] offset:1024 sc1
	global_store_dwordx4 v0, v[76:79], s[72:73] offset:2048 sc1
	global_store_dwordx4 v0, v[80:83], s[72:73] offset:3072 sc1
	s_add_u32 s55, s55, 8

; __device__ __forceinline__ float lo_bf(unsigned w) { return __uint_as_float(w << 16); }
; __device__ __forceinline__ float hi_bf(unsigned w) { return __uint_as_float(w & 0xffff0000u); }
; __device__ __forceinline__ void phase_final(const Params& p) {
;     ...
;         f32x4 v[4], m[4], f[4]; float sm = 0.f, sf = 0.f;
; #pragma unroll
;         for (int j = 0; j < 4; ++j) { v[j] = *(const f32x4*)(p.out + (size_t)row * D + 4 * lane + 256 * j);
;             const u32x2 wm = *(const u32x2*)(Fm + (size_t)row * D + 4 * lane + 256 * j), wf = *(const u32x2*)(F2 + (size_t)row * D + 4 * lane + 256 * j);
;             m[j] = (f32x4){lo_bf(wm.x), hi_bf(wm.x), lo_bf(wm.y), hi_bf(wm.y)}; f[j] = (f32x4){lo_bf(wf.x), hi_bf(wf.x), lo_bf(wf.y), hi_bf(wf.y)};
;             sm += (m[j].x * m[j].x + m[j].y * m[j].y) + (m[j].z * m[j].z + m[j].w * m[j].w); sf += (f[j].x * f[j].x + f[j].y * f[j].y) + (f[j].z * f[j].z + f[j].w * f[j].w); }
;         const float rm = 1.0f / sqrtf(wave_sum(sm) * (1.0f / D) + EPS), rf = 1.0f / sqrtf(wave_sum(sf) * (1.0f / D) + EPS) * 0.5f;
.Lrp15_pk7:
	s_waitcnt vmcnt(32)
	v_lshlrev_b32_e32 v112, 16, v20
	v_and_b32_e32 v113, 0xffff0000, v20
	v_lshlrev_b32_e32 v114, 16, v21
	v_and_b32_e32 v115, 0xffff0000, v21
	v_lshlrev_b32_e32 v116, 16, v22
	v_and_b32_e32 v117, 0xffff0000, v22
	v_lshlrev_b32_e32 v118, 16, v23
	v_and_b32_e32 v119, 0xffff0000, v23
	v_lshlrev_b32_e32 v120, 16, v24
	v_and_b32_e32 v121, 0xffff0000, v24
	v_lshlrev_b32_e32 v122, 16, v25
	v_and_b32_e32 v123, 0xffff0000, v25
	v_lshlrev_b32_e32 v124, 16, v26
	v_and_b32_e32 v125, 0xffff0000, v26
	v_lshlrev_b32_e32 v100, 16, v27
	v_and_b32_e32 v101, 0xffff0000, v27
	v_pk_mul_f32 v[102:103], v[112:113], v[112:113]
	v_pk_mul_f32 v[106:107], v[114:115], v[114:115]
	v_pk_fma_f32 v[102:103], v[116:117], v[116:117], v[102:103]
	v_pk_fma_f32 v[106:107], v[118:119], v[118:119], v[106:107]
	v_pk_fma_f32 v[102:103], v[120:121], v[120:121], v[102:103]
	v_pk_fma_f32 v[106:107], v[122:123], v[122:123], v[106:107]
	v_pk_fma_f32 v[102:103], v[124:125], v[124:125], v[102:103]
	v_pk_fma_f32 v[106:107], v[100:101], v[100:101], v[106:107]
	s_nop 0
	v_pk_add_f32 v[102:103], v[102:103], v[106:107]
	s_nop 0
	v_add_f32_e32 v102, v102, v103
	v_mov_b32_e32 v104, v102
	v_lshlrev_b32_e32 v112, 16, v28
	v_and_b32_e32 v113, 0xffff0000, v28
	v_lshlrev_b32_e32 v114, 16, v29
	v_and_b32_e32 v115, 0xffff0000, v29
	v_lshlrev_b32_e32 v116, 16, v30
	v_and_b32_e32 v117, 0xffff0000, v30
	v_lshlrev_b32_e32 v118, 16, v31
	v_and_b32_e32 v119, 0xffff0000, v31
	v_lshlrev_b32_e32 v120, 16, v32
	v_and_b32_e32 v121, 0xffff0000, v32
	v_lshlrev_b32_e32 v122, 16, v33
	v_and_b32_e32 v123, 0xffff0000, v33
	v_lshlrev_b32_e32 v124, 16, v34
	v_and_b32_e32 v125, 0xffff0000, v34
	v_lshlrev_b32_e32 v100, 16, v35
	v_and_b32_e32 v101, 0xffff0000, v35
	v_pk_mul_f32 v[102:103], v[112:113], v[112:113]
	v_pk_mul_f32 v[106:107], v[114:115], v[114:115]
	v_pk_fma_f32 v[102:103], v[116:117], v[116:117], v[102:103]
	v_pk_fma_f32 v[106:107], v[118:119], v[118:119], v[106:107]
	v_pk_fma_f32 v[102:103], v[120:121], v[120:121], v[102:103]
	v_pk_fma_f32 v[106:107], v[122:123], v[122:123], v[106:107]
	v_pk_fma_f32 v[102:103], v[124:125], v[124:125], v[102:103]
	v_pk_fma_f32 v[106:107], v[100:101], v[100:101], v[106:107]
	s_nop 0
	v_pk_add_f32 v[102:103], v[102:103], v[106:107]
	s_nop 0
	v_add_f32_e32 v102, v102, v103
	s_nop 1
	v_add_f32_dpp v104, v104, v104 quad_perm:[1,0,3,2] row_mask:0xf bank_mask:0xf
	v_add_f32_dpp v102, v102, v102 quad_perm:[1,0,3,2] row_mask:0xf bank_mask:0xf
	s_nop 1
	v_add_f32_dpp v104, v104, v104 quad_perm:[2,3,0,1] row_mask:0xf bank_mask:0xf
	v_add_f32_dpp v102, v102, v102 quad_perm:[2,3,0,1] row_mask:0xf bank_mask:0xf
	s_nop 1
	v_add_f32_dpp v104, v104, v104 row_half_mirror row_mask:0xf bank_mask:0xf
	v_add_f32_dpp v102, v102, v102 row_half_mirror row_mask:0xf bank_mask:0xf
	s_nop 1
	v_add_f32_dpp v104, v104, v104 row_mirror row_mask:0xf bank_mask:0xf
	v_add_f32_dpp v102, v102, v102 row_mirror row_mask:0xf bank_mask:0xf
	s_nop 1
	v_add_f32_dpp v104, v104, v104 row_bcast:15 row_mask:0xa bank_mask:0xf
	v_add_f32_dpp v102, v102, v102 row_bcast:15 row_mask:0xa bank_mask:0xf
	s_nop 1
	v_add_f32_dpp v104, v104, v104 row_bcast:31 row_mask:0xc bank_mask:0xf
	v_add_f32_dpp v102, v102, v102 row_bcast:31 row_mask:0xc bank_mask:0xf
	s_nop 1
	v_readlane_b32 s74, v104, 63
	v_readlane_b32 s75, v102, 63
	s_nop 2
	v_mov_b32_e32 v102, s74
	v_fmamk_f32 v102, v102, 0x3a800000, v2
	v_mul_f32_e32 v103, 0x4f800000, v102
	v_cmp_gt_f32_e32 vcc, 0xf800000, v102
	s_nop 1
	v_cndmask_b32_e32 v102, v102, v103, vcc
	v_sqrt_f32_e32 v103, v102
	s_nop 0
	v_add_u32_e32 v104, -1, v103
	v_add_u32_e32 v106, 1, v103
	v_fma_f32 v107, -v104, v103, v102
	v_fma_f32 v108, -v106, v103, v102
	v_cmp_ge_f32_e64 s[76:77], 0, v107
	s_nop 1
	v_cndmask_b32_e64 v103, v103, v104, s[76:77]
	v_cmp_lt_f32_e64 s[76:77], 0, v108
	s_nop 1
	v_cndmask_b32_e64 v103, v103, v106, s[76:77]
	v_mul_f32_e32 v104, 0x37800000, v103
	v_cndmask_b32_e32 v103, v103, v104, vcc
	v_cmp_class_f32_e32 vcc, v102, v3
	s_nop 1
	v_cndmask_b32_e32 v102, v103, v102, vcc
	v_div_scale_f32 v103, s[76:77], v102, v102, 1.0
	v_rcp_f32_e32 v104, v103
	v_div_scale_f32 v106, vcc, 1.0, v102, 1.0
	v_fma_f32 v107, -v103, v104, 1.0
	v_fmac_f32_e32 v104, v107, v104
	v_mul_f32_e32 v107, v106, v104
	v_fma_f32 v108, -v103, v107, v106
	v_fmac_f32_e32 v107, v108, v104
	v_fma_f32 v103, -v103, v107, v106
	v_div_fmas_f32 v103, v103, v104, v107
	v_div_fixup_f32 v110, v103, v102, 1.0
	v_mov_b32_e32 v102, s75
	v_fmamk_f32 v102, v102, 0x3a800000, v2
	v_mul_f32_e32 v103, 0x4f800000, v102
	v_cmp_gt_f32_e32 vcc, 0xf800000, v102
	s_nop 1
	v_cndmask_b32_e32 v102, v102, v103, vcc
	v_sqrt_f32_e32 v103, v102
	s_nop 0
	v_add_u32_e32 v104, -1, v103
	v_add_u32_e32 v106, 1, v103
	v_fma_f32 v107, -v104, v103, v102
	v_fma_f32 v108, -v106, v103, v102
	v_cmp_ge_f32_e64 s[76:77], 0, v107
	s_nop 1
	v_cndmask_b32_e64 v103, v103, v104, s[76:77]
	v_cmp_lt_f32_e64 s[76:77], 0, v108
	s_nop 1
	v_cndmask_b32_e64 v103, v103, v106, s[76:77]
	v_mul_f32_e32 v104, 0x37800000, v103
	v_cndmask_b32_e32 v103, v103, v104, vcc
	v_cmp_class_f32_e32 vcc, v102, v3
	s_nop 1
	v_cndmask_b32_e32 v102, v103, v102, vcc
	v_div_scale_f32 v103, s[76:77], v102, v102, 1.0
	v_rcp_f32_e32 v104, v103
	v_div_scale_f32 v106, vcc, 1.0, v102, 1.0
	v_fma_f32 v107, -v103, v104, 1.0
	v_fmac_f32_e32 v104, v107, v104
	v_mul_f32_e32 v107, v106, v104
	v_fma_f32 v108, -v103, v107, v106
	v_fmac_f32_e32 v107, v108, v104
	v_fma_f32 v103, -v103, v107, v106
	v_div_fmas_f32 v103, v103, v104, v107
	v_div_fixup_f32 v108, v103, v102, 1.0
	v_mul_f32_e32 v108, 0.5, v108
	v_pk_mul_f32 v[112:113], v[112:113], v[108:109] op_sel_hi:[1,0]
; __device__ __forceinline__ float lo_bf(unsigned w) { return __uint_as_float(w << 16); }
; __device__ __forceinline__ float hi_bf(unsigned w) { return __uint_as_float(w & 0xffff0000u); }
; __device__ __forceinline__ void phase_final(const Params& p) {
;     ...
;     for (int row = gw; row < T; row += NGW) {
;         const int b = row_batch(row);
;         f32x4 v[4], m[4], f[4]; float sm = 0.f, sf = 0.f;
; #pragma unroll
;         for (int j = 0; j < 4; ++j) { v[j] = *(const f32x4*)(p.out + (size_t)row * D + 4 * lane + 256 * j);
;             const u32x2 wm = *(const u32x2*)(Fm + (size_t)row * D + 4 * lane + 256 * j), wf = *(const u32x2*)(F2 + (size_t)row * D + 4 * lane + 256 * j);
;             m[j] = (f32x4){lo_bf(wm.x), hi_bf(wm.x), lo_bf(wm.y), hi_bf(wm.y)}; f[j] = (f32x4){lo_bf(wf.x), hi_bf(wf.x), lo_bf(wf.y), hi_bf(wf.y)};
;             sm += (m[j].x * m[j].x + m[j].y * m[j].y) + (m[j].z * m[j].z + m[j].w * m[j].w); sf += (f[j].x * f[j].x + f[j].y * f[j].y) + (f[j].z * f[j].z + f[j].w * f[j].w); }
;         const float rm = 1.0f / sqrtf(wave_sum(sm) * (1.0f / D) + EPS), rf = 1.0f / sqrtf(wave_sum(sf) * (1.0f / D) + EPS) * 0.5f;
;         const float* g1 = mod + b * 9216 + 1 * 3072 + 2048; const float* g2 = mod + b * 9216 + 2 * 3072 + 2048;
;         const float* q1 = p.in[7] + 1 * D; const float* q2 = p.in[7] + 2 * D;
; #pragma unroll
;         for (int j = 0; j < 4; ++j) { const int c = 4 * lane + 256 * j;
;             const f32x4 x2 = v[j] + *(const f32x4*)(g1 + c) * (m[j] * rm * *(const f32x4*)(q1 + c));
;             *(f32x4*)(p.out + (size_t)row * D + c) = x2 + *(const f32x4*)(g2 + c) * (f[j] * rf * *(const f32x4*)(q2 + c)); }
;     }
	v_pk_mul_f32 v[114:115], v[114:115], v[108:109] op_sel_hi:[1,0]
	v_pk_mul_f32 v[116:117], v[116:117], v[108:109] op_sel_hi:[1,0]
	v_pk_mul_f32 v[118:119], v[118:119], v[108:109] op_sel_hi:[1,0]
	v_pk_mul_f32 v[120:121], v[120:121], v[108:109] op_sel_hi:[1,0]
	v_pk_mul_f32 v[122:123], v[122:123], v[108:109] op_sel_hi:[1,0]
	v_pk_mul_f32 v[124:125], v[124:125], v[108:109] op_sel_hi:[1,0]
	v_pk_mul_f32 v[100:101], v[100:101], v[108:109] op_sel_hi:[1,0]
	v_pk_mul_f32 v[112:113], v[112:113], v[208:209]
	v_pk_mul_f32 v[114:115], v[114:115], v[210:211]
	v_pk_mul_f32 v[116:117], v[116:117], v[212:213]
	v_pk_mul_f32 v[118:119], v[118:119], v[214:215]
	v_pk_mul_f32 v[120:121], v[120:121], v[216:217]
	v_pk_mul_f32 v[122:123], v[122:123], v[218:219]
	v_pk_mul_f32 v[124:125], v[124:125], v[220:221]
	v_pk_mul_f32 v[100:101], v[100:101], v[222:223]
	v_lshlrev_b32_e32 v28, 16, v20
	v_and_b32_e32 v29, 0xffff0000, v20
	v_lshlrev_b32_e32 v30, 16, v21
	v_and_b32_e32 v31, 0xffff0000, v21
	v_lshlrev_b32_e32 v32, 16, v22
	v_and_b32_e32 v33, 0xffff0000, v22
	v_lshlrev_b32_e32 v34, 16, v23
	v_and_b32_e32 v35, 0xffff0000, v23
	v_lshlrev_b32_e32 v240, 16, v24
	v_and_b32_e32 v241, 0xffff0000, v24
	v_lshlrev_b32_e32 v242, 16, v25
	v_and_b32_e32 v243, 0xffff0000, v25
	v_lshlrev_b32_e32 v244, 16, v26
	v_and_b32_e32 v245, 0xffff0000, v26
	v_lshlrev_b32_e32 v246, 16, v27
	v_and_b32_e32 v247, 0xffff0000, v27
	v_pk_mul_f32 v[28:29], v[28:29], v[110:111] op_sel_hi:[1,0]
	v_pk_mul_f32 v[30:31], v[30:31], v[110:111] op_sel_hi:[1,0]
	v_pk_mul_f32 v[32:33], v[32:33], v[110:111] op_sel_hi:[1,0]
	v_pk_mul_f32 v[34:35], v[34:35], v[110:111] op_sel_hi:[1,0]
	v_pk_mul_f32 v[240:241], v[240:241], v[110:111] op_sel_hi:[1,0]
	v_pk_mul_f32 v[242:243], v[242:243], v[110:111] op_sel_hi:[1,0]
	v_pk_mul_f32 v[244:245], v[244:245], v[110:111] op_sel_hi:[1,0]
	v_pk_mul_f32 v[246:247], v[246:247], v[110:111] op_sel_hi:[1,0]
	v_pk_mul_f32 v[28:29], v[28:29], v[176:177]
	v_pk_mul_f32 v[30:31], v[30:31], v[178:179]
	v_pk_mul_f32 v[32:33], v[32:33], v[180:181]
	v_pk_mul_f32 v[34:35], v[34:35], v[182:183]
	v_pk_mul_f32 v[240:241], v[240:241], v[184:185]
	v_pk_mul_f32 v[242:243], v[242:243], v[186:187]
	v_pk_mul_f32 v[244:245], v[244:245], v[188:189]
	v_pk_mul_f32 v[246:247], v[246:247], v[190:191]
	v_pk_fma_f32 v[4:5], v[160:161], v[28:29], v[4:5]
	v_pk_fma_f32 v[6:7], v[162:163], v[30:31], v[6:7]
	v_pk_fma_f32 v[8:9], v[164:165], v[32:33], v[8:9]
	v_pk_fma_f32 v[10:11], v[166:167], v[34:35], v[10:11]
	v_pk_fma_f32 v[12:13], v[168:169], v[240:241], v[12:13]
	v_pk_fma_f32 v[14:15], v[170:171], v[242:243], v[14:15]
	v_pk_fma_f32 v[16:17], v[172:173], v[244:245], v[16:17]
	v_pk_fma_f32 v[18:19], v[174:175], v[246:247], v[18:19]
	v_pk_fma_f32 v[4:5], v[192:193], v[112:113], v[4:5]
	v_pk_fma_f32 v[6:7], v[194:195], v[114:115], v[6:7]
	v_pk_fma_f32 v[8:9], v[196:197], v[116:117], v[8:9]
	v_pk_fma_f32 v[10:11], v[198:199], v[118:119], v[10:11]
	v_pk_fma_f32 v[12:13], v[200:201], v[120:121], v[12:13]
	v_pk_fma_f32 v[14:15], v[202:203], v[122:123], v[14:15]
	v_pk_fma_f32 v[16:17], v[204:205], v[124:125], v[16:17]
	v_pk_fma_f32 v[18:19], v[206:207], v[100:101], v[18:19]
	s_lshl_b32 s60, s55, 12
	s_add_u32 s72, s84, s60
	s_addc_u32 s73, s85, 0
	global_store_dwordx4 v0, v[4:7], s[72:73] sc1
	global_store_dwordx4 v0, v[8:11], s[72:73] offset:1024 sc1
	global_store_dwordx4 v0, v[12:15], s[72:73] offset:2048 sc1
	global_store_dwordx4 v0, v[16:19], s[72:73] offset:3072 sc1
	s_add_u32 s55, s55, 8
	s_add_u32 s57, s55, 16
	s_min_u32 s57, s57, s54
	s_lshl_b32 s60, s57, 12
	s_add_u32 s64, s84, s60
	s_addc_u32 s65, s85, 0
	s_lshl_b32 s60, s57, 11
	s_add_u32 s66, s82, s60
	s_addc_u32 s67, s83, 0
	s_lshl_b32 s60, s57, 11
	s_add_u32 s68, s78, s60
	s_addc_u32 s69, s79, 0
	global_load_dwordx4 v[4:7], v0, s[64:65] nt
	global_load_dwordx4 v[8:11], v0, s[64:65] offset:1024 nt
	global_load_dwordx4 v[12:15], v0, s[64:65] offset:2048 nt
	global_load_dwordx4 v[16:19], v0, s[64:65] offset:3072 nt
	global_load_dwordx2 v[20:21], v1, s[66:67] nt
	global_load_dwordx2 v[22:23], v1, s[66:67] offset:512 nt
	global_load_dwordx2 v[24:25], v1, s[66:67] offset:1024 nt
	global_load_dwordx2 v[26:27], v1, s[66:67] offset:1536 nt
	global_load_dwordx2 v[28:29], v1, s[68:69] nt
	global_load_dwordx2 v[30:31], v1, s[68:69] offset:512 nt
	global_load_dwordx2 v[32:33], v1, s[68:69] offset:1024 nt
	global_load_dwordx2 v[34:35], v1, s[68:69] offset:1536 nt
	s_lshr_b32 s60, s55, 11
	s_sub_u32 s61, s55, 0x8000
	s_lshr_b32 s61, s61, 12
	s_add_u32 s61, s61, 16
	s_cmp_lt_u32 s55, 0x8000
	s_cselect_b32 s63, s60, s61
	s_cmp_eq_u32 s63, s56
	s_cbranch_scc1 .Lrp15_pk8
	s_mov_b32 s56, s63
	s_mul_i32 s60, s56, 0x9000
	s_add_u32 s60, s60, 0x3185000
	s_add_u32 s0, s92, s60
	s_addc_u32 s1, s93, 0
	global_load_dwordx4 v[160:163], v0, s[0:1]
	global_load_dwordx4 v[164:167], v0, s[0:1] offset:1024
	global_load_dwordx4 v[168:171], v0, s[0:1] offset:2048
	global_load_dwordx4 v[172:175], v0, s[0:1] offset:3072
	s_add_u32 s0, s22, 0x1000
	s_addc_u32 s1, s23, 0
	global_load_dwordx4 v[176:179], v0, s[0:1]
	global_load_dwordx4 v[180:183], v0, s[0:1] offset:1024
	global_load_dwordx4 v[184:187], v0, s[0:1] offset:2048
	global_load_dwordx4 v[188:191], v0, s[0:1] offset:3072
	s_mul_i32 s60, s56, 0x9000
	s_add_u32 s60, s60, 0x3188000
	s_add_u32 s0, s92, s60
	s_addc_u32 s1, s93, 0
	global_load_dwordx4 v[192:195], v0, s[0:1]
	global_load_dwordx4 v[196:199], v0, s[0:1] offset:1024
	global_load_dwordx4 v[200:203], v0, s[0:1] offset:2048
	global_load_dwordx4 v[204:207], v0, s[0:1] offset:3072
	s_add_u32 s0, s22, 0x2000
	s_addc_u32 s1, s23, 0
	global_load_dwordx4 v[208:211], v0, s[0:1]
	global_load_dwordx4 v[212:215], v0, s[0:1] offset:1024
	global_load_dwordx4 v[216:219], v0, s[0:1] offset:2048
	global_load_dwordx4 v[220:223], v0, s[0:1] offset:3072
	s_waitcnt vmcnt(0)
; __device__ __forceinline__ float lo_bf(unsigned w) { return __uint_as_float(w << 16); }
; __device__ __forceinline__ float hi_bf(unsigned w) { return __uint_as_float(w & 0xffff0000u); }
; __device__ __forceinline__ void phase_final(const Params& p) {
;     ...
;         const int b = row_batch(row);
;         f32x4 v[4], m[4], f[4]; float sm = 0.f, sf = 0.f;
; #pragma unroll
;         for (int j = 0; j < 4; ++j) { v[j] = *(const f32x4*)(p.out + (size_t)row * D + 4 * lane + 256 * j);
;             const u32x2 wm = *(const u32x2*)(Fm + (size_t)row * D + 4 * lane + 256 * j), wf = *(const u32x2*)(F2 + (size_t)row * D + 4 * lane + 256 * j);
;             m[j] = (f32x4){lo_bf(wm.x), hi_bf(wm.x), lo_bf(wm.y), hi_bf(wm.y)}; f[j] = (f32x4){lo_bf(wf.x), hi_bf(wf.x), lo_bf(wf.y), hi_bf(wf.y)};
;             sm += (m[j].x * m[j].x + m[j].y * m[j].y) + (m[j].z * m[j].z + m[j].w * m[j].w); sf += (f[j].x * f[j].x + f[j].y * f[j].y) + (f[j].z * f[j].z + f[j].w * f[j].w); }
;         const float rm = 1.0f / sqrtf(wave_sum(sm) * (1.0f / D) + EPS), rf = 1.0f / sqrtf(wave_sum(sf) * (1.0f / D) + EPS) * 0.5f;
.Lrp15_pk8:
	s_waitcnt vmcnt(32)
	v_lshlrev_b32_e32 v112, 16, v52
	v_and_b32_e32 v113, 0xffff0000, v52
	v_lshlrev_b32_e32 v114, 16, v53
	v_and_b32_e32 v115, 0xffff0000, v53
	v_lshlrev_b32_e32 v116, 16, v54
	v_and_b32_e32 v117, 0xffff0000, v54
	v_lshlrev_b32_e32 v118, 16, v55
	v_and_b32_e32 v119, 0xffff0000, v55
	v_lshlrev_b32_e32 v120, 16, v56
	v_and_b32_e32 v121, 0xffff0000, v56
	v_lshlrev_b32_e32 v122, 16, v57
	v_and_b32_e32 v123, 0xffff0000, v57
	v_lshlrev_b32_e32 v124, 16, v58
	v_and_b32_e32 v125, 0xffff0000, v58
	v_lshlrev_b32_e32 v100, 16, v59
	v_and_b32_e32 v101, 0xffff0000, v59
	v_pk_mul_f32 v[102:103], v[112:113], v[112:113]
	v_pk_mul_f32 v[106:107], v[114:115], v[114:115]
	v_pk_fma_f32 v[102:103], v[116:117], v[116:117], v[102:103]
	v_pk_fma_f32 v[106:107], v[118:119], v[118:119], v[106:107]
	v_pk_fma_f32 v[102:103], v[120:121], v[120:121], v[102:103]
	v_pk_fma_f32 v[106:107], v[122:123], v[122:123], v[106:107]
	v_pk_fma_f32 v[102:103], v[124:125], v[124:125], v[102:103]
	v_pk_fma_f32 v[106:107], v[100:101], v[100:101], v[106:107]
	s_nop 0
	v_pk_add_f32 v[102:103], v[102:103], v[106:107]
	s_nop 0
	v_add_f32_e32 v102, v102, v103
	v_mov_b32_e32 v104, v102
	v_lshlrev_b32_e32 v112, 16, v60
	v_and_b32_e32 v113, 0xffff0000, v60
	v_lshlrev_b32_e32 v114, 16, v61
	v_and_b32_e32 v115, 0xffff0000, v61
	v_lshlrev_b32_e32 v116, 16, v62
	v_and_b32_e32 v117, 0xffff0000, v62
	v_lshlrev_b32_e32 v118, 16, v63
	v_and_b32_e32 v119, 0xffff0000, v63
	v_lshlrev_b32_e32 v120, 16, v64
	v_and_b32_e32 v121, 0xffff0000, v64
	v_lshlrev_b32_e32 v122, 16, v65
	v_and_b32_e32 v123, 0xffff0000, v65
	v_lshlrev_b32_e32 v124, 16, v66
	v_and_b32_e32 v125, 0xffff0000, v66
	v_lshlrev_b32_e32 v100, 16, v67
	v_and_b32_e32 v101, 0xffff0000, v67
	v_pk_mul_f32 v[102:103], v[112:113], v[112:113]
	v_pk_mul_f32 v[106:107], v[114:115], v[114:115]
	v_pk_fma_f32 v[102:103], v[116:117], v[116:117], v[102:103]
	v_pk_fma_f32 v[106:107], v[118:119], v[118:119], v[106:107]
	v_pk_fma_f32 v[102:103], v[120:121], v[120:121], v[102:103]
	v_pk_fma_f32 v[106:107], v[122:123], v[122:123], v[106:107]
	v_pk_fma_f32 v[102:103], v[124:125], v[124:125], v[102:103]
	v_pk_fma_f32 v[106:107], v[100:101], v[100:101], v[106:107]
	s_nop 0
	v_pk_add_f32 v[102:103], v[102:103], v[106:107]
	s_nop 0
	v_add_f32_e32 v102, v102, v103
	s_nop 1
	v_add_f32_dpp v104, v104, v104 quad_perm:[1,0,3,2] row_mask:0xf bank_mask:0xf
	v_add_f32_dpp v102, v102, v102 quad_perm:[1,0,3,2] row_mask:0xf bank_mask:0xf
	s_nop 1
	v_add_f32_dpp v104, v104, v104 quad_perm:[2,3,0,1] row_mask:0xf bank_mask:0xf
	v_add_f32_dpp v102, v102, v102 quad_perm:[2,3,0,1] row_mask:0xf bank_mask:0xf
	s_nop 1
	v_add_f32_dpp v104, v104, v104 row_half_mirror row_mask:0xf bank_mask:0xf
	v_add_f32_dpp v102, v102, v102 row_half_mirror row_mask:0xf bank_mask:0xf
	s_nop 1
	v_add_f32_dpp v104, v104, v104 row_mirror row_mask:0xf bank_mask:0xf
	v_add_f32_dpp v102, v102, v102 row_mirror row_mask:0xf bank_mask:0xf
	s_nop 1
	v_add_f32_dpp v104, v104, v104 row_bcast:15 row_mask:0xa bank_mask:0xf
	v_add_f32_dpp v102, v102, v102 row_bcast:15 row_mask:0xa bank_mask:0xf
	s_nop 1
	v_add_f32_dpp v104, v104, v104 row_bcast:31 row_mask:0xc bank_mask:0xf
	v_add_f32_dpp v102, v102, v102 row_bcast:31 row_mask:0xc bank_mask:0xf
	s_nop 1
	v_readlane_b32 s74, v104, 63
	v_readlane_b32 s75, v102, 63
	s_nop 2
	v_mov_b32_e32 v102, s74
	v_fmamk_f32 v102, v102, 0x3a800000, v2
	v_mul_f32_e32 v103, 0x4f800000, v102
	v_cmp_gt_f32_e32 vcc, 0xf800000, v102
	s_nop 1
	v_cndmask_b32_e32 v102, v102, v103, vcc
	v_sqrt_f32_e32 v103, v102
	s_nop 0
	v_add_u32_e32 v104, -1, v103
	v_add_u32_e32 v106, 1, v103
	v_fma_f32 v107, -v104, v103, v102
	v_fma_f32 v108, -v106, v103, v102
	v_cmp_ge_f32_e64 s[76:77], 0, v107
	s_nop 1
	v_cndmask_b32_e64 v103, v103, v104, s[76:77]
	v_cmp_lt_f32_e64 s[76:77], 0, v108
	s_nop 1
	v_cndmask_b32_e64 v103, v103, v106, s[76:77]
	v_mul_f32_e32 v104, 0x37800000, v103
	v_cndmask_b32_e32 v103, v103, v104, vcc
	v_cmp_class_f32_e32 vcc, v102, v3
	s_nop 1
	v_cndmask_b32_e32 v102, v103, v102, vcc
	v_div_scale_f32 v103, s[76:77], v102, v102, 1.0
	v_rcp_f32_e32 v104, v103
	v_div_scale_f32 v106, vcc, 1.0, v102, 1.0
	v_fma_f32 v107, -v103, v104, 1.0
	v_fmac_f32_e32 v104, v107, v104
	v_mul_f32_e32 v107, v106, v104
	v_fma_f32 v108, -v103, v107, v106
	v_fmac_f32_e32 v107, v108, v104
	v_fma_f32 v103, -v103, v107, v106
	v_div_fmas_f32 v103, v103, v104, v107
	v_div_fixup_f32 v110, v103, v102, 1.0
	v_mov_b32_e32 v102, s75
	v_fmamk_f32 v102, v102, 0x3a800000, v2
	v_mul_f32_e32 v103, 0x4f800000, v102
	v_cmp_gt_f32_e32 vcc, 0xf800000, v102
	s_nop 1
	v_cndmask_b32_e32 v102, v102, v103, vcc
	v_sqrt_f32_e32 v103, v102
	s_nop 0
	v_add_u32_e32 v104, -1, v103
	v_add_u32_e32 v106, 1, v103
	v_fma_f32 v107, -v104, v103, v102
	v_fma_f32 v108, -v106, v103, v102
	v_cmp_ge_f32_e64 s[76:77], 0, v107
	s_nop 1
	v_cndmask_b32_e64 v103, v103, v104, s[76:77]
	v_cmp_lt_f32_e64 s[76:77], 0, v108
	s_nop 1
	v_cndmask_b32_e64 v103, v103, v106, s[76:77]
	v_mul_f32_e32 v104, 0x37800000, v103
	v_cndmask_b32_e32 v103, v103, v104, vcc
	v_cmp_class_f32_e32 vcc, v102, v3
	s_nop 1
	v_cndmask_b32_e32 v102, v103, v102, vcc
	v_div_scale_f32 v103, s[76:77], v102, v102, 1.0
	v_rcp_f32_e32 v104, v103
	v_div_scale_f32 v106, vcc, 1.0, v102, 1.0
	v_fma_f32 v107, -v103, v104, 1.0
	v_fmac_f32_e32 v104, v107, v104
	v_mul_f32_e32 v107, v106, v104
	v_fma_f32 v108, -v103, v107, v106
	v_fmac_f32_e32 v107, v108, v104
	v_fma_f32 v103, -v103, v107, v106
	v_div_fmas_f32 v103, v103, v104, v107
	v_div_fixup_f32 v108, v103, v102, 1.0
	v_mul_f32_e32 v108, 0.5, v108
	v_pk_mul_f32 v[112:113], v[112:113], v[108:109] op_sel_hi:[1,0]
; __device__ __forceinline__ float lo_bf(unsigned w) { return __uint_as_float(w << 16); }
; __device__ __forceinline__ float hi_bf(unsigned w) { return __uint_as_float(w & 0xffff0000u); }
; __device__ __forceinline__ void phase_final(const Params& p) {
;     ...
;     for (int row = gw; row < T; row += NGW) {
;         const int b = row_batch(row);
;         f32x4 v[4], m[4], f[4]; float sm = 0.f, sf = 0.f;
; #pragma unroll
;         for (int j = 0; j < 4; ++j) { v[j] = *(const f32x4*)(p.out + (size_t)row * D + 4 * lane + 256 * j);
;             const u32x2 wm = *(const u32x2*)(Fm + (size_t)row * D + 4 * lane + 256 * j), wf = *(const u32x2*)(F2 + (size_t)row * D + 4 * lane + 256 * j);
;             m[j] = (f32x4){lo_bf(wm.x), hi_bf(wm.x), lo_bf(wm.y), hi_bf(wm.y)}; f[j] = (f32x4){lo_bf(wf.x), hi_bf(wf.x), lo_bf(wf.y), hi_bf(wf.y)};
;             sm += (m[j].x * m[j].x + m[j].y * m[j].y) + (m[j].z * m[j].z + m[j].w * m[j].w); sf += (f[j].x * f[j].x + f[j].y * f[j].y) + (f[j].z * f[j].z + f[j].w * f[j].w); }
;         const float rm = 1.0f / sqrtf(wave_sum(sm) * (1.0f / D) + EPS), rf = 1.0f / sqrtf(wave_sum(sf) * (1.0f / D) + EPS) * 0.5f;
;         const float* g1 = mod + b * 9216 + 1 * 3072 + 2048; const float* g2 = mod + b * 9216 + 2 * 3072 + 2048;
;         const float* q1 = p.in[7] + 1 * D; const float* q2 = p.in[7] + 2 * D;
; #pragma unroll
;         for (int j = 0; j < 4; ++j) { const int c = 4 * lane + 256 * j;
;             const f32x4 x2 = v[j] + *(const f32x4*)(g1 + c) * (m[j] * rm * *(const f32x4*)(q1 + c));
;             *(f32x4*)(p.out + (size_t)row * D + c) = x2 + *(const f32x4*)(g2 + c) * (f[j] * rf * *(const f32x4*)(q2 + c)); }
;     }
	v_pk_mul_f32 v[114:115], v[114:115], v[108:109] op_sel_hi:[1,0]
	v_pk_mul_f32 v[116:117], v[116:117], v[108:109] op_sel_hi:[1,0]
	v_pk_mul_f32 v[118:119], v[118:119], v[108:109] op_sel_hi:[1,0]
	v_pk_mul_f32 v[120:121], v[120:121], v[108:109] op_sel_hi:[1,0]
	v_pk_mul_f32 v[122:123], v[122:123], v[108:109] op_sel_hi:[1,0]
	v_pk_mul_f32 v[124:125], v[124:125], v[108:109] op_sel_hi:[1,0]
	v_pk_mul_f32 v[100:101], v[100:101], v[108:109] op_sel_hi:[1,0]
	v_pk_mul_f32 v[112:113], v[112:113], v[208:209]
	v_pk_mul_f32 v[114:115], v[114:115], v[210:211]
	v_pk_mul_f32 v[116:117], v[116:117], v[212:213]
	v_pk_mul_f32 v[118:119], v[118:119], v[214:215]
	v_pk_mul_f32 v[120:121], v[120:121], v[216:217]
	v_pk_mul_f32 v[122:123], v[122:123], v[218:219]
	v_pk_mul_f32 v[124:125], v[124:125], v[220:221]
	v_pk_mul_f32 v[100:101], v[100:101], v[222:223]
	v_lshlrev_b32_e32 v60, 16, v52
	v_and_b32_e32 v61, 0xffff0000, v52
	v_lshlrev_b32_e32 v62, 16, v53
	v_and_b32_e32 v63, 0xffff0000, v53
	v_lshlrev_b32_e32 v64, 16, v54
	v_and_b32_e32 v65, 0xffff0000, v54
	v_lshlrev_b32_e32 v66, 16, v55
	v_and_b32_e32 v67, 0xffff0000, v55
	v_lshlrev_b32_e32 v240, 16, v56
	v_and_b32_e32 v241, 0xffff0000, v56
	v_lshlrev_b32_e32 v242, 16, v57
	v_and_b32_e32 v243, 0xffff0000, v57
	v_lshlrev_b32_e32 v244, 16, v58
	v_and_b32_e32 v245, 0xffff0000, v58
	v_lshlrev_b32_e32 v246, 16, v59
	v_and_b32_e32 v247, 0xffff0000, v59
	v_pk_mul_f32 v[60:61], v[60:61], v[110:111] op_sel_hi:[1,0]
	v_pk_mul_f32 v[62:63], v[62:63], v[110:111] op_sel_hi:[1,0]
	v_pk_mul_f32 v[64:65], v[64:65], v[110:111] op_sel_hi:[1,0]
	v_pk_mul_f32 v[66:67], v[66:67], v[110:111] op_sel_hi:[1,0]
	v_pk_mul_f32 v[240:241], v[240:241], v[110:111] op_sel_hi:[1,0]
	v_pk_mul_f32 v[242:243], v[242:243], v[110:111] op_sel_hi:[1,0]
	v_pk_mul_f32 v[244:245], v[244:245], v[110:111] op_sel_hi:[1,0]
	v_pk_mul_f32 v[246:247], v[246:247], v[110:111] op_sel_hi:[1,0]
	v_pk_mul_f32 v[60:61], v[60:61], v[176:177]
	v_pk_mul_f32 v[62:63], v[62:63], v[178:179]
	v_pk_mul_f32 v[64:65], v[64:65], v[180:181]
	v_pk_mul_f32 v[66:67], v[66:67], v[182:183]
	v_pk_mul_f32 v[240:241], v[240:241], v[184:185]
	v_pk_mul_f32 v[242:243], v[242:243], v[186:187]
	v_pk_mul_f32 v[244:245], v[244:245], v[188:189]
	v_pk_mul_f32 v[246:247], v[246:247], v[190:191]
	v_pk_fma_f32 v[36:37], v[160:161], v[60:61], v[36:37]
	v_pk_fma_f32 v[38:39], v[162:163], v[62:63], v[38:39]
	v_pk_fma_f32 v[40:41], v[164:165], v[64:65], v[40:41]
	v_pk_fma_f32 v[42:43], v[166:167], v[66:67], v[42:43]
	v_pk_fma_f32 v[44:45], v[168:169], v[240:241], v[44:45]
	v_pk_fma_f32 v[46:47], v[170:171], v[242:243], v[46:47]
	v_pk_fma_f32 v[48:49], v[172:173], v[244:245], v[48:49]
	v_pk_fma_f32 v[50:51], v[174:175], v[246:247], v[50:51]
	v_pk_fma_f32 v[36:37], v[192:193], v[112:113], v[36:37]
	v_pk_fma_f32 v[38:39], v[194:195], v[114:115], v[38:39]
	v_pk_fma_f32 v[40:41], v[196:197], v[116:117], v[40:41]
	v_pk_fma_f32 v[42:43], v[198:199], v[118:119], v[42:43]
	v_pk_fma_f32 v[44:45], v[200:201], v[120:121], v[44:45]
	v_pk_fma_f32 v[46:47], v[202:203], v[122:123], v[46:47]
	v_pk_fma_f32 v[48:49], v[204:205], v[124:125], v[48:49]
	v_pk_fma_f32 v[50:51], v[206:207], v[100:101], v[50:51]
	s_lshl_b32 s60, s55, 12
	s_add_u32 s72, s84, s60
	s_addc_u32 s73, s85, 0
	global_store_dwordx4 v0, v[36:39], s[72:73] sc1
	global_store_dwordx4 v0, v[40:43], s[72:73] offset:1024 sc1
	global_store_dwordx4 v0, v[44:47], s[72:73] offset:2048 sc1
	global_store_dwordx4 v0, v[48:51], s[72:73] offset:3072 sc1
	s_add_u32 s55, s55, 8
	s_add_u32 s57, s55, 16
	s_min_u32 s57, s57, s54
	s_lshl_b32 s60, s57, 12
	s_add_u32 s64, s84, s60
	s_addc_u32 s65, s85, 0
	s_lshl_b32 s60, s57, 11
	s_add_u32 s66, s82, s60
	s_addc_u32 s67, s83, 0
	s_lshl_b32 s60, s57, 11
	s_add_u32 s68, s78, s60
	s_addc_u32 s69, s79, 0
	global_load_dwordx4 v[36:39], v0, s[64:65] nt
	global_load_dwordx4 v[40:43], v0, s[64:65] offset:1024 nt
	global_load_dwordx4 v[44:47], v0, s[64:65] offset:2048 nt
	global_load_dwordx4 v[48:51], v0, s[64:65] offset:3072 nt
	global_load_dwordx2 v[52:53], v1, s[66:67] nt
	global_load_dwordx2 v[54:55], v1, s[66:67] offset:512 nt
	global_load_dwordx2 v[56:57], v1, s[66:67] offset:1024 nt
	global_load_dwordx2 v[58:59], v1, s[66:67] offset:1536 nt
	global_load_dwordx2 v[60:61], v1, s[68:69] nt
	global_load_dwordx2 v[62:63], v1, s[68:69] offset:512 nt
	global_load_dwordx2 v[64:65], v1, s[68:69] offset:1024 nt
	global_load_dwordx2 v[66:67], v1, s[68:69] offset:1536 nt
	s_lshr_b32 s60, s55, 11
	s_sub_u32 s61, s55, 0x8000
	s_lshr_b32 s61, s61, 12
	s_add_u32 s61, s61, 16
	s_cmp_lt_u32 s55, 0x8000
	s_cselect_b32 s63, s60, s61
	s_cmp_eq_u32 s63, s56
	s_cbranch_scc1 .Lrp15_pk9
	s_mov_b32 s56, s63
	s_mul_i32 s60, s56, 0x9000
	s_add_u32 s60, s60, 0x3185000
	s_add_u32 s0, s92, s60
	s_addc_u32 s1, s93, 0
	global_load_dwordx4 v[160:163], v0, s[0:1]
	global_load_dwordx4 v[164:167], v0, s[0:1] offset:1024
	global_load_dwordx4 v[168:171], v0, s[0:1] offset:2048
	global_load_dwordx4 v[172:175], v0, s[0:1] offset:3072
	s_add_u32 s0, s22, 0x1000
	s_addc_u32 s1, s23, 0
	global_load_dwordx4 v[176:179], v0, s[0:1]
	global_load_dwordx4 v[180:183], v0, s[0:1] offset:1024
	global_load_dwordx4 v[184:187], v0, s[0:1] offset:2048
	global_load_dwordx4 v[188:191], v0, s[0:1] offset:3072
	s_mul_i32 s60, s56, 0x9000
	s_add_u32 s60, s60, 0x3188000
	s_add_u32 s0, s92, s60
	s_addc_u32 s1, s93, 0
	global_load_dwordx4 v[192:195], v0, s[0:1]
	global_load_dwordx4 v[196:199], v0, s[0:1] offset:1024
	global_load_dwordx4 v[200:203], v0, s[0:1] offset:2048
	global_load_dwordx4 v[204:207], v0, s[0:1] offset:3072
	s_add_u32 s0, s22, 0x2000
	s_addc_u32 s1, s23, 0
	global_load_dwordx4 v[208:211], v0, s[0:1]
	global_load_dwordx4 v[212:215], v0, s[0:1] offset:1024
	global_load_dwordx4 v[216:219], v0, s[0:1] offset:2048
	global_load_dwordx4 v[220:223], v0, s[0:1] offset:3072
	s_waitcnt vmcnt(0)
; __device__ __forceinline__ float lo_bf(unsigned w) { return __uint_as_float(w << 16); }
; __device__ __forceinline__ float hi_bf(unsigned w) { return __uint_as_float(w & 0xffff0000u); }
; __device__ __forceinline__ void phase_final(const Params& p) {
;     ...
;         const int b = row_batch(row);
;         f32x4 v[4], m[4], f[4]; float sm = 0.f, sf = 0.f;
; #pragma unroll
;         for (int j = 0; j < 4; ++j) { v[j] = *(const f32x4*)(p.out + (size_t)row * D + 4 * lane + 256 * j);
;             const u32x2 wm = *(const u32x2*)(Fm + (size_t)row * D + 4 * lane + 256 * j), wf = *(const u32x2*)(F2 + (size_t)row * D + 4 * lane + 256 * j);
;             m[j] = (f32x4){lo_bf(wm.x), hi_bf(wm.x), lo_bf(wm.y), hi_bf(wm.y)}; f[j] = (f32x4){lo_bf(wf.x), hi_bf(wf.x), lo_bf(wf.y), hi_bf(wf.y)};
;             sm += (m[j].x * m[j].x + m[j].y * m[j].y) + (m[j].z * m[j].z + m[j].w * m[j].w); sf += (f[j].x * f[j].x + f[j].y * f[j].y) + (f[j].z * f[j].z + f[j].w * f[j].w); }
;         const float rm = 1.0f / sqrtf(wave_sum(sm) * (1.0f / D) + EPS), rf = 1.0f / sqrtf(wave_sum(sf) * (1.0f / D) + EPS) * 0.5f;
.Lrp15_pk9:
	s_waitcnt vmcnt(32)
	v_lshlrev_b32_e32 v112, 16, v84
	v_and_b32_e32 v113, 0xffff0000, v84
	v_lshlrev_b32_e32 v114, 16, v85
	v_and_b32_e32 v115, 0xffff0000, v85
	v_lshlrev_b32_e32 v116, 16, v86
	v_and_b32_e32 v117, 0xffff0000, v86
	v_lshlrev_b32_e32 v118, 16, v87
	v_and_b32_e32 v119, 0xffff0000, v87
	v_lshlrev_b32_e32 v120, 16, v88
	v_and_b32_e32 v121, 0xffff0000, v88
	v_lshlrev_b32_e32 v122, 16, v89
	v_and_b32_e32 v123, 0xffff0000, v89
	v_lshlrev_b32_e32 v124, 16, v90
	v_and_b32_e32 v125, 0xffff0000, v90
	v_lshlrev_b32_e32 v100, 16, v91
	v_and_b32_e32 v101, 0xffff0000, v91
	v_pk_mul_f32 v[102:103], v[112:113], v[112:113]
	v_pk_mul_f32 v[106:107], v[114:115], v[114:115]
	v_pk_fma_f32 v[102:103], v[116:117], v[116:117], v[102:103]
	v_pk_fma_f32 v[106:107], v[118:119], v[118:119], v[106:107]
	v_pk_fma_f32 v[102:103], v[120:121], v[120:121], v[102:103]
	v_pk_fma_f32 v[106:107], v[122:123], v[122:123], v[106:107]
	v_pk_fma_f32 v[102:103], v[124:125], v[124:125], v[102:103]
	v_pk_fma_f32 v[106:107], v[100:101], v[100:101], v[106:107]
	s_nop 0
	v_pk_add_f32 v[102:103], v[102:103], v[106:107]
	s_nop 0
	v_add_f32_e32 v102, v102, v103
	v_mov_b32_e32 v104, v102
	v_lshlrev_b32_e32 v112, 16, v92
	v_and_b32_e32 v113, 0xffff0000, v92
	v_lshlrev_b32_e32 v114, 16, v93
	v_and_b32_e32 v115, 0xffff0000, v93
	v_lshlrev_b32_e32 v116, 16, v94
	v_and_b32_e32 v117, 0xffff0000, v94
	v_lshlrev_b32_e32 v118, 16, v95
	v_and_b32_e32 v119, 0xffff0000, v95
	v_lshlrev_b32_e32 v120, 16, v96
	v_and_b32_e32 v121, 0xffff0000, v96
	v_lshlrev_b32_e32 v122, 16, v97
	v_and_b32_e32 v123, 0xffff0000, v97
	v_lshlrev_b32_e32 v124, 16, v98
	v_and_b32_e32 v125, 0xffff0000, v98
	v_lshlrev_b32_e32 v100, 16, v99
	v_and_b32_e32 v101, 0xffff0000, v99
	v_pk_mul_f32 v[102:103], v[112:113], v[112:113]
	v_pk_mul_f32 v[106:107], v[114:115], v[114:115]
	v_pk_fma_f32 v[102:103], v[116:117], v[116:117], v[102:103]
	v_pk_fma_f32 v[106:107], v[118:119], v[118:119], v[106:107]
	v_pk_fma_f32 v[102:103], v[120:121], v[120:121], v[102:103]
	v_pk_fma_f32 v[106:107], v[122:123], v[122:123], v[106:107]
	v_pk_fma_f32 v[102:103], v[124:125], v[124:125], v[102:103]
	v_pk_fma_f32 v[106:107], v[100:101], v[100:101], v[106:107]
	s_nop 0
	v_pk_add_f32 v[102:103], v[102:103], v[106:107]
	s_nop 0
	v_add_f32_e32 v102, v102, v103
	s_nop 1
	v_add_f32_dpp v104, v104, v104 quad_perm:[1,0,3,2] row_mask:0xf bank_mask:0xf
	v_add_f32_dpp v102, v102, v102 quad_perm:[1,0,3,2] row_mask:0xf bank_mask:0xf
	s_nop 1
	v_add_f32_dpp v104, v104, v104 quad_perm:[2,3,0,1] row_mask:0xf bank_mask:0xf
	v_add_f32_dpp v102, v102, v102 quad_perm:[2,3,0,1] row_mask:0xf bank_mask:0xf
	s_nop 1
	v_add_f32_dpp v104, v104, v104 row_half_mirror row_mask:0xf bank_mask:0xf
	v_add_f32_dpp v102, v102, v102 row_half_mirror row_mask:0xf bank_mask:0xf
	s_nop 1
	v_add_f32_dpp v104, v104, v104 row_mirror row_mask:0xf bank_mask:0xf
	v_add_f32_dpp v102, v102, v102 row_mirror row_mask:0xf bank_mask:0xf
	s_nop 1
	v_add_f32_dpp v104, v104, v104 row_bcast:15 row_mask:0xa bank_mask:0xf
	v_add_f32_dpp v102, v102, v102 row_bcast:15 row_mask:0xa bank_mask:0xf
	s_nop 1
	v_add_f32_dpp v104, v104, v104 row_bcast:31 row_mask:0xc bank_mask:0xf
	v_add_f32_dpp v102, v102, v102 row_bcast:31 row_mask:0xc bank_mask:0xf
	s_nop 1
	v_readlane_b32 s74, v104, 63
	v_readlane_b32 s75, v102, 63
	s_nop 2
	v_mov_b32_e32 v102, s74
	v_fmamk_f32 v102, v102, 0x3a800000, v2
	v_mul_f32_e32 v103, 0x4f800000, v102
	v_cmp_gt_f32_e32 vcc, 0xf800000, v102
	s_nop 1
	v_cndmask_b32_e32 v102, v102, v103, vcc
	v_sqrt_f32_e32 v103, v102
	s_nop 0
	v_add_u32_e32 v104, -1, v103
	v_add_u32_e32 v106, 1, v103
	v_fma_f32 v107, -v104, v103, v102
	v_fma_f32 v108, -v106, v103, v102
	v_cmp_ge_f32_e64 s[76:77], 0, v107
	s_nop 1
	v_cndmask_b32_e64 v103, v103, v104, s[76:77]
	v_cmp_lt_f32_e64 s[76:77], 0, v108
	s_nop 1
	v_cndmask_b32_e64 v103, v103, v106, s[76:77]
	v_mul_f32_e32 v104, 0x37800000, v103
	v_cndmask_b32_e32 v103, v103, v104, vcc
	v_cmp_class_f32_e32 vcc, v102, v3
	s_nop 1
	v_cndmask_b32_e32 v102, v103, v102, vcc
	v_div_scale_f32 v103, s[76:77], v102, v102, 1.0
	v_rcp_f32_e32 v104, v103
	v_div_scale_f32 v106, vcc, 1.0, v102, 1.0
	v_fma_f32 v107, -v103, v104, 1.0
	v_fmac_f32_e32 v104, v107, v104
	v_mul_f32_e32 v107, v106, v104
	v_fma_f32 v108, -v103, v107, v106
	v_fmac_f32_e32 v107, v108, v104
	v_fma_f32 v103, -v103, v107, v106
	v_div_fmas_f32 v103, v103, v104, v107
	v_div_fixup_f32 v110, v103, v102, 1.0
	v_mov_b32_e32 v102, s75
	v_fmamk_f32 v102, v102, 0x3a800000, v2
	v_mul_f32_e32 v103, 0x4f800000, v102
	v_cmp_gt_f32_e32 vcc, 0xf800000, v102
	s_nop 1
	v_cndmask_b32_e32 v102, v102, v103, vcc
; __device__ __forceinline__ void phase_final(const Params& p) {
;     ...
;         const float rm = 1.0f / sqrtf(wave_sum(sm) * (1.0f / D) + EPS), rf = 1.0f / sqrtf(wave_sum(sf) * (1.0f / D) + EPS) * 0.5f;
;         const float* g1 = mod + b * 9216 + 1 * 3072 + 2048; const float* g2 = mod + b * 9216 + 2 * 3072 + 2048;
;         const float* q1 = p.in[7] + 1 * D; const float* q2 = p.in[7] + 2 * D;
; #pragma unroll
;         for (int j = 0; j < 4; ++j) { const int c = 4 * lane + 256 * j;
;             const f32x4 x2 = v[j] + *(const f32x4*)(g1 + c) * (m[j] * rm * *(const f32x4*)(q1 + c));
;             *(f32x4*)(p.out + (size_t)row * D + c) = x2 + *(const f32x4*)(g2 + c) * (f[j] * rf * *(const f32x4*)(q2 + c)); }
;     }
	v_sqrt_f32_e32 v103, v102
	s_nop 0
	v_add_u32_e32 v104, -1, v103
	v_add_u32_e32 v106, 1, v103
	v_fma_f32 v107, -v104, v103, v102
	v_fma_f32 v108, -v106, v103, v102
	v_cmp_ge_f32_e64 s[76:77], 0, v107
	s_nop 1
	v_cndmask_b32_e64 v103, v103, v104, s[76:77]
	v_cmp_lt_f32_e64 s[76:77], 0, v108
	s_nop 1
	v_cndmask_b32_e64 v103, v103, v106, s[76:77]
	v_mul_f32_e32 v104, 0x37800000, v103
	v_cndmask_b32_e32 v103, v103, v104, vcc
	v_cmp_class_f32_e32 vcc, v102, v3
	s_nop 1
	v_cndmask_b32_e32 v102, v103, v102, vcc
	v_div_scale_f32 v103, s[76:77], v102, v102, 1.0
	v_rcp_f32_e32 v104, v103
	v_div_scale_f32 v106, vcc, 1.0, v102, 1.0
	v_fma_f32 v107, -v103, v104, 1.0
	v_fmac_f32_e32 v104, v107, v104
	v_mul_f32_e32 v107, v106, v104
	v_fma_f32 v108, -v103, v107, v106
	v_fmac_f32_e32 v107, v108, v104
	v_fma_f32 v103, -v103, v107, v106
	v_div_fmas_f32 v103, v103, v104, v107
	v_div_fixup_f32 v108, v103, v102, 1.0
	v_mul_f32_e32 v108, 0.5, v108
	v_pk_mul_f32 v[112:113], v[112:113], v[108:109] op_sel_hi:[1,0]
	v_pk_mul_f32 v[114:115], v[114:115], v[108:109] op_sel_hi:[1,0]
	v_pk_mul_f32 v[116:117], v[116:117], v[108:109] op_sel_hi:[1,0]
	v_pk_mul_f32 v[118:119], v[118:119], v[108:109] op_sel_hi:[1,0]
	v_pk_mul_f32 v[120:121], v[120:121], v[108:109] op_sel_hi:[1,0]
	v_pk_mul_f32 v[122:123], v[122:123], v[108:109] op_sel_hi:[1,0]
	v_pk_mul_f32 v[124:125], v[124:125], v[108:109] op_sel_hi:[1,0]
	v_pk_mul_f32 v[100:101], v[100:101], v[108:109] op_sel_hi:[1,0]
	v_pk_mul_f32 v[112:113], v[112:113], v[208:209]
	v_pk_mul_f32 v[114:115], v[114:115], v[210:211]
	v_pk_mul_f32 v[116:117], v[116:117], v[212:213]
	v_pk_mul_f32 v[118:119], v[118:119], v[214:215]
	v_pk_mul_f32 v[120:121], v[120:121], v[216:217]
	v_pk_mul_f32 v[122:123], v[122:123], v[218:219]
	v_pk_mul_f32 v[124:125], v[124:125], v[220:221]
	v_pk_mul_f32 v[100:101], v[100:101], v[222:223]
	v_lshlrev_b32_e32 v92, 16, v84
	v_and_b32_e32 v93, 0xffff0000, v84
	v_lshlrev_b32_e32 v94, 16, v85
	v_and_b32_e32 v95, 0xffff0000, v85
	v_lshlrev_b32_e32 v96, 16, v86
	v_and_b32_e32 v97, 0xffff0000, v86
	v_lshlrev_b32_e32 v98, 16, v87
	v_and_b32_e32 v99, 0xffff0000, v87
	v_lshlrev_b32_e32 v240, 16, v88
	v_and_b32_e32 v241, 0xffff0000, v88
	v_lshlrev_b32_e32 v242, 16, v89
	v_and_b32_e32 v243, 0xffff0000, v89
	v_lshlrev_b32_e32 v244, 16, v90
	v_and_b32_e32 v245, 0xffff0000, v90
	v_lshlrev_b32_e32 v246, 16, v91
	v_and_b32_e32 v247, 0xffff0000, v91
	v_pk_mul_f32 v[92:93], v[92:93], v[110:111] op_sel_hi:[1,0]
	v_pk_mul_f32 v[94:95], v[94:95], v[110:111] op_sel_hi:[1,0]
	v_pk_mul_f32 v[96:97], v[96:97], v[110:111] op_sel_hi:[1,0]
	v_pk_mul_f32 v[98:99], v[98:99], v[110:111] op_sel_hi:[1,0]
	v_pk_mul_f32 v[240:241], v[240:241], v[110:111] op_sel_hi:[1,0]
	v_pk_mul_f32 v[242:243], v[242:243], v[110:111] op_sel_hi:[1,0]
	v_pk_mul_f32 v[244:245], v[244:245], v[110:111] op_sel_hi:[1,0]
	v_pk_mul_f32 v[246:247], v[246:247], v[110:111] op_sel_hi:[1,0]
	v_pk_mul_f32 v[92:93], v[92:93], v[176:177]
	v_pk_mul_f32 v[94:95], v[94:95], v[178:179]
	v_pk_mul_f32 v[96:97], v[96:97], v[180:181]
	v_pk_mul_f32 v[98:99], v[98:99], v[182:183]
	v_pk_mul_f32 v[240:241], v[240:241], v[184:185]
	v_pk_mul_f32 v[242:243], v[242:243], v[186:187]
	v_pk_mul_f32 v[244:245], v[244:245], v[188:189]
	v_pk_mul_f32 v[246:247], v[246:247], v[190:191]
	v_pk_fma_f32 v[68:69], v[160:161], v[92:93], v[68:69]
	v_pk_fma_f32 v[70:71], v[162:163], v[94:95], v[70:71]
	v_pk_fma_f32 v[72:73], v[164:165], v[96:97], v[72:73]
	v_pk_fma_f32 v[74:75], v[166:167], v[98:99], v[74:75]
	v_pk_fma_f32 v[76:77], v[168:169], v[240:241], v[76:77]
	v_pk_fma_f32 v[78:79], v[170:171], v[242:243], v[78:79]
	v_pk_fma_f32 v[80:81], v[172:173], v[244:245], v[80:81]
	v_pk_fma_f32 v[82:83], v[174:175], v[246:247], v[82:83]
	v_pk_fma_f32 v[68:69], v[192:193], v[112:113], v[68:69]
	v_pk_fma_f32 v[70:71], v[194:195], v[114:115], v[70:71]
	v_pk_fma_f32 v[72:73], v[196:197], v[116:117], v[72:73]
	v_pk_fma_f32 v[74:75], v[198:199], v[118:119], v[74:75]
	v_pk_fma_f32 v[76:77], v[200:201], v[120:121], v[76:77]
	v_pk_fma_f32 v[78:79], v[202:203], v[122:123], v[78:79]
	v_pk_fma_f32 v[80:81], v[204:205], v[124:125], v[80:81]
	v_pk_fma_f32 v[82:83], v[206:207], v[100:101], v[82:83]
	s_lshl_b32 s60, s55, 12
	s_add_u32 s72, s84, s60
	s_addc_u32 s73, s85, 0
	global_store_dwordx4 v0, v[68:71], s[72:73] sc1
	global_store_dwordx4 v0, v[72:75], s[72:73] offset:1024 sc1
	global_store_dwordx4 v0, v[76:79], s[72:73] offset:2048 sc1
	global_store_dwordx4 v0, v[80:83], s[72:73] offset:3072 sc1
	s_add_u32 s55, s55, 8
	s_cmp_le_u32 s55, s54
	s_cbranch_scc1 .Lrp15_loop3
	s_add_u32 s51, s51, s52
	s_branch .Lrp15_chunk1
